# baseline (speedup 1.0000x reference)
; #define STAGE_A(P,br,kt) STAGE_G(P,c.A,c.lda,br,(long)(kt)*c.kstr)
; #define STAGE_B(P,br,kt) STAGE_G(P,c.Bt,c.K,br,(long)(kt)*BK)
; #define LDA(dst,b,h) for(int m=0;m<4;++m)for(int k=0;k<2;++k) \
;     dst[m][k]=*reinterpret_cast<const bf16x8*>((char*)SA(b,h)+lds_byte(wr*64+m*16+fr,k*32+fq*8))
; #define LDB(dst,b,h) for(int n=0;n<2;++n)for(int k=0;k<2;++k) \
;     dst[n][k]=*reinterpret_cast<const bf16x8*>((char*)SB(b,h)+lds_byte(wc*32+n*16+fr,k*32+fq*8))
; #define MMA(ai,bj,At,Bt_) do{__builtin_amdgcn_s_setprio(1); \
;     for(int m=0;m<4;++m)for(int n=0;n<2;++n)for(int k=0;k<2;++k) \
;       acc[ai][bj][m][n]=__builtin_amdgcn_mfma_f32_16x16x32_bf16(Bt_[n][k],At[m][k],acc[ai][bj][m][n],0,0,0); \
;     __builtin_amdgcn_s_setprio(0);}while(0)
; #define WAIT_V(n) asm volatile("s_waitcnt vmcnt(" #n ")":::"memory")
; #define WAIT_L(n) asm volatile("s_waitcnt lgkmcnt(" #n ")":::"memory")
; #define BAR __builtin_amdgcn_s_barrier()
; #define SCHED __builtin_amdgcn_sched_barrier(0)
; template <int EPI>
; __device__ __forceinline__ void gemm_run(const GD& c, const bool has_next, const GD& nx, const Ctx& e, bf16* shm, float* rs, float* rs_nxt, float* racc_) {
;     ...
;   for(int t=0;t<nt-2;t+=2){
;     LDB(B0,0,0); SCHED; LDA(At,0,0); STAGE_A(SA(1,1),brow+HALF,t+1);
;     WAIT_L(8); BAR; WAIT_L(0); MMA(0,0,At,B0); BAR; SCHED;
;     LDB(B1,0,1); STAGE_B(SB(0,0),bcol,t+2);
;     BAR; WAIT_L(0); MMA(0,1,At,B1); BAR;
;     LDA(At,0,1); STAGE_A(SA(0,0),brow,t+2);
;     BAR; WAIT_L(0); MMA(1,0,At,B0); BAR; SCHED;
;     STAGE_B(SB(0,1),bcol+HALF,t+2);
;     WAIT_V(6); BAR; MMA(1,1,At,B1); BAR;
.LBB0_267:
	ds_read_b128 v[158:161], v154
	ds_read_b128 v[166:169], v154 offset:1024
	ds_read_b128 v[170:173], v154 offset:2048
	ds_read_b128 v[190:193], v154 offset:3072
	v_add_u32_e32 v162, 0xc000, v141
	v_lshl_add_u64 v[174:175], s[4:5], 0, v[130:131]
	v_readfirstlane_b32 s3, v162
	v_add_u32_e32 v163, 0xe000, v141
	v_lshl_add_u64 v[156:157], v[174:175], 0, s[94:95]
	s_mov_b32 m0, s3
	v_lshl_add_u64 v[186:187], s[4:5], 0, v[132:133]
	v_readfirstlane_b32 s3, v163
	ds_read_b128 v[194:197], v145
	ds_read_b128 v[198:201], v145 offset:1024
	ds_read_b128 v[202:205], v144
	ds_read_b128 v[206:209], v144 offset:1024
	ds_read_b128 v[210:213], v143
	ds_read_b128 v[214:217], v143 offset:1024
	ds_read_b128 v[218:221], v142
	ds_read_b128 v[222:225], v142 offset:1024
	global_load_lds_dwordx4 v[156:157], off
	v_lshl_add_u64 v[156:157], v[186:187], 0, s[94:95]
	s_mov_b32 m0, s3
	s_nop 0
	global_load_lds_dwordx4 v[156:157], off
	s_waitcnt lgkmcnt(8)
	s_barrier
	s_waitcnt lgkmcnt(0)
	v_mfma_f32_16x16x32_bf16 v[126:129], v[158:161], v[194:197], v[126:129]
	v_mfma_f32_16x16x32_bf16 v[122:125], v[170:173], v[194:197], v[122:125]
	v_mfma_f32_16x16x32_bf16 v[118:121], v[158:161], v[202:205], v[118:121]
	v_mfma_f32_16x16x32_bf16 v[114:117], v[170:173], v[202:205], v[114:117]
	v_mfma_f32_16x16x32_bf16 v[110:113], v[158:161], v[210:213], v[110:113]
	v_mfma_f32_16x16x32_bf16 v[106:109], v[170:173], v[210:213], v[106:109]
	v_mfma_f32_16x16x32_bf16 v[102:105], v[158:161], v[218:221], v[102:105]
	v_mfma_f32_16x16x32_bf16 v[98:101], v[170:173], v[218:221], v[98:101]
	v_mfma_f32_16x16x32_bf16 v[126:129], v[166:169], v[198:201], v[126:129]
	v_mfma_f32_16x16x32_bf16 v[122:125], v[190:193], v[198:201], v[122:125]
	v_mfma_f32_16x16x32_bf16 v[118:121], v[166:169], v[206:209], v[118:121]
	v_mfma_f32_16x16x32_bf16 v[114:117], v[190:193], v[206:209], v[114:117]
	v_mfma_f32_16x16x32_bf16 v[110:113], v[166:169], v[214:217], v[110:113]
	v_mfma_f32_16x16x32_bf16 v[106:109], v[190:193], v[214:217], v[106:109]
	v_mfma_f32_16x16x32_bf16 v[102:105], v[166:169], v[222:225], v[102:105]
	v_mfma_f32_16x16x32_bf16 v[98:101], v[190:193], v[222:225], v[98:101]
	s_barrier
	v_add_u32_e32 v155, s33, v147
	v_lshl_add_u64 v[188:189], s[4:5], 0, v[136:137]
	v_readfirstlane_b32 s3, v155
	v_lshl_add_u64 v[156:157], v[188:189], 0, s[68:69]
	s_mov_b32 m0, s3
	ds_read_b128 v[226:229], v153
	ds_read_b128 v[230:233], v153 offset:1024
	ds_read_b128 v[234:237], v153 offset:2048
	ds_read_b128 v[238:241], v153 offset:3072
	global_load_lds_dwordx4 v[156:157], off
	v_add_u32_e32 v156, 0x2000, v155
	v_lshl_add_u64 v[246:247], s[4:5], 0, v[138:139]
	v_readfirstlane_b32 s3, v156
	v_lshl_add_u64 v[242:243], v[246:247], 0, s[68:69]
	s_mov_b32 m0, s3
	s_nop 0
	global_load_lds_dwordx4 v[242:243], off
	s_barrier
	s_waitcnt lgkmcnt(0)
	v_mfma_f32_16x16x32_bf16 v[94:97], v[226:229], v[194:197], v[94:97]
	v_mfma_f32_16x16x32_bf16 v[90:93], v[234:237], v[194:197], v[90:93]
	v_mfma_f32_16x16x32_bf16 v[86:89], v[226:229], v[202:205], v[86:89]
	v_mfma_f32_16x16x32_bf16 v[82:85], v[234:237], v[202:205], v[82:85]
	v_mfma_f32_16x16x32_bf16 v[78:81], v[226:229], v[210:213], v[78:81]
	v_mfma_f32_16x16x32_bf16 v[74:77], v[234:237], v[210:213], v[74:77]
	v_mfma_f32_16x16x32_bf16 v[70:73], v[226:229], v[218:221], v[70:73]
	v_mfma_f32_16x16x32_bf16 v[66:69], v[234:237], v[218:221], v[66:69]
	v_mfma_f32_16x16x32_bf16 v[94:97], v[230:233], v[198:201], v[94:97]
	v_mfma_f32_16x16x32_bf16 v[90:93], v[238:241], v[198:201], v[90:93]
	v_mfma_f32_16x16x32_bf16 v[86:89], v[230:233], v[206:209], v[86:89]
	v_mfma_f32_16x16x32_bf16 v[82:85], v[238:241], v[206:209], v[82:85]
	v_mfma_f32_16x16x32_bf16 v[78:81], v[230:233], v[214:217], v[78:81]
	v_mfma_f32_16x16x32_bf16 v[74:77], v[238:241], v[214:217], v[74:77]
	v_mfma_f32_16x16x32_bf16 v[70:73], v[230:233], v[222:225], v[70:73]
	v_mfma_f32_16x16x32_bf16 v[66:69], v[238:241], v[222:225], v[66:69]
	s_barrier
	v_readfirstlane_b32 s3, v141
	v_add_u32_e32 v157, 0x2000, v141
	v_lshl_add_u64 v[242:243], v[174:175], 0, s[84:85]
	s_mov_b32 m0, s3
	v_readfirstlane_b32 s3, v157
	ds_read_b128 v[194:197], v145 offset:16384
	ds_read_b128 v[198:201], v145 offset:17408
	ds_read_b128 v[202:205], v144 offset:16384
	ds_read_b128 v[206:209], v144 offset:17408
	ds_read_b128 v[210:213], v143 offset:16384
	ds_read_b128 v[214:217], v143 offset:17408
	ds_read_b128 v[218:221], v142 offset:16384
	ds_read_b128 v[222:225], v142 offset:17408
	global_load_lds_dwordx4 v[242:243], off
	v_lshl_add_u64 v[242:243], v[186:187], 0, s[84:85]
	s_mov_b32 m0, s3
	s_nop 0
	global_load_lds_dwordx4 v[242:243], off
	s_barrier
	s_waitcnt lgkmcnt(0)
	v_mfma_f32_16x16x32_bf16 v[62:65], v[158:161], v[194:197], v[62:65]
	v_mfma_f32_16x16x32_bf16 v[58:61], v[170:173], v[194:197], v[58:61]
	v_mfma_f32_16x16x32_bf16 v[54:57], v[158:161], v[202:205], v[54:57]
	v_mfma_f32_16x16x32_bf16 v[50:53], v[170:173], v[202:205], v[50:53]
	v_mfma_f32_16x16x32_bf16 v[46:49], v[158:161], v[210:213], v[46:49]
	v_mfma_f32_16x16x32_bf16 v[42:45], v[170:173], v[210:213], v[42:45]
	v_mfma_f32_16x16x32_bf16 v[38:41], v[158:161], v[218:221], v[38:41]
	v_mfma_f32_16x16x32_bf16 v[34:37], v[170:173], v[218:221], v[34:37]
	v_mfma_f32_16x16x32_bf16 v[62:65], v[166:169], v[198:201], v[62:65]
	v_mfma_f32_16x16x32_bf16 v[58:61], v[190:193], v[198:201], v[58:61]
	v_mfma_f32_16x16x32_bf16 v[54:57], v[166:169], v[206:209], v[54:57]
	v_mfma_f32_16x16x32_bf16 v[50:53], v[190:193], v[206:209], v[50:53]
	v_mfma_f32_16x16x32_bf16 v[46:49], v[166:169], v[214:217], v[46:49]
	v_mfma_f32_16x16x32_bf16 v[42:45], v[190:193], v[214:217], v[42:45]
	v_mfma_f32_16x16x32_bf16 v[38:41], v[166:169], v[222:225], v[38:41]
	v_mfma_f32_16x16x32_bf16 v[34:37], v[190:193], v[222:225], v[34:37]
	s_barrier
; #define STAGE_A(P,br,kt) STAGE_G(P,c.A,c.lda,br,(long)(kt)*c.kstr)
; #define STAGE_B(P,br,kt) STAGE_G(P,c.Bt,c.K,br,(long)(kt)*BK)
; #define LDA(dst,b,h) for(int m=0;m<4;++m)for(int k=0;k<2;++k) \
;     dst[m][k]=*reinterpret_cast<const bf16x8*>((char*)SA(b,h)+lds_byte(wr*64+m*16+fr,k*32+fq*8))
; #define LDB(dst,b,h) for(int n=0;n<2;++n)for(int k=0;k<2;++k) \
;     dst[n][k]=*reinterpret_cast<const bf16x8*>((char*)SB(b,h)+lds_byte(wc*32+n*16+fr,k*32+fq*8))
; #define MMA(ai,bj,At,Bt_) do{__builtin_amdgcn_s_setprio(1); \
;     for(int m=0;m<4;++m)for(int n=0;n<2;++n)for(int k=0;k<2;++k) \
;       acc[ai][bj][m][n]=__builtin_amdgcn_mfma_f32_16x16x32_bf16(Bt_[n][k],At[m][k],acc[ai][bj][m][n],0,0,0); \
;     __builtin_amdgcn_s_setprio(0);}while(0)
; #define WAIT_V(n) asm volatile("s_waitcnt vmcnt(" #n ")":::"memory")
; #define WAIT_L(n) asm volatile("s_waitcnt lgkmcnt(" #n ")":::"memory")
; #define BAR __builtin_amdgcn_s_barrier()
; #define SCHED __builtin_amdgcn_sched_barrier(0)
; template <int EPI>
; __device__ __forceinline__ void gemm_run(const GD& c, const bool has_next, const GD& nx, const Ctx& e, bf16* shm, float* rs, float* rs_nxt, float* racc_) {
;     ...
;     STAGE_B(SB(0,1),bcol+HALF,t+2);
;     WAIT_V(6); BAR; MMA(1,1,At,B1); BAR;
;     LDB(B0,1,0); SCHED; LDA(At,1,0); STAGE_A(SA(0,1),brow+HALF,t+2);
;     WAIT_L(8); BAR; WAIT_L(0); MMA(0,0,At,B0); BAR; SCHED;
;     LDB(B1,1,1); STAGE_B(SB(1,0),bcol,t+3);
;     BAR; WAIT_L(0); MMA(0,1,At,B1); BAR;
;     LDA(At,1,1); STAGE_A(SA(1,0),brow,t+3);
;     BAR; WAIT_L(0); MMA(1,0,At,B0); BAR; SCHED;
;     STAGE_B(SB(1,1),bcol+HALF,t+3);
;     WAIT_V(6); BAR; MMA(1,1,At,B1); BAR;
	v_add_u32_e32 v158, s86, v147
	v_add_u32_e32 v159, 0x2000, v158
	v_readfirstlane_b32 s3, v158
	v_lshl_add_u64 v[160:161], v[188:189], 0, s[14:15]
	s_mov_b32 m0, s3
	v_readfirstlane_b32 s3, v159
	global_load_lds_dwordx4 v[160:161], off
	v_lshl_add_u64 v[160:161], v[246:247], 0, s[14:15]
	s_mov_b32 m0, s3
	s_nop 0
	global_load_lds_dwordx4 v[160:161], off
	s_waitcnt vmcnt(6)
	s_barrier
	v_mfma_f32_16x16x32_bf16 v[30:33], v[226:229], v[194:197], v[30:33]
	v_mfma_f32_16x16x32_bf16 v[26:29], v[234:237], v[194:197], v[26:29]
	v_mfma_f32_16x16x32_bf16 v[22:25], v[226:229], v[202:205], v[22:25]
	v_mfma_f32_16x16x32_bf16 v[18:21], v[234:237], v[202:205], v[18:21]
	v_mfma_f32_16x16x32_bf16 v[14:17], v[226:229], v[210:213], v[14:17]
	v_mfma_f32_16x16x32_bf16 v[10:13], v[234:237], v[210:213], v[10:13]
	v_mfma_f32_16x16x32_bf16 v[6:9], v[226:229], v[218:221], v[6:9]
	v_mfma_f32_16x16x32_bf16 v[2:5], v[234:237], v[218:221], v[2:5]
	v_mfma_f32_16x16x32_bf16 v[30:33], v[230:233], v[198:201], v[30:33]
	v_mfma_f32_16x16x32_bf16 v[26:29], v[238:241], v[198:201], v[26:29]
	v_mfma_f32_16x16x32_bf16 v[22:25], v[230:233], v[206:209], v[22:25]
	v_mfma_f32_16x16x32_bf16 v[18:21], v[238:241], v[206:209], v[18:21]
	v_mfma_f32_16x16x32_bf16 v[14:17], v[230:233], v[214:217], v[14:17]
	v_mfma_f32_16x16x32_bf16 v[10:13], v[238:241], v[214:217], v[10:13]
	v_mfma_f32_16x16x32_bf16 v[6:9], v[230:233], v[222:225], v[6:9]
	v_mfma_f32_16x16x32_bf16 v[2:5], v[238:241], v[222:225], v[2:5]
	s_barrier
	ds_read_b128 v[166:169], v148
	ds_read_b128 v[170:173], v148 offset:1024
	ds_read_b128 v[190:193], v148 offset:2048
	ds_read_b128 v[194:197], v148 offset:3072
	v_add_u32_e32 v160, 0x4000, v141
	v_add_u32_e32 v161, 0x6000, v141
	v_readfirstlane_b32 s3, v160
	v_lshl_add_u64 v[230:231], v[174:175], 0, s[92:93]
	s_mov_b32 m0, s3
	v_readfirstlane_b32 s3, v161
	ds_read_b128 v[198:201], v145 offset:32768
	ds_read_b128 v[202:205], v145 offset:33792
	ds_read_b128 v[206:209], v144 offset:32768
	ds_read_b128 v[210:213], v144 offset:33792
	ds_read_b128 v[214:217], v143 offset:32768
	ds_read_b128 v[218:221], v143 offset:33792
	ds_read_b128 v[222:225], v142 offset:32768
	ds_read_b128 v[226:229], v142 offset:33792
	global_load_lds_dwordx4 v[230:231], off
	v_lshl_add_u64 v[230:231], v[186:187], 0, s[92:93]
	s_mov_b32 m0, s3
	s_nop 0
	global_load_lds_dwordx4 v[230:231], off
	s_waitcnt lgkmcnt(8)
	s_barrier
	s_waitcnt lgkmcnt(0)
	v_mfma_f32_16x16x32_bf16 v[126:129], v[166:169], v[198:201], v[126:129]
	v_mfma_f32_16x16x32_bf16 v[122:125], v[190:193], v[198:201], v[122:125]
	v_mfma_f32_16x16x32_bf16 v[118:121], v[166:169], v[206:209], v[118:121]
	v_mfma_f32_16x16x32_bf16 v[114:117], v[190:193], v[206:209], v[114:117]
	v_mfma_f32_16x16x32_bf16 v[110:113], v[166:169], v[214:217], v[110:113]
	v_mfma_f32_16x16x32_bf16 v[106:109], v[190:193], v[214:217], v[106:109]
	v_mfma_f32_16x16x32_bf16 v[102:105], v[166:169], v[222:225], v[102:105]
	v_mfma_f32_16x16x32_bf16 v[98:101], v[190:193], v[222:225], v[98:101]
	v_mfma_f32_16x16x32_bf16 v[126:129], v[170:173], v[202:205], v[126:129]
	v_mfma_f32_16x16x32_bf16 v[122:125], v[194:197], v[202:205], v[122:125]
	v_mfma_f32_16x16x32_bf16 v[118:121], v[170:173], v[210:213], v[118:121]
	v_mfma_f32_16x16x32_bf16 v[114:117], v[194:197], v[210:213], v[114:117]
	v_mfma_f32_16x16x32_bf16 v[110:113], v[170:173], v[218:221], v[110:113]
	v_mfma_f32_16x16x32_bf16 v[106:109], v[194:197], v[218:221], v[106:109]
	v_mfma_f32_16x16x32_bf16 v[102:105], v[170:173], v[226:229], v[102:105]
	v_mfma_f32_16x16x32_bf16 v[98:101], v[194:197], v[226:229], v[98:101]
	s_barrier
	v_readfirstlane_b32 s3, v149
	v_add_u32_e32 v176, 0x2000, v149
	v_lshl_add_u64 v[248:249], v[188:189], 0, s[26:27]
	s_mov_b32 m0, s3
	v_readfirstlane_b32 s3, v176
	ds_read_b128 v[230:233], v146
	ds_read_b128 v[234:237], v146 offset:1024
	ds_read_b128 v[238:241], v146 offset:2048
	ds_read_b128 v[242:245], v146 offset:3072
	global_load_lds_dwordx4 v[248:249], off
	v_lshl_add_u64 v[248:249], v[246:247], 0, s[26:27]
	s_mov_b32 m0, s3
	s_nop 0
	global_load_lds_dwordx4 v[248:249], off
	s_barrier
	s_waitcnt lgkmcnt(0)
	v_mfma_f32_16x16x32_bf16 v[94:97], v[230:233], v[198:201], v[94:97]
	v_mfma_f32_16x16x32_bf16 v[90:93], v[238:241], v[198:201], v[90:93]
	v_mfma_f32_16x16x32_bf16 v[86:89], v[230:233], v[206:209], v[86:89]
	v_mfma_f32_16x16x32_bf16 v[82:85], v[238:241], v[206:209], v[82:85]
	v_mfma_f32_16x16x32_bf16 v[78:81], v[230:233], v[214:217], v[78:81]
	v_mfma_f32_16x16x32_bf16 v[74:77], v[238:241], v[214:217], v[74:77]
	v_mfma_f32_16x16x32_bf16 v[70:73], v[230:233], v[222:225], v[70:73]
	v_mfma_f32_16x16x32_bf16 v[66:69], v[238:241], v[222:225], v[66:69]
	v_mfma_f32_16x16x32_bf16 v[94:97], v[234:237], v[202:205], v[94:97]
	v_mfma_f32_16x16x32_bf16 v[90:93], v[242:245], v[202:205], v[90:93]
	v_mfma_f32_16x16x32_bf16 v[86:89], v[234:237], v[210:213], v[86:89]
	v_mfma_f32_16x16x32_bf16 v[82:85], v[242:245], v[210:213], v[82:85]
	v_mfma_f32_16x16x32_bf16 v[78:81], v[234:237], v[218:221], v[78:81]
	v_mfma_f32_16x16x32_bf16 v[74:77], v[242:245], v[218:221], v[74:77]
	v_mfma_f32_16x16x32_bf16 v[70:73], v[234:237], v[226:229], v[70:73]
	v_mfma_f32_16x16x32_bf16 v[66:69], v[242:245], v[226:229], v[66:69]
	s_barrier
	v_readfirstlane_b32 s3, v150
	v_lshl_add_u64 v[174:175], v[174:175], 0, s[80:81]
	s_mov_b32 m0, s3
	v_readfirstlane_b32 s3, v151
	ds_read_b128 v[198:201], v145 offset:49152
	ds_read_b128 v[202:205], v145 offset:50176
	ds_read_b128 v[206:209], v144 offset:49152
	ds_read_b128 v[210:213], v144 offset:50176
	ds_read_b128 v[214:217], v143 offset:49152
	ds_read_b128 v[218:221], v143 offset:50176
	ds_read_b128 v[222:225], v142 offset:49152
	ds_read_b128 v[226:229], v142 offset:50176
	global_load_lds_dwordx4 v[174:175], off
	v_lshl_add_u64 v[174:175], v[186:187], 0, s[80:81]
	s_mov_b32 m0, s3
	s_nop 0
	global_load_lds_dwordx4 v[174:175], off
	s_barrier
; #define STAGE_A(P,br,kt) STAGE_G(P,c.A,c.lda,br,(long)(kt)*c.kstr)
; #define STAGE_B(P,br,kt) STAGE_G(P,c.Bt,c.K,br,(long)(kt)*BK)
; #define LDA(dst,b,h) for(int m=0;m<4;++m)for(int k=0;k<2;++k) \
;     dst[m][k]=*reinterpret_cast<const bf16x8*>((char*)SA(b,h)+lds_byte(wr*64+m*16+fr,k*32+fq*8))
; #define LDB(dst,b,h) for(int n=0;n<2;++n)for(int k=0;k<2;++k) \
;     dst[n][k]=*reinterpret_cast<const bf16x8*>((char*)SB(b,h)+lds_byte(wc*32+n*16+fr,k*32+fq*8))
; #define MMA(ai,bj,At,Bt_) do{__builtin_amdgcn_s_setprio(1); \
;     for(int m=0;m<4;++m)for(int n=0;n<2;++n)for(int k=0;k<2;++k) \
;       acc[ai][bj][m][n]=__builtin_amdgcn_mfma_f32_16x16x32_bf16(Bt_[n][k],At[m][k],acc[ai][bj][m][n],0,0,0); \
;     __builtin_amdgcn_s_setprio(0);}while(0)
; #define WAIT_V(n) asm volatile("s_waitcnt vmcnt(" #n ")":::"memory")
; #define WAIT_L(n) asm volatile("s_waitcnt lgkmcnt(" #n ")":::"memory")
; #define BAR __builtin_amdgcn_s_barrier()
; #define SCHED __builtin_amdgcn_sched_barrier(0)
; template <int EPI>
; __device__ __forceinline__ void gemm_run(const GD& c, const bool has_next, const GD& nx, const Ctx& e, bf16* shm, float* rs, float* rs_nxt, float* racc_) {
;     ...
;     WAIT_V(6); BAR; MMA(1,1,At,B1); BAR;
;     LDB(B0,1,0); SCHED; LDA(At,1,0); STAGE_A(SA(0,1),brow+HALF,t+2);
;     WAIT_L(8); BAR; WAIT_L(0); MMA(0,0,At,B0); BAR; SCHED;
;     LDB(B1,1,1); STAGE_B(SB(1,0),bcol,t+3);
;     BAR; WAIT_L(0); MMA(0,1,At,B1); BAR;
;     LDA(At,1,1); STAGE_A(SA(1,0),brow,t+3);
;     BAR; WAIT_L(0); MMA(1,0,At,B0); BAR; SCHED;
;     STAGE_B(SB(1,1),bcol+HALF,t+3);
;     WAIT_V(6); BAR; MMA(1,1,At,B1); BAR;
;   }
;   { LDB(B0,0,0); LDA(At,0,0); STAGE_A(SA(1,1),brow+HALF,nt-1);
;     BAR; WAIT_L(0); MMA(0,0,At,B0); BAR;
;     LDB(B1,0,1); BAR; WAIT_L(0); MMA(0,1,At,B1); BAR;
;     LDA(At,0,1); WAIT_V(4); BAR; WAIT_L(0); MMA(1,0,At,B0); MMA(1,1,At,B1); BAR; }
	s_waitcnt lgkmcnt(0)
	v_mfma_f32_16x16x32_bf16 v[62:65], v[166:169], v[198:201], v[62:65]
	v_mfma_f32_16x16x32_bf16 v[58:61], v[190:193], v[198:201], v[58:61]
	v_mfma_f32_16x16x32_bf16 v[54:57], v[166:169], v[206:209], v[54:57]
	v_mfma_f32_16x16x32_bf16 v[50:53], v[190:193], v[206:209], v[50:53]
	v_mfma_f32_16x16x32_bf16 v[46:49], v[166:169], v[214:217], v[46:49]
	v_mfma_f32_16x16x32_bf16 v[42:45], v[190:193], v[214:217], v[42:45]
	v_mfma_f32_16x16x32_bf16 v[38:41], v[166:169], v[222:225], v[38:41]
	v_mfma_f32_16x16x32_bf16 v[34:37], v[190:193], v[222:225], v[34:37]
	v_mfma_f32_16x16x32_bf16 v[62:65], v[170:173], v[202:205], v[62:65]
	v_mfma_f32_16x16x32_bf16 v[58:61], v[194:197], v[202:205], v[58:61]
	v_mfma_f32_16x16x32_bf16 v[54:57], v[170:173], v[210:213], v[54:57]
	v_mfma_f32_16x16x32_bf16 v[50:53], v[194:197], v[210:213], v[50:53]
	v_mfma_f32_16x16x32_bf16 v[46:49], v[170:173], v[218:221], v[46:49]
	v_mfma_f32_16x16x32_bf16 v[42:45], v[194:197], v[218:221], v[42:45]
	v_mfma_f32_16x16x32_bf16 v[38:41], v[170:173], v[226:229], v[38:41]
	v_mfma_f32_16x16x32_bf16 v[34:37], v[194:197], v[226:229], v[34:37]
	s_barrier
	v_readfirstlane_b32 s3, v152
	v_add_u32_e32 v168, 0x2000, v152
	v_lshl_add_u64 v[166:167], v[188:189], 0, s[28:29]
	s_mov_b32 m0, s3
	v_readfirstlane_b32 s3, v168
	global_load_lds_dwordx4 v[166:167], off
	v_lshl_add_u64 v[166:167], v[246:247], 0, s[28:29]
	s_mov_b32 m0, s3
	s_nop 0
	global_load_lds_dwordx4 v[166:167], off
	s_waitcnt vmcnt(6)
	s_barrier
	v_mfma_f32_16x16x32_bf16 v[30:33], v[230:233], v[198:201], v[30:33]
	v_mfma_f32_16x16x32_bf16 v[26:29], v[238:241], v[198:201], v[26:29]
	v_mfma_f32_16x16x32_bf16 v[22:25], v[230:233], v[206:209], v[22:25]
	v_mfma_f32_16x16x32_bf16 v[18:21], v[238:241], v[206:209], v[18:21]
	s_add_i32 s2, s2, 2
	v_mfma_f32_16x16x32_bf16 v[14:17], v[230:233], v[214:217], v[14:17]
	v_lshl_add_u64 v[130:131], v[130:131], 0, s[88:89]
	v_mfma_f32_16x16x32_bf16 v[10:13], v[238:241], v[214:217], v[10:13]
	v_lshl_add_u64 v[132:133], v[132:133], 0, s[88:89]
	v_mfma_f32_16x16x32_bf16 v[6:9], v[230:233], v[222:225], v[6:9]
	v_lshl_add_u64 v[136:137], v[136:137], 0, s[88:89]
	v_mfma_f32_16x16x32_bf16 v[2:5], v[238:241], v[222:225], v[2:5]
	s_cmp_lt_u32 s2, 12
	v_mfma_f32_16x16x32_bf16 v[30:33], v[234:237], v[202:205], v[30:33]
	v_lshl_add_u64 v[138:139], v[138:139], 0, s[88:89]
	v_mfma_f32_16x16x32_bf16 v[26:29], v[242:245], v[202:205], v[26:29]
	v_mfma_f32_16x16x32_bf16 v[22:25], v[234:237], v[210:213], v[22:25]
	v_mfma_f32_16x16x32_bf16 v[18:21], v[242:245], v[210:213], v[18:21]
	v_mfma_f32_16x16x32_bf16 v[14:17], v[234:237], v[218:221], v[14:17]
	v_mfma_f32_16x16x32_bf16 v[10:13], v[242:245], v[218:221], v[10:13]
	v_mfma_f32_16x16x32_bf16 v[6:9], v[234:237], v[226:229], v[6:9]
	v_mfma_f32_16x16x32_bf16 v[2:5], v[242:245], v[226:229], v[2:5]
	s_barrier
	s_cbranch_scc1 .LBB0_267
	s_or_b32 s2, s10, 0x80
	s_ashr_i32 s3, s2, 31
	s_lshl_b64 s[2:3], s[2:3], 11
	s_add_u32 s2, s18, s2
	s_addc_u32 s3, s19, s3
	v_lshl_add_u64 v[150:151], s[2:3], 0, v[0:1]
	s_mov_b64 s[14:15], 0x780
	v_readfirstlane_b32 s11, v162
	v_lshl_add_u64 v[150:151], v[150:151], 0, s[14:15]
	s_mov_b32 m0, s11
	ds_read_b128 v[130:133], v154
	ds_read_b128 v[136:139], v154 offset:1024
	ds_read_b128 v[166:169], v154 offset:2048
	ds_read_b128 v[170:173], v154 offset:3072
	ds_read_b128 v[190:193], v145
	ds_read_b128 v[194:197], v145 offset:1024
	ds_read_b128 v[198:201], v144
	ds_read_b128 v[202:205], v144 offset:1024
	ds_read_b128 v[206:209], v143
	ds_read_b128 v[210:213], v143 offset:1024
	ds_read_b128 v[214:217], v142
	ds_read_b128 v[218:221], v142 offset:1024
	global_load_lds_dwordx4 v[150:151], off
	v_lshl_add_u64 v[150:151], s[2:3], 0, v[134:135]
	v_readfirstlane_b32 s2, v163
	v_lshl_add_u64 v[150:151], v[150:151], 0, s[14:15]
	s_mov_b32 m0, s2
	s_nop 0
	global_load_lds_dwordx4 v[150:151], off
	s_barrier
	s_waitcnt lgkmcnt(0)
	v_mfma_f32_16x16x32_bf16 v[126:129], v[130:133], v[190:193], v[126:129]
	v_mfma_f32_16x16x32_bf16 v[122:125], v[166:169], v[190:193], v[122:125]
	v_mfma_f32_16x16x32_bf16 v[118:121], v[130:133], v[198:201], v[118:121]
	v_mfma_f32_16x16x32_bf16 v[106:109], v[166:169], v[206:209], v[106:109]
	v_mfma_f32_16x16x32_bf16 v[102:105], v[130:133], v[214:217], v[102:105]
	v_mfma_f32_16x16x32_bf16 v[126:129], v[136:139], v[194:197], v[126:129]
	v_mfma_f32_16x16x32_bf16 v[122:125], v[170:173], v[194:197], v[122:125]
	v_mfma_f32_16x16x32_bf16 v[118:121], v[136:139], v[202:205], v[118:121]
	v_mfma_f32_16x16x32_bf16 v[114:117], v[166:169], v[198:201], v[114:117]
	v_mfma_f32_16x16x32_bf16 v[110:113], v[130:133], v[206:209], v[110:113]
	v_mfma_f32_16x16x32_bf16 v[106:109], v[170:173], v[210:213], v[106:109]
	v_mfma_f32_16x16x32_bf16 v[102:105], v[136:139], v[218:221], v[102:105]
	v_mfma_f32_16x16x32_bf16 v[98:101], v[166:169], v[214:217], v[98:101]
	v_mfma_f32_16x16x32_bf16 v[222:225], v[170:173], v[202:205], v[114:117]
	v_mfma_f32_16x16x32_bf16 v[226:229], v[136:139], v[210:213], v[110:113]
	v_mfma_f32_16x16x32_bf16 v[230:233], v[170:173], v[218:221], v[98:101]
	s_barrier
	s_nop 2
	ds_read_b128 v[98:101], v153
	ds_read_b128 v[110:113], v153 offset:1024
	ds_read_b128 v[114:117], v153 offset:2048
	ds_read_b128 v[150:153], v153 offset:3072
	s_barrier
; #define LDA(dst,b,h) for(int m=0;m<4;++m)for(int k=0;k<2;++k) \
;     dst[m][k]=*reinterpret_cast<const bf16x8*>((char*)SA(b,h)+lds_byte(wr*64+m*16+fr,k*32+fq*8))
; #define LDB(dst,b,h) for(int n=0;n<2;++n)for(int k=0;k<2;++k) \
;     dst[n][k]=*reinterpret_cast<const bf16x8*>((char*)SB(b,h)+lds_byte(wc*32+n*16+fr,k*32+fq*8))
; #define MMA(ai,bj,At,Bt_) do{__builtin_amdgcn_s_setprio(1); \
;     for(int m=0;m<4;++m)for(int n=0;n<2;++n)for(int k=0;k<2;++k) \
;       acc[ai][bj][m][n]=__builtin_amdgcn_mfma_f32_16x16x32_bf16(Bt_[n][k],At[m][k],acc[ai][bj][m][n],0,0,0); \
;     __builtin_amdgcn_s_setprio(0);}while(0)
; #define WAIT_V(n) asm volatile("s_waitcnt vmcnt(" #n ")":::"memory")
; #define WAIT_L(n) asm volatile("s_waitcnt lgkmcnt(" #n ")":::"memory")
; #define BAR __builtin_amdgcn_s_barrier()
; template <int EPI>
; __device__ __forceinline__ void gemm_run(const GD& c, const bool has_next, const GD& nx, const Ctx& e, bf16* shm, float* rs, float* rs_nxt, float* racc_) {
;     ...
;     LDB(B1,0,1); BAR; WAIT_L(0); MMA(0,1,At,B1); BAR;
;     LDA(At,0,1); WAIT_V(4); BAR; WAIT_L(0); MMA(1,0,At,B0); MMA(1,1,At,B1); BAR; }
;   { LDB(B0,1,0); LDA(At,1,0); WAIT_V(2); BAR; WAIT_L(0); MMA(0,0,At,B0); BAR;
	s_waitcnt lgkmcnt(0)
	v_mfma_f32_16x16x32_bf16 v[90:93], v[114:117], v[190:193], v[90:93]
	v_mfma_f32_16x16x32_bf16 v[86:89], v[98:101], v[198:201], v[86:89]
	v_mfma_f32_16x16x32_bf16 v[74:77], v[114:117], v[206:209], v[74:77]
	v_mfma_f32_16x16x32_bf16 v[70:73], v[98:101], v[214:217], v[70:73]
	v_mfma_f32_16x16x32_bf16 v[66:69], v[114:117], v[214:217], v[66:69]
	v_mfma_f32_16x16x32_bf16 v[94:97], v[98:101], v[190:193], v[94:97]
	v_mfma_f32_16x16x32_bf16 v[90:93], v[150:153], v[194:197], v[90:93]
	v_mfma_f32_16x16x32_bf16 v[86:89], v[110:113], v[202:205], v[86:89]
	v_mfma_f32_16x16x32_bf16 v[82:85], v[114:117], v[198:201], v[82:85]
	v_mfma_f32_16x16x32_bf16 v[78:81], v[98:101], v[206:209], v[78:81]
	v_mfma_f32_16x16x32_bf16 v[74:77], v[150:153], v[210:213], v[74:77]
	v_mfma_f32_16x16x32_bf16 v[70:73], v[110:113], v[218:221], v[70:73]
	v_mfma_f32_16x16x32_bf16 v[66:69], v[150:153], v[218:221], v[66:69]
	v_mfma_f32_16x16x32_bf16 v[234:237], v[110:113], v[194:197], v[94:97]
	v_mfma_f32_16x16x32_bf16 v[190:193], v[150:153], v[202:205], v[82:85]
	v_mfma_f32_16x16x32_bf16 v[194:197], v[110:113], v[210:213], v[78:81]
	s_barrier
	s_nop 0
	ds_read_b128 v[78:81], v145 offset:16384
	ds_read_b128 v[82:85], v145 offset:17408
	ds_read_b128 v[94:97], v144 offset:16384
	ds_read_b128 v[198:201], v144 offset:17408
	ds_read_b128 v[202:205], v143 offset:16384
	ds_read_b128 v[206:209], v143 offset:17408
	ds_read_b128 v[210:213], v142 offset:16384
	ds_read_b128 v[214:217], v142 offset:17408
	s_waitcnt vmcnt(4)
	s_barrier
	s_waitcnt lgkmcnt(0)
	v_mfma_f32_16x16x32_bf16 v[62:65], v[130:133], v[78:81], v[62:65]
	v_mfma_f32_16x16x32_bf16 v[58:61], v[166:169], v[78:81], v[58:61]
	v_mfma_f32_16x16x32_bf16 v[54:57], v[130:133], v[94:97], v[54:57]
	v_mfma_f32_16x16x32_bf16 v[42:45], v[166:169], v[202:205], v[42:45]
	v_mfma_f32_16x16x32_bf16 v[38:41], v[130:133], v[210:213], v[38:41]
	v_mfma_f32_16x16x32_bf16 v[62:65], v[136:139], v[82:85], v[62:65]
	v_mfma_f32_16x16x32_bf16 v[58:61], v[170:173], v[82:85], v[58:61]
	v_mfma_f32_16x16x32_bf16 v[54:57], v[136:139], v[198:201], v[54:57]
	v_mfma_f32_16x16x32_bf16 v[50:53], v[166:169], v[94:97], v[50:53]
	v_mfma_f32_16x16x32_bf16 v[46:49], v[130:133], v[202:205], v[46:49]
	v_mfma_f32_16x16x32_bf16 v[42:45], v[170:173], v[206:209], v[42:45]
	v_mfma_f32_16x16x32_bf16 v[38:41], v[136:139], v[214:217], v[38:41]
	v_mfma_f32_16x16x32_bf16 v[34:37], v[166:169], v[210:213], v[34:37]
	v_mfma_f32_16x16x32_bf16 v[218:221], v[170:173], v[198:201], v[50:53]
	v_mfma_f32_16x16x32_bf16 v[238:241], v[136:139], v[206:209], v[46:49]
	v_mfma_f32_16x16x32_bf16 v[136:139], v[170:173], v[214:217], v[34:37]
	v_mfma_f32_16x16x32_bf16 v[26:29], v[114:117], v[78:81], v[26:29]
	v_mfma_f32_16x16x32_bf16 v[22:25], v[98:101], v[94:97], v[22:25]
	v_mfma_f32_16x16x32_bf16 v[10:13], v[114:117], v[202:205], v[10:13]
	v_mfma_f32_16x16x32_bf16 v[6:9], v[98:101], v[210:213], v[6:9]
	v_mfma_f32_16x16x32_bf16 v[30:33], v[98:101], v[78:81], v[30:33]
	v_mfma_f32_16x16x32_bf16 v[26:29], v[150:153], v[82:85], v[26:29]
	v_mfma_f32_16x16x32_bf16 v[22:25], v[110:113], v[198:201], v[22:25]
	v_mfma_f32_16x16x32_bf16 v[18:21], v[114:117], v[94:97], v[18:21]
	v_mfma_f32_16x16x32_bf16 v[14:17], v[98:101], v[202:205], v[14:17]
	v_mfma_f32_16x16x32_bf16 v[10:13], v[150:153], v[206:209], v[10:13]
	v_mfma_f32_16x16x32_bf16 v[6:9], v[110:113], v[214:217], v[6:9]
	v_mfma_f32_16x16x32_bf16 v[2:5], v[114:117], v[210:213], v[2:5]
	v_mfma_f32_16x16x32_bf16 v[166:169], v[110:113], v[82:85], v[30:33]
	v_mfma_f32_16x16x32_bf16 v[170:173], v[150:153], v[198:201], v[18:21]
	v_mfma_f32_16x16x32_bf16 v[198:201], v[110:113], v[206:209], v[14:17]
	v_mfma_f32_16x16x32_bf16 v[2:5], v[150:153], v[214:217], v[2:5]
	s_barrier
	ds_read_b128 v[14:17], v148
	ds_read_b128 v[18:21], v148 offset:1024
	ds_read_b128 v[150:153], v148 offset:2048
	ds_read_b128 v[202:205], v148 offset:3072
	ds_read_b128 v[30:33], v145 offset:32768
	ds_read_b128 v[34:37], v145 offset:33792
	ds_read_b128 v[46:49], v144 offset:32768
	ds_read_b128 v[50:53], v144 offset:33792
	ds_read_b128 v[206:209], v143 offset:32768
	ds_read_b128 v[210:213], v143 offset:33792
	ds_read_b128 v[214:217], v142 offset:32768
	ds_read_b128 v[242:245], v142 offset:33792
	s_waitcnt vmcnt(2)
	s_barrier
; #define LDA(dst,b,h) for(int m=0;m<4;++m)for(int k=0;k<2;++k) \
;     dst[m][k]=*reinterpret_cast<const bf16x8*>((char*)SA(b,h)+lds_byte(wr*64+m*16+fr,k*32+fq*8))
; #define LDB(dst,b,h) for(int n=0;n<2;++n)for(int k=0;k<2;++k) \
;     dst[n][k]=*reinterpret_cast<const bf16x8*>((char*)SB(b,h)+lds_byte(wc*32+n*16+fr,k*32+fq*8))
; #define MMA(ai,bj,At,Bt_) do{__builtin_amdgcn_s_setprio(1); \
;     for(int m=0;m<4;++m)for(int n=0;n<2;++n)for(int k=0;k<2;++k) \
;       acc[ai][bj][m][n]=__builtin_amdgcn_mfma_f32_16x16x32_bf16(Bt_[n][k],At[m][k],acc[ai][bj][m][n],0,0,0); \
;     __builtin_amdgcn_s_setprio(0);}while(0)
; #define WAIT_V(n) asm volatile("s_waitcnt vmcnt(" #n ")":::"memory")
; #define WAIT_L(n) asm volatile("s_waitcnt lgkmcnt(" #n ")":::"memory")
; #define BAR __builtin_amdgcn_s_barrier()
; template <int EPI>
; __device__ __forceinline__ void gemm_run(const GD& c, const bool has_next, const GD& nx, const Ctx& e, bf16* shm, float* rs, float* rs_nxt, float* racc_) {
;     ...
;   { LDB(B0,1,0); LDA(At,1,0); WAIT_V(2); BAR; WAIT_L(0); MMA(0,0,At,B0); BAR;
;     LDB(B1,1,1); WAIT_V(0); BAR; WAIT_L(0); MMA(0,1,At,B1); BAR;
;     LDA(At,1,1); BAR; WAIT_L(0); MMA(1,0,At,B0); MMA(1,1,At,B1); BAR; }
;   if(wr==0)BAR;
	s_waitcnt lgkmcnt(0)
	v_mfma_f32_16x16x32_bf16 v[78:81], v[14:17], v[30:33], v[126:129]
	v_mfma_f32_16x16x32_bf16 v[130:133], v[18:21], v[34:37], v[78:81]
	v_mfma_f32_16x16x32_bf16 v[78:81], v[150:153], v[30:33], v[122:125]
	v_mfma_f32_16x16x32_bf16 v[126:129], v[202:205], v[34:37], v[78:81]
	v_mfma_f32_16x16x32_bf16 v[78:81], v[14:17], v[46:49], v[118:121]
	v_mfma_f32_16x16x32_bf16 v[114:117], v[18:21], v[50:53], v[78:81]
	v_mfma_f32_16x16x32_bf16 v[78:81], v[150:153], v[46:49], v[222:225]
	v_mfma_f32_16x16x32_bf16 v[110:113], v[202:205], v[50:53], v[78:81]
	v_mfma_f32_16x16x32_bf16 v[78:81], v[14:17], v[206:209], v[226:229]
	v_mfma_f32_16x16x32_bf16 v[98:101], v[18:21], v[210:213], v[78:81]
	v_mfma_f32_16x16x32_bf16 v[78:81], v[150:153], v[206:209], v[106:109]
	v_mfma_f32_16x16x32_bf16 v[94:97], v[202:205], v[210:213], v[78:81]
	v_mfma_f32_16x16x32_bf16 v[78:81], v[14:17], v[214:217], v[102:105]
	v_mfma_f32_16x16x32_bf16 v[82:85], v[18:21], v[242:245], v[78:81]
	v_mfma_f32_16x16x32_bf16 v[78:81], v[150:153], v[214:217], v[230:233]
	v_mfma_f32_16x16x32_bf16 v[78:81], v[202:205], v[242:245], v[78:81]
	s_barrier
	ds_read_b128 v[222:225], v146
	ds_read_b128 v[226:229], v146 offset:1024
	ds_read_b128 v[230:233], v146 offset:2048
	ds_read_b128 v[146:149], v146 offset:3072
	s_waitcnt vmcnt(0)
	s_barrier
	s_waitcnt lgkmcnt(0)
	v_mfma_f32_16x16x32_bf16 v[102:105], v[222:225], v[30:33], v[234:237]
	v_mfma_f32_16x16x32_bf16 v[30:33], v[230:233], v[30:33], v[90:93]
	v_mfma_f32_16x16x32_bf16 v[118:121], v[146:149], v[34:37], v[30:33]
	v_mfma_f32_16x16x32_bf16 v[30:33], v[222:225], v[46:49], v[86:89]
	v_mfma_f32_16x16x32_bf16 v[106:109], v[226:229], v[50:53], v[30:33]
	v_mfma_f32_16x16x32_bf16 v[30:33], v[230:233], v[46:49], v[190:193]
	v_mfma_f32_16x16x32_bf16 v[122:125], v[226:229], v[34:37], v[102:105]
	v_mfma_f32_16x16x32_bf16 v[102:105], v[146:149], v[50:53], v[30:33]
	v_mfma_f32_16x16x32_bf16 v[30:33], v[222:225], v[206:209], v[194:197]
	v_mfma_f32_16x16x32_bf16 v[90:93], v[226:229], v[210:213], v[30:33]
	v_mfma_f32_16x16x32_bf16 v[30:33], v[230:233], v[206:209], v[74:77]
	v_mfma_f32_16x16x32_bf16 v[86:89], v[146:149], v[210:213], v[30:33]
	v_mfma_f32_16x16x32_bf16 v[30:33], v[222:225], v[214:217], v[70:73]
	v_mfma_f32_16x16x32_bf16 v[74:77], v[226:229], v[242:245], v[30:33]
	v_mfma_f32_16x16x32_bf16 v[30:33], v[230:233], v[214:217], v[66:69]
	v_mfma_f32_16x16x32_bf16 v[70:73], v[146:149], v[242:245], v[30:33]
	s_barrier
	ds_read_b128 v[190:193], v145 offset:49152
	ds_read_b128 v[194:197], v145 offset:50176
	ds_read_b128 v[206:209], v144 offset:49152
	ds_read_b128 v[210:213], v144 offset:50176
	ds_read_b128 v[214:217], v143 offset:49152
	ds_read_b128 v[234:237], v143 offset:50176
	ds_read_b128 v[242:245], v142 offset:49152
	ds_read_b128 v[142:145], v142 offset:50176
	s_barrier
	s_waitcnt lgkmcnt(0)
	v_mfma_f32_16x16x32_bf16 v[30:33], v[14:17], v[190:193], v[62:65]
	v_mfma_f32_16x16x32_bf16 v[66:69], v[18:21], v[194:197], v[30:33]
	v_mfma_f32_16x16x32_bf16 v[30:33], v[150:153], v[190:193], v[58:61]
	v_mfma_f32_16x16x32_bf16 v[62:65], v[202:205], v[194:197], v[30:33]
	v_mfma_f32_16x16x32_bf16 v[30:33], v[14:17], v[206:209], v[54:57]
	v_mfma_f32_16x16x32_bf16 v[50:53], v[18:21], v[210:213], v[30:33]
	v_mfma_f32_16x16x32_bf16 v[30:33], v[150:153], v[206:209], v[218:221]
	v_mfma_f32_16x16x32_bf16 v[46:49], v[202:205], v[210:213], v[30:33]
	v_mfma_f32_16x16x32_bf16 v[30:33], v[14:17], v[214:217], v[238:241]
	v_mfma_f32_16x16x32_bf16 v[14:17], v[14:17], v[242:245], v[38:41]
	v_mfma_f32_16x16x32_bf16 v[34:37], v[18:21], v[234:237], v[30:33]
	v_mfma_f32_16x16x32_bf16 v[30:33], v[150:153], v[214:217], v[42:45]
	v_mfma_f32_16x16x32_bf16 v[18:21], v[18:21], v[142:145], v[14:17]
	v_mfma_f32_16x16x32_bf16 v[14:17], v[150:153], v[242:245], v[136:139]
	v_mfma_f32_16x16x32_bf16 v[30:33], v[202:205], v[234:237], v[30:33]
	v_mfma_f32_16x16x32_bf16 v[14:17], v[202:205], v[142:145], v[14:17]
	v_mfma_f32_16x16x32_bf16 v[22:25], v[222:225], v[206:209], v[22:25]
	v_mfma_f32_16x16x32_bf16 v[38:41], v[222:225], v[190:193], v[166:169]
	v_mfma_f32_16x16x32_bf16 v[42:45], v[226:229], v[210:213], v[22:25]
	v_mfma_f32_16x16x32_bf16 v[22:25], v[230:233], v[206:209], v[170:173]
	v_mfma_f32_16x16x32_bf16 v[58:61], v[226:229], v[194:197], v[38:41]
	v_mfma_f32_16x16x32_bf16 v[26:29], v[230:233], v[190:193], v[26:29]
	v_mfma_f32_16x16x32_bf16 v[38:41], v[146:149], v[210:213], v[22:25]
	v_mfma_f32_16x16x32_bf16 v[22:25], v[222:225], v[214:217], v[198:201]
	v_mfma_f32_16x16x32_bf16 v[10:13], v[230:233], v[214:217], v[10:13]
	v_mfma_f32_16x16x32_bf16 v[6:9], v[222:225], v[242:245], v[6:9]
	v_mfma_f32_16x16x32_bf16 v[2:5], v[230:233], v[242:245], v[2:5]
	v_mfma_f32_16x16x32_bf16 v[54:57], v[146:149], v[194:197], v[26:29]
	v_mfma_f32_16x16x32_bf16 v[26:29], v[226:229], v[234:237], v[22:25]
	v_mfma_f32_16x16x32_bf16 v[22:25], v[146:149], v[234:237], v[10:13]
	v_mfma_f32_16x16x32_bf16 v[10:13], v[226:229], v[142:145], v[6:9]
	v_mfma_f32_16x16x32_bf16 v[6:9], v[146:149], v[142:145], v[2:5]
	v_cmp_gt_u32_e32 vcc, s96, v140
	s_barrier
	s_and_saveexec_b64 s[2:3], vcc
	s_cbranch_execz .LBB0_270
	s_barrier

; #define STAGE_A(P,br,kt) STAGE_G(P,c.A,c.lda,br,(long)(kt)*c.kstr)
; #define STAGE_B(P,br,kt) STAGE_G(P,c.Bt,c.K,br,(long)(kt)*BK)
; #define LDA(dst,b,h) for(int m=0;m<4;++m)for(int k=0;k<2;++k) \
;     dst[m][k]=*reinterpret_cast<const bf16x8*>((char*)SA(b,h)+lds_byte(wr*64+m*16+fr,k*32+fq*8))
; #define LDB(dst,b,h) for(int n=0;n<2;++n)for(int k=0;k<2;++k) \
;     dst[n][k]=*reinterpret_cast<const bf16x8*>((char*)SB(b,h)+lds_byte(wc*32+n*16+fr,k*32+fq*8))
; #define MMA(ai,bj,At,Bt_) do{__builtin_amdgcn_s_setprio(1); \
;     for(int m=0;m<4;++m)for(int n=0;n<2;++n)for(int k=0;k<2;++k) \
;       acc[ai][bj][m][n]=__builtin_amdgcn_mfma_f32_16x16x32_bf16(Bt_[n][k],At[m][k],acc[ai][bj][m][n],0,0,0); \
;     __builtin_amdgcn_s_setprio(0);}while(0)
; #define WAIT_L(n) asm volatile("s_waitcnt lgkmcnt(" #n ")":::"memory")
; #define BAR __builtin_amdgcn_s_barrier()
; #define SCHED __builtin_amdgcn_sched_barrier(0)
; template <int EPI>
; __device__ __forceinline__ void gemm_run(const GD& c, const bool has_next, const GD& nx, const Ctx& e, bf16* shm, float* rs, float* rs_nxt, float* racc_) {
;     ...
;     LDB(B0,0,0); SCHED; LDA(At,0,0); STAGE_A(SA(1,1),brow+HALF,t+1);
;     WAIT_L(8); BAR; WAIT_L(0); MMA(0,0,At,B0); BAR; SCHED;
;     LDB(B1,0,1); STAGE_B(SB(0,0),bcol,t+2);
;     BAR; WAIT_L(0); MMA(0,1,At,B1); BAR;
;     LDA(At,0,1); STAGE_A(SA(0,0),brow,t+2);
;     BAR; WAIT_L(0); MMA(1,0,At,B0); BAR; SCHED;
.LBB0_326:
	ds_read_b128 v[168:171], v155
	ds_read_b128 v[172:175], v155 offset:1024
	ds_read_b128 v[190:193], v155 offset:2048
	ds_read_b128 v[194:197], v155 offset:3072
	v_add_u32_e32 v163, 0xc000, v142
	v_lshl_add_u64 v[186:187], s[6:7], 0, v[132:133]
	v_readfirstlane_b32 s3, v163
	v_add_u32_e32 v166, 0xe000, v142
	v_lshl_add_u64 v[156:157], v[186:187], 0, s[90:91]
	s_mov_b32 m0, s3
	v_lshl_add_u64 v[188:189], s[6:7], 0, v[134:135]
	v_readfirstlane_b32 s3, v166
	ds_read_b128 v[158:161], v146
	ds_read_b128 v[198:201], v146 offset:1024
	ds_read_b128 v[202:205], v145
	ds_read_b128 v[206:209], v145 offset:1024
	ds_read_b128 v[210:213], v144
	ds_read_b128 v[214:217], v144 offset:1024
	ds_read_b128 v[218:221], v143
	ds_read_b128 v[222:225], v143 offset:1024
	global_load_lds_dwordx4 v[156:157], off
	v_lshl_add_u64 v[156:157], v[188:189], 0, s[90:91]
	s_mov_b32 m0, s3
	s_nop 0
	global_load_lds_dwordx4 v[156:157], off
	s_waitcnt lgkmcnt(8)
	s_barrier
	s_waitcnt lgkmcnt(0)
	v_mfma_f32_16x16x32_bf16 v[126:129], v[168:171], v[158:161], v[126:129]
	v_mfma_f32_16x16x32_bf16 v[122:125], v[190:193], v[158:161], v[122:125]
	v_mfma_f32_16x16x32_bf16 v[118:121], v[168:171], v[202:205], v[118:121]
	v_mfma_f32_16x16x32_bf16 v[114:117], v[190:193], v[202:205], v[114:117]
	v_mfma_f32_16x16x32_bf16 v[110:113], v[168:171], v[210:213], v[110:113]
	v_mfma_f32_16x16x32_bf16 v[106:109], v[190:193], v[210:213], v[106:109]
	v_mfma_f32_16x16x32_bf16 v[102:105], v[168:171], v[218:221], v[102:105]
	v_mfma_f32_16x16x32_bf16 v[98:101], v[190:193], v[218:221], v[98:101]
	v_mfma_f32_16x16x32_bf16 v[126:129], v[172:175], v[198:201], v[126:129]
	v_mfma_f32_16x16x32_bf16 v[122:125], v[194:197], v[198:201], v[122:125]
	v_mfma_f32_16x16x32_bf16 v[118:121], v[172:175], v[206:209], v[118:121]
	v_mfma_f32_16x16x32_bf16 v[114:117], v[194:197], v[206:209], v[114:117]
	v_mfma_f32_16x16x32_bf16 v[110:113], v[172:175], v[214:217], v[110:113]
	v_mfma_f32_16x16x32_bf16 v[106:109], v[194:197], v[214:217], v[106:109]
	v_mfma_f32_16x16x32_bf16 v[102:105], v[172:175], v[222:225], v[102:105]
	v_mfma_f32_16x16x32_bf16 v[98:101], v[194:197], v[222:225], v[98:101]
	s_barrier
	v_add_u32_e32 v156, s33, v147
	v_lshl_add_u64 v[246:247], s[6:7], 0, v[136:137]
	v_readfirstlane_b32 s3, v156
	v_add_u32_e32 v157, 0x2000, v156
	v_lshl_add_u64 v[242:243], v[246:247], 0, s[26:27]
	s_mov_b32 m0, s3
	v_lshl_add_u64 v[248:249], s[6:7], 0, v[138:139]
	v_readfirstlane_b32 s3, v157
	ds_read_b128 v[226:229], v154
	ds_read_b128 v[230:233], v154 offset:1024
	ds_read_b128 v[234:237], v154 offset:2048
	ds_read_b128 v[238:241], v154 offset:3072
	global_load_lds_dwordx4 v[242:243], off
	v_lshl_add_u64 v[242:243], v[248:249], 0, s[26:27]
	s_mov_b32 m0, s3
	s_nop 0
	global_load_lds_dwordx4 v[242:243], off
	s_barrier
	s_waitcnt lgkmcnt(0)
	v_mfma_f32_16x16x32_bf16 v[94:97], v[226:229], v[158:161], v[94:97]
	v_mfma_f32_16x16x32_bf16 v[90:93], v[234:237], v[158:161], v[90:93]
	v_mfma_f32_16x16x32_bf16 v[86:89], v[226:229], v[202:205], v[86:89]
	v_mfma_f32_16x16x32_bf16 v[82:85], v[234:237], v[202:205], v[82:85]
	v_mfma_f32_16x16x32_bf16 v[78:81], v[226:229], v[210:213], v[78:81]
	v_mfma_f32_16x16x32_bf16 v[74:77], v[234:237], v[210:213], v[74:77]
	v_mfma_f32_16x16x32_bf16 v[70:73], v[226:229], v[218:221], v[70:73]
	v_mfma_f32_16x16x32_bf16 v[66:69], v[234:237], v[218:221], v[66:69]
	v_mfma_f32_16x16x32_bf16 v[94:97], v[230:233], v[198:201], v[94:97]
	v_mfma_f32_16x16x32_bf16 v[90:93], v[238:241], v[198:201], v[90:93]
	v_mfma_f32_16x16x32_bf16 v[86:89], v[230:233], v[206:209], v[86:89]
	v_mfma_f32_16x16x32_bf16 v[82:85], v[238:241], v[206:209], v[82:85]
	v_mfma_f32_16x16x32_bf16 v[78:81], v[230:233], v[214:217], v[78:81]
	v_mfma_f32_16x16x32_bf16 v[74:77], v[238:241], v[214:217], v[74:77]
	v_mfma_f32_16x16x32_bf16 v[70:73], v[230:233], v[222:225], v[70:73]
	v_mfma_f32_16x16x32_bf16 v[66:69], v[238:241], v[222:225], v[66:69]
	v_readfirstlane_b32 s3, v142
	v_lshl_add_u64 v[158:159], v[186:187], 0, s[0:1]
	s_mov_b32 m0, s3
	s_barrier
	ds_read_b128 v[198:201], v146 offset:16384
	ds_read_b128 v[202:205], v146 offset:17408
	ds_read_b128 v[206:209], v145 offset:16384
	ds_read_b128 v[210:213], v145 offset:17408
	ds_read_b128 v[214:217], v144 offset:16384
	ds_read_b128 v[218:221], v144 offset:17408
	ds_read_b128 v[222:225], v143 offset:16384
	ds_read_b128 v[242:245], v143 offset:17408
	global_load_lds_dwordx4 v[158:159], off
	v_add_u32_e32 v158, 0x2000, v142
	v_lshl_add_u64 v[160:161], v[188:189], 0, s[0:1]
	v_readfirstlane_b32 s3, v158
	s_mov_b32 m0, s3
	s_nop 0
	global_load_lds_dwordx4 v[160:161], off
	s_barrier
	s_waitcnt lgkmcnt(0)
	v_mfma_f32_16x16x32_bf16 v[62:65], v[168:171], v[198:201], v[62:65]
	v_mfma_f32_16x16x32_bf16 v[58:61], v[190:193], v[198:201], v[58:61]
	v_mfma_f32_16x16x32_bf16 v[54:57], v[168:171], v[206:209], v[54:57]
	v_mfma_f32_16x16x32_bf16 v[50:53], v[190:193], v[206:209], v[50:53]
	v_mfma_f32_16x16x32_bf16 v[46:49], v[168:171], v[214:217], v[46:49]
	v_mfma_f32_16x16x32_bf16 v[42:45], v[190:193], v[214:217], v[42:45]
	v_mfma_f32_16x16x32_bf16 v[38:41], v[168:171], v[222:225], v[38:41]
	v_mfma_f32_16x16x32_bf16 v[34:37], v[190:193], v[222:225], v[34:37]
	v_mfma_f32_16x16x32_bf16 v[62:65], v[172:175], v[202:205], v[62:65]
	v_mfma_f32_16x16x32_bf16 v[58:61], v[194:197], v[202:205], v[58:61]
	v_mfma_f32_16x16x32_bf16 v[54:57], v[172:175], v[210:213], v[54:57]
	v_mfma_f32_16x16x32_bf16 v[50:53], v[194:197], v[210:213], v[50:53]
	v_mfma_f32_16x16x32_bf16 v[46:49], v[172:175], v[218:221], v[46:49]
	v_mfma_f32_16x16x32_bf16 v[42:45], v[194:197], v[218:221], v[42:45]
	v_mfma_f32_16x16x32_bf16 v[38:41], v[172:175], v[242:245], v[38:41]
	v_mfma_f32_16x16x32_bf16 v[34:37], v[194:197], v[242:245], v[34:37]
	s_barrier
; #define STAGE_A(P,br,kt) STAGE_G(P,c.A,c.lda,br,(long)(kt)*c.kstr)
; #define STAGE_B(P,br,kt) STAGE_G(P,c.Bt,c.K,br,(long)(kt)*BK)
; #define LDA(dst,b,h) for(int m=0;m<4;++m)for(int k=0;k<2;++k) \
;     dst[m][k]=*reinterpret_cast<const bf16x8*>((char*)SA(b,h)+lds_byte(wr*64+m*16+fr,k*32+fq*8))
; #define LDB(dst,b,h) for(int n=0;n<2;++n)for(int k=0;k<2;++k) \
;     dst[n][k]=*reinterpret_cast<const bf16x8*>((char*)SB(b,h)+lds_byte(wc*32+n*16+fr,k*32+fq*8))
; #define MMA(ai,bj,At,Bt_) do{__builtin_amdgcn_s_setprio(1); \
;     for(int m=0;m<4;++m)for(int n=0;n<2;++n)for(int k=0;k<2;++k) \
;       acc[ai][bj][m][n]=__builtin_amdgcn_mfma_f32_16x16x32_bf16(Bt_[n][k],At[m][k],acc[ai][bj][m][n],0,0,0); \
;     __builtin_amdgcn_s_setprio(0);}while(0)
; #define WAIT_V(n) asm volatile("s_waitcnt vmcnt(" #n ")":::"memory")
; #define WAIT_L(n) asm volatile("s_waitcnt lgkmcnt(" #n ")":::"memory")
; #define BAR __builtin_amdgcn_s_barrier()
; #define SCHED __builtin_amdgcn_sched_barrier(0)
; template <int EPI>
; __device__ __forceinline__ void gemm_run(const GD& c, const bool has_next, const GD& nx, const Ctx& e, bf16* shm, float* rs, float* rs_nxt, float* racc_) {
;     ...
;     STAGE_B(SB(0,1),bcol+HALF,t+2);
;     WAIT_V(6); BAR; MMA(1,1,At,B1); BAR;
;     LDB(B0,1,0); SCHED; LDA(At,1,0); STAGE_A(SA(0,1),brow+HALF,t+2);
;     WAIT_L(8); BAR; WAIT_L(0); MMA(0,0,At,B0); BAR; SCHED;
;     LDB(B1,1,1); STAGE_B(SB(1,0),bcol,t+3);
;     BAR; WAIT_L(0); MMA(0,1,At,B1); BAR;
;     LDA(At,1,1); STAGE_A(SA(1,0),brow,t+3);
	v_add_u32_e32 v159, s86, v147
	v_lshl_add_u64 v[160:161], v[246:247], 0, s[28:29]
	v_readfirstlane_b32 s3, v159
	s_mov_b32 m0, s3
	v_lshl_add_u64 v[168:169], v[248:249], 0, s[28:29]
	global_load_lds_dwordx4 v[160:161], off
	v_add_u32_e32 v160, 0x2000, v159
	s_nop 0
	v_readfirstlane_b32 s3, v160
	s_mov_b32 m0, s3
	s_nop 0
	global_load_lds_dwordx4 v[168:169], off
	s_waitcnt vmcnt(6)
	s_barrier
	v_mfma_f32_16x16x32_bf16 v[30:33], v[226:229], v[198:201], v[30:33]
	v_mfma_f32_16x16x32_bf16 v[26:29], v[234:237], v[198:201], v[26:29]
	v_mfma_f32_16x16x32_bf16 v[22:25], v[226:229], v[206:209], v[22:25]
	v_mfma_f32_16x16x32_bf16 v[18:21], v[234:237], v[206:209], v[18:21]
	v_mfma_f32_16x16x32_bf16 v[14:17], v[226:229], v[214:217], v[14:17]
	v_mfma_f32_16x16x32_bf16 v[10:13], v[234:237], v[214:217], v[10:13]
	v_mfma_f32_16x16x32_bf16 v[6:9], v[226:229], v[222:225], v[6:9]
	v_mfma_f32_16x16x32_bf16 v[2:5], v[234:237], v[222:225], v[2:5]
	v_mfma_f32_16x16x32_bf16 v[30:33], v[230:233], v[202:205], v[30:33]
	v_mfma_f32_16x16x32_bf16 v[26:29], v[238:241], v[202:205], v[26:29]
	v_mfma_f32_16x16x32_bf16 v[22:25], v[230:233], v[210:213], v[22:25]
	v_mfma_f32_16x16x32_bf16 v[18:21], v[238:241], v[210:213], v[18:21]
	v_mfma_f32_16x16x32_bf16 v[14:17], v[230:233], v[218:221], v[14:17]
	v_mfma_f32_16x16x32_bf16 v[10:13], v[238:241], v[218:221], v[10:13]
	v_mfma_f32_16x16x32_bf16 v[6:9], v[230:233], v[242:245], v[6:9]
	v_mfma_f32_16x16x32_bf16 v[2:5], v[238:241], v[242:245], v[2:5]
	s_barrier
	ds_read_b128 v[168:171], v150
	ds_read_b128 v[172:175], v150 offset:1024
	ds_read_b128 v[190:193], v150 offset:2048
	ds_read_b128 v[194:197], v150 offset:3072
	v_add_u32_e32 v161, 0x4000, v142
	v_add_u32_e32 v162, 0x6000, v142
	v_readfirstlane_b32 s3, v161
	v_lshl_add_u64 v[230:231], v[186:187], 0, s[76:77]
	s_mov_b32 m0, s3
	v_readfirstlane_b32 s3, v162
	ds_read_b128 v[198:201], v146 offset:32768
	ds_read_b128 v[202:205], v146 offset:33792
	ds_read_b128 v[206:209], v145 offset:32768
	ds_read_b128 v[210:213], v145 offset:33792
	ds_read_b128 v[214:217], v144 offset:32768
	ds_read_b128 v[218:221], v144 offset:33792
	ds_read_b128 v[222:225], v143 offset:32768
	ds_read_b128 v[226:229], v143 offset:33792
	global_load_lds_dwordx4 v[230:231], off
	v_lshl_add_u64 v[230:231], v[188:189], 0, s[76:77]
	s_mov_b32 m0, s3
	s_nop 0
	global_load_lds_dwordx4 v[230:231], off
	s_waitcnt lgkmcnt(8)
	s_barrier
	s_waitcnt lgkmcnt(0)
	v_mfma_f32_16x16x32_bf16 v[126:129], v[168:171], v[198:201], v[126:129]
	v_mfma_f32_16x16x32_bf16 v[122:125], v[190:193], v[198:201], v[122:125]
	v_mfma_f32_16x16x32_bf16 v[118:121], v[168:171], v[206:209], v[118:121]
	v_mfma_f32_16x16x32_bf16 v[114:117], v[190:193], v[206:209], v[114:117]
	v_mfma_f32_16x16x32_bf16 v[110:113], v[168:171], v[214:217], v[110:113]
	v_mfma_f32_16x16x32_bf16 v[106:109], v[190:193], v[214:217], v[106:109]
	v_mfma_f32_16x16x32_bf16 v[102:105], v[168:171], v[222:225], v[102:105]
	v_mfma_f32_16x16x32_bf16 v[98:101], v[190:193], v[222:225], v[98:101]
	v_mfma_f32_16x16x32_bf16 v[126:129], v[172:175], v[202:205], v[126:129]
	v_mfma_f32_16x16x32_bf16 v[122:125], v[194:197], v[202:205], v[122:125]
	v_mfma_f32_16x16x32_bf16 v[118:121], v[172:175], v[210:213], v[118:121]
	v_mfma_f32_16x16x32_bf16 v[114:117], v[194:197], v[210:213], v[114:117]
	v_mfma_f32_16x16x32_bf16 v[110:113], v[172:175], v[218:221], v[110:113]
	v_mfma_f32_16x16x32_bf16 v[106:109], v[194:197], v[218:221], v[106:109]
	v_mfma_f32_16x16x32_bf16 v[102:105], v[172:175], v[226:229], v[102:105]
	v_mfma_f32_16x16x32_bf16 v[98:101], v[194:197], v[226:229], v[98:101]
	s_barrier
	v_readfirstlane_b32 s3, v149
	v_add_u32_e32 v167, 0x2000, v149
	v_lshl_add_u64 v[250:251], v[246:247], 0, s[30:31]
	s_mov_b32 m0, s3
	v_readfirstlane_b32 s3, v167
	ds_read_b128 v[230:233], v148
	ds_read_b128 v[234:237], v148 offset:1024
	ds_read_b128 v[238:241], v148 offset:2048
	ds_read_b128 v[242:245], v148 offset:3072
	global_load_lds_dwordx4 v[250:251], off
	v_lshl_add_u64 v[250:251], v[248:249], 0, s[30:31]
	s_mov_b32 m0, s3
	s_nop 0
	global_load_lds_dwordx4 v[250:251], off
	s_barrier
	s_waitcnt lgkmcnt(0)
	v_mfma_f32_16x16x32_bf16 v[94:97], v[230:233], v[198:201], v[94:97]
	v_mfma_f32_16x16x32_bf16 v[90:93], v[238:241], v[198:201], v[90:93]
	v_mfma_f32_16x16x32_bf16 v[86:89], v[230:233], v[206:209], v[86:89]
	v_mfma_f32_16x16x32_bf16 v[82:85], v[238:241], v[206:209], v[82:85]
	v_mfma_f32_16x16x32_bf16 v[78:81], v[230:233], v[214:217], v[78:81]
	v_mfma_f32_16x16x32_bf16 v[74:77], v[238:241], v[214:217], v[74:77]
	v_mfma_f32_16x16x32_bf16 v[70:73], v[230:233], v[222:225], v[70:73]
	v_mfma_f32_16x16x32_bf16 v[66:69], v[238:241], v[222:225], v[66:69]
	v_mfma_f32_16x16x32_bf16 v[94:97], v[234:237], v[202:205], v[94:97]
	v_mfma_f32_16x16x32_bf16 v[90:93], v[242:245], v[202:205], v[90:93]
	v_mfma_f32_16x16x32_bf16 v[86:89], v[234:237], v[210:213], v[86:89]
	v_mfma_f32_16x16x32_bf16 v[82:85], v[242:245], v[210:213], v[82:85]
	v_mfma_f32_16x16x32_bf16 v[78:81], v[234:237], v[218:221], v[78:81]
	v_mfma_f32_16x16x32_bf16 v[74:77], v[242:245], v[218:221], v[74:77]
	v_mfma_f32_16x16x32_bf16 v[70:73], v[234:237], v[226:229], v[70:73]
	v_mfma_f32_16x16x32_bf16 v[66:69], v[242:245], v[226:229], v[66:69]
	s_barrier
	v_readfirstlane_b32 s3, v151
	v_lshl_add_u64 v[186:187], v[186:187], 0, s[74:75]
	s_mov_b32 m0, s3
	v_readfirstlane_b32 s3, v152
	ds_read_b128 v[198:201], v146 offset:49152
	ds_read_b128 v[202:205], v146 offset:50176
	ds_read_b128 v[206:209], v145 offset:49152
	ds_read_b128 v[210:213], v145 offset:50176
	ds_read_b128 v[214:217], v144 offset:49152
	ds_read_b128 v[218:221], v144 offset:50176
	ds_read_b128 v[222:225], v143 offset:49152
	ds_read_b128 v[226:229], v143 offset:50176
	global_load_lds_dwordx4 v[186:187], off
	v_lshl_add_u64 v[186:187], v[188:189], 0, s[74:75]
	s_mov_b32 m0, s3
	s_nop 0
	global_load_lds_dwordx4 v[186:187], off
	s_barrier
; #define STAGE_A(P,br,kt) STAGE_G(P,c.A,c.lda,br,(long)(kt)*c.kstr)
; #define STAGE_B(P,br,kt) STAGE_G(P,c.Bt,c.K,br,(long)(kt)*BK)
; #define LDA(dst,b,h) for(int m=0;m<4;++m)for(int k=0;k<2;++k) \
;     dst[m][k]=*reinterpret_cast<const bf16x8*>((char*)SA(b,h)+lds_byte(wr*64+m*16+fr,k*32+fq*8))
; #define LDB(dst,b,h) for(int n=0;n<2;++n)for(int k=0;k<2;++k) \
;     dst[n][k]=*reinterpret_cast<const bf16x8*>((char*)SB(b,h)+lds_byte(wc*32+n*16+fr,k*32+fq*8))
; #define MMA(ai,bj,At,Bt_) do{__builtin_amdgcn_s_setprio(1); \
;     for(int m=0;m<4;++m)for(int n=0;n<2;++n)for(int k=0;k<2;++k) \
;       acc[ai][bj][m][n]=__builtin_amdgcn_mfma_f32_16x16x32_bf16(Bt_[n][k],At[m][k],acc[ai][bj][m][n],0,0,0); \
;     __builtin_amdgcn_s_setprio(0);}while(0)
; #define WAIT_V(n) asm volatile("s_waitcnt vmcnt(" #n ")":::"memory")
; #define WAIT_L(n) asm volatile("s_waitcnt lgkmcnt(" #n ")":::"memory")
; #define BAR __builtin_amdgcn_s_barrier()
; #define SCHED __builtin_amdgcn_sched_barrier(0)
; template <int EPI>
; __device__ __forceinline__ void gemm_run(const GD& c, const bool has_next, const GD& nx, const Ctx& e, bf16* shm, float* rs, float* rs_nxt, float* racc_) {
;     ...
;     BAR; WAIT_L(0); MMA(1,0,At,B0); BAR; SCHED;
;     STAGE_B(SB(1,1),bcol+HALF,t+3);
;     WAIT_V(6); BAR; MMA(1,1,At,B1); BAR;
;   }
;   { LDB(B0,0,0); LDA(At,0,0); STAGE_A(SA(1,1),brow+HALF,nt-1);
;     BAR; WAIT_L(0); MMA(0,0,At,B0); BAR;
;     LDB(B1,0,1); BAR; WAIT_L(0); MMA(0,1,At,B1); BAR;
	s_waitcnt lgkmcnt(0)
	v_mfma_f32_16x16x32_bf16 v[62:65], v[168:171], v[198:201], v[62:65]
	v_mfma_f32_16x16x32_bf16 v[58:61], v[190:193], v[198:201], v[58:61]
	v_mfma_f32_16x16x32_bf16 v[54:57], v[168:171], v[206:209], v[54:57]
	v_mfma_f32_16x16x32_bf16 v[50:53], v[190:193], v[206:209], v[50:53]
	v_mfma_f32_16x16x32_bf16 v[46:49], v[168:171], v[214:217], v[46:49]
	v_mfma_f32_16x16x32_bf16 v[42:45], v[190:193], v[214:217], v[42:45]
	v_mfma_f32_16x16x32_bf16 v[38:41], v[168:171], v[222:225], v[38:41]
	v_mfma_f32_16x16x32_bf16 v[34:37], v[190:193], v[222:225], v[34:37]
	v_mfma_f32_16x16x32_bf16 v[62:65], v[172:175], v[202:205], v[62:65]
	v_mfma_f32_16x16x32_bf16 v[58:61], v[194:197], v[202:205], v[58:61]
	v_mfma_f32_16x16x32_bf16 v[54:57], v[172:175], v[210:213], v[54:57]
	v_mfma_f32_16x16x32_bf16 v[50:53], v[194:197], v[210:213], v[50:53]
	v_mfma_f32_16x16x32_bf16 v[46:49], v[172:175], v[218:221], v[46:49]
	v_mfma_f32_16x16x32_bf16 v[42:45], v[194:197], v[218:221], v[42:45]
	v_mfma_f32_16x16x32_bf16 v[38:41], v[172:175], v[226:229], v[38:41]
	v_mfma_f32_16x16x32_bf16 v[34:37], v[194:197], v[226:229], v[34:37]
	s_barrier
	v_readfirstlane_b32 s3, v153
	v_add_u32_e32 v167, 0x2000, v153
	v_lshl_add_u64 v[168:169], v[246:247], 0, s[34:35]
	s_mov_b32 m0, s3
	v_readfirstlane_b32 s3, v167
	global_load_lds_dwordx4 v[168:169], off
	v_lshl_add_u64 v[168:169], v[248:249], 0, s[34:35]
	s_mov_b32 m0, s3
	s_nop 0
	global_load_lds_dwordx4 v[168:169], off
	s_waitcnt vmcnt(6)
	s_barrier
	v_mfma_f32_16x16x32_bf16 v[30:33], v[230:233], v[198:201], v[30:33]
	v_mfma_f32_16x16x32_bf16 v[26:29], v[238:241], v[198:201], v[26:29]
	v_mfma_f32_16x16x32_bf16 v[22:25], v[230:233], v[206:209], v[22:25]
	v_mfma_f32_16x16x32_bf16 v[18:21], v[238:241], v[206:209], v[18:21]
	s_add_i32 s2, s2, 2
	v_mfma_f32_16x16x32_bf16 v[14:17], v[230:233], v[214:217], v[14:17]
	v_lshl_add_u64 v[132:133], v[132:133], 0, s[88:89]
	v_mfma_f32_16x16x32_bf16 v[10:13], v[238:241], v[214:217], v[10:13]
	v_lshl_add_u64 v[134:135], v[134:135], 0, s[88:89]
	v_mfma_f32_16x16x32_bf16 v[6:9], v[230:233], v[222:225], v[6:9]
	v_lshl_add_u64 v[136:137], v[136:137], 0, s[88:89]
	v_mfma_f32_16x16x32_bf16 v[2:5], v[238:241], v[222:225], v[2:5]
	s_cmp_lt_u32 s2, 38
	v_mfma_f32_16x16x32_bf16 v[30:33], v[234:237], v[202:205], v[30:33]
	v_lshl_add_u64 v[138:139], v[138:139], 0, s[88:89]
	v_mfma_f32_16x16x32_bf16 v[26:29], v[242:245], v[202:205], v[26:29]
	v_mfma_f32_16x16x32_bf16 v[22:25], v[234:237], v[210:213], v[22:25]
	v_mfma_f32_16x16x32_bf16 v[18:21], v[242:245], v[210:213], v[18:21]
	v_mfma_f32_16x16x32_bf16 v[14:17], v[234:237], v[218:221], v[14:17]
	v_mfma_f32_16x16x32_bf16 v[10:13], v[242:245], v[218:221], v[10:13]
	v_mfma_f32_16x16x32_bf16 v[6:9], v[234:237], v[226:229], v[6:9]
	v_mfma_f32_16x16x32_bf16 v[2:5], v[242:245], v[226:229], v[2:5]
	s_barrier
	s_cbranch_scc1 .LBB0_326
	s_or_b32 s2, s15, 0x80
	s_mul_hi_i32 s3, s2, 0x1500
	s_mulk_i32 s2, 0x1500
	s_add_u32 s2, s21, s2
	s_addc_u32 s3, s22, s3
	v_readfirstlane_b32 s26, v163
	v_lshl_add_u64 v[152:153], s[2:3], 0, v[0:1]
	s_mov_b32 m0, s26
	ds_read_b128 v[132:135], v155
	ds_read_b128 v[136:139], v155 offset:1024
	ds_read_b128 v[168:171], v155 offset:2048
	ds_read_b128 v[172:175], v155 offset:3072
	ds_read_b128 v[190:193], v146
	ds_read_b128 v[194:197], v146 offset:1024
	ds_read_b128 v[198:201], v145
	ds_read_b128 v[202:205], v145 offset:1024
	ds_read_b128 v[206:209], v144
	ds_read_b128 v[210:213], v144 offset:1024
	ds_read_b128 v[214:217], v143
	ds_read_b128 v[218:221], v143 offset:1024
	global_load_lds_dwordx4 v[152:153], off
	v_lshl_add_u64 v[152:153], s[2:3], 0, v[130:131]
	v_readfirstlane_b32 s2, v166
	s_mov_b32 m0, s2
	s_nop 0
	global_load_lds_dwordx4 v[152:153], off
	s_barrier
	s_waitcnt lgkmcnt(0)
	v_mfma_f32_16x16x32_bf16 v[126:129], v[132:135], v[190:193], v[126:129]
	v_mfma_f32_16x16x32_bf16 v[122:125], v[168:171], v[190:193], v[122:125]
	v_mfma_f32_16x16x32_bf16 v[118:121], v[132:135], v[198:201], v[118:121]
	v_mfma_f32_16x16x32_bf16 v[114:117], v[168:171], v[198:201], v[114:117]
	v_mfma_f32_16x16x32_bf16 v[102:105], v[132:135], v[214:217], v[102:105]
	v_mfma_f32_16x16x32_bf16 v[98:101], v[168:171], v[214:217], v[98:101]
	v_mfma_f32_16x16x32_bf16 v[126:129], v[136:139], v[194:197], v[126:129]
	v_mfma_f32_16x16x32_bf16 v[122:125], v[172:175], v[194:197], v[122:125]
	v_mfma_f32_16x16x32_bf16 v[118:121], v[136:139], v[202:205], v[118:121]
	v_mfma_f32_16x16x32_bf16 v[114:117], v[172:175], v[202:205], v[114:117]
	v_mfma_f32_16x16x32_bf16 v[110:113], v[132:135], v[206:209], v[110:113]
	v_mfma_f32_16x16x32_bf16 v[106:109], v[168:171], v[206:209], v[106:109]
	v_mfma_f32_16x16x32_bf16 v[102:105], v[136:139], v[218:221], v[102:105]
	v_mfma_f32_16x16x32_bf16 v[98:101], v[172:175], v[218:221], v[98:101]
	v_mfma_f32_16x16x32_bf16 v[222:225], v[136:139], v[210:213], v[110:113]
	v_mfma_f32_16x16x32_bf16 v[226:229], v[172:175], v[210:213], v[106:109]
	s_barrier
	s_nop 1
	ds_read_b128 v[106:109], v154
	ds_read_b128 v[110:113], v154 offset:1024
	ds_read_b128 v[230:233], v154 offset:2048
	ds_read_b128 v[152:155], v154 offset:3072
	s_barrier
; #define LDA(dst,b,h) for(int m=0;m<4;++m)for(int k=0;k<2;++k) \
;     dst[m][k]=*reinterpret_cast<const bf16x8*>((char*)SA(b,h)+lds_byte(wr*64+m*16+fr,k*32+fq*8))
; #define LDB(dst,b,h) for(int n=0;n<2;++n)for(int k=0;k<2;++k) \
;     dst[n][k]=*reinterpret_cast<const bf16x8*>((char*)SB(b,h)+lds_byte(wc*32+n*16+fr,k*32+fq*8))
; #define MMA(ai,bj,At,Bt_) do{__builtin_amdgcn_s_setprio(1); \
;     for(int m=0;m<4;++m)for(int n=0;n<2;++n)for(int k=0;k<2;++k) \
;       acc[ai][bj][m][n]=__builtin_amdgcn_mfma_f32_16x16x32_bf16(Bt_[n][k],At[m][k],acc[ai][bj][m][n],0,0,0); \
;     __builtin_amdgcn_s_setprio(0);}while(0)
; #define WAIT_V(n) asm volatile("s_waitcnt vmcnt(" #n ")":::"memory")
; #define WAIT_L(n) asm volatile("s_waitcnt lgkmcnt(" #n ")":::"memory")
; #define BAR __builtin_amdgcn_s_barrier()
; template <int EPI>
; __device__ __forceinline__ void gemm_run(const GD& c, const bool has_next, const GD& nx, const Ctx& e, bf16* shm, float* rs, float* rs_nxt, float* racc_) {
;     ...
;     LDB(B1,0,1); BAR; WAIT_L(0); MMA(0,1,At,B1); BAR;
;     LDA(At,0,1); WAIT_V(4); BAR; WAIT_L(0); MMA(1,0,At,B0); MMA(1,1,At,B1); BAR; }
;   { LDB(B0,1,0); LDA(At,1,0); WAIT_V(2); BAR; WAIT_L(0); MMA(0,0,At,B0); BAR;
	s_waitcnt lgkmcnt(0)
	v_mfma_f32_16x16x32_bf16 v[86:89], v[106:109], v[198:201], v[86:89]
	v_mfma_f32_16x16x32_bf16 v[82:85], v[230:233], v[198:201], v[82:85]
	v_mfma_f32_16x16x32_bf16 v[70:73], v[106:109], v[214:217], v[70:73]
	v_mfma_f32_16x16x32_bf16 v[66:69], v[230:233], v[214:217], v[66:69]
	v_mfma_f32_16x16x32_bf16 v[94:97], v[106:109], v[190:193], v[94:97]
	v_mfma_f32_16x16x32_bf16 v[90:93], v[230:233], v[190:193], v[90:93]
	v_mfma_f32_16x16x32_bf16 v[86:89], v[110:113], v[202:205], v[86:89]
	v_mfma_f32_16x16x32_bf16 v[82:85], v[152:155], v[202:205], v[82:85]
	v_mfma_f32_16x16x32_bf16 v[78:81], v[106:109], v[206:209], v[78:81]
	v_mfma_f32_16x16x32_bf16 v[74:77], v[230:233], v[206:209], v[74:77]
	v_mfma_f32_16x16x32_bf16 v[70:73], v[110:113], v[218:221], v[70:73]
	v_mfma_f32_16x16x32_bf16 v[66:69], v[152:155], v[218:221], v[66:69]
	v_mfma_f32_16x16x32_bf16 v[234:237], v[110:113], v[194:197], v[94:97]
	v_mfma_f32_16x16x32_bf16 v[190:193], v[152:155], v[194:197], v[90:93]
	v_mfma_f32_16x16x32_bf16 v[194:197], v[110:113], v[210:213], v[78:81]
	v_mfma_f32_16x16x32_bf16 v[198:201], v[152:155], v[210:213], v[74:77]
	s_barrier
	s_nop 0
	ds_read_b128 v[74:77], v146 offset:16384
	ds_read_b128 v[78:81], v146 offset:17408
	ds_read_b128 v[90:93], v145 offset:16384
	ds_read_b128 v[94:97], v145 offset:17408
	ds_read_b128 v[202:205], v144 offset:16384
	ds_read_b128 v[206:209], v144 offset:17408
	ds_read_b128 v[210:213], v143 offset:16384
	ds_read_b128 v[214:217], v143 offset:17408
	s_waitcnt vmcnt(4)
	s_barrier
	s_waitcnt lgkmcnt(0)
	v_mfma_f32_16x16x32_bf16 v[62:65], v[132:135], v[74:77], v[62:65]
	v_mfma_f32_16x16x32_bf16 v[58:61], v[168:171], v[74:77], v[58:61]
	v_mfma_f32_16x16x32_bf16 v[54:57], v[132:135], v[90:93], v[54:57]
	v_mfma_f32_16x16x32_bf16 v[50:53], v[168:171], v[90:93], v[50:53]
	v_mfma_f32_16x16x32_bf16 v[38:41], v[132:135], v[210:213], v[38:41]
	v_mfma_f32_16x16x32_bf16 v[34:37], v[168:171], v[210:213], v[34:37]
	v_mfma_f32_16x16x32_bf16 v[62:65], v[136:139], v[78:81], v[62:65]
	v_mfma_f32_16x16x32_bf16 v[58:61], v[172:175], v[78:81], v[58:61]
	v_mfma_f32_16x16x32_bf16 v[54:57], v[136:139], v[94:97], v[54:57]
	v_mfma_f32_16x16x32_bf16 v[50:53], v[172:175], v[94:97], v[50:53]
	v_mfma_f32_16x16x32_bf16 v[46:49], v[132:135], v[202:205], v[46:49]
	v_mfma_f32_16x16x32_bf16 v[42:45], v[168:171], v[202:205], v[42:45]
	v_mfma_f32_16x16x32_bf16 v[38:41], v[136:139], v[214:217], v[38:41]
	v_mfma_f32_16x16x32_bf16 v[34:37], v[172:175], v[214:217], v[34:37]
	v_mfma_f32_16x16x32_bf16 v[218:221], v[136:139], v[206:209], v[46:49]
	v_mfma_f32_16x16x32_bf16 v[238:241], v[172:175], v[206:209], v[42:45]
	v_mfma_f32_16x16x32_bf16 v[22:25], v[106:109], v[90:93], v[22:25]
	v_mfma_f32_16x16x32_bf16 v[18:21], v[230:233], v[90:93], v[18:21]
	v_mfma_f32_16x16x32_bf16 v[6:9], v[106:109], v[210:213], v[6:9]
	v_mfma_f32_16x16x32_bf16 v[2:5], v[230:233], v[210:213], v[2:5]
	v_mfma_f32_16x16x32_bf16 v[30:33], v[106:109], v[74:77], v[30:33]
	v_mfma_f32_16x16x32_bf16 v[26:29], v[230:233], v[74:77], v[26:29]
	v_mfma_f32_16x16x32_bf16 v[22:25], v[110:113], v[94:97], v[22:25]
	v_mfma_f32_16x16x32_bf16 v[18:21], v[152:155], v[94:97], v[18:21]
	v_mfma_f32_16x16x32_bf16 v[14:17], v[106:109], v[202:205], v[14:17]
	v_mfma_f32_16x16x32_bf16 v[10:13], v[230:233], v[202:205], v[10:13]
	v_mfma_f32_16x16x32_bf16 v[6:9], v[110:113], v[214:217], v[6:9]
	v_mfma_f32_16x16x32_bf16 v[2:5], v[152:155], v[214:217], v[2:5]
	v_mfma_f32_16x16x32_bf16 v[132:135], v[110:113], v[78:81], v[30:33]
	v_mfma_f32_16x16x32_bf16 v[136:139], v[152:155], v[78:81], v[26:29]
	v_mfma_f32_16x16x32_bf16 v[166:169], v[110:113], v[206:209], v[14:17]
	v_mfma_f32_16x16x32_bf16 v[170:173], v[152:155], v[206:209], v[10:13]
	s_barrier
	s_nop 0
	ds_read_b128 v[10:13], v150
	ds_read_b128 v[14:17], v150 offset:1024
	ds_read_b128 v[152:155], v150 offset:2048
	ds_read_b128 v[202:205], v150 offset:3072
	ds_read_b128 v[26:29], v146 offset:32768
	ds_read_b128 v[30:33], v146 offset:33792
	ds_read_b128 v[42:45], v145 offset:32768
	ds_read_b128 v[46:49], v145 offset:33792
	ds_read_b128 v[206:209], v144 offset:32768
	ds_read_b128 v[210:213], v144 offset:33792
	ds_read_b128 v[214:217], v143 offset:32768
	ds_read_b128 v[230:233], v143 offset:33792
	s_waitcnt vmcnt(2)
	s_barrier
; #define LDA(dst,b,h) for(int m=0;m<4;++m)for(int k=0;k<2;++k) \
;     dst[m][k]=*reinterpret_cast<const bf16x8*>((char*)SA(b,h)+lds_byte(wr*64+m*16+fr,k*32+fq*8))
; #define LDB(dst,b,h) for(int n=0;n<2;++n)for(int k=0;k<2;++k) \
;     dst[n][k]=*reinterpret_cast<const bf16x8*>((char*)SB(b,h)+lds_byte(wc*32+n*16+fr,k*32+fq*8))
; #define MMA(ai,bj,At,Bt_) do{__builtin_amdgcn_s_setprio(1); \
;     for(int m=0;m<4;++m)for(int n=0;n<2;++n)for(int k=0;k<2;++k) \
;       acc[ai][bj][m][n]=__builtin_amdgcn_mfma_f32_16x16x32_bf16(Bt_[n][k],At[m][k],acc[ai][bj][m][n],0,0,0); \
;     __builtin_amdgcn_s_setprio(0);}while(0)
; #define WAIT_V(n) asm volatile("s_waitcnt vmcnt(" #n ")":::"memory")
; #define WAIT_L(n) asm volatile("s_waitcnt lgkmcnt(" #n ")":::"memory")
; #define BAR __builtin_amdgcn_s_barrier()
; template <int EPI>
; __device__ __forceinline__ void gemm_run(const GD& c, const bool has_next, const GD& nx, const Ctx& e, bf16* shm, float* rs, float* rs_nxt, float* racc_) {
;     ...
;   { LDB(B0,1,0); LDA(At,1,0); WAIT_V(2); BAR; WAIT_L(0); MMA(0,0,At,B0); BAR;
;     LDB(B1,1,1); WAIT_V(0); BAR; WAIT_L(0); MMA(0,1,At,B1); BAR;
;     LDA(At,1,1); BAR; WAIT_L(0); MMA(1,0,At,B0); MMA(1,1,At,B1); BAR; }
;   if(wr==0)BAR;
	s_waitcnt lgkmcnt(0)
	v_mfma_f32_16x16x32_bf16 v[74:77], v[10:13], v[26:29], v[126:129]
	v_mfma_f32_16x16x32_bf16 v[126:129], v[14:17], v[30:33], v[74:77]
	v_mfma_f32_16x16x32_bf16 v[74:77], v[152:155], v[26:29], v[122:125]
	v_mfma_f32_16x16x32_bf16 v[122:125], v[202:205], v[30:33], v[74:77]
	v_mfma_f32_16x16x32_bf16 v[74:77], v[10:13], v[42:45], v[118:121]
	v_mfma_f32_16x16x32_bf16 v[110:113], v[14:17], v[46:49], v[74:77]
	v_mfma_f32_16x16x32_bf16 v[74:77], v[152:155], v[42:45], v[114:117]
	v_mfma_f32_16x16x32_bf16 v[106:109], v[202:205], v[46:49], v[74:77]
	v_mfma_f32_16x16x32_bf16 v[74:77], v[10:13], v[206:209], v[222:225]
	v_mfma_f32_16x16x32_bf16 v[94:97], v[14:17], v[210:213], v[74:77]
	v_mfma_f32_16x16x32_bf16 v[74:77], v[152:155], v[206:209], v[226:229]
	v_mfma_f32_16x16x32_bf16 v[90:93], v[202:205], v[210:213], v[74:77]
	v_mfma_f32_16x16x32_bf16 v[74:77], v[10:13], v[214:217], v[102:105]
	v_mfma_f32_16x16x32_bf16 v[78:81], v[14:17], v[230:233], v[74:77]
	v_mfma_f32_16x16x32_bf16 v[74:77], v[152:155], v[214:217], v[98:101]
	v_mfma_f32_16x16x32_bf16 v[74:77], v[202:205], v[230:233], v[74:77]
	s_barrier
	ds_read_b128 v[222:225], v148
	ds_read_b128 v[226:229], v148 offset:1024
	ds_read_b128 v[242:245], v148 offset:2048
	ds_read_b128 v[148:151], v148 offset:3072
	s_waitcnt vmcnt(0)
	s_barrier
	s_waitcnt lgkmcnt(0)
	v_mfma_f32_16x16x32_bf16 v[98:101], v[222:225], v[26:29], v[234:237]
	v_mfma_f32_16x16x32_bf16 v[26:29], v[242:245], v[26:29], v[190:193]
	v_mfma_f32_16x16x32_bf16 v[114:117], v[148:151], v[30:33], v[26:29]
	v_mfma_f32_16x16x32_bf16 v[26:29], v[222:225], v[42:45], v[86:89]
	v_mfma_f32_16x16x32_bf16 v[102:105], v[226:229], v[46:49], v[26:29]
	v_mfma_f32_16x16x32_bf16 v[26:29], v[242:245], v[42:45], v[82:85]
	v_mfma_f32_16x16x32_bf16 v[118:121], v[226:229], v[30:33], v[98:101]
	v_mfma_f32_16x16x32_bf16 v[98:101], v[148:151], v[46:49], v[26:29]
	v_mfma_f32_16x16x32_bf16 v[26:29], v[222:225], v[206:209], v[194:197]
	v_mfma_f32_16x16x32_bf16 v[86:89], v[226:229], v[210:213], v[26:29]
	v_mfma_f32_16x16x32_bf16 v[26:29], v[242:245], v[206:209], v[198:201]
	v_mfma_f32_16x16x32_bf16 v[82:85], v[148:151], v[210:213], v[26:29]
	v_mfma_f32_16x16x32_bf16 v[26:29], v[222:225], v[214:217], v[70:73]
	v_mfma_f32_16x16x32_bf16 v[70:73], v[226:229], v[230:233], v[26:29]
	v_mfma_f32_16x16x32_bf16 v[26:29], v[242:245], v[214:217], v[66:69]
	v_mfma_f32_16x16x32_bf16 v[66:69], v[148:151], v[230:233], v[26:29]
	s_barrier
	ds_read_b128 v[190:193], v146 offset:49152
	ds_read_b128 v[194:197], v146 offset:50176
	ds_read_b128 v[198:201], v145 offset:49152
	ds_read_b128 v[206:209], v145 offset:50176
	ds_read_b128 v[210:213], v144 offset:49152
	ds_read_b128 v[144:147], v144 offset:50176
	ds_read_b128 v[214:217], v143 offset:49152
	ds_read_b128 v[230:233], v143 offset:50176
	s_barrier
	s_waitcnt lgkmcnt(0)
	v_mfma_f32_16x16x32_bf16 v[26:29], v[10:13], v[190:193], v[62:65]
	v_mfma_f32_16x16x32_bf16 v[62:65], v[14:17], v[194:197], v[26:29]
	v_mfma_f32_16x16x32_bf16 v[26:29], v[152:155], v[190:193], v[58:61]
	v_mfma_f32_16x16x32_bf16 v[58:61], v[202:205], v[194:197], v[26:29]
	v_mfma_f32_16x16x32_bf16 v[26:29], v[10:13], v[198:201], v[54:57]
	v_mfma_f32_16x16x32_bf16 v[46:49], v[14:17], v[206:209], v[26:29]
	v_mfma_f32_16x16x32_bf16 v[26:29], v[152:155], v[198:201], v[50:53]
	v_mfma_f32_16x16x32_bf16 v[42:45], v[202:205], v[206:209], v[26:29]
	v_mfma_f32_16x16x32_bf16 v[26:29], v[10:13], v[210:213], v[218:221]
	v_mfma_f32_16x16x32_bf16 v[10:13], v[10:13], v[214:217], v[38:41]
	v_mfma_f32_16x16x32_bf16 v[30:33], v[14:17], v[144:147], v[26:29]
	v_mfma_f32_16x16x32_bf16 v[26:29], v[152:155], v[210:213], v[238:241]
	v_mfma_f32_16x16x32_bf16 v[14:17], v[14:17], v[230:233], v[10:13]
	v_mfma_f32_16x16x32_bf16 v[10:13], v[152:155], v[214:217], v[34:37]
	v_mfma_f32_16x16x32_bf16 v[26:29], v[202:205], v[144:147], v[26:29]
	v_mfma_f32_16x16x32_bf16 v[10:13], v[202:205], v[230:233], v[10:13]
	v_mfma_f32_16x16x32_bf16 v[34:37], v[222:225], v[190:193], v[132:135]
	v_mfma_f32_16x16x32_bf16 v[54:57], v[226:229], v[194:197], v[34:37]
	v_mfma_f32_16x16x32_bf16 v[34:37], v[242:245], v[190:193], v[136:139]
	v_mfma_f32_16x16x32_bf16 v[18:21], v[242:245], v[198:201], v[18:21]
	v_mfma_f32_16x16x32_bf16 v[50:53], v[148:151], v[194:197], v[34:37]
	v_mfma_f32_16x16x32_bf16 v[22:25], v[222:225], v[198:201], v[22:25]
	v_mfma_f32_16x16x32_bf16 v[34:37], v[148:151], v[206:209], v[18:21]
	v_mfma_f32_16x16x32_bf16 v[18:21], v[222:225], v[210:213], v[166:169]
	v_mfma_f32_16x16x32_bf16 v[38:41], v[226:229], v[206:209], v[22:25]
	v_mfma_f32_16x16x32_bf16 v[22:25], v[226:229], v[144:147], v[18:21]
	v_mfma_f32_16x16x32_bf16 v[18:21], v[242:245], v[210:213], v[170:173]
	v_mfma_f32_16x16x32_bf16 v[6:9], v[222:225], v[214:217], v[6:9]
	v_mfma_f32_16x16x32_bf16 v[2:5], v[242:245], v[214:217], v[2:5]
	v_mfma_f32_16x16x32_bf16 v[18:21], v[148:151], v[144:147], v[18:21]
	v_mfma_f32_16x16x32_bf16 v[6:9], v[226:229], v[230:233], v[6:9]
	v_mfma_f32_16x16x32_bf16 v[2:5], v[148:151], v[230:233], v[2:5]
	v_cmp_gt_u32_e32 vcc, s96, v141
	s_barrier
	s_and_saveexec_b64 s[2:3], vcc
	s_cbranch_execz .LBB0_329
	s_barrier

; #define STAGE_A(P,br,kt) STAGE_G(P,c.A,c.lda,br,(long)(kt)*c.kstr)
; #define STAGE_B(P,br,kt) STAGE_G(P,c.Bt,c.K,br,(long)(kt)*BK)
; #define LDA(dst,b,h) for(int m=0;m<4;++m)for(int k=0;k<2;++k) \
;     dst[m][k]=*reinterpret_cast<const bf16x8*>((char*)SA(b,h)+lds_byte(wr*64+m*16+fr,k*32+fq*8))
; #define LDB(dst,b,h) for(int n=0;n<2;++n)for(int k=0;k<2;++k) \
;     dst[n][k]=*reinterpret_cast<const bf16x8*>((char*)SB(b,h)+lds_byte(wc*32+n*16+fr,k*32+fq*8))
; #define MMA(ai,bj,At,Bt_) do{__builtin_amdgcn_s_setprio(1); \
;     for(int m=0;m<4;++m)for(int n=0;n<2;++n)for(int k=0;k<2;++k) \
;       acc[ai][bj][m][n]=__builtin_amdgcn_mfma_f32_16x16x32_bf16(Bt_[n][k],At[m][k],acc[ai][bj][m][n],0,0,0); \
;     __builtin_amdgcn_s_setprio(0);}while(0)
; #define WAIT_L(n) asm volatile("s_waitcnt lgkmcnt(" #n ")":::"memory")
; #define BAR __builtin_amdgcn_s_barrier()
; #define SCHED __builtin_amdgcn_sched_barrier(0)
; template <int EPI>
; __device__ __forceinline__ void gemm_run(const GD& c, const bool has_next, const GD& nx, const Ctx& e, bf16* shm, float* rs, float* rs_nxt, float* racc_) {
;     ...
;     LDB(B0,0,0); SCHED; LDA(At,0,0); STAGE_A(SA(1,1),brow+HALF,t+1);
;     WAIT_L(8); BAR; WAIT_L(0); MMA(0,0,At,B0); BAR; SCHED;
;     LDB(B1,0,1); STAGE_B(SB(0,0),bcol,t+2);
;     BAR; WAIT_L(0); MMA(0,1,At,B1); BAR;
;     LDA(At,0,1); STAGE_A(SA(0,0),brow,t+2);
;     BAR; WAIT_L(0); MMA(1,0,At,B0); BAR; SCHED;
.LBB0_357:
	ds_read_b128 v[158:161], v155
	ds_read_b128 v[166:169], v155 offset:1024
	ds_read_b128 v[170:173], v155 offset:2048
	ds_read_b128 v[190:193], v155 offset:3072
	v_add_u32_e32 v156, 0xc000, v150
	v_lshl_add_u64 v[162:163], v[132:133], 0, s[4:5]
	v_readfirstlane_b32 s12, v156
	v_lshl_add_u64 v[174:175], v[162:163], 0, s[90:91]
	s_mov_b32 m0, s12
	v_add_u32_e32 v157, 0xe000, v150
	ds_read_b128 v[194:197], v145
	ds_read_b128 v[198:201], v145 offset:1024
	ds_read_b128 v[202:205], v144
	ds_read_b128 v[206:209], v144 offset:1024
	ds_read_b128 v[210:213], v143
	ds_read_b128 v[214:217], v143 offset:1024
	ds_read_b128 v[218:221], v142
	ds_read_b128 v[222:225], v142 offset:1024
	global_load_lds_dwordx4 v[174:175], off
	v_lshl_add_u64 v[174:175], v[134:135], 0, s[4:5]
	v_readfirstlane_b32 s12, v157
	v_lshl_add_u64 v[186:187], v[174:175], 0, s[90:91]
	s_mov_b32 m0, s12
	s_nop 0
	global_load_lds_dwordx4 v[186:187], off
	s_waitcnt lgkmcnt(8)
	s_barrier
	s_waitcnt lgkmcnt(0)
	v_mfma_f32_16x16x32_bf16 v[126:129], v[158:161], v[194:197], v[126:129]
	v_mfma_f32_16x16x32_bf16 v[122:125], v[170:173], v[194:197], v[122:125]
	v_mfma_f32_16x16x32_bf16 v[118:121], v[158:161], v[202:205], v[118:121]
	v_mfma_f32_16x16x32_bf16 v[114:117], v[170:173], v[202:205], v[114:117]
	v_mfma_f32_16x16x32_bf16 v[110:113], v[158:161], v[210:213], v[110:113]
	v_mfma_f32_16x16x32_bf16 v[106:109], v[170:173], v[210:213], v[106:109]
	v_mfma_f32_16x16x32_bf16 v[102:105], v[158:161], v[218:221], v[102:105]
	v_mfma_f32_16x16x32_bf16 v[98:101], v[170:173], v[218:221], v[98:101]
	v_mfma_f32_16x16x32_bf16 v[126:129], v[166:169], v[198:201], v[126:129]
	v_mfma_f32_16x16x32_bf16 v[122:125], v[190:193], v[198:201], v[122:125]
	v_mfma_f32_16x16x32_bf16 v[118:121], v[166:169], v[206:209], v[118:121]
	v_mfma_f32_16x16x32_bf16 v[114:117], v[190:193], v[206:209], v[114:117]
	v_mfma_f32_16x16x32_bf16 v[110:113], v[166:169], v[214:217], v[110:113]
	v_mfma_f32_16x16x32_bf16 v[106:109], v[190:193], v[214:217], v[106:109]
	v_mfma_f32_16x16x32_bf16 v[102:105], v[166:169], v[222:225], v[102:105]
	v_mfma_f32_16x16x32_bf16 v[98:101], v[190:193], v[222:225], v[98:101]
	s_barrier
	v_add_u32_e32 v176, s33, v146
	v_lshl_add_u64 v[186:187], v[136:137], 0, s[4:5]
	v_readfirstlane_b32 s12, v176
	v_lshl_add_u64 v[188:189], v[186:187], 0, s[26:27]
	s_mov_b32 m0, s12
	v_add_u32_e32 v176, 0x2000, v176
	ds_read_b128 v[226:229], v154
	ds_read_b128 v[230:233], v154 offset:1024
	ds_read_b128 v[234:237], v154 offset:2048
	ds_read_b128 v[238:241], v154 offset:3072
	global_load_lds_dwordx4 v[188:189], off
	v_lshl_add_u64 v[188:189], v[138:139], 0, s[4:5]
	v_readfirstlane_b32 s12, v176
	v_lshl_add_u64 v[242:243], v[188:189], 0, s[26:27]
	s_mov_b32 m0, s12
	s_add_i32 s11, s11, 2
	global_load_lds_dwordx4 v[242:243], off
	s_barrier
	s_waitcnt lgkmcnt(0)
	v_mfma_f32_16x16x32_bf16 v[94:97], v[226:229], v[194:197], v[94:97]
	v_mfma_f32_16x16x32_bf16 v[90:93], v[234:237], v[194:197], v[90:93]
	v_mfma_f32_16x16x32_bf16 v[86:89], v[226:229], v[202:205], v[86:89]
	v_mfma_f32_16x16x32_bf16 v[82:85], v[234:237], v[202:205], v[82:85]
	v_mfma_f32_16x16x32_bf16 v[78:81], v[226:229], v[210:213], v[78:81]
	v_mfma_f32_16x16x32_bf16 v[74:77], v[234:237], v[210:213], v[74:77]
	v_mfma_f32_16x16x32_bf16 v[70:73], v[226:229], v[218:221], v[70:73]
	v_mfma_f32_16x16x32_bf16 v[66:69], v[234:237], v[218:221], v[66:69]
	v_mfma_f32_16x16x32_bf16 v[94:97], v[230:233], v[198:201], v[94:97]
	v_mfma_f32_16x16x32_bf16 v[90:93], v[238:241], v[198:201], v[90:93]
	v_mfma_f32_16x16x32_bf16 v[86:89], v[230:233], v[206:209], v[86:89]
	v_mfma_f32_16x16x32_bf16 v[82:85], v[238:241], v[206:209], v[82:85]
	v_mfma_f32_16x16x32_bf16 v[78:81], v[230:233], v[214:217], v[78:81]
	v_mfma_f32_16x16x32_bf16 v[74:77], v[238:241], v[214:217], v[74:77]
	v_mfma_f32_16x16x32_bf16 v[70:73], v[230:233], v[222:225], v[70:73]
	v_mfma_f32_16x16x32_bf16 v[66:69], v[238:241], v[222:225], v[66:69]
	s_barrier
	v_readfirstlane_b32 s12, v150
	v_add_u32_e32 v176, 0x2000, v150
	v_lshl_add_u64 v[242:243], v[162:163], 0, s[0:1]
	s_mov_b32 m0, s12
	v_readfirstlane_b32 s12, v176
	ds_read_b128 v[194:197], v145 offset:16384
	ds_read_b128 v[198:201], v145 offset:17408
	ds_read_b128 v[202:205], v144 offset:16384
	ds_read_b128 v[206:209], v144 offset:17408
	ds_read_b128 v[210:213], v143 offset:16384
	ds_read_b128 v[214:217], v143 offset:17408
	ds_read_b128 v[218:221], v142 offset:16384
	ds_read_b128 v[222:225], v142 offset:17408
	global_load_lds_dwordx4 v[242:243], off
	v_lshl_add_u64 v[242:243], v[174:175], 0, s[0:1]
	s_mov_b32 m0, s12
	s_nop 0
	global_load_lds_dwordx4 v[242:243], off
	s_barrier
	s_waitcnt lgkmcnt(0)
	v_mfma_f32_16x16x32_bf16 v[62:65], v[158:161], v[194:197], v[62:65]
	v_mfma_f32_16x16x32_bf16 v[58:61], v[170:173], v[194:197], v[58:61]
	v_mfma_f32_16x16x32_bf16 v[54:57], v[158:161], v[202:205], v[54:57]
	v_mfma_f32_16x16x32_bf16 v[50:53], v[170:173], v[202:205], v[50:53]
	v_mfma_f32_16x16x32_bf16 v[46:49], v[158:161], v[210:213], v[46:49]
	v_mfma_f32_16x16x32_bf16 v[42:45], v[170:173], v[210:213], v[42:45]
	v_mfma_f32_16x16x32_bf16 v[38:41], v[158:161], v[218:221], v[38:41]
	v_mfma_f32_16x16x32_bf16 v[34:37], v[170:173], v[218:221], v[34:37]
	v_mfma_f32_16x16x32_bf16 v[62:65], v[166:169], v[198:201], v[62:65]
	v_mfma_f32_16x16x32_bf16 v[58:61], v[190:193], v[198:201], v[58:61]
	v_mfma_f32_16x16x32_bf16 v[54:57], v[166:169], v[206:209], v[54:57]
	v_mfma_f32_16x16x32_bf16 v[50:53], v[190:193], v[206:209], v[50:53]
	v_mfma_f32_16x16x32_bf16 v[46:49], v[166:169], v[214:217], v[46:49]
	v_mfma_f32_16x16x32_bf16 v[42:45], v[190:193], v[214:217], v[42:45]
	v_mfma_f32_16x16x32_bf16 v[38:41], v[166:169], v[222:225], v[38:41]
	v_mfma_f32_16x16x32_bf16 v[34:37], v[190:193], v[222:225], v[34:37]
	s_barrier
; #define STAGE_A(P,br,kt) STAGE_G(P,c.A,c.lda,br,(long)(kt)*c.kstr)
; #define STAGE_B(P,br,kt) STAGE_G(P,c.Bt,c.K,br,(long)(kt)*BK)
; #define LDA(dst,b,h) for(int m=0;m<4;++m)for(int k=0;k<2;++k) \
;     dst[m][k]=*reinterpret_cast<const bf16x8*>((char*)SA(b,h)+lds_byte(wr*64+m*16+fr,k*32+fq*8))
; #define LDB(dst,b,h) for(int n=0;n<2;++n)for(int k=0;k<2;++k) \
;     dst[n][k]=*reinterpret_cast<const bf16x8*>((char*)SB(b,h)+lds_byte(wc*32+n*16+fr,k*32+fq*8))
; #define MMA(ai,bj,At,Bt_) do{__builtin_amdgcn_s_setprio(1); \
;     for(int m=0;m<4;++m)for(int n=0;n<2;++n)for(int k=0;k<2;++k) \
;       acc[ai][bj][m][n]=__builtin_amdgcn_mfma_f32_16x16x32_bf16(Bt_[n][k],At[m][k],acc[ai][bj][m][n],0,0,0); \
;     __builtin_amdgcn_s_setprio(0);}while(0)
; #define WAIT_V(n) asm volatile("s_waitcnt vmcnt(" #n ")":::"memory")
; #define WAIT_L(n) asm volatile("s_waitcnt lgkmcnt(" #n ")":::"memory")
; #define BAR __builtin_amdgcn_s_barrier()
; #define SCHED __builtin_amdgcn_sched_barrier(0)
; template <int EPI>
; __device__ __forceinline__ void gemm_run(const GD& c, const bool has_next, const GD& nx, const Ctx& e, bf16* shm, float* rs, float* rs_nxt, float* racc_) {
;     ...
;     STAGE_B(SB(0,1),bcol+HALF,t+2);
;     WAIT_V(6); BAR; MMA(1,1,At,B1); BAR;
;     LDB(B0,1,0); SCHED; LDA(At,1,0); STAGE_A(SA(0,1),brow+HALF,t+2);
;     WAIT_L(8); BAR; WAIT_L(0); MMA(0,0,At,B0); BAR; SCHED;
;     LDB(B1,1,1); STAGE_B(SB(1,0),bcol,t+3);
;     BAR; WAIT_L(0); MMA(0,1,At,B1); BAR;
;     LDA(At,1,1); STAGE_A(SA(1,0),brow,t+3);
	v_add_u32_e32 v160, s86, v146
	v_lshl_add_u64 v[158:159], v[186:187], 0, s[28:29]
	v_readfirstlane_b32 s12, v160
	v_add_u32_e32 v160, 0x2000, v160
	s_mov_b32 m0, s12
	v_readfirstlane_b32 s12, v160
	global_load_lds_dwordx4 v[158:159], off
	v_lshl_add_u64 v[158:159], v[188:189], 0, s[28:29]
	s_mov_b32 m0, s12
	s_nop 0
	global_load_lds_dwordx4 v[158:159], off
	s_waitcnt vmcnt(6)
	s_barrier
	v_mfma_f32_16x16x32_bf16 v[30:33], v[226:229], v[194:197], v[30:33]
	v_mfma_f32_16x16x32_bf16 v[26:29], v[234:237], v[194:197], v[26:29]
	v_mfma_f32_16x16x32_bf16 v[22:25], v[226:229], v[202:205], v[22:25]
	v_mfma_f32_16x16x32_bf16 v[18:21], v[234:237], v[202:205], v[18:21]
	v_mfma_f32_16x16x32_bf16 v[14:17], v[226:229], v[210:213], v[14:17]
	v_mfma_f32_16x16x32_bf16 v[10:13], v[234:237], v[210:213], v[10:13]
	v_mfma_f32_16x16x32_bf16 v[6:9], v[226:229], v[218:221], v[6:9]
	v_mfma_f32_16x16x32_bf16 v[2:5], v[234:237], v[218:221], v[2:5]
	v_mfma_f32_16x16x32_bf16 v[30:33], v[230:233], v[198:201], v[30:33]
	v_mfma_f32_16x16x32_bf16 v[26:29], v[238:241], v[198:201], v[26:29]
	v_mfma_f32_16x16x32_bf16 v[22:25], v[230:233], v[206:209], v[22:25]
	v_mfma_f32_16x16x32_bf16 v[18:21], v[238:241], v[206:209], v[18:21]
	v_mfma_f32_16x16x32_bf16 v[14:17], v[230:233], v[214:217], v[14:17]
	v_mfma_f32_16x16x32_bf16 v[10:13], v[238:241], v[214:217], v[10:13]
	v_mfma_f32_16x16x32_bf16 v[6:9], v[230:233], v[222:225], v[6:9]
	v_mfma_f32_16x16x32_bf16 v[2:5], v[238:241], v[222:225], v[2:5]
	s_barrier
	ds_read_b128 v[158:161], v149
	ds_read_b128 v[166:169], v149 offset:1024
	ds_read_b128 v[170:173], v149 offset:2048
	ds_read_b128 v[190:193], v149 offset:3072
	v_add_u32_e32 v176, 0x4000, v150
	v_lshl_add_u64 v[226:227], v[162:163], 0, s[76:77]
	v_readfirstlane_b32 s12, v176
	v_add_u32_e32 v176, 0x6000, v150
	s_mov_b32 m0, s12
	v_readfirstlane_b32 s12, v176
	ds_read_b128 v[194:197], v145 offset:32768
	ds_read_b128 v[198:201], v145 offset:33792
	ds_read_b128 v[202:205], v144 offset:32768
	ds_read_b128 v[206:209], v144 offset:33792
	ds_read_b128 v[210:213], v143 offset:32768
	ds_read_b128 v[214:217], v143 offset:33792
	ds_read_b128 v[218:221], v142 offset:32768
	ds_read_b128 v[222:225], v142 offset:33792
	global_load_lds_dwordx4 v[226:227], off
	v_lshl_add_u64 v[226:227], v[174:175], 0, s[76:77]
	s_mov_b32 m0, s12
	s_nop 0
	global_load_lds_dwordx4 v[226:227], off
	s_waitcnt lgkmcnt(8)
	s_barrier
	s_waitcnt lgkmcnt(0)
	v_mfma_f32_16x16x32_bf16 v[126:129], v[158:161], v[194:197], v[126:129]
	v_mfma_f32_16x16x32_bf16 v[122:125], v[170:173], v[194:197], v[122:125]
	v_mfma_f32_16x16x32_bf16 v[118:121], v[158:161], v[202:205], v[118:121]
	v_mfma_f32_16x16x32_bf16 v[114:117], v[170:173], v[202:205], v[114:117]
	v_mfma_f32_16x16x32_bf16 v[110:113], v[158:161], v[210:213], v[110:113]
	v_mfma_f32_16x16x32_bf16 v[106:109], v[170:173], v[210:213], v[106:109]
	v_mfma_f32_16x16x32_bf16 v[102:105], v[158:161], v[218:221], v[102:105]
	v_mfma_f32_16x16x32_bf16 v[98:101], v[170:173], v[218:221], v[98:101]
	v_mfma_f32_16x16x32_bf16 v[126:129], v[166:169], v[198:201], v[126:129]
	v_mfma_f32_16x16x32_bf16 v[122:125], v[190:193], v[198:201], v[122:125]
	v_mfma_f32_16x16x32_bf16 v[118:121], v[166:169], v[206:209], v[118:121]
	v_mfma_f32_16x16x32_bf16 v[114:117], v[190:193], v[206:209], v[114:117]
	v_mfma_f32_16x16x32_bf16 v[110:113], v[166:169], v[214:217], v[110:113]
	v_mfma_f32_16x16x32_bf16 v[106:109], v[190:193], v[214:217], v[106:109]
	v_mfma_f32_16x16x32_bf16 v[102:105], v[166:169], v[222:225], v[102:105]
	v_mfma_f32_16x16x32_bf16 v[98:101], v[190:193], v[222:225], v[98:101]
	s_barrier
	v_readfirstlane_b32 s12, v148
	v_add_u32_e32 v176, 0x2000, v148
	v_lshl_add_u64 v[242:243], v[186:187], 0, s[30:31]
	s_mov_b32 m0, s12
	v_readfirstlane_b32 s12, v176
	ds_read_b128 v[226:229], v147
	ds_read_b128 v[230:233], v147 offset:1024
	ds_read_b128 v[234:237], v147 offset:2048
	ds_read_b128 v[238:241], v147 offset:3072
	global_load_lds_dwordx4 v[242:243], off
	v_lshl_add_u64 v[242:243], v[188:189], 0, s[30:31]
	s_mov_b32 m0, s12
	s_nop 0
	global_load_lds_dwordx4 v[242:243], off
	s_barrier
	s_waitcnt lgkmcnt(0)
	v_mfma_f32_16x16x32_bf16 v[94:97], v[226:229], v[194:197], v[94:97]
	v_mfma_f32_16x16x32_bf16 v[90:93], v[234:237], v[194:197], v[90:93]
	v_mfma_f32_16x16x32_bf16 v[86:89], v[226:229], v[202:205], v[86:89]
	v_mfma_f32_16x16x32_bf16 v[82:85], v[234:237], v[202:205], v[82:85]
	v_mfma_f32_16x16x32_bf16 v[78:81], v[226:229], v[210:213], v[78:81]
	v_mfma_f32_16x16x32_bf16 v[74:77], v[234:237], v[210:213], v[74:77]
	v_mfma_f32_16x16x32_bf16 v[70:73], v[226:229], v[218:221], v[70:73]
	v_mfma_f32_16x16x32_bf16 v[66:69], v[234:237], v[218:221], v[66:69]
	v_mfma_f32_16x16x32_bf16 v[94:97], v[230:233], v[198:201], v[94:97]
	v_mfma_f32_16x16x32_bf16 v[90:93], v[238:241], v[198:201], v[90:93]
	v_mfma_f32_16x16x32_bf16 v[86:89], v[230:233], v[206:209], v[86:89]
	v_mfma_f32_16x16x32_bf16 v[82:85], v[238:241], v[206:209], v[82:85]
	v_mfma_f32_16x16x32_bf16 v[78:81], v[230:233], v[214:217], v[78:81]
	v_mfma_f32_16x16x32_bf16 v[74:77], v[238:241], v[214:217], v[74:77]
	v_mfma_f32_16x16x32_bf16 v[70:73], v[230:233], v[222:225], v[70:73]
	v_mfma_f32_16x16x32_bf16 v[66:69], v[238:241], v[222:225], v[66:69]
	s_barrier
	v_readfirstlane_b32 s12, v151
	v_lshl_add_u64 v[162:163], v[162:163], 0, s[74:75]
	s_mov_b32 m0, s12
	v_readfirstlane_b32 s12, v152
	ds_read_b128 v[194:197], v145 offset:49152
	ds_read_b128 v[198:201], v145 offset:50176
	ds_read_b128 v[202:205], v144 offset:49152
	ds_read_b128 v[206:209], v144 offset:50176
	ds_read_b128 v[210:213], v143 offset:49152
	ds_read_b128 v[214:217], v143 offset:50176
	ds_read_b128 v[218:221], v142 offset:49152
	ds_read_b128 v[222:225], v142 offset:50176
	global_load_lds_dwordx4 v[162:163], off
	v_lshl_add_u64 v[162:163], v[174:175], 0, s[74:75]
	s_mov_b32 m0, s12
	s_nop 0
	global_load_lds_dwordx4 v[162:163], off
	s_barrier
; #define STAGE_A(P,br,kt) STAGE_G(P,c.A,c.lda,br,(long)(kt)*c.kstr)
; #define STAGE_B(P,br,kt) STAGE_G(P,c.Bt,c.K,br,(long)(kt)*BK)
; #define LDA(dst,b,h) for(int m=0;m<4;++m)for(int k=0;k<2;++k) \
;     dst[m][k]=*reinterpret_cast<const bf16x8*>((char*)SA(b,h)+lds_byte(wr*64+m*16+fr,k*32+fq*8))
; #define LDB(dst,b,h) for(int n=0;n<2;++n)for(int k=0;k<2;++k) \
;     dst[n][k]=*reinterpret_cast<const bf16x8*>((char*)SB(b,h)+lds_byte(wc*32+n*16+fr,k*32+fq*8))
; #define MMA(ai,bj,At,Bt_) do{__builtin_amdgcn_s_setprio(1); \
;     for(int m=0;m<4;++m)for(int n=0;n<2;++n)for(int k=0;k<2;++k) \
;       acc[ai][bj][m][n]=__builtin_amdgcn_mfma_f32_16x16x32_bf16(Bt_[n][k],At[m][k],acc[ai][bj][m][n],0,0,0); \
;     __builtin_amdgcn_s_setprio(0);}while(0)
; #define WAIT_V(n) asm volatile("s_waitcnt vmcnt(" #n ")":::"memory")
; #define WAIT_L(n) asm volatile("s_waitcnt lgkmcnt(" #n ")":::"memory")
; #define BAR __builtin_amdgcn_s_barrier()
; #define SCHED __builtin_amdgcn_sched_barrier(0)
; template <int EPI>
; __device__ __forceinline__ void gemm_run(const GD& c, const bool has_next, const GD& nx, const Ctx& e, bf16* shm, float* rs, float* rs_nxt, float* racc_) {
;     ...
;     BAR; WAIT_L(0); MMA(1,0,At,B0); BAR; SCHED;
;     STAGE_B(SB(1,1),bcol+HALF,t+3);
;     WAIT_V(6); BAR; MMA(1,1,At,B1); BAR;
;   }
;   { LDB(B0,0,0); LDA(At,0,0); STAGE_A(SA(1,1),brow+HALF,nt-1);
;     BAR; WAIT_L(0); MMA(0,0,At,B0); BAR;
;     LDB(B1,0,1); BAR; WAIT_L(0); MMA(0,1,At,B1); BAR;
	s_waitcnt lgkmcnt(0)
	v_mfma_f32_16x16x32_bf16 v[62:65], v[158:161], v[194:197], v[62:65]
	v_mfma_f32_16x16x32_bf16 v[58:61], v[170:173], v[194:197], v[58:61]
	v_mfma_f32_16x16x32_bf16 v[54:57], v[158:161], v[202:205], v[54:57]
	v_mfma_f32_16x16x32_bf16 v[50:53], v[170:173], v[202:205], v[50:53]
	v_mfma_f32_16x16x32_bf16 v[46:49], v[158:161], v[210:213], v[46:49]
	v_mfma_f32_16x16x32_bf16 v[42:45], v[170:173], v[210:213], v[42:45]
	v_mfma_f32_16x16x32_bf16 v[38:41], v[158:161], v[218:221], v[38:41]
	v_mfma_f32_16x16x32_bf16 v[34:37], v[170:173], v[218:221], v[34:37]
	v_mfma_f32_16x16x32_bf16 v[62:65], v[166:169], v[198:201], v[62:65]
	v_mfma_f32_16x16x32_bf16 v[58:61], v[190:193], v[198:201], v[58:61]
	v_mfma_f32_16x16x32_bf16 v[54:57], v[166:169], v[206:209], v[54:57]
	v_mfma_f32_16x16x32_bf16 v[50:53], v[190:193], v[206:209], v[50:53]
	v_mfma_f32_16x16x32_bf16 v[46:49], v[166:169], v[214:217], v[46:49]
	v_mfma_f32_16x16x32_bf16 v[42:45], v[190:193], v[214:217], v[42:45]
	v_mfma_f32_16x16x32_bf16 v[38:41], v[166:169], v[222:225], v[38:41]
	v_mfma_f32_16x16x32_bf16 v[34:37], v[190:193], v[222:225], v[34:37]
	s_barrier
	v_readfirstlane_b32 s12, v153
	v_add_u32_e32 v160, 0x2000, v153
	v_lshl_add_u64 v[158:159], v[186:187], 0, s[34:35]
	s_mov_b32 m0, s12
	v_readfirstlane_b32 s12, v160
	global_load_lds_dwordx4 v[158:159], off
	v_lshl_add_u64 v[158:159], v[188:189], 0, s[34:35]
	s_mov_b32 m0, s12
	s_nop 0
	global_load_lds_dwordx4 v[158:159], off
	s_waitcnt vmcnt(6)
	s_barrier
	v_mfma_f32_16x16x32_bf16 v[30:33], v[226:229], v[194:197], v[30:33]
	v_mfma_f32_16x16x32_bf16 v[26:29], v[234:237], v[194:197], v[26:29]
	v_mfma_f32_16x16x32_bf16 v[22:25], v[226:229], v[202:205], v[22:25]
	v_mfma_f32_16x16x32_bf16 v[18:21], v[234:237], v[202:205], v[18:21]
	v_lshl_add_u64 v[132:133], v[132:133], 0, s[88:89]
	v_mfma_f32_16x16x32_bf16 v[14:17], v[226:229], v[210:213], v[14:17]
	v_lshl_add_u64 v[134:135], v[134:135], 0, s[88:89]
	v_mfma_f32_16x16x32_bf16 v[10:13], v[234:237], v[210:213], v[10:13]
	v_lshl_add_u64 v[136:137], v[136:137], 0, s[88:89]
	v_mfma_f32_16x16x32_bf16 v[6:9], v[226:229], v[218:221], v[6:9]
	s_cmp_lt_u32 s11, s10
	v_mfma_f32_16x16x32_bf16 v[2:5], v[234:237], v[218:221], v[2:5]
	v_lshl_add_u64 v[138:139], v[138:139], 0, s[88:89]
	v_mfma_f32_16x16x32_bf16 v[30:33], v[230:233], v[198:201], v[30:33]
	v_mfma_f32_16x16x32_bf16 v[26:29], v[238:241], v[198:201], v[26:29]
	v_mfma_f32_16x16x32_bf16 v[22:25], v[230:233], v[206:209], v[22:25]
	v_mfma_f32_16x16x32_bf16 v[18:21], v[238:241], v[206:209], v[18:21]
	v_mfma_f32_16x16x32_bf16 v[14:17], v[230:233], v[214:217], v[14:17]
	v_mfma_f32_16x16x32_bf16 v[10:13], v[238:241], v[214:217], v[10:13]
	v_mfma_f32_16x16x32_bf16 v[6:9], v[230:233], v[222:225], v[6:9]
	v_mfma_f32_16x16x32_bf16 v[2:5], v[238:241], v[222:225], v[2:5]
	s_barrier
	s_cbranch_scc1 .LBB0_357
	s_lshl_b32 s4, s9, 7
	s_add_u32 s2, s2, s4
	s_addc_u32 s3, s3, 0
	s_movk_i32 s10, 0xff80
	v_lshl_add_u64 v[162:163], s[2:3], 0, v[0:1]
	s_mov_b32 s11, -1
	v_readfirstlane_b32 s4, v156
	v_lshl_add_u64 v[162:163], v[162:163], 0, s[10:11]
	s_mov_b32 m0, s4
	v_lshl_add_u64 v[130:131], s[2:3], 0, v[130:131]
	v_readfirstlane_b32 s2, v157
	ds_read_b128 v[132:135], v155
	ds_read_b128 v[136:139], v155 offset:1024
	ds_read_b128 v[150:153], v155 offset:2048
	ds_read_b128 v[158:161], v155 offset:3072
	ds_read_b128 v[166:169], v145
	ds_read_b128 v[170:173], v145 offset:1024
	ds_read_b128 v[190:193], v144
	ds_read_b128 v[194:197], v144 offset:1024
	ds_read_b128 v[198:201], v143
	ds_read_b128 v[202:205], v143 offset:1024
	ds_read_b128 v[206:209], v142
	ds_read_b128 v[210:213], v142 offset:1024
	global_load_lds_dwordx4 v[162:163], off
	v_lshl_add_u64 v[130:131], v[130:131], 0, s[10:11]
	s_mov_b32 m0, s2
	s_nop 0
	global_load_lds_dwordx4 v[130:131], off
	s_barrier
	s_waitcnt lgkmcnt(0)
	v_mfma_f32_16x16x32_bf16 v[126:129], v[132:135], v[166:169], v[126:129]
	v_mfma_f32_16x16x32_bf16 v[122:125], v[150:153], v[166:169], v[122:125]
	v_mfma_f32_16x16x32_bf16 v[118:121], v[132:135], v[190:193], v[118:121]
	v_mfma_f32_16x16x32_bf16 v[114:117], v[150:153], v[190:193], v[114:117]
	v_mfma_f32_16x16x32_bf16 v[110:113], v[132:135], v[198:201], v[110:113]
	v_mfma_f32_16x16x32_bf16 v[106:109], v[150:153], v[198:201], v[106:109]
	v_mfma_f32_16x16x32_bf16 v[102:105], v[132:135], v[206:209], v[102:105]
	v_mfma_f32_16x16x32_bf16 v[98:101], v[150:153], v[206:209], v[98:101]
	v_mfma_f32_16x16x32_bf16 v[126:129], v[136:139], v[170:173], v[126:129]
	v_mfma_f32_16x16x32_bf16 v[122:125], v[158:161], v[170:173], v[122:125]
	v_mfma_f32_16x16x32_bf16 v[118:121], v[136:139], v[194:197], v[118:121]
	v_mfma_f32_16x16x32_bf16 v[114:117], v[158:161], v[194:197], v[114:117]
	v_mfma_f32_16x16x32_bf16 v[110:113], v[136:139], v[202:205], v[110:113]
	v_mfma_f32_16x16x32_bf16 v[106:109], v[158:161], v[202:205], v[106:109]
	v_mfma_f32_16x16x32_bf16 v[102:105], v[136:139], v[210:213], v[102:105]
	v_mfma_f32_16x16x32_bf16 v[98:101], v[158:161], v[210:213], v[98:101]
	s_barrier
	ds_read_b128 v[214:217], v154
	ds_read_b128 v[218:221], v154 offset:1024
	ds_read_b128 v[222:225], v154 offset:2048
	ds_read_b128 v[154:157], v154 offset:3072
	s_barrier
; #define LDA(dst,b,h) for(int m=0;m<4;++m)for(int k=0;k<2;++k) \
;     dst[m][k]=*reinterpret_cast<const bf16x8*>((char*)SA(b,h)+lds_byte(wr*64+m*16+fr,k*32+fq*8))
; #define LDB(dst,b,h) for(int n=0;n<2;++n)for(int k=0;k<2;++k) \
;     dst[n][k]=*reinterpret_cast<const bf16x8*>((char*)SB(b,h)+lds_byte(wc*32+n*16+fr,k*32+fq*8))
; #define MMA(ai,bj,At,Bt_) do{__builtin_amdgcn_s_setprio(1); \
;     for(int m=0;m<4;++m)for(int n=0;n<2;++n)for(int k=0;k<2;++k) \
;       acc[ai][bj][m][n]=__builtin_amdgcn_mfma_f32_16x16x32_bf16(Bt_[n][k],At[m][k],acc[ai][bj][m][n],0,0,0); \
;     __builtin_amdgcn_s_setprio(0);}while(0)
; #define WAIT_V(n) asm volatile("s_waitcnt vmcnt(" #n ")":::"memory")
; #define WAIT_L(n) asm volatile("s_waitcnt lgkmcnt(" #n ")":::"memory")
; #define BAR __builtin_amdgcn_s_barrier()
; template <int EPI>
; __device__ __forceinline__ void gemm_run(const GD& c, const bool has_next, const GD& nx, const Ctx& e, bf16* shm, float* rs, float* rs_nxt, float* racc_) {
;     ...
;     LDB(B1,0,1); BAR; WAIT_L(0); MMA(0,1,At,B1); BAR;
;     LDA(At,0,1); WAIT_V(4); BAR; WAIT_L(0); MMA(1,0,At,B0); MMA(1,1,At,B1); BAR; }
;   { LDB(B0,1,0); LDA(At,1,0); WAIT_V(2); BAR; WAIT_L(0); MMA(0,0,At,B0); BAR;
	s_waitcnt lgkmcnt(0)
	v_mfma_f32_16x16x32_bf16 v[94:97], v[214:217], v[166:169], v[94:97]
	v_mfma_f32_16x16x32_bf16 v[90:93], v[222:225], v[166:169], v[90:93]
	v_mfma_f32_16x16x32_bf16 v[86:89], v[214:217], v[190:193], v[86:89]
	v_mfma_f32_16x16x32_bf16 v[82:85], v[222:225], v[190:193], v[82:85]
	v_mfma_f32_16x16x32_bf16 v[74:77], v[222:225], v[198:201], v[74:77]
	v_mfma_f32_16x16x32_bf16 v[70:73], v[214:217], v[206:209], v[70:73]
	v_mfma_f32_16x16x32_bf16 v[94:97], v[218:221], v[170:173], v[94:97]
	v_mfma_f32_16x16x32_bf16 v[90:93], v[154:157], v[170:173], v[90:93]
	v_mfma_f32_16x16x32_bf16 v[86:89], v[218:221], v[194:197], v[86:89]
	v_mfma_f32_16x16x32_bf16 v[82:85], v[154:157], v[194:197], v[82:85]
	v_mfma_f32_16x16x32_bf16 v[78:81], v[214:217], v[198:201], v[78:81]
	v_mfma_f32_16x16x32_bf16 v[74:77], v[154:157], v[202:205], v[74:77]
	v_mfma_f32_16x16x32_bf16 v[70:73], v[218:221], v[210:213], v[70:73]
	v_mfma_f32_16x16x32_bf16 v[66:69], v[222:225], v[206:209], v[66:69]
	v_mfma_f32_16x16x32_bf16 v[166:169], v[218:221], v[202:205], v[78:81]
	v_mfma_f32_16x16x32_bf16 v[170:173], v[154:157], v[210:213], v[66:69]
	s_barrier
	s_nop 3
	ds_read_b128 v[66:69], v145 offset:16384
	ds_read_b128 v[78:81], v145 offset:17408
	ds_read_b128 v[190:193], v144 offset:16384
	ds_read_b128 v[194:197], v144 offset:17408
	ds_read_b128 v[198:201], v143 offset:16384
	ds_read_b128 v[202:205], v143 offset:17408
	ds_read_b128 v[206:209], v142 offset:16384
	ds_read_b128 v[210:213], v142 offset:17408
	s_waitcnt vmcnt(4)
	s_barrier
	s_waitcnt lgkmcnt(0)
	v_mfma_f32_16x16x32_bf16 v[62:65], v[132:135], v[66:69], v[62:65]
	v_mfma_f32_16x16x32_bf16 v[54:57], v[132:135], v[190:193], v[54:57]
	v_mfma_f32_16x16x32_bf16 v[46:49], v[132:135], v[198:201], v[46:49]
	v_mfma_f32_16x16x32_bf16 v[38:41], v[132:135], v[206:209], v[38:41]
	v_mfma_f32_16x16x32_bf16 v[62:65], v[136:139], v[78:81], v[62:65]
	v_mfma_f32_16x16x32_bf16 v[58:61], v[150:153], v[66:69], v[58:61]
	v_mfma_f32_16x16x32_bf16 v[54:57], v[136:139], v[194:197], v[54:57]
	v_mfma_f32_16x16x32_bf16 v[50:53], v[150:153], v[190:193], v[50:53]
	v_mfma_f32_16x16x32_bf16 v[46:49], v[136:139], v[202:205], v[46:49]
	v_mfma_f32_16x16x32_bf16 v[42:45], v[150:153], v[198:201], v[42:45]
	v_mfma_f32_16x16x32_bf16 v[38:41], v[136:139], v[210:213], v[38:41]
	v_mfma_f32_16x16x32_bf16 v[34:37], v[150:153], v[206:209], v[34:37]
	v_mfma_f32_16x16x32_bf16 v[226:229], v[158:161], v[78:81], v[58:61]
	v_mfma_f32_16x16x32_bf16 v[230:233], v[158:161], v[194:197], v[50:53]
	v_mfma_f32_16x16x32_bf16 v[234:237], v[158:161], v[202:205], v[42:45]
	v_mfma_f32_16x16x32_bf16 v[130:133], v[158:161], v[210:213], v[34:37]
	v_mfma_f32_16x16x32_bf16 v[30:33], v[214:217], v[66:69], v[30:33]
	v_mfma_f32_16x16x32_bf16 v[26:29], v[222:225], v[66:69], v[26:29]
	v_mfma_f32_16x16x32_bf16 v[22:25], v[214:217], v[190:193], v[22:25]
	v_mfma_f32_16x16x32_bf16 v[18:21], v[222:225], v[190:193], v[18:21]
	v_mfma_f32_16x16x32_bf16 v[14:17], v[214:217], v[198:201], v[14:17]
	v_mfma_f32_16x16x32_bf16 v[10:13], v[222:225], v[198:201], v[10:13]
	v_mfma_f32_16x16x32_bf16 v[6:9], v[214:217], v[206:209], v[6:9]
	v_mfma_f32_16x16x32_bf16 v[2:5], v[222:225], v[206:209], v[2:5]
	v_mfma_f32_16x16x32_bf16 v[134:137], v[218:221], v[78:81], v[30:33]
	v_mfma_f32_16x16x32_bf16 v[150:153], v[154:157], v[78:81], v[26:29]
	v_mfma_f32_16x16x32_bf16 v[158:161], v[218:221], v[194:197], v[22:25]
	v_mfma_f32_16x16x32_bf16 v[190:193], v[154:157], v[194:197], v[18:21]
	v_mfma_f32_16x16x32_bf16 v[194:197], v[218:221], v[202:205], v[14:17]
	v_mfma_f32_16x16x32_bf16 v[198:201], v[154:157], v[202:205], v[10:13]
	v_mfma_f32_16x16x32_bf16 v[202:205], v[218:221], v[210:213], v[6:9]
	v_mfma_f32_16x16x32_bf16 v[154:157], v[154:157], v[210:213], v[2:5]
	s_barrier
	ds_read_b128 v[34:37], v149
	ds_read_b128 v[206:209], v149 offset:1024
	ds_read_b128 v[210:213], v149 offset:2048
	ds_read_b128 v[214:217], v149 offset:3072
	ds_read_b128 v[42:45], v145 offset:32768
	ds_read_b128 v[50:53], v145 offset:33792
	ds_read_b128 v[58:61], v144 offset:32768
	ds_read_b128 v[66:69], v144 offset:33792
	ds_read_b128 v[218:221], v143 offset:32768
	ds_read_b128 v[222:225], v143 offset:33792
	ds_read_b128 v[238:241], v142 offset:32768
	ds_read_b128 v[242:245], v142 offset:33792
	s_waitcnt vmcnt(2)
	s_barrier
; #define LDA(dst,b,h) for(int m=0;m<4;++m)for(int k=0;k<2;++k) \
;     dst[m][k]=*reinterpret_cast<const bf16x8*>((char*)SA(b,h)+lds_byte(wr*64+m*16+fr,k*32+fq*8))
; #define LDB(dst,b,h) for(int n=0;n<2;++n)for(int k=0;k<2;++k) \
;     dst[n][k]=*reinterpret_cast<const bf16x8*>((char*)SB(b,h)+lds_byte(wc*32+n*16+fr,k*32+fq*8))
; #define MMA(ai,bj,At,Bt_) do{__builtin_amdgcn_s_setprio(1); \
;     for(int m=0;m<4;++m)for(int n=0;n<2;++n)for(int k=0;k<2;++k) \
;       acc[ai][bj][m][n]=__builtin_amdgcn_mfma_f32_16x16x32_bf16(Bt_[n][k],At[m][k],acc[ai][bj][m][n],0,0,0); \
;     __builtin_amdgcn_s_setprio(0);}while(0)
; #define WAIT_V(n) asm volatile("s_waitcnt vmcnt(" #n ")":::"memory")
; #define WAIT_L(n) asm volatile("s_waitcnt lgkmcnt(" #n ")":::"memory")
; #define BAR __builtin_amdgcn_s_barrier()
; template <int EPI>
; __device__ __forceinline__ void gemm_run(const GD& c, const bool has_next, const GD& nx, const Ctx& e, bf16* shm, float* rs, float* rs_nxt, float* racc_) {
;     ...
;   { LDB(B0,1,0); LDA(At,1,0); WAIT_V(2); BAR; WAIT_L(0); MMA(0,0,At,B0); BAR;
;     LDB(B1,1,1); WAIT_V(0); BAR; WAIT_L(0); MMA(0,1,At,B1); BAR;
;     LDA(At,1,1); BAR; WAIT_L(0); MMA(1,0,At,B0); MMA(1,1,At,B1); BAR; }
;   if(wr==0)BAR;
	s_waitcnt lgkmcnt(0)
	v_mfma_f32_16x16x32_bf16 v[2:5], v[34:37], v[42:45], v[126:129]
	v_mfma_f32_16x16x32_bf16 v[26:29], v[206:209], v[50:53], v[2:5]
	v_mfma_f32_16x16x32_bf16 v[2:5], v[210:213], v[42:45], v[122:125]
	v_mfma_f32_16x16x32_bf16 v[30:33], v[214:217], v[50:53], v[2:5]
	v_mfma_f32_16x16x32_bf16 v[2:5], v[34:37], v[58:61], v[118:121]
	v_mfma_f32_16x16x32_bf16 v[18:21], v[206:209], v[66:69], v[2:5]
	v_mfma_f32_16x16x32_bf16 v[2:5], v[210:213], v[58:61], v[114:117]
	v_mfma_f32_16x16x32_bf16 v[22:25], v[214:217], v[66:69], v[2:5]
	v_mfma_f32_16x16x32_bf16 v[2:5], v[34:37], v[218:221], v[110:113]
	v_mfma_f32_16x16x32_bf16 v[10:13], v[206:209], v[222:225], v[2:5]
	v_mfma_f32_16x16x32_bf16 v[2:5], v[210:213], v[218:221], v[106:109]
	v_mfma_f32_16x16x32_bf16 v[14:17], v[214:217], v[222:225], v[2:5]
	v_mfma_f32_16x16x32_bf16 v[2:5], v[34:37], v[238:241], v[102:105]
	v_mfma_f32_16x16x32_bf16 v[6:9], v[210:213], v[238:241], v[98:101]
	v_mfma_f32_16x16x32_bf16 v[2:5], v[206:209], v[242:245], v[2:5]
	v_mfma_f32_16x16x32_bf16 v[6:9], v[214:217], v[242:245], v[6:9]
	s_barrier
	ds_read_b128 v[246:249], v147
	ds_read_b128 v[250:253], v147 offset:1024
	ds_read_b128 v[186:189], v147 offset:2048
	ds_read_b128 v[146:149], v147 offset:3072
	s_waitcnt vmcnt(0)
	s_barrier
	s_waitcnt lgkmcnt(0)
	v_mfma_f32_16x16x32_bf16 v[78:81], v[246:249], v[42:45], v[94:97]
	v_mfma_f32_16x16x32_bf16 v[42:45], v[186:189], v[42:45], v[90:93]
	v_mfma_f32_16x16x32_bf16 v[102:105], v[146:149], v[50:53], v[42:45]
	v_mfma_f32_16x16x32_bf16 v[42:45], v[246:249], v[58:61], v[86:89]
	v_mfma_f32_16x16x32_bf16 v[98:101], v[250:253], v[50:53], v[78:81]
	v_mfma_f32_16x16x32_bf16 v[78:81], v[250:253], v[66:69], v[42:45]
	v_mfma_f32_16x16x32_bf16 v[42:45], v[186:189], v[58:61], v[82:85]
	v_mfma_f32_16x16x32_bf16 v[86:89], v[146:149], v[66:69], v[42:45]
	v_mfma_f32_16x16x32_bf16 v[42:45], v[246:249], v[218:221], v[166:169]
	v_mfma_f32_16x16x32_bf16 v[58:61], v[250:253], v[222:225], v[42:45]
	v_mfma_f32_16x16x32_bf16 v[42:45], v[186:189], v[218:221], v[74:77]
	v_mfma_f32_16x16x32_bf16 v[66:69], v[146:149], v[222:225], v[42:45]
	v_mfma_f32_16x16x32_bf16 v[42:45], v[246:249], v[238:241], v[70:73]
	v_mfma_f32_16x16x32_bf16 v[50:53], v[186:189], v[238:241], v[170:173]
	v_mfma_f32_16x16x32_bf16 v[42:45], v[250:253], v[242:245], v[42:45]
	v_mfma_f32_16x16x32_bf16 v[50:53], v[146:149], v[242:245], v[50:53]
	s_barrier
	ds_read_b128 v[74:77], v145 offset:49152
	ds_read_b128 v[94:97], v145 offset:50176
	ds_read_b128 v[106:109], v144 offset:49152
	ds_read_b128 v[110:113], v144 offset:50176
	ds_read_b128 v[166:169], v143 offset:49152
	ds_read_b128 v[170:173], v143 offset:50176
	ds_read_b128 v[218:221], v142 offset:49152
	ds_read_b128 v[142:145], v142 offset:50176
	s_barrier
	s_waitcnt lgkmcnt(0)
	v_mfma_f32_16x16x32_bf16 v[62:65], v[34:37], v[74:77], v[62:65]
	v_mfma_f32_16x16x32_bf16 v[82:85], v[206:209], v[94:97], v[62:65]
	v_mfma_f32_16x16x32_bf16 v[62:65], v[210:213], v[74:77], v[226:229]
	v_mfma_f32_16x16x32_bf16 v[54:57], v[34:37], v[106:109], v[54:57]
	v_mfma_f32_16x16x32_bf16 v[90:93], v[214:217], v[94:97], v[62:65]
	v_mfma_f32_16x16x32_bf16 v[62:65], v[206:209], v[110:113], v[54:57]
	v_mfma_f32_16x16x32_bf16 v[54:57], v[210:213], v[106:109], v[230:233]
	v_mfma_f32_16x16x32_bf16 v[70:73], v[214:217], v[110:113], v[54:57]
	v_mfma_f32_16x16x32_bf16 v[46:49], v[34:37], v[166:169], v[46:49]
	v_mfma_f32_16x16x32_bf16 v[54:57], v[210:213], v[166:169], v[234:237]
	v_mfma_f32_16x16x32_bf16 v[34:37], v[34:37], v[218:221], v[38:41]
	v_mfma_f32_16x16x32_bf16 v[38:41], v[210:213], v[218:221], v[130:133]
	v_mfma_f32_16x16x32_bf16 v[46:49], v[206:209], v[170:173], v[46:49]
	v_mfma_f32_16x16x32_bf16 v[54:57], v[214:217], v[170:173], v[54:57]
	v_mfma_f32_16x16x32_bf16 v[34:37], v[206:209], v[142:145], v[34:37]
	v_mfma_f32_16x16x32_bf16 v[38:41], v[214:217], v[142:145], v[38:41]
	v_mfma_f32_16x16x32_bf16 v[114:117], v[246:249], v[74:77], v[134:137]
	v_mfma_f32_16x16x32_bf16 v[74:77], v[186:189], v[74:77], v[150:153]
	v_mfma_f32_16x16x32_bf16 v[126:129], v[146:149], v[94:97], v[74:77]
	v_mfma_f32_16x16x32_bf16 v[74:77], v[246:249], v[106:109], v[158:161]
	v_mfma_f32_16x16x32_bf16 v[122:125], v[250:253], v[94:97], v[114:117]
	v_mfma_f32_16x16x32_bf16 v[114:117], v[250:253], v[110:113], v[74:77]
	v_mfma_f32_16x16x32_bf16 v[74:77], v[186:189], v[106:109], v[190:193]
	v_mfma_f32_16x16x32_bf16 v[118:121], v[146:149], v[110:113], v[74:77]
	v_mfma_f32_16x16x32_bf16 v[74:77], v[246:249], v[166:169], v[194:197]
	v_mfma_f32_16x16x32_bf16 v[106:109], v[250:253], v[170:173], v[74:77]
	v_mfma_f32_16x16x32_bf16 v[74:77], v[186:189], v[166:169], v[198:201]
	v_mfma_f32_16x16x32_bf16 v[110:113], v[146:149], v[170:173], v[74:77]
	v_mfma_f32_16x16x32_bf16 v[74:77], v[246:249], v[218:221], v[202:205]
	v_mfma_f32_16x16x32_bf16 v[94:97], v[250:253], v[142:145], v[74:77]
	v_mfma_f32_16x16x32_bf16 v[74:77], v[186:189], v[218:221], v[154:157]
	v_mfma_f32_16x16x32_bf16 v[74:77], v[146:149], v[142:145], v[74:77]
	v_cmp_gt_u32_e32 vcc, s96, v141
	s_barrier
	s_and_saveexec_b64 s[2:3], vcc
	s_cbranch_execz .LBB0_353
	s_barrier
	s_branch .LBB0_353

; #define STAGE_A(P,br,kt) STAGE_G(P,c.A,c.lda,br,(long)(kt)*c.kstr)
; #define STAGE_B(P,br,kt) STAGE_G(P,c.Bt,c.K,br,(long)(kt)*BK)
; #define LDA(dst,b,h) for(int m=0;m<4;++m)for(int k=0;k<2;++k) \
;     dst[m][k]=*reinterpret_cast<const bf16x8*>((char*)SA(b,h)+lds_byte(wr*64+m*16+fr,k*32+fq*8))
; #define LDB(dst,b,h) for(int n=0;n<2;++n)for(int k=0;k<2;++k) \
;     dst[n][k]=*reinterpret_cast<const bf16x8*>((char*)SB(b,h)+lds_byte(wc*32+n*16+fr,k*32+fq*8))
; #define MMA(ai,bj,At,Bt_) do{__builtin_amdgcn_s_setprio(1); \
;     for(int m=0;m<4;++m)for(int n=0;n<2;++n)for(int k=0;k<2;++k) \
;       acc[ai][bj][m][n]=__builtin_amdgcn_mfma_f32_16x16x32_bf16(Bt_[n][k],At[m][k],acc[ai][bj][m][n],0,0,0); \
;     __builtin_amdgcn_s_setprio(0);}while(0)
; #define WAIT_L(n) asm volatile("s_waitcnt lgkmcnt(" #n ")":::"memory")
; #define BAR __builtin_amdgcn_s_barrier()
; #define SCHED __builtin_amdgcn_sched_barrier(0)
; template <int EPI>
; __device__ __forceinline__ void gemm_run(const GD& c, const bool has_next, const GD& nx, const Ctx& e, bf16* shm, float* rs, float* rs_nxt, float* racc_) {
;     ...
;     LDB(B0,0,0); SCHED; LDA(At,0,0); STAGE_A(SA(1,1),brow+HALF,t+1);
;     WAIT_L(8); BAR; WAIT_L(0); MMA(0,0,At,B0); BAR; SCHED;
;     LDB(B1,0,1); STAGE_B(SB(0,0),bcol,t+2);
;     BAR; WAIT_L(0); MMA(0,1,At,B1); BAR;
;     LDA(At,0,1); STAGE_A(SA(0,0),brow,t+2);
;     BAR; WAIT_L(0); MMA(1,0,At,B0); BAR; SCHED;
.LBB0_464:
	ds_read_b128 v[158:161], v154
	ds_read_b128 v[166:169], v154 offset:1024
	ds_read_b128 v[170:173], v154 offset:2048
	ds_read_b128 v[190:193], v154 offset:3072
	v_add_u32_e32 v162, 0xc000, v141
	v_lshl_add_u64 v[174:175], s[14:15], 0, v[130:131]
	v_readfirstlane_b32 s3, v162
	v_add_u32_e32 v163, 0xe000, v141
	v_lshl_add_u64 v[156:157], v[174:175], 0, s[94:95]
	s_mov_b32 m0, s3
	v_lshl_add_u64 v[186:187], s[14:15], 0, v[132:133]
	v_readfirstlane_b32 s3, v163
	ds_read_b128 v[194:197], v145
	ds_read_b128 v[198:201], v145 offset:1024
	ds_read_b128 v[202:205], v144
	ds_read_b128 v[206:209], v144 offset:1024
	ds_read_b128 v[210:213], v143
	ds_read_b128 v[214:217], v143 offset:1024
	ds_read_b128 v[218:221], v142
	ds_read_b128 v[222:225], v142 offset:1024
	global_load_lds_dwordx4 v[156:157], off
	v_lshl_add_u64 v[156:157], v[186:187], 0, s[94:95]
	s_mov_b32 m0, s3
	s_nop 0
	global_load_lds_dwordx4 v[156:157], off
	s_waitcnt lgkmcnt(8)
	s_barrier
	s_waitcnt lgkmcnt(0)
	v_mfma_f32_16x16x32_bf16 v[126:129], v[158:161], v[194:197], v[126:129]
	v_mfma_f32_16x16x32_bf16 v[122:125], v[170:173], v[194:197], v[122:125]
	v_mfma_f32_16x16x32_bf16 v[118:121], v[158:161], v[202:205], v[118:121]
	v_mfma_f32_16x16x32_bf16 v[114:117], v[170:173], v[202:205], v[114:117]
	v_mfma_f32_16x16x32_bf16 v[110:113], v[158:161], v[210:213], v[110:113]
	v_mfma_f32_16x16x32_bf16 v[106:109], v[170:173], v[210:213], v[106:109]
	v_mfma_f32_16x16x32_bf16 v[102:105], v[158:161], v[218:221], v[102:105]
	v_mfma_f32_16x16x32_bf16 v[98:101], v[170:173], v[218:221], v[98:101]
	v_mfma_f32_16x16x32_bf16 v[126:129], v[166:169], v[198:201], v[126:129]
	v_mfma_f32_16x16x32_bf16 v[122:125], v[190:193], v[198:201], v[122:125]
	v_mfma_f32_16x16x32_bf16 v[118:121], v[166:169], v[206:209], v[118:121]
	v_mfma_f32_16x16x32_bf16 v[114:117], v[190:193], v[206:209], v[114:117]
	v_mfma_f32_16x16x32_bf16 v[110:113], v[166:169], v[214:217], v[110:113]
	v_mfma_f32_16x16x32_bf16 v[106:109], v[190:193], v[214:217], v[106:109]
	v_mfma_f32_16x16x32_bf16 v[102:105], v[166:169], v[222:225], v[102:105]
	v_mfma_f32_16x16x32_bf16 v[98:101], v[190:193], v[222:225], v[98:101]
	s_barrier
	v_add_u32_e32 v155, s33, v147
	v_lshl_add_u64 v[246:247], s[14:15], 0, v[136:137]
	v_readfirstlane_b32 s3, v155
	v_lshl_add_u64 v[156:157], v[246:247], 0, s[6:7]
	s_mov_b32 m0, s3
	ds_read_b128 v[226:229], v153
	ds_read_b128 v[230:233], v153 offset:1024
	ds_read_b128 v[234:237], v153 offset:2048
	ds_read_b128 v[238:241], v153 offset:3072
	global_load_lds_dwordx4 v[156:157], off
	v_add_u32_e32 v156, 0x2000, v155
	v_lshl_add_u64 v[248:249], s[14:15], 0, v[138:139]
	v_readfirstlane_b32 s3, v156
	v_lshl_add_u64 v[242:243], v[248:249], 0, s[6:7]
	s_mov_b32 m0, s3
	s_nop 0
	global_load_lds_dwordx4 v[242:243], off
	s_barrier
	s_waitcnt lgkmcnt(0)
	v_mfma_f32_16x16x32_bf16 v[94:97], v[226:229], v[194:197], v[94:97]
	v_mfma_f32_16x16x32_bf16 v[90:93], v[234:237], v[194:197], v[90:93]
	v_mfma_f32_16x16x32_bf16 v[86:89], v[226:229], v[202:205], v[86:89]
	v_mfma_f32_16x16x32_bf16 v[82:85], v[234:237], v[202:205], v[82:85]
	v_mfma_f32_16x16x32_bf16 v[78:81], v[226:229], v[210:213], v[78:81]
	v_mfma_f32_16x16x32_bf16 v[74:77], v[234:237], v[210:213], v[74:77]
	v_mfma_f32_16x16x32_bf16 v[70:73], v[226:229], v[218:221], v[70:73]
	v_mfma_f32_16x16x32_bf16 v[66:69], v[234:237], v[218:221], v[66:69]
	v_mfma_f32_16x16x32_bf16 v[94:97], v[230:233], v[198:201], v[94:97]
	v_mfma_f32_16x16x32_bf16 v[90:93], v[238:241], v[198:201], v[90:93]
	v_mfma_f32_16x16x32_bf16 v[86:89], v[230:233], v[206:209], v[86:89]
	v_mfma_f32_16x16x32_bf16 v[82:85], v[238:241], v[206:209], v[82:85]
	v_mfma_f32_16x16x32_bf16 v[78:81], v[230:233], v[214:217], v[78:81]
	v_mfma_f32_16x16x32_bf16 v[74:77], v[238:241], v[214:217], v[74:77]
	v_mfma_f32_16x16x32_bf16 v[70:73], v[230:233], v[222:225], v[70:73]
	v_mfma_f32_16x16x32_bf16 v[66:69], v[238:241], v[222:225], v[66:69]
	s_barrier
	v_readfirstlane_b32 s3, v141
	v_add_u32_e32 v157, 0x2000, v141
	v_lshl_add_u64 v[242:243], v[174:175], 0, s[84:85]
	s_mov_b32 m0, s3
	v_readfirstlane_b32 s3, v157
	ds_read_b128 v[194:197], v145 offset:16384
	ds_read_b128 v[198:201], v145 offset:17408
	ds_read_b128 v[202:205], v144 offset:16384
	ds_read_b128 v[206:209], v144 offset:17408
	ds_read_b128 v[210:213], v143 offset:16384
	ds_read_b128 v[214:217], v143 offset:17408
	ds_read_b128 v[218:221], v142 offset:16384
	ds_read_b128 v[222:225], v142 offset:17408
	global_load_lds_dwordx4 v[242:243], off
	v_lshl_add_u64 v[242:243], v[186:187], 0, s[84:85]
	s_mov_b32 m0, s3
	s_nop 0
	global_load_lds_dwordx4 v[242:243], off
	s_barrier
	s_waitcnt lgkmcnt(0)
	v_mfma_f32_16x16x32_bf16 v[62:65], v[158:161], v[194:197], v[62:65]
	v_mfma_f32_16x16x32_bf16 v[58:61], v[170:173], v[194:197], v[58:61]
	v_mfma_f32_16x16x32_bf16 v[54:57], v[158:161], v[202:205], v[54:57]
	v_mfma_f32_16x16x32_bf16 v[50:53], v[170:173], v[202:205], v[50:53]
	v_mfma_f32_16x16x32_bf16 v[46:49], v[158:161], v[210:213], v[46:49]
	v_mfma_f32_16x16x32_bf16 v[42:45], v[170:173], v[210:213], v[42:45]
	v_mfma_f32_16x16x32_bf16 v[38:41], v[158:161], v[218:221], v[38:41]
	v_mfma_f32_16x16x32_bf16 v[34:37], v[170:173], v[218:221], v[34:37]
	v_mfma_f32_16x16x32_bf16 v[62:65], v[166:169], v[198:201], v[62:65]
	v_mfma_f32_16x16x32_bf16 v[58:61], v[190:193], v[198:201], v[58:61]
	v_mfma_f32_16x16x32_bf16 v[54:57], v[166:169], v[206:209], v[54:57]
	v_mfma_f32_16x16x32_bf16 v[50:53], v[190:193], v[206:209], v[50:53]
	v_mfma_f32_16x16x32_bf16 v[46:49], v[166:169], v[214:217], v[46:49]
	v_mfma_f32_16x16x32_bf16 v[42:45], v[190:193], v[214:217], v[42:45]
	v_mfma_f32_16x16x32_bf16 v[38:41], v[166:169], v[222:225], v[38:41]
	v_mfma_f32_16x16x32_bf16 v[34:37], v[190:193], v[222:225], v[34:37]
	s_barrier
; #define STAGE_A(P,br,kt) STAGE_G(P,c.A,c.lda,br,(long)(kt)*c.kstr)
; #define STAGE_B(P,br,kt) STAGE_G(P,c.Bt,c.K,br,(long)(kt)*BK)
; #define LDA(dst,b,h) for(int m=0;m<4;++m)for(int k=0;k<2;++k) \
;     dst[m][k]=*reinterpret_cast<const bf16x8*>((char*)SA(b,h)+lds_byte(wr*64+m*16+fr,k*32+fq*8))
; #define LDB(dst,b,h) for(int n=0;n<2;++n)for(int k=0;k<2;++k) \
;     dst[n][k]=*reinterpret_cast<const bf16x8*>((char*)SB(b,h)+lds_byte(wc*32+n*16+fr,k*32+fq*8))
; #define MMA(ai,bj,At,Bt_) do{__builtin_amdgcn_s_setprio(1); \
;     for(int m=0;m<4;++m)for(int n=0;n<2;++n)for(int k=0;k<2;++k) \
;       acc[ai][bj][m][n]=__builtin_amdgcn_mfma_f32_16x16x32_bf16(Bt_[n][k],At[m][k],acc[ai][bj][m][n],0,0,0); \
;     __builtin_amdgcn_s_setprio(0);}while(0)
; #define WAIT_V(n) asm volatile("s_waitcnt vmcnt(" #n ")":::"memory")
; #define WAIT_L(n) asm volatile("s_waitcnt lgkmcnt(" #n ")":::"memory")
; #define BAR __builtin_amdgcn_s_barrier()
; #define SCHED __builtin_amdgcn_sched_barrier(0)
; template <int EPI>
; __device__ __forceinline__ void gemm_run(const GD& c, const bool has_next, const GD& nx, const Ctx& e, bf16* shm, float* rs, float* rs_nxt, float* racc_) {
;     ...
;     STAGE_B(SB(0,1),bcol+HALF,t+2);
;     WAIT_V(6); BAR; MMA(1,1,At,B1); BAR;
;     LDB(B0,1,0); SCHED; LDA(At,1,0); STAGE_A(SA(0,1),brow+HALF,t+2);
;     WAIT_L(8); BAR; WAIT_L(0); MMA(0,0,At,B0); BAR; SCHED;
;     LDB(B1,1,1); STAGE_B(SB(1,0),bcol,t+3);
;     BAR; WAIT_L(0); MMA(0,1,At,B1); BAR;
;     LDA(At,1,1); STAGE_A(SA(1,0),brow,t+3);
	v_add_u32_e32 v158, s86, v147
	v_add_u32_e32 v159, 0x2000, v158
	v_readfirstlane_b32 s3, v158
	v_lshl_add_u64 v[160:161], v[246:247], 0, s[40:41]
	s_mov_b32 m0, s3
	v_readfirstlane_b32 s3, v159
	global_load_lds_dwordx4 v[160:161], off
	v_lshl_add_u64 v[160:161], v[248:249], 0, s[40:41]
	s_mov_b32 m0, s3
	s_nop 0
	global_load_lds_dwordx4 v[160:161], off
	s_waitcnt vmcnt(6)
	s_barrier
	v_mfma_f32_16x16x32_bf16 v[30:33], v[226:229], v[194:197], v[30:33]
	v_mfma_f32_16x16x32_bf16 v[26:29], v[234:237], v[194:197], v[26:29]
	v_mfma_f32_16x16x32_bf16 v[22:25], v[226:229], v[202:205], v[22:25]
	v_mfma_f32_16x16x32_bf16 v[18:21], v[234:237], v[202:205], v[18:21]
	v_mfma_f32_16x16x32_bf16 v[14:17], v[226:229], v[210:213], v[14:17]
	v_mfma_f32_16x16x32_bf16 v[10:13], v[234:237], v[210:213], v[10:13]
	v_mfma_f32_16x16x32_bf16 v[6:9], v[226:229], v[218:221], v[6:9]
	v_mfma_f32_16x16x32_bf16 v[2:5], v[234:237], v[218:221], v[2:5]
	v_mfma_f32_16x16x32_bf16 v[30:33], v[230:233], v[198:201], v[30:33]
	v_mfma_f32_16x16x32_bf16 v[26:29], v[238:241], v[198:201], v[26:29]
	v_mfma_f32_16x16x32_bf16 v[22:25], v[230:233], v[206:209], v[22:25]
	v_mfma_f32_16x16x32_bf16 v[18:21], v[238:241], v[206:209], v[18:21]
	v_mfma_f32_16x16x32_bf16 v[14:17], v[230:233], v[214:217], v[14:17]
	v_mfma_f32_16x16x32_bf16 v[10:13], v[238:241], v[214:217], v[10:13]
	v_mfma_f32_16x16x32_bf16 v[6:9], v[230:233], v[222:225], v[6:9]
	v_mfma_f32_16x16x32_bf16 v[2:5], v[238:241], v[222:225], v[2:5]
	s_barrier
	ds_read_b128 v[166:169], v148
	ds_read_b128 v[170:173], v148 offset:1024
	ds_read_b128 v[190:193], v148 offset:2048
	ds_read_b128 v[194:197], v148 offset:3072
	v_add_u32_e32 v160, 0x4000, v141
	v_add_u32_e32 v161, 0x6000, v141
	v_readfirstlane_b32 s3, v160
	v_lshl_add_u64 v[230:231], v[174:175], 0, s[92:93]
	s_mov_b32 m0, s3
	v_readfirstlane_b32 s3, v161
	ds_read_b128 v[198:201], v145 offset:32768
	ds_read_b128 v[202:205], v145 offset:33792
	ds_read_b128 v[206:209], v144 offset:32768
	ds_read_b128 v[210:213], v144 offset:33792
	ds_read_b128 v[214:217], v143 offset:32768
	ds_read_b128 v[218:221], v143 offset:33792
	ds_read_b128 v[222:225], v142 offset:32768
	ds_read_b128 v[226:229], v142 offset:33792
	global_load_lds_dwordx4 v[230:231], off
	v_lshl_add_u64 v[230:231], v[186:187], 0, s[92:93]
	s_mov_b32 m0, s3
	s_nop 0
	global_load_lds_dwordx4 v[230:231], off
	s_waitcnt lgkmcnt(8)
	s_barrier
	s_waitcnt lgkmcnt(0)
	v_mfma_f32_16x16x32_bf16 v[126:129], v[166:169], v[198:201], v[126:129]
	v_mfma_f32_16x16x32_bf16 v[122:125], v[190:193], v[198:201], v[122:125]
	v_mfma_f32_16x16x32_bf16 v[118:121], v[166:169], v[206:209], v[118:121]
	v_mfma_f32_16x16x32_bf16 v[114:117], v[190:193], v[206:209], v[114:117]
	v_mfma_f32_16x16x32_bf16 v[110:113], v[166:169], v[214:217], v[110:113]
	v_mfma_f32_16x16x32_bf16 v[106:109], v[190:193], v[214:217], v[106:109]
	v_mfma_f32_16x16x32_bf16 v[102:105], v[166:169], v[222:225], v[102:105]
	v_mfma_f32_16x16x32_bf16 v[98:101], v[190:193], v[222:225], v[98:101]
	v_mfma_f32_16x16x32_bf16 v[126:129], v[170:173], v[202:205], v[126:129]
	v_mfma_f32_16x16x32_bf16 v[122:125], v[194:197], v[202:205], v[122:125]
	v_mfma_f32_16x16x32_bf16 v[118:121], v[170:173], v[210:213], v[118:121]
	v_mfma_f32_16x16x32_bf16 v[114:117], v[194:197], v[210:213], v[114:117]
	v_mfma_f32_16x16x32_bf16 v[110:113], v[170:173], v[218:221], v[110:113]
	v_mfma_f32_16x16x32_bf16 v[106:109], v[194:197], v[218:221], v[106:109]
	v_mfma_f32_16x16x32_bf16 v[102:105], v[170:173], v[226:229], v[102:105]
	v_mfma_f32_16x16x32_bf16 v[98:101], v[194:197], v[226:229], v[98:101]
	s_barrier
	v_readfirstlane_b32 s3, v149
	v_add_u32_e32 v176, 0x2000, v149
	v_lshl_add_u64 v[250:251], v[246:247], 0, s[42:43]
	s_mov_b32 m0, s3
	v_readfirstlane_b32 s3, v176
	ds_read_b128 v[230:233], v146
	ds_read_b128 v[234:237], v146 offset:1024
	ds_read_b128 v[238:241], v146 offset:2048
	ds_read_b128 v[242:245], v146 offset:3072
	global_load_lds_dwordx4 v[250:251], off
	v_lshl_add_u64 v[250:251], v[248:249], 0, s[42:43]
	s_mov_b32 m0, s3
	s_nop 0
	global_load_lds_dwordx4 v[250:251], off
	s_barrier
	s_waitcnt lgkmcnt(0)
	v_mfma_f32_16x16x32_bf16 v[94:97], v[230:233], v[198:201], v[94:97]
	v_mfma_f32_16x16x32_bf16 v[90:93], v[238:241], v[198:201], v[90:93]
	v_mfma_f32_16x16x32_bf16 v[86:89], v[230:233], v[206:209], v[86:89]
	v_mfma_f32_16x16x32_bf16 v[82:85], v[238:241], v[206:209], v[82:85]
	v_mfma_f32_16x16x32_bf16 v[78:81], v[230:233], v[214:217], v[78:81]
	v_mfma_f32_16x16x32_bf16 v[74:77], v[238:241], v[214:217], v[74:77]
	v_mfma_f32_16x16x32_bf16 v[70:73], v[230:233], v[222:225], v[70:73]
	v_mfma_f32_16x16x32_bf16 v[66:69], v[238:241], v[222:225], v[66:69]
	v_mfma_f32_16x16x32_bf16 v[94:97], v[234:237], v[202:205], v[94:97]
	v_mfma_f32_16x16x32_bf16 v[90:93], v[242:245], v[202:205], v[90:93]
	v_mfma_f32_16x16x32_bf16 v[86:89], v[234:237], v[210:213], v[86:89]
	v_mfma_f32_16x16x32_bf16 v[82:85], v[242:245], v[210:213], v[82:85]
	v_mfma_f32_16x16x32_bf16 v[78:81], v[234:237], v[218:221], v[78:81]
	v_mfma_f32_16x16x32_bf16 v[74:77], v[242:245], v[218:221], v[74:77]
	v_mfma_f32_16x16x32_bf16 v[70:73], v[234:237], v[226:229], v[70:73]
	v_mfma_f32_16x16x32_bf16 v[66:69], v[242:245], v[226:229], v[66:69]
	s_barrier
	v_readfirstlane_b32 s3, v150
	v_lshl_add_u64 v[174:175], v[174:175], 0, s[80:81]
	s_mov_b32 m0, s3
	v_readfirstlane_b32 s3, v151
	ds_read_b128 v[198:201], v145 offset:49152
	ds_read_b128 v[202:205], v145 offset:50176
	ds_read_b128 v[206:209], v144 offset:49152
	ds_read_b128 v[210:213], v144 offset:50176
	ds_read_b128 v[214:217], v143 offset:49152
	ds_read_b128 v[218:221], v143 offset:50176
	ds_read_b128 v[222:225], v142 offset:49152
	ds_read_b128 v[226:229], v142 offset:50176
	global_load_lds_dwordx4 v[174:175], off
	v_lshl_add_u64 v[174:175], v[186:187], 0, s[80:81]
	s_mov_b32 m0, s3
	s_nop 0
	global_load_lds_dwordx4 v[174:175], off
	s_barrier
; #define STAGE_A(P,br,kt) STAGE_G(P,c.A,c.lda,br,(long)(kt)*c.kstr)
; #define STAGE_B(P,br,kt) STAGE_G(P,c.Bt,c.K,br,(long)(kt)*BK)
; #define LDA(dst,b,h) for(int m=0;m<4;++m)for(int k=0;k<2;++k) \
;     dst[m][k]=*reinterpret_cast<const bf16x8*>((char*)SA(b,h)+lds_byte(wr*64+m*16+fr,k*32+fq*8))
; #define LDB(dst,b,h) for(int n=0;n<2;++n)for(int k=0;k<2;++k) \
;     dst[n][k]=*reinterpret_cast<const bf16x8*>((char*)SB(b,h)+lds_byte(wc*32+n*16+fr,k*32+fq*8))
; #define MMA(ai,bj,At,Bt_) do{__builtin_amdgcn_s_setprio(1); \
;     for(int m=0;m<4;++m)for(int n=0;n<2;++n)for(int k=0;k<2;++k) \
;       acc[ai][bj][m][n]=__builtin_amdgcn_mfma_f32_16x16x32_bf16(Bt_[n][k],At[m][k],acc[ai][bj][m][n],0,0,0); \
;     __builtin_amdgcn_s_setprio(0);}while(0)
; #define WAIT_V(n) asm volatile("s_waitcnt vmcnt(" #n ")":::"memory")
; #define WAIT_L(n) asm volatile("s_waitcnt lgkmcnt(" #n ")":::"memory")
; #define BAR __builtin_amdgcn_s_barrier()
; #define SCHED __builtin_amdgcn_sched_barrier(0)
; template <int EPI>
; __device__ __forceinline__ void gemm_run(const GD& c, const bool has_next, const GD& nx, const Ctx& e, bf16* shm, float* rs, float* rs_nxt, float* racc_) {
;     ...
;     BAR; WAIT_L(0); MMA(1,0,At,B0); BAR; SCHED;
;     STAGE_B(SB(1,1),bcol+HALF,t+3);
;     WAIT_V(6); BAR; MMA(1,1,At,B1); BAR;
;   }
;   { LDB(B0,0,0); LDA(At,0,0); STAGE_A(SA(1,1),brow+HALF,nt-1);
;     BAR; WAIT_L(0); MMA(0,0,At,B0); BAR;
;     LDB(B1,0,1); BAR; WAIT_L(0); MMA(0,1,At,B1); BAR;
	s_waitcnt lgkmcnt(0)
	v_mfma_f32_16x16x32_bf16 v[62:65], v[166:169], v[198:201], v[62:65]
	v_mfma_f32_16x16x32_bf16 v[58:61], v[190:193], v[198:201], v[58:61]
	v_mfma_f32_16x16x32_bf16 v[54:57], v[166:169], v[206:209], v[54:57]
	v_mfma_f32_16x16x32_bf16 v[50:53], v[190:193], v[206:209], v[50:53]
	v_mfma_f32_16x16x32_bf16 v[46:49], v[166:169], v[214:217], v[46:49]
	v_mfma_f32_16x16x32_bf16 v[42:45], v[190:193], v[214:217], v[42:45]
	v_mfma_f32_16x16x32_bf16 v[38:41], v[166:169], v[222:225], v[38:41]
	v_mfma_f32_16x16x32_bf16 v[34:37], v[190:193], v[222:225], v[34:37]
	v_mfma_f32_16x16x32_bf16 v[62:65], v[170:173], v[202:205], v[62:65]
	v_mfma_f32_16x16x32_bf16 v[58:61], v[194:197], v[202:205], v[58:61]
	v_mfma_f32_16x16x32_bf16 v[54:57], v[170:173], v[210:213], v[54:57]
	v_mfma_f32_16x16x32_bf16 v[50:53], v[194:197], v[210:213], v[50:53]
	v_mfma_f32_16x16x32_bf16 v[46:49], v[170:173], v[218:221], v[46:49]
	v_mfma_f32_16x16x32_bf16 v[42:45], v[194:197], v[218:221], v[42:45]
	v_mfma_f32_16x16x32_bf16 v[38:41], v[170:173], v[226:229], v[38:41]
	v_mfma_f32_16x16x32_bf16 v[34:37], v[194:197], v[226:229], v[34:37]
	s_barrier
	v_readfirstlane_b32 s3, v152
	v_add_u32_e32 v168, 0x2000, v152
	v_lshl_add_u64 v[166:167], v[246:247], 0, s[44:45]
	s_mov_b32 m0, s3
	v_readfirstlane_b32 s3, v168
	global_load_lds_dwordx4 v[166:167], off
	v_lshl_add_u64 v[166:167], v[248:249], 0, s[44:45]
	s_mov_b32 m0, s3
	s_nop 0
	global_load_lds_dwordx4 v[166:167], off
	s_waitcnt vmcnt(6)
	s_barrier
	v_mfma_f32_16x16x32_bf16 v[30:33], v[230:233], v[198:201], v[30:33]
	v_mfma_f32_16x16x32_bf16 v[26:29], v[238:241], v[198:201], v[26:29]
	v_mfma_f32_16x16x32_bf16 v[22:25], v[230:233], v[206:209], v[22:25]
	v_mfma_f32_16x16x32_bf16 v[18:21], v[238:241], v[206:209], v[18:21]
	s_add_i32 s2, s2, 2
	v_mfma_f32_16x16x32_bf16 v[14:17], v[230:233], v[214:217], v[14:17]
	v_lshl_add_u64 v[130:131], v[130:131], 0, s[88:89]
	v_mfma_f32_16x16x32_bf16 v[10:13], v[238:241], v[214:217], v[10:13]
	v_lshl_add_u64 v[132:133], v[132:133], 0, s[88:89]
	v_mfma_f32_16x16x32_bf16 v[6:9], v[230:233], v[222:225], v[6:9]
	v_lshl_add_u64 v[136:137], v[136:137], 0, s[88:89]
	v_mfma_f32_16x16x32_bf16 v[2:5], v[238:241], v[222:225], v[2:5]
	s_cmp_lt_u32 s2, 12
	v_mfma_f32_16x16x32_bf16 v[30:33], v[234:237], v[202:205], v[30:33]
	v_lshl_add_u64 v[138:139], v[138:139], 0, s[88:89]
	v_mfma_f32_16x16x32_bf16 v[26:29], v[242:245], v[202:205], v[26:29]
	v_mfma_f32_16x16x32_bf16 v[22:25], v[234:237], v[210:213], v[22:25]
	v_mfma_f32_16x16x32_bf16 v[18:21], v[242:245], v[210:213], v[18:21]
	v_mfma_f32_16x16x32_bf16 v[14:17], v[234:237], v[218:221], v[14:17]
	v_mfma_f32_16x16x32_bf16 v[10:13], v[242:245], v[218:221], v[10:13]
	v_mfma_f32_16x16x32_bf16 v[6:9], v[234:237], v[226:229], v[6:9]
	v_mfma_f32_16x16x32_bf16 v[2:5], v[242:245], v[226:229], v[2:5]
	s_barrier
	s_cbranch_scc1 .LBB0_464
	s_or_b32 s2, s36, 0x80
	s_ashr_i32 s3, s2, 31
	s_lshl_b64 s[2:3], s[2:3], 11
	s_add_u32 s2, s50, s2
	s_addc_u32 s3, s51, s3
	v_lshl_add_u64 v[150:151], s[2:3], 0, v[0:1]
	s_mov_b64 s[40:41], 0x780
	v_readfirstlane_b32 s6, v162
	v_lshl_add_u64 v[150:151], v[150:151], 0, s[40:41]
	s_mov_b32 m0, s6
	ds_read_b128 v[130:133], v154
	ds_read_b128 v[136:139], v154 offset:1024
	ds_read_b128 v[166:169], v154 offset:2048
	ds_read_b128 v[170:173], v154 offset:3072
	ds_read_b128 v[190:193], v145
	ds_read_b128 v[194:197], v145 offset:1024
	ds_read_b128 v[198:201], v144
	ds_read_b128 v[202:205], v144 offset:1024
	ds_read_b128 v[206:209], v143
	ds_read_b128 v[210:213], v143 offset:1024
	ds_read_b128 v[214:217], v142
	ds_read_b128 v[218:221], v142 offset:1024
	global_load_lds_dwordx4 v[150:151], off
	v_lshl_add_u64 v[150:151], s[2:3], 0, v[134:135]
	v_readfirstlane_b32 s2, v163
	v_lshl_add_u64 v[150:151], v[150:151], 0, s[40:41]
	s_mov_b32 m0, s2
	s_nop 0
	global_load_lds_dwordx4 v[150:151], off
	s_barrier
	s_waitcnt lgkmcnt(0)
	v_mfma_f32_16x16x32_bf16 v[126:129], v[130:133], v[190:193], v[126:129]
	v_mfma_f32_16x16x32_bf16 v[122:125], v[166:169], v[190:193], v[122:125]
	v_mfma_f32_16x16x32_bf16 v[118:121], v[130:133], v[198:201], v[118:121]
	v_mfma_f32_16x16x32_bf16 v[106:109], v[166:169], v[206:209], v[106:109]
	v_mfma_f32_16x16x32_bf16 v[102:105], v[130:133], v[214:217], v[102:105]
	v_mfma_f32_16x16x32_bf16 v[126:129], v[136:139], v[194:197], v[126:129]
	v_mfma_f32_16x16x32_bf16 v[122:125], v[170:173], v[194:197], v[122:125]
	v_mfma_f32_16x16x32_bf16 v[118:121], v[136:139], v[202:205], v[118:121]
	v_mfma_f32_16x16x32_bf16 v[114:117], v[166:169], v[198:201], v[114:117]
	v_mfma_f32_16x16x32_bf16 v[110:113], v[130:133], v[206:209], v[110:113]
	v_mfma_f32_16x16x32_bf16 v[106:109], v[170:173], v[210:213], v[106:109]
	v_mfma_f32_16x16x32_bf16 v[102:105], v[136:139], v[218:221], v[102:105]
	v_mfma_f32_16x16x32_bf16 v[98:101], v[166:169], v[214:217], v[98:101]
	v_mfma_f32_16x16x32_bf16 v[222:225], v[170:173], v[202:205], v[114:117]
	v_mfma_f32_16x16x32_bf16 v[226:229], v[136:139], v[210:213], v[110:113]
	v_mfma_f32_16x16x32_bf16 v[230:233], v[170:173], v[218:221], v[98:101]
	s_barrier
	s_nop 2
	ds_read_b128 v[98:101], v153
	ds_read_b128 v[110:113], v153 offset:1024
	ds_read_b128 v[114:117], v153 offset:2048
	ds_read_b128 v[150:153], v153 offset:3072
	s_barrier
; #define LDA(dst,b,h) for(int m=0;m<4;++m)for(int k=0;k<2;++k) \
;     dst[m][k]=*reinterpret_cast<const bf16x8*>((char*)SA(b,h)+lds_byte(wr*64+m*16+fr,k*32+fq*8))
; #define LDB(dst,b,h) for(int n=0;n<2;++n)for(int k=0;k<2;++k) \
;     dst[n][k]=*reinterpret_cast<const bf16x8*>((char*)SB(b,h)+lds_byte(wc*32+n*16+fr,k*32+fq*8))
; #define MMA(ai,bj,At,Bt_) do{__builtin_amdgcn_s_setprio(1); \
;     for(int m=0;m<4;++m)for(int n=0;n<2;++n)for(int k=0;k<2;++k) \
;       acc[ai][bj][m][n]=__builtin_amdgcn_mfma_f32_16x16x32_bf16(Bt_[n][k],At[m][k],acc[ai][bj][m][n],0,0,0); \
;     __builtin_amdgcn_s_setprio(0);}while(0)
; #define WAIT_V(n) asm volatile("s_waitcnt vmcnt(" #n ")":::"memory")
; #define WAIT_L(n) asm volatile("s_waitcnt lgkmcnt(" #n ")":::"memory")
; #define BAR __builtin_amdgcn_s_barrier()
; template <int EPI>
; __device__ __forceinline__ void gemm_run(const GD& c, const bool has_next, const GD& nx, const Ctx& e, bf16* shm, float* rs, float* rs_nxt, float* racc_) {
;     ...
;     LDB(B1,0,1); BAR; WAIT_L(0); MMA(0,1,At,B1); BAR;
;     LDA(At,0,1); WAIT_V(4); BAR; WAIT_L(0); MMA(1,0,At,B0); MMA(1,1,At,B1); BAR; }
;   { LDB(B0,1,0); LDA(At,1,0); WAIT_V(2); BAR; WAIT_L(0); MMA(0,0,At,B0); BAR;
	s_waitcnt lgkmcnt(0)
	v_mfma_f32_16x16x32_bf16 v[90:93], v[114:117], v[190:193], v[90:93]
	v_mfma_f32_16x16x32_bf16 v[86:89], v[98:101], v[198:201], v[86:89]
	v_mfma_f32_16x16x32_bf16 v[74:77], v[114:117], v[206:209], v[74:77]
	v_mfma_f32_16x16x32_bf16 v[70:73], v[98:101], v[214:217], v[70:73]
	v_mfma_f32_16x16x32_bf16 v[66:69], v[114:117], v[214:217], v[66:69]
	v_mfma_f32_16x16x32_bf16 v[94:97], v[98:101], v[190:193], v[94:97]
	v_mfma_f32_16x16x32_bf16 v[90:93], v[150:153], v[194:197], v[90:93]
	v_mfma_f32_16x16x32_bf16 v[86:89], v[110:113], v[202:205], v[86:89]
	v_mfma_f32_16x16x32_bf16 v[82:85], v[114:117], v[198:201], v[82:85]
	v_mfma_f32_16x16x32_bf16 v[78:81], v[98:101], v[206:209], v[78:81]
	v_mfma_f32_16x16x32_bf16 v[74:77], v[150:153], v[210:213], v[74:77]
	v_mfma_f32_16x16x32_bf16 v[70:73], v[110:113], v[218:221], v[70:73]
	v_mfma_f32_16x16x32_bf16 v[66:69], v[150:153], v[218:221], v[66:69]
	v_mfma_f32_16x16x32_bf16 v[234:237], v[110:113], v[194:197], v[94:97]
	v_mfma_f32_16x16x32_bf16 v[190:193], v[150:153], v[202:205], v[82:85]
	v_mfma_f32_16x16x32_bf16 v[194:197], v[110:113], v[210:213], v[78:81]
	s_barrier
	s_nop 0
	ds_read_b128 v[78:81], v145 offset:16384
	ds_read_b128 v[82:85], v145 offset:17408
	ds_read_b128 v[94:97], v144 offset:16384
	ds_read_b128 v[198:201], v144 offset:17408
	ds_read_b128 v[202:205], v143 offset:16384
	ds_read_b128 v[206:209], v143 offset:17408
	ds_read_b128 v[210:213], v142 offset:16384
	ds_read_b128 v[214:217], v142 offset:17408
	s_waitcnt vmcnt(4)
	s_barrier
	s_waitcnt lgkmcnt(0)
	v_mfma_f32_16x16x32_bf16 v[62:65], v[130:133], v[78:81], v[62:65]
	v_mfma_f32_16x16x32_bf16 v[58:61], v[166:169], v[78:81], v[58:61]
	v_mfma_f32_16x16x32_bf16 v[54:57], v[130:133], v[94:97], v[54:57]
	v_mfma_f32_16x16x32_bf16 v[42:45], v[166:169], v[202:205], v[42:45]
	v_mfma_f32_16x16x32_bf16 v[38:41], v[130:133], v[210:213], v[38:41]
	v_mfma_f32_16x16x32_bf16 v[62:65], v[136:139], v[82:85], v[62:65]
	v_mfma_f32_16x16x32_bf16 v[58:61], v[170:173], v[82:85], v[58:61]
	v_mfma_f32_16x16x32_bf16 v[54:57], v[136:139], v[198:201], v[54:57]
	v_mfma_f32_16x16x32_bf16 v[50:53], v[166:169], v[94:97], v[50:53]
	v_mfma_f32_16x16x32_bf16 v[46:49], v[130:133], v[202:205], v[46:49]
	v_mfma_f32_16x16x32_bf16 v[42:45], v[170:173], v[206:209], v[42:45]
	v_mfma_f32_16x16x32_bf16 v[38:41], v[136:139], v[214:217], v[38:41]
	v_mfma_f32_16x16x32_bf16 v[34:37], v[166:169], v[210:213], v[34:37]
	v_mfma_f32_16x16x32_bf16 v[218:221], v[170:173], v[198:201], v[50:53]
	v_mfma_f32_16x16x32_bf16 v[238:241], v[136:139], v[206:209], v[46:49]
	v_mfma_f32_16x16x32_bf16 v[136:139], v[170:173], v[214:217], v[34:37]
	v_mfma_f32_16x16x32_bf16 v[26:29], v[114:117], v[78:81], v[26:29]
	v_mfma_f32_16x16x32_bf16 v[22:25], v[98:101], v[94:97], v[22:25]
	v_mfma_f32_16x16x32_bf16 v[10:13], v[114:117], v[202:205], v[10:13]
	v_mfma_f32_16x16x32_bf16 v[6:9], v[98:101], v[210:213], v[6:9]
	v_mfma_f32_16x16x32_bf16 v[30:33], v[98:101], v[78:81], v[30:33]
	v_mfma_f32_16x16x32_bf16 v[26:29], v[150:153], v[82:85], v[26:29]
	v_mfma_f32_16x16x32_bf16 v[22:25], v[110:113], v[198:201], v[22:25]
	v_mfma_f32_16x16x32_bf16 v[18:21], v[114:117], v[94:97], v[18:21]
	v_mfma_f32_16x16x32_bf16 v[14:17], v[98:101], v[202:205], v[14:17]
	v_mfma_f32_16x16x32_bf16 v[10:13], v[150:153], v[206:209], v[10:13]
	v_mfma_f32_16x16x32_bf16 v[6:9], v[110:113], v[214:217], v[6:9]
	v_mfma_f32_16x16x32_bf16 v[2:5], v[114:117], v[210:213], v[2:5]
	v_mfma_f32_16x16x32_bf16 v[166:169], v[110:113], v[82:85], v[30:33]
	v_mfma_f32_16x16x32_bf16 v[170:173], v[150:153], v[198:201], v[18:21]
	v_mfma_f32_16x16x32_bf16 v[198:201], v[110:113], v[206:209], v[14:17]
	v_mfma_f32_16x16x32_bf16 v[2:5], v[150:153], v[214:217], v[2:5]
	s_barrier
	ds_read_b128 v[14:17], v148
	ds_read_b128 v[18:21], v148 offset:1024
	ds_read_b128 v[150:153], v148 offset:2048
	ds_read_b128 v[202:205], v148 offset:3072
	ds_read_b128 v[30:33], v145 offset:32768
	ds_read_b128 v[34:37], v145 offset:33792
	ds_read_b128 v[46:49], v144 offset:32768
	ds_read_b128 v[50:53], v144 offset:33792
	ds_read_b128 v[206:209], v143 offset:32768
	ds_read_b128 v[210:213], v143 offset:33792
	ds_read_b128 v[214:217], v142 offset:32768
	ds_read_b128 v[242:245], v142 offset:33792
	s_waitcnt vmcnt(2)
	s_barrier
; #define LDA(dst,b,h) for(int m=0;m<4;++m)for(int k=0;k<2;++k) \
;     dst[m][k]=*reinterpret_cast<const bf16x8*>((char*)SA(b,h)+lds_byte(wr*64+m*16+fr,k*32+fq*8))
; #define LDB(dst,b,h) for(int n=0;n<2;++n)for(int k=0;k<2;++k) \
;     dst[n][k]=*reinterpret_cast<const bf16x8*>((char*)SB(b,h)+lds_byte(wc*32+n*16+fr,k*32+fq*8))
; #define MMA(ai,bj,At,Bt_) do{__builtin_amdgcn_s_setprio(1); \
;     for(int m=0;m<4;++m)for(int n=0;n<2;++n)for(int k=0;k<2;++k) \
;       acc[ai][bj][m][n]=__builtin_amdgcn_mfma_f32_16x16x32_bf16(Bt_[n][k],At[m][k],acc[ai][bj][m][n],0,0,0); \
;     __builtin_amdgcn_s_setprio(0);}while(0)
; #define WAIT_V(n) asm volatile("s_waitcnt vmcnt(" #n ")":::"memory")
; #define WAIT_L(n) asm volatile("s_waitcnt lgkmcnt(" #n ")":::"memory")
; #define BAR __builtin_amdgcn_s_barrier()
; template <int EPI>
; __device__ __forceinline__ void gemm_run(const GD& c, const bool has_next, const GD& nx, const Ctx& e, bf16* shm, float* rs, float* rs_nxt, float* racc_) {
;     ...
;   { LDB(B0,1,0); LDA(At,1,0); WAIT_V(2); BAR; WAIT_L(0); MMA(0,0,At,B0); BAR;
;     LDB(B1,1,1); WAIT_V(0); BAR; WAIT_L(0); MMA(0,1,At,B1); BAR;
;     LDA(At,1,1); BAR; WAIT_L(0); MMA(1,0,At,B0); MMA(1,1,At,B1); BAR; }
;   if(wr==0)BAR;
	s_waitcnt lgkmcnt(0)
	v_mfma_f32_16x16x32_bf16 v[78:81], v[14:17], v[30:33], v[126:129]
	v_mfma_f32_16x16x32_bf16 v[130:133], v[18:21], v[34:37], v[78:81]
	v_mfma_f32_16x16x32_bf16 v[78:81], v[150:153], v[30:33], v[122:125]
	v_mfma_f32_16x16x32_bf16 v[126:129], v[202:205], v[34:37], v[78:81]
	v_mfma_f32_16x16x32_bf16 v[78:81], v[14:17], v[46:49], v[118:121]
	v_mfma_f32_16x16x32_bf16 v[114:117], v[18:21], v[50:53], v[78:81]
	v_mfma_f32_16x16x32_bf16 v[78:81], v[150:153], v[46:49], v[222:225]
	v_mfma_f32_16x16x32_bf16 v[110:113], v[202:205], v[50:53], v[78:81]
	v_mfma_f32_16x16x32_bf16 v[78:81], v[14:17], v[206:209], v[226:229]
	v_mfma_f32_16x16x32_bf16 v[98:101], v[18:21], v[210:213], v[78:81]
	v_mfma_f32_16x16x32_bf16 v[78:81], v[150:153], v[206:209], v[106:109]
	v_mfma_f32_16x16x32_bf16 v[94:97], v[202:205], v[210:213], v[78:81]
	v_mfma_f32_16x16x32_bf16 v[78:81], v[14:17], v[214:217], v[102:105]
	v_mfma_f32_16x16x32_bf16 v[82:85], v[18:21], v[242:245], v[78:81]
	v_mfma_f32_16x16x32_bf16 v[78:81], v[150:153], v[214:217], v[230:233]
	v_mfma_f32_16x16x32_bf16 v[78:81], v[202:205], v[242:245], v[78:81]
	s_barrier
	ds_read_b128 v[222:225], v146
	ds_read_b128 v[226:229], v146 offset:1024
	ds_read_b128 v[230:233], v146 offset:2048
	ds_read_b128 v[146:149], v146 offset:3072
	s_waitcnt vmcnt(0)
	s_barrier
	s_waitcnt lgkmcnt(0)
	v_mfma_f32_16x16x32_bf16 v[102:105], v[222:225], v[30:33], v[234:237]
	v_mfma_f32_16x16x32_bf16 v[30:33], v[230:233], v[30:33], v[90:93]
	v_mfma_f32_16x16x32_bf16 v[118:121], v[146:149], v[34:37], v[30:33]
	v_mfma_f32_16x16x32_bf16 v[30:33], v[222:225], v[46:49], v[86:89]
	v_mfma_f32_16x16x32_bf16 v[106:109], v[226:229], v[50:53], v[30:33]
	v_mfma_f32_16x16x32_bf16 v[30:33], v[230:233], v[46:49], v[190:193]
	v_mfma_f32_16x16x32_bf16 v[122:125], v[226:229], v[34:37], v[102:105]
	v_mfma_f32_16x16x32_bf16 v[102:105], v[146:149], v[50:53], v[30:33]
	v_mfma_f32_16x16x32_bf16 v[30:33], v[222:225], v[206:209], v[194:197]
	v_mfma_f32_16x16x32_bf16 v[90:93], v[226:229], v[210:213], v[30:33]
	v_mfma_f32_16x16x32_bf16 v[30:33], v[230:233], v[206:209], v[74:77]
	v_mfma_f32_16x16x32_bf16 v[86:89], v[146:149], v[210:213], v[30:33]
	v_mfma_f32_16x16x32_bf16 v[30:33], v[222:225], v[214:217], v[70:73]
	v_mfma_f32_16x16x32_bf16 v[74:77], v[226:229], v[242:245], v[30:33]
	v_mfma_f32_16x16x32_bf16 v[30:33], v[230:233], v[214:217], v[66:69]
	v_mfma_f32_16x16x32_bf16 v[70:73], v[146:149], v[242:245], v[30:33]
	s_barrier
	ds_read_b128 v[190:193], v145 offset:49152
	ds_read_b128 v[194:197], v145 offset:50176
	ds_read_b128 v[206:209], v144 offset:49152
	ds_read_b128 v[210:213], v144 offset:50176
	ds_read_b128 v[214:217], v143 offset:49152
	ds_read_b128 v[234:237], v143 offset:50176
	ds_read_b128 v[242:245], v142 offset:49152
	ds_read_b128 v[142:145], v142 offset:50176
	s_barrier
	s_waitcnt lgkmcnt(0)
	v_mfma_f32_16x16x32_bf16 v[30:33], v[14:17], v[190:193], v[62:65]
	v_mfma_f32_16x16x32_bf16 v[66:69], v[18:21], v[194:197], v[30:33]
	v_mfma_f32_16x16x32_bf16 v[30:33], v[150:153], v[190:193], v[58:61]
	v_mfma_f32_16x16x32_bf16 v[62:65], v[202:205], v[194:197], v[30:33]
	v_mfma_f32_16x16x32_bf16 v[30:33], v[14:17], v[206:209], v[54:57]
	v_mfma_f32_16x16x32_bf16 v[50:53], v[18:21], v[210:213], v[30:33]
	v_mfma_f32_16x16x32_bf16 v[30:33], v[150:153], v[206:209], v[218:221]
	v_mfma_f32_16x16x32_bf16 v[46:49], v[202:205], v[210:213], v[30:33]
	v_mfma_f32_16x16x32_bf16 v[30:33], v[14:17], v[214:217], v[238:241]
	v_mfma_f32_16x16x32_bf16 v[14:17], v[14:17], v[242:245], v[38:41]
	v_mfma_f32_16x16x32_bf16 v[34:37], v[18:21], v[234:237], v[30:33]
	v_mfma_f32_16x16x32_bf16 v[30:33], v[150:153], v[214:217], v[42:45]
	v_mfma_f32_16x16x32_bf16 v[18:21], v[18:21], v[142:145], v[14:17]
	v_mfma_f32_16x16x32_bf16 v[14:17], v[150:153], v[242:245], v[136:139]
	v_mfma_f32_16x16x32_bf16 v[30:33], v[202:205], v[234:237], v[30:33]
	v_mfma_f32_16x16x32_bf16 v[14:17], v[202:205], v[142:145], v[14:17]
	v_mfma_f32_16x16x32_bf16 v[22:25], v[222:225], v[206:209], v[22:25]
	v_mfma_f32_16x16x32_bf16 v[38:41], v[222:225], v[190:193], v[166:169]
	v_mfma_f32_16x16x32_bf16 v[42:45], v[226:229], v[210:213], v[22:25]
	v_mfma_f32_16x16x32_bf16 v[22:25], v[230:233], v[206:209], v[170:173]
	v_mfma_f32_16x16x32_bf16 v[58:61], v[226:229], v[194:197], v[38:41]
	v_mfma_f32_16x16x32_bf16 v[26:29], v[230:233], v[190:193], v[26:29]
	v_mfma_f32_16x16x32_bf16 v[38:41], v[146:149], v[210:213], v[22:25]
	v_mfma_f32_16x16x32_bf16 v[22:25], v[222:225], v[214:217], v[198:201]
	v_mfma_f32_16x16x32_bf16 v[10:13], v[230:233], v[214:217], v[10:13]
	v_mfma_f32_16x16x32_bf16 v[6:9], v[222:225], v[242:245], v[6:9]
	v_mfma_f32_16x16x32_bf16 v[2:5], v[230:233], v[242:245], v[2:5]
	v_mfma_f32_16x16x32_bf16 v[54:57], v[146:149], v[194:197], v[26:29]
	v_mfma_f32_16x16x32_bf16 v[26:29], v[226:229], v[234:237], v[22:25]
	v_mfma_f32_16x16x32_bf16 v[22:25], v[146:149], v[234:237], v[10:13]
	v_mfma_f32_16x16x32_bf16 v[10:13], v[226:229], v[142:145], v[6:9]
	v_mfma_f32_16x16x32_bf16 v[6:9], v[146:149], v[142:145], v[2:5]
	v_cmp_gt_u32_e32 vcc, s96, v140
	s_barrier
	s_and_saveexec_b64 s[2:3], vcc
	s_cbranch_execz .LBB0_467
	s_barrier

; #define STAGE_A(P,br,kt) STAGE_G(P,c.A,c.lda,br,(long)(kt)*c.kstr)
; #define STAGE_B(P,br,kt) STAGE_G(P,c.Bt,c.K,br,(long)(kt)*BK)
; #define LDA(dst,b,h) for(int m=0;m<4;++m)for(int k=0;k<2;++k) \
;     dst[m][k]=*reinterpret_cast<const bf16x8*>((char*)SA(b,h)+lds_byte(wr*64+m*16+fr,k*32+fq*8))
; #define LDB(dst,b,h) for(int n=0;n<2;++n)for(int k=0;k<2;++k) \
;     dst[n][k]=*reinterpret_cast<const bf16x8*>((char*)SB(b,h)+lds_byte(wc*32+n*16+fr,k*32+fq*8))
; #define WAIT_V(n) asm volatile("s_waitcnt vmcnt(" #n ")":::"memory")
; #define BAR __builtin_amdgcn_s_barrier()
; #define SCHED __builtin_amdgcn_sched_barrier(0)
; template <int EPI>
; __device__ __forceinline__ void gemm_run(const GD& c, const bool has_next, const GD& nx, const Ctx& e, bf16* shm, float* rs, float* rs_nxt, float* racc_) {
;     ...
;   if(wr==1)BAR;
;   WAIT_V(0); BAR;
;   STAGE_B(SB(1,0),bcol,1); STAGE_A(SA(1,0),brow,1); STAGE_B(SB(1,1),bcol+HALF,1);
;   BAR;
;   for(int t=0;t<nt-2;t+=2){
;     LDB(B0,0,0); SCHED; LDA(At,0,0); STAGE_A(SA(1,1),brow+HALF,t+1);
.LBB0_745:
	s_or_b64 exec, exec, s[2:3]
	v_bfe_i32 v2, v92, 27, 1
	v_lshlrev_b32_e32 v20, 4, v92
	v_lshrrev_b32_e32 v2, 22, v2
	v_add_u32_e32 v2, v20, v2
	v_and_b32_e32 v2, 0xfffffc00, v2
	v_sub_u32_e32 v2, v20, v2
	v_lshrrev_b32_e32 v3, 4, v2
	v_bitop3_b32 v2, v3, v2, 32 bitop3:0x6c
	v_ashrrev_i32_e32 v0, 31, v92
	v_ashrrev_i32_e32 v4, 31, v2
	v_lshrrev_b32_e32 v0, 26, v0
	v_lshrrev_b32_e32 v4, 26, v4
	v_add_u32_e32 v0, v92, v0
	v_add_u32_e32 v4, v2, v4
	s_lshl_b32 s2, s31, 8
	v_ashrrev_i32_e32 v0, 6, v0
	v_lshrrev_b32_e32 v5, 6, v4
	v_and_b32_e32 v4, 0xc0, v4
	s_ashr_i32 s3, s2, 31
	v_lshlrev_b32_e32 v3, 3, v0
	v_lshlrev_b32_e32 v0, 5, v0
	v_sub_u32_e32 v2, v2, v4
	s_lshl_b32 s12, s20, 8
	s_lshl_b64 s[20:21], s[2:3], 9
	v_and_b32_e32 v3, 0x7ffff0, v3
	v_and_b32_e32 v0, 32, v0
	v_ashrrev_i16_sdwa v2, v177, sext(v2) dst_sel:DWORD dst_unused:UNUSED_PAD src0_sel:DWORD src1_sel:BYTE_0
	s_add_u32 s34, s25, s20
	v_add_u32_sdwa v0, v0, sext(v2) dst_sel:DWORD dst_unused:UNUSED_PAD src0_sel:DWORD src1_sel:WORD_0
	v_add_lshl_u32 v2, v5, v3, 9
	v_readlane_b32 s38, v254, 23
	s_addc_u32 s35, s26, s21
	v_lshl_add_u32 v0, v0, 1, v2
	v_add_u32_e32 v6, s38, v20
	v_lshl_add_u64 v[2:3], s[34:35], 0, v[0:1]
	v_readfirstlane_b32 s20, v6
	v_lshl_add_u64 v[4:5], v[2:3], 0, s[66:67]
	s_mov_b32 m0, s20
	v_add_u32_e32 v21, 0x2000, v20
	s_waitcnt vmcnt(0)
	s_barrier
	global_load_lds_dwordx4 v[4:5], off
	v_ashrrev_i32_e32 v4, 31, v21
	v_lshrrev_b32_e32 v4, 22, v4
	v_add_u32_e32 v4, v21, v4
	v_ashrrev_i32_e32 v4, 10, v4
	v_mul_i32_i24_e32 v5, 0x400, v4
	v_sub_u32_e32 v5, v21, v5
	v_lshrrev_b32_e32 v6, 4, v5
	v_bitop3_b32 v5, v6, v5, 32 bitop3:0x6c
	v_ashrrev_i32_e32 v7, 31, v5
	v_lshrrev_b32_e32 v7, 26, v7
	v_add_u32_e32 v7, v5, v7
	v_lshrrev_b32_e32 v8, 6, v7
	v_and_b32_e32 v7, 0xc0, v7
	v_lshlrev_b32_e32 v6, 3, v4
	v_lshlrev_b32_e32 v4, 5, v4
	v_sub_u32_e32 v5, v5, v7
	s_ashr_i32 s13, s12, 31
	v_and_b32_e32 v6, 0x7ffff0, v6
	v_and_b32_e32 v4, 32, v4
	v_ashrrev_i16_sdwa v5, v177, sext(v5) dst_sel:DWORD dst_unused:UNUSED_PAD src0_sel:DWORD src1_sel:BYTE_0
	s_lshl_b64 s[36:37], s[12:13], 9
	v_add_u32_sdwa v4, v4, sext(v5) dst_sel:DWORD dst_unused:UNUSED_PAD src0_sel:DWORD src1_sel:WORD_0
	v_add_lshl_u32 v5, v8, v6, 9
	s_add_u32 s36, s23, s36
	v_lshl_add_u32 v90, v4, 1, v5
	v_mov_b32_e32 v91, v1
	v_add_u32_e32 v6, s38, v21
	s_addc_u32 s37, s24, s37
	v_add_u32_e32 v93, 0, v20
	s_bitset1_b32 s2, 7
	v_lshl_add_u64 v[12:13], s[34:35], 0, v[90:91]
	v_readfirstlane_b32 s34, v6
	v_add_u32_e32 v6, 0x8000, v93
	s_ashr_i32 s3, s2, 31
	v_lshl_add_u64 v[4:5], v[12:13], 0, s[66:67]
	s_mov_b32 m0, s34
	v_lshl_add_u64 v[8:9], s[36:37], 0, v[0:1]
	v_readfirstlane_b32 s21, v6
	v_add_u32_e32 v6, 0xa000, v93
	s_lshl_b64 s[2:3], s[2:3], 9
	global_load_lds_dwordx4 v[4:5], off
	v_lshl_add_u64 v[4:5], v[8:9], 0, s[66:67]
	s_mov_b32 m0, s21
	v_lshl_add_u64 v[10:11], s[36:37], 0, v[90:91]
	v_readfirstlane_b32 s13, v6
	s_add_u32 s36, s25, s2
	v_readlane_b32 s35, v254, 24
	global_load_lds_dwordx4 v[4:5], off
	v_lshl_add_u64 v[4:5], v[10:11], 0, s[66:67]
	s_mov_b32 m0, s13
	s_addc_u32 s37, s26, s3
	v_add_u32_e32 v16, s35, v20
	global_load_lds_dwordx4 v[4:5], off
	v_lshl_add_u64 v[4:5], s[36:37], 0, v[0:1]
	v_readfirstlane_b32 s2, v16
	v_lshl_add_u64 v[6:7], v[4:5], 0, s[66:67]
	s_mov_b32 m0, s2
	v_add_u32_e32 v19, s35, v21
	global_load_lds_dwordx4 v[6:7], off
	v_lshl_add_u64 v[6:7], s[36:37], 0, v[90:91]
	v_readfirstlane_b32 s3, v19
	v_lshl_add_u64 v[16:17], v[6:7], 0, s[66:67]
	s_mov_b32 m0, s3
	v_and_b32_e32 v15, 15, v92
	global_load_lds_dwordx4 v[16:17], off
	v_lshlrev_b32_e32 v19, 2, v92
	v_and_b32_e32 v18, 48, v92
	v_lshlrev_b32_e32 v16, 6, v92
	v_lshlrev_b32_e32 v15, 6, v15
	v_and_b32_e32 v22, 32, v19
	v_and_b32_e32 v17, 0x3000, v16
	v_bitop3_b32 v15, v15, v22, v18 bitop3:0x36
	v_add3_u32 v139, s33, v15, v17
	v_and_b32_e32 v16, 0x3c0, v16
	s_barrier
	v_bitop3_b32 v16, v16, v22, v18 bitop3:0x36
	v_add_u32_e32 v138, s33, v20
	v_add_u32_e32 v126, s33, v21
	v_add_u32_e32 v96, s86, v20
	v_add_u32_e32 v176, s86, v21
	ds_read_b128 v[20:23], v139
	ds_read_b128 v[24:27], v139 offset:1024
	ds_read_b128 v[28:31], v139 offset:2048
	ds_read_b128 v[32:35], v139 offset:3072
	v_lshlrev_b32_e32 v14, 13, v14
	s_or_b32 s36, s12, 0x80
	v_add3_u32 v19, 0, v15, v14
	v_add3_u32 v18, 0, v16, v14
	v_add_u32_e32 v68, 0xc000, v93
	v_add_u32_e32 v70, 0xe000, v93
	v_add_u32_e32 v97, 0x2000, v93
	v_add_u32_e32 v95, 0x4000, v93
	v_add_u32_e32 v94, 0x6000, v93
	s_ashr_i32 s37, s36, 31
	v_add3_u32 v170, s86, v15, v17
	v_add3_u32 v182, s38, v15, v17
	v_add3_u32 v183, s35, v15, v17
	s_lshl_b64 s[36:37], s[36:37], 9
	s_add_u32 s38, s23, s36
	s_addc_u32 s39, s24, s37
	v_lshl_add_u64 v[14:15], s[38:39], 0, v[0:1]
	v_readfirstlane_b32 s36, v68
	v_lshl_add_u64 v[16:17], v[14:15], 0, s[66:67]
	s_mov_b32 m0, s36
	ds_read_b128 v[36:39], v19
	ds_read_b128 v[40:43], v19 offset:1024
	ds_read_b128 v[44:47], v18 offset:2048
	ds_read_b128 v[48:51], v18 offset:3072
	ds_read_b128 v[52:55], v18 offset:4096
	ds_read_b128 v[56:59], v18 offset:5120
	ds_read_b128 v[60:63], v18 offset:6144
	ds_read_b128 v[64:67], v18 offset:7168
	global_load_lds_dwordx4 v[16:17], off
	v_lshl_add_u64 v[16:17], s[38:39], 0, v[90:91]
	v_readfirstlane_b32 s35, v70
	v_lshl_add_u64 v[68:69], v[16:17], 0, s[66:67]
	s_mov_b32 m0, s35
	s_nop 0
	global_load_lds_dwordx4 v[68:69], off
	s_waitcnt lgkmcnt(8)
	s_barrier
; #define STAGE_A(P,br,kt) STAGE_G(P,c.A,c.lda,br,(long)(kt)*c.kstr)
; #define STAGE_B(P,br,kt) STAGE_G(P,c.Bt,c.K,br,(long)(kt)*BK)
; #define LDA(dst,b,h) for(int m=0;m<4;++m)for(int k=0;k<2;++k) \
;     dst[m][k]=*reinterpret_cast<const bf16x8*>((char*)SA(b,h)+lds_byte(wr*64+m*16+fr,k*32+fq*8))
; #define LDB(dst,b,h) for(int n=0;n<2;++n)for(int k=0;k<2;++k) \
;     dst[n][k]=*reinterpret_cast<const bf16x8*>((char*)SB(b,h)+lds_byte(wc*32+n*16+fr,k*32+fq*8))
; #define MMA(ai,bj,At,Bt_) do{__builtin_amdgcn_s_setprio(1); \
;     for(int m=0;m<4;++m)for(int n=0;n<2;++n)for(int k=0;k<2;++k) \
;       acc[ai][bj][m][n]=__builtin_amdgcn_mfma_f32_16x16x32_bf16(Bt_[n][k],At[m][k],acc[ai][bj][m][n],0,0,0); \
;     __builtin_amdgcn_s_setprio(0);}while(0)
; #define WAIT_V(n) asm volatile("s_waitcnt vmcnt(" #n ")":::"memory")
; #define WAIT_L(n) asm volatile("s_waitcnt lgkmcnt(" #n ")":::"memory")
; #define BAR __builtin_amdgcn_s_barrier()
; #define SCHED __builtin_amdgcn_sched_barrier(0)
; template <int EPI>
; __device__ __forceinline__ void gemm_run(const GD& c, const bool has_next, const GD& nx, const Ctx& e, bf16* shm, float* rs, float* rs_nxt, float* racc_) {
;     ...
;     LDB(B0,0,0); SCHED; LDA(At,0,0); STAGE_A(SA(1,1),brow+HALF,t+1);
;     WAIT_L(8); BAR; WAIT_L(0); MMA(0,0,At,B0); BAR; SCHED;
;     LDB(B1,0,1); STAGE_B(SB(0,0),bcol,t+2);
;     BAR; WAIT_L(0); MMA(0,1,At,B1); BAR;
;     LDA(At,0,1); STAGE_A(SA(0,0),brow,t+2);
;     BAR; WAIT_L(0); MMA(1,0,At,B0); BAR; SCHED;
;     STAGE_B(SB(0,1),bcol+HALF,t+2);
;     WAIT_V(6); BAR; MMA(1,1,At,B1); BAR;
	s_waitcnt lgkmcnt(0)
	v_mfma_f32_16x16x32_bf16 v[68:71], v[20:23], v[36:39], 0
	v_mfma_f32_16x16x32_bf16 v[72:75], v[28:31], v[36:39], 0
	v_mfma_f32_16x16x32_bf16 v[76:79], v[20:23], v[44:47], 0
	v_mfma_f32_16x16x32_bf16 v[80:83], v[28:31], v[44:47], 0
	v_mfma_f32_16x16x32_bf16 v[84:87], v[20:23], v[52:55], 0
	v_mfma_f32_16x16x32_bf16 v[98:101], v[28:31], v[52:55], 0
	v_mfma_f32_16x16x32_bf16 v[102:105], v[20:23], v[60:63], 0
	v_mfma_f32_16x16x32_bf16 v[106:109], v[28:31], v[60:63], 0
	v_mfma_f32_16x16x32_bf16 v[68:71], v[24:27], v[40:43], v[68:71]
	v_mfma_f32_16x16x32_bf16 v[72:75], v[32:35], v[40:43], v[72:75]
	v_mfma_f32_16x16x32_bf16 v[76:79], v[24:27], v[48:51], v[76:79]
	v_mfma_f32_16x16x32_bf16 v[80:83], v[32:35], v[48:51], v[80:83]
	v_mfma_f32_16x16x32_bf16 v[84:87], v[24:27], v[56:59], v[84:87]
	v_mfma_f32_16x16x32_bf16 v[98:101], v[32:35], v[56:59], v[98:101]
	v_mfma_f32_16x16x32_bf16 v[102:105], v[24:27], v[64:67], v[102:105]
	v_mfma_f32_16x16x32_bf16 v[106:109], v[32:35], v[64:67], v[106:109]
	s_barrier
	v_readfirstlane_b32 s37, v138
	v_lshl_add_u64 v[88:89], v[2:3], 0, s[88:89]
	s_mov_b32 m0, s37
	v_readfirstlane_b32 s37, v126
	ds_read_b128 v[110:113], v170
	ds_read_b128 v[114:117], v170 offset:1024
	ds_read_b128 v[118:121], v170 offset:2048
	ds_read_b128 v[122:125], v170 offset:3072
	global_load_lds_dwordx4 v[88:89], off
	v_lshl_add_u64 v[88:89], v[12:13], 0, s[88:89]
	s_mov_b32 m0, s37
	s_nop 0
	global_load_lds_dwordx4 v[88:89], off
	s_barrier
	s_waitcnt lgkmcnt(0)
	v_mfma_f32_16x16x32_bf16 v[126:129], v[110:113], v[36:39], 0
	v_mfma_f32_16x16x32_bf16 v[36:39], v[118:121], v[36:39], 0
	v_mfma_f32_16x16x32_bf16 v[126:129], v[114:117], v[40:43], v[126:129]
	v_mfma_f32_16x16x32_bf16 v[36:39], v[122:125], v[40:43], v[36:39]
	v_mfma_f32_16x16x32_bf16 v[40:43], v[110:113], v[44:47], 0
	v_mfma_f32_16x16x32_bf16 v[44:47], v[118:121], v[44:47], 0
	v_mfma_f32_16x16x32_bf16 v[40:43], v[114:117], v[48:51], v[40:43]
	v_mfma_f32_16x16x32_bf16 v[44:47], v[122:125], v[48:51], v[44:47]
	v_mfma_f32_16x16x32_bf16 v[48:51], v[110:113], v[52:55], 0
	v_mfma_f32_16x16x32_bf16 v[52:55], v[118:121], v[52:55], 0
	v_mfma_f32_16x16x32_bf16 v[48:51], v[114:117], v[56:59], v[48:51]
	v_mfma_f32_16x16x32_bf16 v[52:55], v[122:125], v[56:59], v[52:55]
	v_mfma_f32_16x16x32_bf16 v[56:59], v[110:113], v[60:63], 0
	v_mfma_f32_16x16x32_bf16 v[60:63], v[118:121], v[60:63], 0
	v_mfma_f32_16x16x32_bf16 v[56:59], v[114:117], v[64:67], v[56:59]
	v_mfma_f32_16x16x32_bf16 v[60:63], v[122:125], v[64:67], v[60:63]
	s_barrier
	v_readfirstlane_b32 s37, v93
	v_lshl_add_u64 v[88:89], v[8:9], 0, s[88:89]
	s_mov_b32 m0, s37
	v_readfirstlane_b32 s37, v97
	ds_read_b128 v[64:67], v19 offset:16384
	ds_read_b128 v[130:133], v19 offset:17408
	ds_read_b128 v[134:137], v18 offset:18432
	ds_read_b128 v[140:143], v18 offset:19456
	ds_read_b128 v[144:147], v18 offset:20480
	ds_read_b128 v[148:151], v18 offset:21504
	ds_read_b128 v[152:155], v18 offset:22528
	ds_read_b128 v[156:159], v18 offset:23552
	global_load_lds_dwordx4 v[88:89], off
	v_lshl_add_u64 v[88:89], v[10:11], 0, s[88:89]
	s_mov_b32 m0, s37
	s_nop 0
	global_load_lds_dwordx4 v[88:89], off
	s_barrier
	s_waitcnt lgkmcnt(0)
	v_mfma_f32_16x16x32_bf16 v[160:163], v[20:23], v[64:67], 0
	v_mfma_f32_16x16x32_bf16 v[172:175], v[20:23], v[134:137], 0
	v_mfma_f32_16x16x32_bf16 v[190:193], v[20:23], v[144:147], 0
	v_mfma_f32_16x16x32_bf16 v[20:23], v[20:23], v[152:155], 0
	v_mfma_f32_16x16x32_bf16 v[160:163], v[24:27], v[130:133], v[160:163]
	v_mfma_f32_16x16x32_bf16 v[172:175], v[24:27], v[140:143], v[172:175]
	v_mfma_f32_16x16x32_bf16 v[190:193], v[24:27], v[148:151], v[190:193]
	v_mfma_f32_16x16x32_bf16 v[20:23], v[24:27], v[156:159], v[20:23]
	v_mfma_f32_16x16x32_bf16 v[24:27], v[28:31], v[152:155], 0
	v_mfma_f32_16x16x32_bf16 v[166:169], v[28:31], v[64:67], 0
	v_mfma_f32_16x16x32_bf16 v[186:189], v[28:31], v[134:137], 0
	v_mfma_f32_16x16x32_bf16 v[194:197], v[28:31], v[144:147], 0
	v_mfma_f32_16x16x32_bf16 v[24:27], v[32:35], v[156:159], v[24:27]
	v_mfma_f32_16x16x32_bf16 v[166:169], v[32:35], v[130:133], v[166:169]
	v_mfma_f32_16x16x32_bf16 v[186:189], v[32:35], v[140:143], v[186:189]
	v_mfma_f32_16x16x32_bf16 v[194:197], v[32:35], v[148:151], v[194:197]
	s_barrier
	v_readfirstlane_b32 s37, v96
	v_lshl_add_u64 v[28:29], v[4:5], 0, s[88:89]
	s_mov_b32 m0, s37
	v_readfirstlane_b32 s37, v176
	global_load_lds_dwordx4 v[28:29], off
	v_lshl_add_u64 v[28:29], v[6:7], 0, s[88:89]
	s_mov_b32 m0, s37
	s_nop 0
	global_load_lds_dwordx4 v[28:29], off
	s_waitcnt vmcnt(6)
	s_barrier
	v_mfma_f32_16x16x32_bf16 v[28:31], v[110:113], v[64:67], 0
	v_mfma_f32_16x16x32_bf16 v[32:35], v[118:121], v[64:67], 0
	v_mfma_f32_16x16x32_bf16 v[28:31], v[114:117], v[130:133], v[28:31]
	v_mfma_f32_16x16x32_bf16 v[32:35], v[122:125], v[130:133], v[32:35]
	v_mfma_f32_16x16x32_bf16 v[64:67], v[110:113], v[134:137], 0
	v_mfma_f32_16x16x32_bf16 v[130:133], v[118:121], v[134:137], 0
	v_mfma_f32_16x16x32_bf16 v[134:137], v[110:113], v[144:147], 0
	v_mfma_f32_16x16x32_bf16 v[110:113], v[110:113], v[152:155], 0
	v_mfma_f32_16x16x32_bf16 v[64:67], v[114:117], v[140:143], v[64:67]
	v_mfma_f32_16x16x32_bf16 v[134:137], v[114:117], v[148:151], v[134:137]
	v_mfma_f32_16x16x32_bf16 v[110:113], v[114:117], v[156:159], v[110:113]
	v_mfma_f32_16x16x32_bf16 v[114:117], v[118:121], v[152:155], 0
	v_mfma_f32_16x16x32_bf16 v[130:133], v[122:125], v[140:143], v[130:133]
	v_mfma_f32_16x16x32_bf16 v[140:143], v[118:121], v[144:147], 0
	v_mfma_f32_16x16x32_bf16 v[114:117], v[122:125], v[156:159], v[114:117]
	v_mfma_f32_16x16x32_bf16 v[140:143], v[122:125], v[148:151], v[140:143]
	s_barrier
; #define STAGE_A(P,br,kt) STAGE_G(P,c.A,c.lda,br,(long)(kt)*c.kstr)
; #define STAGE_B(P,br,kt) STAGE_G(P,c.Bt,c.K,br,(long)(kt)*BK)
; #define LDA(dst,b,h) for(int m=0;m<4;++m)for(int k=0;k<2;++k) \
;     dst[m][k]=*reinterpret_cast<const bf16x8*>((char*)SA(b,h)+lds_byte(wr*64+m*16+fr,k*32+fq*8))
; #define LDB(dst,b,h) for(int n=0;n<2;++n)for(int k=0;k<2;++k) \
;     dst[n][k]=*reinterpret_cast<const bf16x8*>((char*)SB(b,h)+lds_byte(wc*32+n*16+fr,k*32+fq*8))
; #define MMA(ai,bj,At,Bt_) do{__builtin_amdgcn_s_setprio(1); \
;     for(int m=0;m<4;++m)for(int n=0;n<2;++n)for(int k=0;k<2;++k) \
;       acc[ai][bj][m][n]=__builtin_amdgcn_mfma_f32_16x16x32_bf16(Bt_[n][k],At[m][k],acc[ai][bj][m][n],0,0,0); \
;     __builtin_amdgcn_s_setprio(0);}while(0)
; #define WAIT_V(n) asm volatile("s_waitcnt vmcnt(" #n ")":::"memory")
; #define WAIT_L(n) asm volatile("s_waitcnt lgkmcnt(" #n ")":::"memory")
; #define BAR __builtin_amdgcn_s_barrier()
; #define SCHED __builtin_amdgcn_sched_barrier(0)
; template <int EPI>
; __device__ __forceinline__ void gemm_run(const GD& c, const bool has_next, const GD& nx, const Ctx& e, bf16* shm, float* rs, float* rs_nxt, float* racc_) {
;     ...
;     LDB(B0,1,0); SCHED; LDA(At,1,0); STAGE_A(SA(0,1),brow+HALF,t+2);
;     WAIT_L(8); BAR; WAIT_L(0); MMA(0,0,At,B0); BAR; SCHED;
;     LDB(B1,1,1); STAGE_B(SB(1,0),bcol,t+3);
;     BAR; WAIT_L(0); MMA(0,1,At,B1); BAR;
;     LDA(At,1,1); STAGE_A(SA(1,0),brow,t+3);
;     BAR; WAIT_L(0); MMA(1,0,At,B0); BAR; SCHED;
;     STAGE_B(SB(1,1),bcol+HALF,t+3);
;     WAIT_V(6); BAR; MMA(1,1,At,B1); BAR;
	ds_read_b128 v[118:121], v182
	ds_read_b128 v[122:125], v182 offset:1024
	ds_read_b128 v[144:147], v182 offset:2048
	ds_read_b128 v[148:151], v182 offset:3072
	v_readfirstlane_b32 s37, v95
	v_lshl_add_u64 v[88:89], v[14:15], 0, s[88:89]
	s_mov_b32 m0, s37
	v_readfirstlane_b32 s37, v94
	ds_read_b128 v[152:155], v19 offset:32768
	ds_read_b128 v[156:159], v19 offset:33792
	ds_read_b128 v[198:201], v18 offset:34816
	ds_read_b128 v[202:205], v18 offset:35840
	ds_read_b128 v[206:209], v18 offset:36864
	ds_read_b128 v[210:213], v18 offset:37888
	ds_read_b128 v[214:217], v18 offset:38912
	ds_read_b128 v[218:221], v18 offset:39936
	global_load_lds_dwordx4 v[88:89], off
	v_lshl_add_u64 v[88:89], v[16:17], 0, s[88:89]
	s_mov_b32 m0, s37
	s_nop 0
	global_load_lds_dwordx4 v[88:89], off
	s_waitcnt lgkmcnt(8)
	s_barrier
	s_waitcnt lgkmcnt(0)
	v_mfma_f32_16x16x32_bf16 v[68:71], v[118:121], v[152:155], v[68:71]
	v_mfma_f32_16x16x32_bf16 v[72:75], v[144:147], v[152:155], v[72:75]
	v_mfma_f32_16x16x32_bf16 v[76:79], v[118:121], v[198:201], v[76:79]
	v_mfma_f32_16x16x32_bf16 v[80:83], v[144:147], v[198:201], v[80:83]
	v_mfma_f32_16x16x32_bf16 v[84:87], v[118:121], v[206:209], v[84:87]
	v_mfma_f32_16x16x32_bf16 v[98:101], v[144:147], v[206:209], v[98:101]
	v_mfma_f32_16x16x32_bf16 v[102:105], v[118:121], v[214:217], v[102:105]
	v_mfma_f32_16x16x32_bf16 v[106:109], v[144:147], v[214:217], v[106:109]
	v_mfma_f32_16x16x32_bf16 v[68:71], v[122:125], v[156:159], v[68:71]
	v_mfma_f32_16x16x32_bf16 v[72:75], v[148:151], v[156:159], v[72:75]
	v_mfma_f32_16x16x32_bf16 v[76:79], v[122:125], v[202:205], v[76:79]
	v_mfma_f32_16x16x32_bf16 v[80:83], v[148:151], v[202:205], v[80:83]
	v_mfma_f32_16x16x32_bf16 v[84:87], v[122:125], v[210:213], v[84:87]
	v_mfma_f32_16x16x32_bf16 v[98:101], v[148:151], v[210:213], v[98:101]
	v_mfma_f32_16x16x32_bf16 v[102:105], v[122:125], v[218:221], v[102:105]
	v_mfma_f32_16x16x32_bf16 v[106:109], v[148:151], v[218:221], v[106:109]
	s_barrier
	s_mov_b64 s[38:39], 0x180
	s_mov_b32 m0, s20
	v_lshl_add_u64 v[2:3], v[2:3], 0, s[38:39]
	ds_read_b128 v[222:225], v183
	ds_read_b128 v[226:229], v183 offset:1024
	ds_read_b128 v[230:233], v183 offset:2048
	ds_read_b128 v[234:237], v183 offset:3072
	global_load_lds_dwordx4 v[2:3], off
	v_lshl_add_u64 v[2:3], v[12:13], 0, s[38:39]
	s_mov_b32 m0, s34
	s_nop 0
	global_load_lds_dwordx4 v[2:3], off
	s_barrier
	s_waitcnt lgkmcnt(0)
	v_mfma_f32_16x16x32_bf16 v[126:129], v[222:225], v[152:155], v[126:129]
	v_mfma_f32_16x16x32_bf16 v[36:39], v[230:233], v[152:155], v[36:39]
	v_mfma_f32_16x16x32_bf16 v[40:43], v[222:225], v[198:201], v[40:43]
	v_mfma_f32_16x16x32_bf16 v[44:47], v[230:233], v[198:201], v[44:47]
	v_mfma_f32_16x16x32_bf16 v[48:51], v[222:225], v[206:209], v[48:51]
	v_mfma_f32_16x16x32_bf16 v[52:55], v[230:233], v[206:209], v[52:55]
	v_mfma_f32_16x16x32_bf16 v[56:59], v[222:225], v[214:217], v[56:59]
	v_mfma_f32_16x16x32_bf16 v[60:63], v[230:233], v[214:217], v[60:63]
	v_mfma_f32_16x16x32_bf16 v[126:129], v[226:229], v[156:159], v[126:129]
	v_mfma_f32_16x16x32_bf16 v[36:39], v[234:237], v[156:159], v[36:39]
	v_mfma_f32_16x16x32_bf16 v[40:43], v[226:229], v[202:205], v[40:43]
	v_mfma_f32_16x16x32_bf16 v[44:47], v[234:237], v[202:205], v[44:47]
	v_mfma_f32_16x16x32_bf16 v[48:51], v[226:229], v[210:213], v[48:51]
	v_mfma_f32_16x16x32_bf16 v[52:55], v[234:237], v[210:213], v[52:55]
	v_mfma_f32_16x16x32_bf16 v[56:59], v[226:229], v[218:221], v[56:59]
	v_mfma_f32_16x16x32_bf16 v[60:63], v[234:237], v[218:221], v[60:63]
	s_barrier
	s_mov_b32 m0, s21
	v_lshl_add_u64 v[2:3], v[8:9], 0, s[38:39]
	ds_read_b128 v[152:155], v19 offset:49152
	ds_read_b128 v[156:159], v19 offset:50176
	ds_read_b128 v[198:201], v18 offset:51200
	ds_read_b128 v[202:205], v18 offset:52224
	ds_read_b128 v[206:209], v18 offset:53248
	ds_read_b128 v[210:213], v18 offset:54272
	ds_read_b128 v[214:217], v18 offset:55296
	ds_read_b128 v[218:221], v18 offset:56320
	global_load_lds_dwordx4 v[2:3], off
	v_lshl_add_u64 v[2:3], v[10:11], 0, s[38:39]
	s_mov_b32 m0, s13
	s_nop 0
	global_load_lds_dwordx4 v[2:3], off
	s_barrier
	s_waitcnt lgkmcnt(0)
	v_mfma_f32_16x16x32_bf16 v[8:11], v[118:121], v[152:155], v[160:163]
	v_mfma_f32_16x16x32_bf16 v[20:23], v[118:121], v[214:217], v[20:23]
	v_mfma_f32_16x16x32_bf16 v[24:27], v[144:147], v[214:217], v[24:27]
	v_mfma_f32_16x16x32_bf16 v[8:11], v[122:125], v[156:159], v[8:11]
	v_mfma_f32_16x16x32_bf16 v[160:163], v[144:147], v[152:155], v[166:169]
	v_mfma_f32_16x16x32_bf16 v[166:169], v[118:121], v[198:201], v[172:175]
	v_mfma_f32_16x16x32_bf16 v[172:175], v[144:147], v[198:201], v[186:189]
	v_mfma_f32_16x16x32_bf16 v[186:189], v[118:121], v[206:209], v[190:193]
	v_mfma_f32_16x16x32_bf16 v[190:193], v[144:147], v[206:209], v[194:197]
	v_mfma_f32_16x16x32_bf16 v[20:23], v[122:125], v[218:221], v[20:23]
	v_mfma_f32_16x16x32_bf16 v[24:27], v[148:151], v[218:221], v[24:27]
	v_mfma_f32_16x16x32_bf16 v[160:163], v[148:151], v[156:159], v[160:163]
	v_mfma_f32_16x16x32_bf16 v[166:169], v[122:125], v[202:205], v[166:169]
	v_mfma_f32_16x16x32_bf16 v[172:175], v[148:151], v[202:205], v[172:175]
	v_mfma_f32_16x16x32_bf16 v[186:189], v[122:125], v[210:213], v[186:189]
	v_mfma_f32_16x16x32_bf16 v[190:193], v[148:151], v[210:213], v[190:193]
	s_barrier
	s_mov_b32 m0, s2
	v_lshl_add_u64 v[2:3], v[4:5], 0, s[38:39]
	global_load_lds_dwordx4 v[2:3], off
	v_lshl_add_u64 v[2:3], v[6:7], 0, s[38:39]
	s_mov_b32 m0, s3
	s_nop 0
	global_load_lds_dwordx4 v[2:3], off
	s_waitcnt vmcnt(6)
	s_barrier
; #define STAGE_A(P,br,kt) STAGE_G(P,c.A,c.lda,br,(long)(kt)*c.kstr)
; #define LDA(dst,b,h) for(int m=0;m<4;++m)for(int k=0;k<2;++k) \
;     dst[m][k]=*reinterpret_cast<const bf16x8*>((char*)SA(b,h)+lds_byte(wr*64+m*16+fr,k*32+fq*8))
; #define LDB(dst,b,h) for(int n=0;n<2;++n)for(int k=0;k<2;++k) \
;     dst[n][k]=*reinterpret_cast<const bf16x8*>((char*)SB(b,h)+lds_byte(wc*32+n*16+fr,k*32+fq*8))
; #define MMA(ai,bj,At,Bt_) do{__builtin_amdgcn_s_setprio(1); \
;     for(int m=0;m<4;++m)for(int n=0;n<2;++n)for(int k=0;k<2;++k) \
;       acc[ai][bj][m][n]=__builtin_amdgcn_mfma_f32_16x16x32_bf16(Bt_[n][k],At[m][k],acc[ai][bj][m][n],0,0,0); \
;     __builtin_amdgcn_s_setprio(0);}while(0)
; #define WAIT_V(n) asm volatile("s_waitcnt vmcnt(" #n ")":::"memory")
; #define WAIT_L(n) asm volatile("s_waitcnt lgkmcnt(" #n ")":::"memory")
; #define BAR __builtin_amdgcn_s_barrier()
; template <int EPI>
; __device__ __forceinline__ void gemm_run(const GD& c, const bool has_next, const GD& nx, const Ctx& e, bf16* shm, float* rs, float* rs_nxt, float* racc_) {
;     ...
;     WAIT_V(6); BAR; MMA(1,1,At,B1); BAR;
;   }
;   { LDB(B0,0,0); LDA(At,0,0); STAGE_A(SA(1,1),brow+HALF,nt-1);
;     BAR; WAIT_L(0); MMA(0,0,At,B0); BAR;
;     LDB(B1,0,1); BAR; WAIT_L(0); MMA(0,1,At,B1); BAR;
;     LDA(At,0,1); WAIT_V(4); BAR; WAIT_L(0); MMA(1,0,At,B0); MMA(1,1,At,B1); BAR; }
	v_mfma_f32_16x16x32_bf16 v[2:5], v[222:225], v[152:155], v[28:31]
	v_mfma_f32_16x16x32_bf16 v[28:31], v[230:233], v[152:155], v[32:35]
	v_mfma_f32_16x16x32_bf16 v[32:35], v[222:225], v[198:201], v[64:67]
	v_mfma_f32_16x16x32_bf16 v[64:67], v[230:233], v[198:201], v[130:133]
	v_mfma_f32_16x16x32_bf16 v[118:121], v[222:225], v[206:209], v[134:137]
	v_mfma_f32_16x16x32_bf16 v[122:125], v[230:233], v[206:209], v[140:143]
	v_mfma_f32_16x16x32_bf16 v[110:113], v[222:225], v[214:217], v[110:113]
	v_mfma_f32_16x16x32_bf16 v[114:117], v[230:233], v[214:217], v[114:117]
	v_mfma_f32_16x16x32_bf16 v[2:5], v[226:229], v[156:159], v[2:5]
	v_mfma_f32_16x16x32_bf16 v[28:31], v[234:237], v[156:159], v[28:31]
	v_mfma_f32_16x16x32_bf16 v[32:35], v[226:229], v[202:205], v[32:35]
	v_mfma_f32_16x16x32_bf16 v[64:67], v[234:237], v[202:205], v[64:67]
	v_mfma_f32_16x16x32_bf16 v[118:121], v[226:229], v[210:213], v[118:121]
	v_mfma_f32_16x16x32_bf16 v[122:125], v[234:237], v[210:213], v[122:125]
	v_mfma_f32_16x16x32_bf16 v[110:113], v[226:229], v[218:221], v[110:113]
	v_mfma_f32_16x16x32_bf16 v[114:117], v[234:237], v[218:221], v[114:117]
	s_barrier
	s_mov_b32 m0, s36
	v_lshl_add_u64 v[6:7], v[14:15], 0, s[38:39]
	ds_read_b128 v[130:133], v139
	ds_read_b128 v[134:137], v139 offset:1024
	ds_read_b128 v[140:143], v139 offset:2048
	ds_read_b128 v[144:147], v139 offset:3072
	ds_read_b128 v[148:151], v19
	ds_read_b128 v[152:155], v19 offset:1024
	ds_read_b128 v[156:159], v18 offset:2048
	ds_read_b128 v[194:197], v18 offset:3072
	ds_read_b128 v[198:201], v18 offset:4096
	ds_read_b128 v[202:205], v18 offset:5120
	ds_read_b128 v[206:209], v18 offset:6144
	ds_read_b128 v[210:213], v18 offset:7168
	global_load_lds_dwordx4 v[6:7], off
	v_lshl_add_u64 v[6:7], v[16:17], 0, s[38:39]
	s_mov_b32 m0, s35
	s_nop 0
	global_load_lds_dwordx4 v[6:7], off
	s_barrier
	s_waitcnt lgkmcnt(0)
	v_mfma_f32_16x16x32_bf16 v[12:15], v[130:133], v[148:151], v[68:71]
	v_mfma_f32_16x16x32_bf16 v[68:71], v[140:143], v[148:151], v[72:75]
	v_mfma_f32_16x16x32_bf16 v[72:75], v[130:133], v[156:159], v[76:79]
	v_mfma_f32_16x16x32_bf16 v[76:79], v[140:143], v[156:159], v[80:83]
	v_mfma_f32_16x16x32_bf16 v[80:83], v[130:133], v[198:201], v[84:87]
	v_mfma_f32_16x16x32_bf16 v[84:87], v[140:143], v[198:201], v[98:101]
	v_mfma_f32_16x16x32_bf16 v[98:101], v[130:133], v[206:209], v[102:105]
	v_mfma_f32_16x16x32_bf16 v[102:105], v[140:143], v[206:209], v[106:109]
	v_mfma_f32_16x16x32_bf16 v[12:15], v[134:137], v[152:155], v[12:15]
	v_mfma_f32_16x16x32_bf16 v[68:71], v[144:147], v[152:155], v[68:71]
	v_mfma_f32_16x16x32_bf16 v[72:75], v[134:137], v[194:197], v[72:75]
	v_mfma_f32_16x16x32_bf16 v[76:79], v[144:147], v[194:197], v[76:79]
	v_mfma_f32_16x16x32_bf16 v[80:83], v[134:137], v[202:205], v[80:83]
	v_mfma_f32_16x16x32_bf16 v[84:87], v[144:147], v[202:205], v[84:87]
	v_mfma_f32_16x16x32_bf16 v[98:101], v[134:137], v[210:213], v[98:101]
	v_mfma_f32_16x16x32_bf16 v[102:105], v[144:147], v[210:213], v[102:105]
	s_barrier
	ds_read_b128 v[106:109], v170
	ds_read_b128 v[214:217], v170 offset:1024
	ds_read_b128 v[218:221], v170 offset:2048
	ds_read_b128 v[222:225], v170 offset:3072
	s_barrier
	s_waitcnt lgkmcnt(0)
	v_mfma_f32_16x16x32_bf16 v[36:39], v[218:221], v[148:151], v[36:39]
	v_mfma_f32_16x16x32_bf16 v[126:129], v[106:109], v[148:151], v[126:129]
	v_mfma_f32_16x16x32_bf16 v[148:151], v[222:225], v[152:155], v[36:39]
	v_mfma_f32_16x16x32_bf16 v[36:39], v[106:109], v[156:159], v[40:43]
	v_mfma_f32_16x16x32_bf16 v[126:129], v[214:217], v[152:155], v[126:129]
	v_mfma_f32_16x16x32_bf16 v[152:155], v[214:217], v[194:197], v[36:39]
	v_mfma_f32_16x16x32_bf16 v[36:39], v[218:221], v[156:159], v[44:47]
	v_mfma_f32_16x16x32_bf16 v[156:159], v[222:225], v[194:197], v[36:39]
	v_mfma_f32_16x16x32_bf16 v[36:39], v[106:109], v[198:201], v[48:51]
	v_mfma_f32_16x16x32_bf16 v[46:49], v[214:217], v[202:205], v[36:39]
	v_mfma_f32_16x16x32_bf16 v[36:39], v[218:221], v[198:201], v[52:55]
	v_mfma_f32_16x16x32_bf16 v[50:53], v[222:225], v[202:205], v[36:39]
	v_mfma_f32_16x16x32_bf16 v[36:39], v[106:109], v[206:209], v[56:59]
	v_mfma_f32_16x16x32_bf16 v[54:57], v[214:217], v[210:213], v[36:39]
	v_mfma_f32_16x16x32_bf16 v[36:39], v[218:221], v[206:209], v[60:63]
	v_mfma_f32_16x16x32_bf16 v[194:197], v[222:225], v[210:213], v[36:39]
	s_barrier
	s_nop 4
	ds_read_b128 v[36:39], v19 offset:16384
	ds_read_b128 v[40:43], v19 offset:17408
	ds_read_b128 v[58:61], v18 offset:18432
	ds_read_b128 v[198:201], v18 offset:19456
	ds_read_b128 v[202:205], v18 offset:20480
	ds_read_b128 v[206:209], v18 offset:21504
	ds_read_b128 v[210:213], v18 offset:22528
	ds_read_b128 v[226:229], v18 offset:23552
	s_waitcnt vmcnt(4)
	s_barrier
; #define LDA(dst,b,h) for(int m=0;m<4;++m)for(int k=0;k<2;++k) \
;     dst[m][k]=*reinterpret_cast<const bf16x8*>((char*)SA(b,h)+lds_byte(wr*64+m*16+fr,k*32+fq*8))
; #define LDB(dst,b,h) for(int n=0;n<2;++n)for(int k=0;k<2;++k) \
;     dst[n][k]=*reinterpret_cast<const bf16x8*>((char*)SB(b,h)+lds_byte(wc*32+n*16+fr,k*32+fq*8))
; #define MMA(ai,bj,At,Bt_) do{__builtin_amdgcn_s_setprio(1); \
;     for(int m=0;m<4;++m)for(int n=0;n<2;++n)for(int k=0;k<2;++k) \
;       acc[ai][bj][m][n]=__builtin_amdgcn_mfma_f32_16x16x32_bf16(Bt_[n][k],At[m][k],acc[ai][bj][m][n],0,0,0); \
;     __builtin_amdgcn_s_setprio(0);}while(0)
; #define WAIT_V(n) asm volatile("s_waitcnt vmcnt(" #n ")":::"memory")
; #define WAIT_L(n) asm volatile("s_waitcnt lgkmcnt(" #n ")":::"memory")
; #define BAR __builtin_amdgcn_s_barrier()
; template <int EPI>
; __device__ __forceinline__ void gemm_run(const GD& c, const bool has_next, const GD& nx, const Ctx& e, bf16* shm, float* rs, float* rs_nxt, float* racc_) {
;     ...
;     LDA(At,0,1); WAIT_V(4); BAR; WAIT_L(0); MMA(1,0,At,B0); MMA(1,1,At,B1); BAR; }
;   { LDB(B0,1,0); LDA(At,1,0); WAIT_V(2); BAR; WAIT_L(0); MMA(0,0,At,B0); BAR;
	s_waitcnt lgkmcnt(0)
	v_mfma_f32_16x16x32_bf16 v[20:23], v[130:133], v[210:213], v[20:23]
	v_mfma_f32_16x16x32_bf16 v[6:9], v[130:133], v[36:39], v[8:11]
	v_mfma_f32_16x16x32_bf16 v[166:169], v[130:133], v[58:61], v[166:169]
	v_mfma_f32_16x16x32_bf16 v[186:189], v[130:133], v[202:205], v[186:189]
	v_mfma_f32_16x16x32_bf16 v[130:133], v[134:137], v[226:229], v[20:23]
	v_mfma_f32_16x16x32_bf16 v[20:23], v[140:143], v[210:213], v[24:27]
	v_mfma_f32_16x16x32_bf16 v[6:9], v[134:137], v[40:43], v[6:9]
	v_mfma_f32_16x16x32_bf16 v[160:163], v[140:143], v[36:39], v[160:163]
	v_mfma_f32_16x16x32_bf16 v[166:169], v[134:137], v[198:201], v[166:169]
	v_mfma_f32_16x16x32_bf16 v[172:175], v[140:143], v[58:61], v[172:175]
	v_mfma_f32_16x16x32_bf16 v[186:189], v[134:137], v[206:209], v[186:189]
	v_mfma_f32_16x16x32_bf16 v[190:193], v[140:143], v[202:205], v[190:193]
	v_mfma_f32_16x16x32_bf16 v[134:137], v[144:147], v[226:229], v[20:23]
	v_mfma_f32_16x16x32_bf16 v[160:163], v[144:147], v[40:43], v[160:163]
	v_mfma_f32_16x16x32_bf16 v[172:175], v[144:147], v[198:201], v[172:175]
	v_mfma_f32_16x16x32_bf16 v[190:193], v[144:147], v[206:209], v[190:193]
	v_mfma_f32_16x16x32_bf16 v[2:5], v[106:109], v[36:39], v[2:5]
	v_mfma_f32_16x16x32_bf16 v[140:143], v[214:217], v[40:43], v[2:5]
	v_mfma_f32_16x16x32_bf16 v[2:5], v[218:221], v[36:39], v[28:31]
	v_mfma_f32_16x16x32_bf16 v[144:147], v[222:225], v[40:43], v[2:5]
	v_mfma_f32_16x16x32_bf16 v[2:5], v[106:109], v[58:61], v[32:35]
	v_mfma_f32_16x16x32_bf16 v[230:233], v[214:217], v[198:201], v[2:5]
	v_mfma_f32_16x16x32_bf16 v[2:5], v[218:221], v[58:61], v[64:67]
	v_mfma_f32_16x16x32_bf16 v[198:201], v[222:225], v[198:201], v[2:5]
	v_mfma_f32_16x16x32_bf16 v[2:5], v[106:109], v[202:205], v[118:121]
	v_mfma_f32_16x16x32_bf16 v[234:237], v[214:217], v[206:209], v[2:5]
	v_mfma_f32_16x16x32_bf16 v[2:5], v[218:221], v[202:205], v[122:125]
	v_mfma_f32_16x16x32_bf16 v[202:205], v[222:225], v[206:209], v[2:5]
	v_mfma_f32_16x16x32_bf16 v[2:5], v[106:109], v[210:213], v[110:113]
	v_mfma_f32_16x16x32_bf16 v[206:209], v[214:217], v[226:229], v[2:5]
	v_mfma_f32_16x16x32_bf16 v[2:5], v[218:221], v[210:213], v[114:117]
	v_mfma_f32_16x16x32_bf16 v[210:213], v[222:225], v[226:229], v[2:5]
	s_barrier
	s_nop 4
	ds_read_b128 v[2:5], v182
	ds_read_b128 v[214:217], v182 offset:1024
	ds_read_b128 v[218:221], v182 offset:2048
	ds_read_b128 v[222:225], v182 offset:3072
	ds_read_b128 v[20:23], v19 offset:32768
	ds_read_b128 v[24:27], v19 offset:33792
	ds_read_b128 v[62:65], v18 offset:34816
	ds_read_b128 v[106:109], v18 offset:35840
	ds_read_b128 v[122:125], v18 offset:36864
	ds_read_b128 v[226:229], v18 offset:37888
	ds_read_b128 v[238:241], v18 offset:38912
	ds_read_b128 v[242:245], v18 offset:39936
	s_waitcnt vmcnt(2)
	s_barrier
	s_waitcnt lgkmcnt(0)
	v_mfma_f32_16x16x32_bf16 v[10:13], v[2:5], v[20:23], v[12:15]
	v_mfma_f32_16x16x32_bf16 v[42:45], v[214:217], v[24:27], v[10:13]
	v_mfma_f32_16x16x32_bf16 v[10:13], v[218:221], v[20:23], v[68:71]
	v_mfma_f32_16x16x32_bf16 v[58:61], v[222:225], v[24:27], v[10:13]
	v_mfma_f32_16x16x32_bf16 v[10:13], v[2:5], v[62:65], v[72:75]
	v_mfma_f32_16x16x32_bf16 v[38:41], v[214:217], v[106:109], v[10:13]
	v_mfma_f32_16x16x32_bf16 v[10:13], v[218:221], v[62:65], v[76:79]
	v_mfma_f32_16x16x32_bf16 v[66:69], v[222:225], v[106:109], v[10:13]
	v_mfma_f32_16x16x32_bf16 v[10:13], v[2:5], v[122:125], v[80:83]
	v_mfma_f32_16x16x32_bf16 v[34:37], v[214:217], v[226:229], v[10:13]
	v_mfma_f32_16x16x32_bf16 v[10:13], v[218:221], v[122:125], v[84:87]
	v_mfma_f32_16x16x32_bf16 v[70:73], v[222:225], v[226:229], v[10:13]
	v_mfma_f32_16x16x32_bf16 v[10:13], v[2:5], v[238:241], v[98:101]
	v_mfma_f32_16x16x32_bf16 v[30:33], v[214:217], v[242:245], v[10:13]
	v_mfma_f32_16x16x32_bf16 v[10:13], v[218:221], v[238:241], v[102:105]
	v_mfma_f32_16x16x32_bf16 v[78:81], v[222:225], v[242:245], v[10:13]
	s_barrier
; #define LDA(dst,b,h) for(int m=0;m<4;++m)for(int k=0;k<2;++k) \
;     dst[m][k]=*reinterpret_cast<const bf16x8*>((char*)SA(b,h)+lds_byte(wr*64+m*16+fr,k*32+fq*8))
; #define LDB(dst,b,h) for(int n=0;n<2;++n)for(int k=0;k<2;++k) \
;     dst[n][k]=*reinterpret_cast<const bf16x8*>((char*)SB(b,h)+lds_byte(wc*32+n*16+fr,k*32+fq*8))
; #define MMA(ai,bj,At,Bt_) do{__builtin_amdgcn_s_setprio(1); \
;     for(int m=0;m<4;++m)for(int n=0;n<2;++n)for(int k=0;k<2;++k) \
;       acc[ai][bj][m][n]=__builtin_amdgcn_mfma_f32_16x16x32_bf16(Bt_[n][k],At[m][k],acc[ai][bj][m][n],0,0,0); \
;     __builtin_amdgcn_s_setprio(0);}while(0)
; #define WAIT_V(n) asm volatile("s_waitcnt vmcnt(" #n ")":::"memory")
; #define WAIT_L(n) asm volatile("s_waitcnt lgkmcnt(" #n ")":::"memory")
; #define BAR __builtin_amdgcn_s_barrier()
; template <int EPI>
; __device__ __forceinline__ void gemm_run(const GD& c, const bool has_next, const GD& nx, const Ctx& e, bf16* shm, float* rs, float* rs_nxt, float* racc_) {
;     ...
;     LDB(B1,1,1); WAIT_V(0); BAR; WAIT_L(0); MMA(0,1,At,B1); BAR;
;     LDA(At,1,1); BAR; WAIT_L(0); MMA(1,0,At,B0); MMA(1,1,At,B1); BAR; }
;   if(wr==0)BAR;
	s_nop 4
	ds_read_b128 v[10:13], v183
	ds_read_b128 v[14:17], v183 offset:1024
	ds_read_b128 v[246:249], v183 offset:2048
	ds_read_b128 v[250:253], v183 offset:3072
	s_waitcnt vmcnt(0)
	s_barrier
	s_waitcnt lgkmcnt(0)
	v_mfma_f32_16x16x32_bf16 v[74:77], v[10:13], v[20:23], v[126:129]
	v_mfma_f32_16x16x32_bf16 v[20:23], v[246:249], v[20:23], v[148:151]
	v_mfma_f32_16x16x32_bf16 v[82:85], v[250:253], v[24:27], v[20:23]
	v_mfma_f32_16x16x32_bf16 v[20:23], v[10:13], v[62:65], v[152:155]
	v_mfma_f32_16x16x32_bf16 v[114:117], v[14:17], v[106:109], v[20:23]
	v_mfma_f32_16x16x32_bf16 v[20:23], v[246:249], v[62:65], v[156:159]
	v_mfma_f32_16x16x32_bf16 v[110:113], v[14:17], v[24:27], v[74:77]
	v_mfma_f32_16x16x32_bf16 v[74:77], v[250:253], v[106:109], v[20:23]
	v_mfma_f32_16x16x32_bf16 v[20:23], v[10:13], v[122:125], v[46:49]
	v_mfma_f32_16x16x32_bf16 v[118:121], v[14:17], v[226:229], v[20:23]
	v_mfma_f32_16x16x32_bf16 v[20:23], v[246:249], v[122:125], v[50:53]
	v_mfma_f32_16x16x32_bf16 v[62:65], v[250:253], v[226:229], v[20:23]
	v_mfma_f32_16x16x32_bf16 v[20:23], v[10:13], v[238:241], v[54:57]
	v_mfma_f32_16x16x32_bf16 v[122:125], v[14:17], v[242:245], v[20:23]
	v_mfma_f32_16x16x32_bf16 v[20:23], v[246:249], v[238:241], v[194:197]
	v_mfma_f32_16x16x32_bf16 v[54:57], v[250:253], v[242:245], v[20:23]
	s_barrier
	ds_read_b128 v[46:49], v19 offset:49152
	ds_read_b128 v[50:53], v19 offset:50176
	ds_read_b128 v[148:151], v18 offset:51200
	ds_read_b128 v[152:155], v18 offset:52224
	ds_read_b128 v[156:159], v18 offset:53248
	ds_read_b128 v[194:197], v18 offset:54272
	ds_read_b128 v[226:229], v18 offset:55296
	ds_read_b128 v[238:241], v18 offset:56320
	s_barrier
	s_waitcnt lgkmcnt(0)
	v_mfma_f32_16x16x32_bf16 v[6:9], v[2:5], v[46:49], v[6:9]
	v_mfma_f32_16x16x32_bf16 v[26:29], v[214:217], v[50:53], v[6:9]
	v_mfma_f32_16x16x32_bf16 v[6:9], v[218:221], v[46:49], v[160:163]
	v_mfma_f32_16x16x32_bf16 v[98:101], v[222:225], v[50:53], v[6:9]
	v_mfma_f32_16x16x32_bf16 v[6:9], v[2:5], v[148:151], v[166:169]
	v_mfma_f32_16x16x32_bf16 v[22:25], v[214:217], v[152:155], v[6:9]
	v_mfma_f32_16x16x32_bf16 v[6:9], v[218:221], v[148:151], v[172:175]
	v_mfma_f32_16x16x32_bf16 v[102:105], v[222:225], v[152:155], v[6:9]
	v_mfma_f32_16x16x32_bf16 v[6:9], v[2:5], v[156:159], v[186:189]
	v_mfma_f32_16x16x32_bf16 v[18:21], v[214:217], v[194:197], v[6:9]
	v_mfma_f32_16x16x32_bf16 v[6:9], v[218:221], v[156:159], v[190:193]
	v_mfma_f32_16x16x32_bf16 v[106:109], v[222:225], v[194:197], v[6:9]
	v_mfma_f32_16x16x32_bf16 v[2:5], v[2:5], v[226:229], v[130:133]
	v_mfma_f32_16x16x32_bf16 v[6:9], v[218:221], v[226:229], v[134:137]
	v_mfma_f32_16x16x32_bf16 v[2:5], v[214:217], v[238:241], v[2:5]
	v_mfma_f32_16x16x32_bf16 v[6:9], v[222:225], v[238:241], v[6:9]
	v_mfma_f32_16x16x32_bf16 v[86:89], v[10:13], v[46:49], v[140:143]
	v_mfma_f32_16x16x32_bf16 v[46:49], v[246:249], v[46:49], v[144:147]
	v_mfma_f32_16x16x32_bf16 v[126:129], v[14:17], v[50:53], v[86:89]
	v_mfma_f32_16x16x32_bf16 v[86:89], v[250:253], v[50:53], v[46:49]
	v_mfma_f32_16x16x32_bf16 v[46:49], v[10:13], v[148:151], v[230:233]
	v_mfma_f32_16x16x32_bf16 v[130:133], v[14:17], v[152:155], v[46:49]
	v_mfma_f32_16x16x32_bf16 v[46:49], v[246:249], v[148:151], v[198:201]
	v_mfma_f32_16x16x32_bf16 v[50:53], v[250:253], v[152:155], v[46:49]
	v_mfma_f32_16x16x32_bf16 v[46:49], v[10:13], v[156:159], v[234:237]
	v_mfma_f32_16x16x32_bf16 v[10:13], v[10:13], v[226:229], v[206:209]
	v_mfma_f32_16x16x32_bf16 v[134:137], v[14:17], v[194:197], v[46:49]
	v_mfma_f32_16x16x32_bf16 v[46:49], v[246:249], v[156:159], v[202:205]
	v_mfma_f32_16x16x32_bf16 v[10:13], v[14:17], v[238:241], v[10:13]
	v_mfma_f32_16x16x32_bf16 v[14:17], v[246:249], v[226:229], v[210:213]
	v_mfma_f32_16x16x32_bf16 v[46:49], v[250:253], v[194:197], v[46:49]
	v_mfma_f32_16x16x32_bf16 v[14:17], v[250:253], v[238:241], v[14:17]
	v_cmp_gt_u32_e32 vcc, s96, v92
	s_barrier
	s_and_saveexec_b64 s[2:3], vcc
	s_cbranch_execz .LBB0_747
	s_barrier

; #define STAGE_A(P,br,kt) STAGE_G(P,c.A,c.lda,br,(long)(kt)*c.kstr)
; #define STAGE_B(P,br,kt) STAGE_G(P,c.Bt,c.K,br,(long)(kt)*BK)
; #define LDA(dst,b,h) for(int m=0;m<4;++m)for(int k=0;k<2;++k) \
;     dst[m][k]=*reinterpret_cast<const bf16x8*>((char*)SA(b,h)+lds_byte(wr*64+m*16+fr,k*32+fq*8))
; #define LDB(dst,b,h) for(int n=0;n<2;++n)for(int k=0;k<2;++k) \
;     dst[n][k]=*reinterpret_cast<const bf16x8*>((char*)SB(b,h)+lds_byte(wc*32+n*16+fr,k*32+fq*8))
; #define MMA(ai,bj,At,Bt_) do{__builtin_amdgcn_s_setprio(1); \
;     for(int m=0;m<4;++m)for(int n=0;n<2;++n)for(int k=0;k<2;++k) \
;       acc[ai][bj][m][n]=__builtin_amdgcn_mfma_f32_16x16x32_bf16(Bt_[n][k],At[m][k],acc[ai][bj][m][n],0,0,0); \
;     __builtin_amdgcn_s_setprio(0);}while(0)
; #define WAIT_L(n) asm volatile("s_waitcnt lgkmcnt(" #n ")":::"memory")
; #define BAR __builtin_amdgcn_s_barrier()
; #define SCHED __builtin_amdgcn_sched_barrier(0)
; template <int EPI>
; __device__ __forceinline__ void gemm_run(const GD& c, const bool has_next, const GD& nx, const Ctx& e, bf16* shm, float* rs, float* rs_nxt, float* racc_) {
;     ...
;     LDB(B0,0,0); SCHED; LDA(At,0,0); STAGE_A(SA(1,1),brow+HALF,t+1);
;     WAIT_L(8); BAR; WAIT_L(0); MMA(0,0,At,B0); BAR; SCHED;
;     LDB(B1,0,1); STAGE_B(SB(0,0),bcol,t+2);
;     BAR; WAIT_L(0); MMA(0,1,At,B1); BAR;
;     LDA(At,0,1); STAGE_A(SA(0,0),brow,t+2);
;     BAR; WAIT_L(0); MMA(1,0,At,B0); BAR; SCHED;
.LBB0_972:
	ds_read_b128 v[172:175], v159
	ds_read_b128 v[186:189], v159 offset:1024
	ds_read_b128 v[190:193], v159 offset:2048
	ds_read_b128 v[194:197], v159 offset:3072
	v_add_u32_e32 v169, 0xc000, v146
	v_lshl_add_u64 v[246:247], s[6:7], 0, v[136:137]
	v_readfirstlane_b32 s19, v169
	v_add_u32_e32 v170, 0xe000, v146
	v_lshl_add_u64 v[160:161], v[246:247], 0, s[22:23]
	s_mov_b32 m0, s19
	v_lshl_add_u64 v[248:249], s[6:7], 0, v[138:139]
	v_readfirstlane_b32 s19, v170
	ds_read_b128 v[198:201], v150
	ds_read_b128 v[202:205], v150 offset:1024
	ds_read_b128 v[206:209], v149
	ds_read_b128 v[210:213], v149 offset:1024
	ds_read_b128 v[214:217], v148
	ds_read_b128 v[218:221], v148 offset:1024
	ds_read_b128 v[222:225], v147
	ds_read_b128 v[226:229], v147 offset:1024
	global_load_lds_dwordx4 v[160:161], off
	v_lshl_add_u64 v[160:161], v[248:249], 0, s[22:23]
	s_mov_b32 m0, s19
	s_nop 0
	global_load_lds_dwordx4 v[160:161], off
	s_waitcnt lgkmcnt(8)
	s_barrier
	s_waitcnt lgkmcnt(0)
	v_mfma_f32_16x16x32_bf16 v[126:129], v[172:175], v[198:201], v[126:129]
	v_mfma_f32_16x16x32_bf16 v[122:125], v[190:193], v[198:201], v[122:125]
	v_mfma_f32_16x16x32_bf16 v[118:121], v[172:175], v[206:209], v[118:121]
	v_mfma_f32_16x16x32_bf16 v[114:117], v[190:193], v[206:209], v[114:117]
	v_mfma_f32_16x16x32_bf16 v[110:113], v[172:175], v[214:217], v[110:113]
	v_mfma_f32_16x16x32_bf16 v[106:109], v[190:193], v[214:217], v[106:109]
	v_mfma_f32_16x16x32_bf16 v[102:105], v[172:175], v[222:225], v[102:105]
	v_mfma_f32_16x16x32_bf16 v[98:101], v[190:193], v[222:225], v[98:101]
	v_mfma_f32_16x16x32_bf16 v[126:129], v[186:189], v[202:205], v[126:129]
	v_mfma_f32_16x16x32_bf16 v[122:125], v[194:197], v[202:205], v[122:125]
	v_mfma_f32_16x16x32_bf16 v[118:121], v[186:189], v[210:213], v[118:121]
	v_mfma_f32_16x16x32_bf16 v[114:117], v[194:197], v[210:213], v[114:117]
	v_mfma_f32_16x16x32_bf16 v[110:113], v[186:189], v[218:221], v[110:113]
	v_mfma_f32_16x16x32_bf16 v[106:109], v[194:197], v[218:221], v[106:109]
	v_mfma_f32_16x16x32_bf16 v[102:105], v[186:189], v[226:229], v[102:105]
	v_mfma_f32_16x16x32_bf16 v[98:101], v[194:197], v[226:229], v[98:101]
	s_barrier
	v_add_u32_e32 v160, s33, v151
	v_lshl_add_u64 v[250:251], s[6:7], 0, v[140:141]
	v_readfirstlane_b32 s19, v160
	v_add_u32_e32 v161, 0x2000, v160
	v_lshl_add_u64 v[162:163], v[250:251], 0, s[24:25]
	s_mov_b32 m0, s19
	v_lshl_add_u64 v[252:253], s[6:7], 0, v[142:143]
	v_readfirstlane_b32 s19, v161
	ds_read_b128 v[230:233], v157
	ds_read_b128 v[234:237], v157 offset:1024
	ds_read_b128 v[238:241], v157 offset:2048
	ds_read_b128 v[242:245], v157 offset:3072
	global_load_lds_dwordx4 v[162:163], off
	v_lshl_add_u64 v[162:163], v[252:253], 0, s[24:25]
	s_mov_b32 m0, s19
	s_nop 0
	global_load_lds_dwordx4 v[162:163], off
	s_barrier
	s_waitcnt lgkmcnt(0)
	v_mfma_f32_16x16x32_bf16 v[94:97], v[230:233], v[198:201], v[94:97]
	v_mfma_f32_16x16x32_bf16 v[90:93], v[238:241], v[198:201], v[90:93]
	v_mfma_f32_16x16x32_bf16 v[86:89], v[230:233], v[206:209], v[86:89]
	v_mfma_f32_16x16x32_bf16 v[82:85], v[238:241], v[206:209], v[82:85]
	v_mfma_f32_16x16x32_bf16 v[78:81], v[230:233], v[214:217], v[78:81]
	v_mfma_f32_16x16x32_bf16 v[74:77], v[238:241], v[214:217], v[74:77]
	v_mfma_f32_16x16x32_bf16 v[70:73], v[230:233], v[222:225], v[70:73]
	v_mfma_f32_16x16x32_bf16 v[66:69], v[238:241], v[222:225], v[66:69]
	v_mfma_f32_16x16x32_bf16 v[94:97], v[234:237], v[202:205], v[94:97]
	v_mfma_f32_16x16x32_bf16 v[90:93], v[242:245], v[202:205], v[90:93]
	v_mfma_f32_16x16x32_bf16 v[86:89], v[234:237], v[210:213], v[86:89]
	v_mfma_f32_16x16x32_bf16 v[82:85], v[242:245], v[210:213], v[82:85]
	v_mfma_f32_16x16x32_bf16 v[78:81], v[234:237], v[218:221], v[78:81]
	v_mfma_f32_16x16x32_bf16 v[74:77], v[242:245], v[218:221], v[74:77]
	v_mfma_f32_16x16x32_bf16 v[70:73], v[234:237], v[226:229], v[70:73]
	v_mfma_f32_16x16x32_bf16 v[66:69], v[242:245], v[226:229], v[66:69]
	s_barrier
	v_readfirstlane_b32 s19, v146
	v_lshl_add_u64 v[162:163], v[246:247], 0, s[20:21]
	s_mov_b32 m0, s19
	ds_read_b128 v[198:201], v150 offset:16384
	ds_read_b128 v[202:205], v150 offset:17408
	ds_read_b128 v[206:209], v149 offset:16384
	ds_read_b128 v[210:213], v149 offset:17408
	ds_read_b128 v[214:217], v148 offset:16384
	ds_read_b128 v[218:221], v148 offset:17408
	ds_read_b128 v[222:225], v147 offset:16384
	ds_read_b128 v[226:229], v147 offset:17408
	global_load_lds_dwordx4 v[162:163], off
	v_add_u32_e32 v162, 0x2000, v146
	v_lshl_add_u64 v[166:167], v[248:249], 0, s[20:21]
	v_readfirstlane_b32 s19, v162
	s_mov_b32 m0, s19
	s_nop 0
	global_load_lds_dwordx4 v[166:167], off
	s_barrier
	s_waitcnt lgkmcnt(0)
	v_mfma_f32_16x16x32_bf16 v[62:65], v[172:175], v[198:201], v[62:65]
	v_mfma_f32_16x16x32_bf16 v[58:61], v[190:193], v[198:201], v[58:61]
	v_mfma_f32_16x16x32_bf16 v[54:57], v[172:175], v[206:209], v[54:57]
	v_mfma_f32_16x16x32_bf16 v[50:53], v[190:193], v[206:209], v[50:53]
	v_mfma_f32_16x16x32_bf16 v[46:49], v[172:175], v[214:217], v[46:49]
	v_mfma_f32_16x16x32_bf16 v[42:45], v[190:193], v[214:217], v[42:45]
	v_mfma_f32_16x16x32_bf16 v[38:41], v[172:175], v[222:225], v[38:41]
	v_mfma_f32_16x16x32_bf16 v[34:37], v[190:193], v[222:225], v[34:37]
	v_mfma_f32_16x16x32_bf16 v[62:65], v[186:189], v[202:205], v[62:65]
	v_mfma_f32_16x16x32_bf16 v[58:61], v[194:197], v[202:205], v[58:61]
	v_mfma_f32_16x16x32_bf16 v[54:57], v[186:189], v[210:213], v[54:57]
	v_mfma_f32_16x16x32_bf16 v[50:53], v[194:197], v[210:213], v[50:53]
	v_mfma_f32_16x16x32_bf16 v[46:49], v[186:189], v[218:221], v[46:49]
	v_mfma_f32_16x16x32_bf16 v[42:45], v[194:197], v[218:221], v[42:45]
	v_mfma_f32_16x16x32_bf16 v[38:41], v[186:189], v[226:229], v[38:41]
	v_mfma_f32_16x16x32_bf16 v[34:37], v[194:197], v[226:229], v[34:37]
	s_barrier
; #define STAGE_A(P,br,kt) STAGE_G(P,c.A,c.lda,br,(long)(kt)*c.kstr)
; #define STAGE_B(P,br,kt) STAGE_G(P,c.Bt,c.K,br,(long)(kt)*BK)
; #define LDA(dst,b,h) for(int m=0;m<4;++m)for(int k=0;k<2;++k) \
;     dst[m][k]=*reinterpret_cast<const bf16x8*>((char*)SA(b,h)+lds_byte(wr*64+m*16+fr,k*32+fq*8))
; #define LDB(dst,b,h) for(int n=0;n<2;++n)for(int k=0;k<2;++k) \
;     dst[n][k]=*reinterpret_cast<const bf16x8*>((char*)SB(b,h)+lds_byte(wc*32+n*16+fr,k*32+fq*8))
; #define MMA(ai,bj,At,Bt_) do{__builtin_amdgcn_s_setprio(1); \
;     for(int m=0;m<4;++m)for(int n=0;n<2;++n)for(int k=0;k<2;++k) \
;       acc[ai][bj][m][n]=__builtin_amdgcn_mfma_f32_16x16x32_bf16(Bt_[n][k],At[m][k],acc[ai][bj][m][n],0,0,0); \
;     __builtin_amdgcn_s_setprio(0);}while(0)
; #define WAIT_V(n) asm volatile("s_waitcnt vmcnt(" #n ")":::"memory")
; #define WAIT_L(n) asm volatile("s_waitcnt lgkmcnt(" #n ")":::"memory")
; #define BAR __builtin_amdgcn_s_barrier()
; #define SCHED __builtin_amdgcn_sched_barrier(0)
; template <int EPI>
; __device__ __forceinline__ void gemm_run(const GD& c, const bool has_next, const GD& nx, const Ctx& e, bf16* shm, float* rs, float* rs_nxt, float* racc_) {
;     ...
;     STAGE_B(SB(0,1),bcol+HALF,t+2);
;     WAIT_V(6); BAR; MMA(1,1,At,B1); BAR;
;     LDB(B0,1,0); SCHED; LDA(At,1,0); STAGE_A(SA(0,1),brow+HALF,t+2);
;     WAIT_L(8); BAR; WAIT_L(0); MMA(0,0,At,B0); BAR; SCHED;
;     LDB(B1,1,1); STAGE_B(SB(1,0),bcol,t+3);
;     BAR; WAIT_L(0); MMA(0,1,At,B1); BAR;
;     LDA(At,1,1); STAGE_A(SA(1,0),brow,t+3);
	v_add_u32_e32 v163, s86, v151
	v_lshl_add_u64 v[166:167], v[250:251], 0, s[26:27]
	v_readfirstlane_b32 s19, v163
	s_mov_b32 m0, s19
	v_lshl_add_u64 v[172:173], v[252:253], 0, s[26:27]
	global_load_lds_dwordx4 v[166:167], off
	v_add_u32_e32 v166, 0x2000, v163
	s_nop 0
	v_readfirstlane_b32 s19, v166
	s_mov_b32 m0, s19
	s_nop 0
	global_load_lds_dwordx4 v[172:173], off
	s_waitcnt vmcnt(6)
	s_barrier
	v_mfma_f32_16x16x32_bf16 v[30:33], v[230:233], v[198:201], v[30:33]
	v_mfma_f32_16x16x32_bf16 v[26:29], v[238:241], v[198:201], v[26:29]
	v_mfma_f32_16x16x32_bf16 v[22:25], v[230:233], v[206:209], v[22:25]
	v_mfma_f32_16x16x32_bf16 v[18:21], v[238:241], v[206:209], v[18:21]
	v_mfma_f32_16x16x32_bf16 v[14:17], v[230:233], v[214:217], v[14:17]
	v_mfma_f32_16x16x32_bf16 v[10:13], v[238:241], v[214:217], v[10:13]
	v_mfma_f32_16x16x32_bf16 v[6:9], v[230:233], v[222:225], v[6:9]
	v_mfma_f32_16x16x32_bf16 v[2:5], v[238:241], v[222:225], v[2:5]
	v_mfma_f32_16x16x32_bf16 v[30:33], v[234:237], v[202:205], v[30:33]
	v_mfma_f32_16x16x32_bf16 v[26:29], v[242:245], v[202:205], v[26:29]
	v_mfma_f32_16x16x32_bf16 v[22:25], v[234:237], v[210:213], v[22:25]
	v_mfma_f32_16x16x32_bf16 v[18:21], v[242:245], v[210:213], v[18:21]
	v_mfma_f32_16x16x32_bf16 v[14:17], v[234:237], v[218:221], v[14:17]
	v_mfma_f32_16x16x32_bf16 v[10:13], v[242:245], v[218:221], v[10:13]
	v_mfma_f32_16x16x32_bf16 v[6:9], v[234:237], v[226:229], v[6:9]
	v_mfma_f32_16x16x32_bf16 v[2:5], v[242:245], v[226:229], v[2:5]
	s_barrier
	ds_read_b128 v[172:175], v154
	ds_read_b128 v[186:189], v154 offset:1024
	ds_read_b128 v[190:193], v154 offset:2048
	ds_read_b128 v[194:197], v154 offset:3072
	v_add_u32_e32 v167, 0x4000, v146
	v_add_u32_e32 v168, 0x6000, v146
	v_readfirstlane_b32 s19, v167
	v_lshl_add_u64 v[230:231], v[246:247], 0, s[28:29]
	s_mov_b32 m0, s19
	v_readfirstlane_b32 s19, v168
	ds_read_b128 v[198:201], v150 offset:32768
	ds_read_b128 v[202:205], v150 offset:33792
	ds_read_b128 v[206:209], v149 offset:32768
	ds_read_b128 v[210:213], v149 offset:33792
	ds_read_b128 v[214:217], v148 offset:32768
	ds_read_b128 v[218:221], v148 offset:33792
	ds_read_b128 v[222:225], v147 offset:32768
	ds_read_b128 v[226:229], v147 offset:33792
	global_load_lds_dwordx4 v[230:231], off
	v_lshl_add_u64 v[230:231], v[248:249], 0, s[28:29]
	s_mov_b32 m0, s19
	s_nop 0
	global_load_lds_dwordx4 v[230:231], off
	s_waitcnt lgkmcnt(8)
	s_barrier
	s_waitcnt lgkmcnt(0)
	v_mfma_f32_16x16x32_bf16 v[126:129], v[172:175], v[198:201], v[126:129]
	v_mfma_f32_16x16x32_bf16 v[122:125], v[190:193], v[198:201], v[122:125]
	v_mfma_f32_16x16x32_bf16 v[118:121], v[172:175], v[206:209], v[118:121]
	v_mfma_f32_16x16x32_bf16 v[114:117], v[190:193], v[206:209], v[114:117]
	v_mfma_f32_16x16x32_bf16 v[110:113], v[172:175], v[214:217], v[110:113]
	v_mfma_f32_16x16x32_bf16 v[106:109], v[190:193], v[214:217], v[106:109]
	v_mfma_f32_16x16x32_bf16 v[102:105], v[172:175], v[222:225], v[102:105]
	v_mfma_f32_16x16x32_bf16 v[98:101], v[190:193], v[222:225], v[98:101]
	v_mfma_f32_16x16x32_bf16 v[126:129], v[186:189], v[202:205], v[126:129]
	v_mfma_f32_16x16x32_bf16 v[122:125], v[194:197], v[202:205], v[122:125]
	v_mfma_f32_16x16x32_bf16 v[118:121], v[186:189], v[210:213], v[118:121]
	v_mfma_f32_16x16x32_bf16 v[114:117], v[194:197], v[210:213], v[114:117]
	v_mfma_f32_16x16x32_bf16 v[110:113], v[186:189], v[218:221], v[110:113]
	v_mfma_f32_16x16x32_bf16 v[106:109], v[194:197], v[218:221], v[106:109]
	v_mfma_f32_16x16x32_bf16 v[102:105], v[186:189], v[226:229], v[102:105]
	v_mfma_f32_16x16x32_bf16 v[98:101], v[194:197], v[226:229], v[98:101]
	s_barrier
	v_readfirstlane_b32 s19, v153
	v_add_u32_e32 v171, 0x2000, v153
	v_lshl_add_u64 v[182:183], v[250:251], 0, s[42:43]
	s_mov_b32 m0, s19
	v_readfirstlane_b32 s19, v171
	ds_read_b128 v[230:233], v152
	ds_read_b128 v[234:237], v152 offset:1024
	ds_read_b128 v[238:241], v152 offset:2048
	ds_read_b128 v[242:245], v152 offset:3072
	global_load_lds_dwordx4 v[182:183], off
	v_lshl_add_u64 v[182:183], v[252:253], 0, s[42:43]
	s_mov_b32 m0, s19
	s_nop 0
	global_load_lds_dwordx4 v[182:183], off
	s_barrier
	s_waitcnt lgkmcnt(0)
	v_mfma_f32_16x16x32_bf16 v[94:97], v[230:233], v[198:201], v[94:97]
	v_mfma_f32_16x16x32_bf16 v[90:93], v[238:241], v[198:201], v[90:93]
	v_mfma_f32_16x16x32_bf16 v[86:89], v[230:233], v[206:209], v[86:89]
	v_mfma_f32_16x16x32_bf16 v[82:85], v[238:241], v[206:209], v[82:85]
	v_mfma_f32_16x16x32_bf16 v[78:81], v[230:233], v[214:217], v[78:81]
	v_mfma_f32_16x16x32_bf16 v[74:77], v[238:241], v[214:217], v[74:77]
	v_mfma_f32_16x16x32_bf16 v[70:73], v[230:233], v[222:225], v[70:73]
	v_mfma_f32_16x16x32_bf16 v[66:69], v[238:241], v[222:225], v[66:69]
	v_mfma_f32_16x16x32_bf16 v[94:97], v[234:237], v[202:205], v[94:97]
	v_mfma_f32_16x16x32_bf16 v[90:93], v[242:245], v[202:205], v[90:93]
	v_mfma_f32_16x16x32_bf16 v[86:89], v[234:237], v[210:213], v[86:89]
	v_mfma_f32_16x16x32_bf16 v[82:85], v[242:245], v[210:213], v[82:85]
	v_mfma_f32_16x16x32_bf16 v[78:81], v[234:237], v[218:221], v[78:81]
	v_mfma_f32_16x16x32_bf16 v[74:77], v[242:245], v[218:221], v[74:77]
	v_mfma_f32_16x16x32_bf16 v[70:73], v[234:237], v[226:229], v[70:73]
	v_mfma_f32_16x16x32_bf16 v[66:69], v[242:245], v[226:229], v[66:69]
	s_barrier
	v_readfirstlane_b32 s19, v155
	v_lshl_add_u64 v[182:183], v[246:247], 0, s[44:45]
	s_mov_b32 m0, s19
	v_readfirstlane_b32 s19, v156
	ds_read_b128 v[198:201], v150 offset:49152
	ds_read_b128 v[202:205], v150 offset:50176
	ds_read_b128 v[206:209], v149 offset:49152
	ds_read_b128 v[210:213], v149 offset:50176
	ds_read_b128 v[214:217], v148 offset:49152
	ds_read_b128 v[218:221], v148 offset:50176
	ds_read_b128 v[222:225], v147 offset:49152
	ds_read_b128 v[226:229], v147 offset:50176
	global_load_lds_dwordx4 v[182:183], off
	v_lshl_add_u64 v[182:183], v[248:249], 0, s[44:45]
	s_mov_b32 m0, s19
	s_nop 0
	global_load_lds_dwordx4 v[182:183], off
	s_barrier
; #define STAGE_A(P,br,kt) STAGE_G(P,c.A,c.lda,br,(long)(kt)*c.kstr)
; #define STAGE_B(P,br,kt) STAGE_G(P,c.Bt,c.K,br,(long)(kt)*BK)
; #define LDA(dst,b,h) for(int m=0;m<4;++m)for(int k=0;k<2;++k) \
;     dst[m][k]=*reinterpret_cast<const bf16x8*>((char*)SA(b,h)+lds_byte(wr*64+m*16+fr,k*32+fq*8))
; #define LDB(dst,b,h) for(int n=0;n<2;++n)for(int k=0;k<2;++k) \
;     dst[n][k]=*reinterpret_cast<const bf16x8*>((char*)SB(b,h)+lds_byte(wc*32+n*16+fr,k*32+fq*8))
; #define MMA(ai,bj,At,Bt_) do{__builtin_amdgcn_s_setprio(1); \
;     for(int m=0;m<4;++m)for(int n=0;n<2;++n)for(int k=0;k<2;++k) \
;       acc[ai][bj][m][n]=__builtin_amdgcn_mfma_f32_16x16x32_bf16(Bt_[n][k],At[m][k],acc[ai][bj][m][n],0,0,0); \
;     __builtin_amdgcn_s_setprio(0);}while(0)
; #define WAIT_V(n) asm volatile("s_waitcnt vmcnt(" #n ")":::"memory")
; #define WAIT_L(n) asm volatile("s_waitcnt lgkmcnt(" #n ")":::"memory")
; #define BAR __builtin_amdgcn_s_barrier()
; #define SCHED __builtin_amdgcn_sched_barrier(0)
; template <int EPI>
; __device__ __forceinline__ void gemm_run(const GD& c, const bool has_next, const GD& nx, const Ctx& e, bf16* shm, float* rs, float* rs_nxt, float* racc_) {
;     ...
;     BAR; WAIT_L(0); MMA(1,0,At,B0); BAR; SCHED;
;     STAGE_B(SB(1,1),bcol+HALF,t+3);
;     WAIT_V(6); BAR; MMA(1,1,At,B1); BAR;
;   }
;   { LDB(B0,0,0); LDA(At,0,0); STAGE_A(SA(1,1),brow+HALF,nt-1);
;     BAR; WAIT_L(0); MMA(0,0,At,B0); BAR;
	s_waitcnt lgkmcnt(0)
	v_mfma_f32_16x16x32_bf16 v[62:65], v[172:175], v[198:201], v[62:65]
	v_mfma_f32_16x16x32_bf16 v[58:61], v[190:193], v[198:201], v[58:61]
	v_mfma_f32_16x16x32_bf16 v[54:57], v[172:175], v[206:209], v[54:57]
	v_mfma_f32_16x16x32_bf16 v[50:53], v[190:193], v[206:209], v[50:53]
	v_mfma_f32_16x16x32_bf16 v[46:49], v[172:175], v[214:217], v[46:49]
	v_mfma_f32_16x16x32_bf16 v[42:45], v[190:193], v[214:217], v[42:45]
	v_mfma_f32_16x16x32_bf16 v[38:41], v[172:175], v[222:225], v[38:41]
	v_mfma_f32_16x16x32_bf16 v[34:37], v[190:193], v[222:225], v[34:37]
	v_mfma_f32_16x16x32_bf16 v[62:65], v[186:189], v[202:205], v[62:65]
	v_mfma_f32_16x16x32_bf16 v[58:61], v[194:197], v[202:205], v[58:61]
	v_mfma_f32_16x16x32_bf16 v[54:57], v[186:189], v[210:213], v[54:57]
	v_mfma_f32_16x16x32_bf16 v[50:53], v[194:197], v[210:213], v[50:53]
	v_mfma_f32_16x16x32_bf16 v[46:49], v[186:189], v[218:221], v[46:49]
	v_mfma_f32_16x16x32_bf16 v[42:45], v[194:197], v[218:221], v[42:45]
	v_mfma_f32_16x16x32_bf16 v[38:41], v[186:189], v[226:229], v[38:41]
	v_mfma_f32_16x16x32_bf16 v[34:37], v[194:197], v[226:229], v[34:37]
	s_barrier
	v_readfirstlane_b32 s19, v158
	v_add_u32_e32 v171, 0x2000, v158
	v_lshl_add_u64 v[172:173], v[250:251], 0, s[46:47]
	s_mov_b32 m0, s19
	v_readfirstlane_b32 s19, v171
	global_load_lds_dwordx4 v[172:173], off
	v_lshl_add_u64 v[172:173], v[252:253], 0, s[46:47]
	s_mov_b32 m0, s19
	s_nop 0
	global_load_lds_dwordx4 v[172:173], off
	s_waitcnt vmcnt(6)
	s_barrier
	v_mfma_f32_16x16x32_bf16 v[30:33], v[230:233], v[198:201], v[30:33]
	v_mfma_f32_16x16x32_bf16 v[26:29], v[238:241], v[198:201], v[26:29]
	v_mfma_f32_16x16x32_bf16 v[22:25], v[230:233], v[206:209], v[22:25]
	v_mfma_f32_16x16x32_bf16 v[18:21], v[238:241], v[206:209], v[18:21]
	s_add_i32 s18, s18, 2
	v_mfma_f32_16x16x32_bf16 v[14:17], v[230:233], v[214:217], v[14:17]
	v_lshl_add_u64 v[136:137], v[136:137], 0, s[20:21]
	v_mfma_f32_16x16x32_bf16 v[10:13], v[238:241], v[214:217], v[10:13]
	v_lshl_add_u64 v[138:139], v[138:139], 0, s[20:21]
	v_mfma_f32_16x16x32_bf16 v[6:9], v[230:233], v[222:225], v[6:9]
	v_lshl_add_u64 v[140:141], v[140:141], 0, s[88:89]
	v_mfma_f32_16x16x32_bf16 v[2:5], v[238:241], v[222:225], v[2:5]
	s_cmp_lt_u32 s18, 4
	v_mfma_f32_16x16x32_bf16 v[30:33], v[234:237], v[202:205], v[30:33]
	v_lshl_add_u64 v[142:143], v[142:143], 0, s[88:89]
	v_mfma_f32_16x16x32_bf16 v[26:29], v[242:245], v[202:205], v[26:29]
	v_mfma_f32_16x16x32_bf16 v[22:25], v[234:237], v[210:213], v[22:25]
	v_mfma_f32_16x16x32_bf16 v[18:21], v[242:245], v[210:213], v[18:21]
	v_mfma_f32_16x16x32_bf16 v[14:17], v[234:237], v[218:221], v[14:17]
	v_mfma_f32_16x16x32_bf16 v[10:13], v[242:245], v[218:221], v[10:13]
	v_mfma_f32_16x16x32_bf16 v[6:9], v[234:237], v[226:229], v[6:9]
	v_mfma_f32_16x16x32_bf16 v[2:5], v[242:245], v[226:229], v[2:5]
	s_barrier
	s_cbranch_scc1 .LBB0_972
	s_or_b32 s26, s12, 0x80
	s_ashr_i32 s27, s26, 31
	s_mul_i32 s18, s26, 0x600
	s_mul_hi_i32 s19, s26, 0x600
	s_add_u32 s18, s6, s18
	s_addc_u32 s19, s7, s19
	v_lshl_add_u64 v[132:133], s[18:19], 0, v[132:133]
	s_mov_b64 s[22:23], 0x540
	v_readfirstlane_b32 s20, v169
	v_lshl_add_u64 v[132:133], v[132:133], 0, s[22:23]
	s_mov_b32 m0, s20
	ds_read_b128 v[136:139], v159
	ds_read_b128 v[140:143], v159 offset:1024
	ds_read_b128 v[172:175], v159 offset:2048
	ds_read_b128 v[186:189], v159 offset:3072
	ds_read_b128 v[190:193], v150
	ds_read_b128 v[194:197], v150 offset:1024
	ds_read_b128 v[198:201], v149
	ds_read_b128 v[202:205], v149 offset:1024
	ds_read_b128 v[206:209], v148
	ds_read_b128 v[210:213], v148 offset:1024
	ds_read_b128 v[214:217], v147
	ds_read_b128 v[218:221], v147 offset:1024
	global_load_lds_dwordx4 v[132:133], off
	v_lshl_add_u64 v[132:133], s[18:19], 0, v[134:135]
	v_readfirstlane_b32 s18, v170
	v_lshl_add_u64 v[132:133], v[132:133], 0, s[22:23]
	s_mov_b32 m0, s18
	s_nop 0
	global_load_lds_dwordx4 v[132:133], off
	s_barrier
	s_waitcnt lgkmcnt(0)
	v_mfma_f32_16x16x32_bf16 v[126:129], v[136:139], v[190:193], v[126:129]
	v_mfma_f32_16x16x32_bf16 v[122:125], v[172:175], v[190:193], v[122:125]
	v_mfma_f32_16x16x32_bf16 v[118:121], v[136:139], v[198:201], v[118:121]
	v_mfma_f32_16x16x32_bf16 v[114:117], v[172:175], v[198:201], v[114:117]
	v_mfma_f32_16x16x32_bf16 v[102:105], v[136:139], v[214:217], v[102:105]
	v_mfma_f32_16x16x32_bf16 v[98:101], v[172:175], v[214:217], v[98:101]
	v_mfma_f32_16x16x32_bf16 v[126:129], v[140:143], v[194:197], v[126:129]
	v_mfma_f32_16x16x32_bf16 v[122:125], v[186:189], v[194:197], v[122:125]
	v_mfma_f32_16x16x32_bf16 v[118:121], v[140:143], v[202:205], v[118:121]
	v_mfma_f32_16x16x32_bf16 v[114:117], v[186:189], v[202:205], v[114:117]
	v_mfma_f32_16x16x32_bf16 v[110:113], v[136:139], v[206:209], v[110:113]
	v_mfma_f32_16x16x32_bf16 v[106:109], v[172:175], v[206:209], v[106:109]
	v_mfma_f32_16x16x32_bf16 v[102:105], v[140:143], v[218:221], v[102:105]
	v_mfma_f32_16x16x32_bf16 v[98:101], v[186:189], v[218:221], v[98:101]
	v_mfma_f32_16x16x32_bf16 v[132:135], v[140:143], v[210:213], v[110:113]
	v_mfma_f32_16x16x32_bf16 v[222:225], v[186:189], v[210:213], v[106:109]
	s_barrier
	s_nop 1
	ds_read_b128 v[106:109], v157
	ds_read_b128 v[110:113], v157 offset:1024
	ds_read_b128 v[226:229], v157 offset:2048
	ds_read_b128 v[156:159], v157 offset:3072
	s_barrier
; #define LDA(dst,b,h) for(int m=0;m<4;++m)for(int k=0;k<2;++k) \
;     dst[m][k]=*reinterpret_cast<const bf16x8*>((char*)SA(b,h)+lds_byte(wr*64+m*16+fr,k*32+fq*8))
; #define LDB(dst,b,h) for(int n=0;n<2;++n)for(int k=0;k<2;++k) \
;     dst[n][k]=*reinterpret_cast<const bf16x8*>((char*)SB(b,h)+lds_byte(wc*32+n*16+fr,k*32+fq*8))
; #define MMA(ai,bj,At,Bt_) do{__builtin_amdgcn_s_setprio(1); \
;     for(int m=0;m<4;++m)for(int n=0;n<2;++n)for(int k=0;k<2;++k) \
;       acc[ai][bj][m][n]=__builtin_amdgcn_mfma_f32_16x16x32_bf16(Bt_[n][k],At[m][k],acc[ai][bj][m][n],0,0,0); \
;     __builtin_amdgcn_s_setprio(0);}while(0)
; #define WAIT_V(n) asm volatile("s_waitcnt vmcnt(" #n ")":::"memory")
; #define WAIT_L(n) asm volatile("s_waitcnt lgkmcnt(" #n ")":::"memory")
; #define BAR __builtin_amdgcn_s_barrier()
; template <int EPI>
; __device__ __forceinline__ void gemm_run(const GD& c, const bool has_next, const GD& nx, const Ctx& e, bf16* shm, float* rs, float* rs_nxt, float* racc_) {
;     ...
;     LDB(B1,0,1); BAR; WAIT_L(0); MMA(0,1,At,B1); BAR;
;     LDA(At,0,1); WAIT_V(4); BAR; WAIT_L(0); MMA(1,0,At,B0); MMA(1,1,At,B1); BAR; }
;   { LDB(B0,1,0); LDA(At,1,0); WAIT_V(2); BAR; WAIT_L(0); MMA(0,0,At,B0); BAR;
	s_waitcnt lgkmcnt(0)
	v_mfma_f32_16x16x32_bf16 v[86:89], v[106:109], v[198:201], v[86:89]
	v_mfma_f32_16x16x32_bf16 v[82:85], v[226:229], v[198:201], v[82:85]
	v_mfma_f32_16x16x32_bf16 v[70:73], v[106:109], v[214:217], v[70:73]
	v_mfma_f32_16x16x32_bf16 v[66:69], v[226:229], v[214:217], v[66:69]
	v_mfma_f32_16x16x32_bf16 v[94:97], v[106:109], v[190:193], v[94:97]
	v_mfma_f32_16x16x32_bf16 v[90:93], v[226:229], v[190:193], v[90:93]
	v_mfma_f32_16x16x32_bf16 v[86:89], v[110:113], v[202:205], v[86:89]
	v_mfma_f32_16x16x32_bf16 v[82:85], v[156:159], v[202:205], v[82:85]
	v_mfma_f32_16x16x32_bf16 v[78:81], v[106:109], v[206:209], v[78:81]
	v_mfma_f32_16x16x32_bf16 v[74:77], v[226:229], v[206:209], v[74:77]
	v_mfma_f32_16x16x32_bf16 v[70:73], v[110:113], v[218:221], v[70:73]
	v_mfma_f32_16x16x32_bf16 v[66:69], v[156:159], v[218:221], v[66:69]
	v_mfma_f32_16x16x32_bf16 v[230:233], v[110:113], v[194:197], v[94:97]
	v_mfma_f32_16x16x32_bf16 v[190:193], v[156:159], v[194:197], v[90:93]
	v_mfma_f32_16x16x32_bf16 v[194:197], v[110:113], v[210:213], v[78:81]
	v_mfma_f32_16x16x32_bf16 v[198:201], v[156:159], v[210:213], v[74:77]
	s_barrier
	s_nop 0
	ds_read_b128 v[74:77], v150 offset:16384
	ds_read_b128 v[78:81], v150 offset:17408
	ds_read_b128 v[90:93], v149 offset:16384
	ds_read_b128 v[94:97], v149 offset:17408
	ds_read_b128 v[202:205], v148 offset:16384
	ds_read_b128 v[206:209], v148 offset:17408
	ds_read_b128 v[210:213], v147 offset:16384
	ds_read_b128 v[214:217], v147 offset:17408
	s_waitcnt vmcnt(4)
	s_barrier
	s_waitcnt lgkmcnt(0)
	v_mfma_f32_16x16x32_bf16 v[62:65], v[136:139], v[74:77], v[62:65]
	v_mfma_f32_16x16x32_bf16 v[58:61], v[172:175], v[74:77], v[58:61]
	v_mfma_f32_16x16x32_bf16 v[54:57], v[136:139], v[90:93], v[54:57]
	v_mfma_f32_16x16x32_bf16 v[50:53], v[172:175], v[90:93], v[50:53]
	v_mfma_f32_16x16x32_bf16 v[38:41], v[136:139], v[210:213], v[38:41]
	v_mfma_f32_16x16x32_bf16 v[34:37], v[172:175], v[210:213], v[34:37]
	v_mfma_f32_16x16x32_bf16 v[62:65], v[140:143], v[78:81], v[62:65]
	v_mfma_f32_16x16x32_bf16 v[58:61], v[186:189], v[78:81], v[58:61]
	v_mfma_f32_16x16x32_bf16 v[54:57], v[140:143], v[94:97], v[54:57]
	v_mfma_f32_16x16x32_bf16 v[50:53], v[186:189], v[94:97], v[50:53]
	v_mfma_f32_16x16x32_bf16 v[46:49], v[136:139], v[202:205], v[46:49]
	v_mfma_f32_16x16x32_bf16 v[42:45], v[172:175], v[202:205], v[42:45]
	v_mfma_f32_16x16x32_bf16 v[38:41], v[140:143], v[214:217], v[38:41]
	v_mfma_f32_16x16x32_bf16 v[34:37], v[186:189], v[214:217], v[34:37]
	v_mfma_f32_16x16x32_bf16 v[218:221], v[140:143], v[206:209], v[46:49]
	v_mfma_f32_16x16x32_bf16 v[234:237], v[186:189], v[206:209], v[42:45]
	v_mfma_f32_16x16x32_bf16 v[22:25], v[106:109], v[90:93], v[22:25]
	v_mfma_f32_16x16x32_bf16 v[18:21], v[226:229], v[90:93], v[18:21]
	v_mfma_f32_16x16x32_bf16 v[6:9], v[106:109], v[210:213], v[6:9]
	v_mfma_f32_16x16x32_bf16 v[2:5], v[226:229], v[210:213], v[2:5]
	v_mfma_f32_16x16x32_bf16 v[30:33], v[106:109], v[74:77], v[30:33]
	v_mfma_f32_16x16x32_bf16 v[26:29], v[226:229], v[74:77], v[26:29]
	v_mfma_f32_16x16x32_bf16 v[22:25], v[110:113], v[94:97], v[22:25]
	v_mfma_f32_16x16x32_bf16 v[18:21], v[156:159], v[94:97], v[18:21]
	v_mfma_f32_16x16x32_bf16 v[14:17], v[106:109], v[202:205], v[14:17]
	v_mfma_f32_16x16x32_bf16 v[10:13], v[226:229], v[202:205], v[10:13]
	v_mfma_f32_16x16x32_bf16 v[6:9], v[110:113], v[214:217], v[6:9]
	v_mfma_f32_16x16x32_bf16 v[2:5], v[156:159], v[214:217], v[2:5]
	v_mfma_f32_16x16x32_bf16 v[136:139], v[110:113], v[78:81], v[30:33]
	v_mfma_f32_16x16x32_bf16 v[140:143], v[156:159], v[78:81], v[26:29]
	v_mfma_f32_16x16x32_bf16 v[170:173], v[110:113], v[206:209], v[14:17]
	v_mfma_f32_16x16x32_bf16 v[186:189], v[156:159], v[206:209], v[10:13]
	s_barrier
	s_nop 0
	ds_read_b128 v[10:13], v154
	ds_read_b128 v[14:17], v154 offset:1024
	ds_read_b128 v[156:159], v154 offset:2048
	ds_read_b128 v[202:205], v154 offset:3072
	ds_read_b128 v[26:29], v150 offset:32768
	ds_read_b128 v[30:33], v150 offset:33792
	ds_read_b128 v[42:45], v149 offset:32768
	ds_read_b128 v[46:49], v149 offset:33792
	ds_read_b128 v[206:209], v148 offset:32768
	ds_read_b128 v[210:213], v148 offset:33792
	ds_read_b128 v[214:217], v147 offset:32768
	ds_read_b128 v[226:229], v147 offset:33792
	s_waitcnt vmcnt(2)
	s_barrier
; #define LDA(dst,b,h) for(int m=0;m<4;++m)for(int k=0;k<2;++k) \
;     dst[m][k]=*reinterpret_cast<const bf16x8*>((char*)SA(b,h)+lds_byte(wr*64+m*16+fr,k*32+fq*8))
; #define LDB(dst,b,h) for(int n=0;n<2;++n)for(int k=0;k<2;++k) \
;     dst[n][k]=*reinterpret_cast<const bf16x8*>((char*)SB(b,h)+lds_byte(wc*32+n*16+fr,k*32+fq*8))
; #define MMA(ai,bj,At,Bt_) do{__builtin_amdgcn_s_setprio(1); \
;     for(int m=0;m<4;++m)for(int n=0;n<2;++n)for(int k=0;k<2;++k) \
;       acc[ai][bj][m][n]=__builtin_amdgcn_mfma_f32_16x16x32_bf16(Bt_[n][k],At[m][k],acc[ai][bj][m][n],0,0,0); \
;     __builtin_amdgcn_s_setprio(0);}while(0)
; #define WAIT_V(n) asm volatile("s_waitcnt vmcnt(" #n ")":::"memory")
; #define WAIT_L(n) asm volatile("s_waitcnt lgkmcnt(" #n ")":::"memory")
; #define BAR __builtin_amdgcn_s_barrier()
; template <int EPI>
; __device__ __forceinline__ void gemm_run(const GD& c, const bool has_next, const GD& nx, const Ctx& e, bf16* shm, float* rs, float* rs_nxt, float* racc_) {
;     ...
;   { LDB(B0,1,0); LDA(At,1,0); WAIT_V(2); BAR; WAIT_L(0); MMA(0,0,At,B0); BAR;
;     LDB(B1,1,1); WAIT_V(0); BAR; WAIT_L(0); MMA(0,1,At,B1); BAR;
;     LDA(At,1,1); BAR; WAIT_L(0); MMA(1,0,At,B0); MMA(1,1,At,B1); BAR; }
;   if(wr==0)BAR;
	s_waitcnt lgkmcnt(0)
	v_mfma_f32_16x16x32_bf16 v[74:77], v[10:13], v[26:29], v[126:129]
	v_mfma_f32_16x16x32_bf16 v[126:129], v[14:17], v[30:33], v[74:77]
	v_mfma_f32_16x16x32_bf16 v[74:77], v[156:159], v[26:29], v[122:125]
	v_mfma_f32_16x16x32_bf16 v[122:125], v[202:205], v[30:33], v[74:77]
	v_mfma_f32_16x16x32_bf16 v[74:77], v[10:13], v[42:45], v[118:121]
	v_mfma_f32_16x16x32_bf16 v[110:113], v[14:17], v[46:49], v[74:77]
	v_mfma_f32_16x16x32_bf16 v[74:77], v[156:159], v[42:45], v[114:117]
	v_mfma_f32_16x16x32_bf16 v[106:109], v[202:205], v[46:49], v[74:77]
	v_mfma_f32_16x16x32_bf16 v[74:77], v[10:13], v[206:209], v[132:135]
	v_mfma_f32_16x16x32_bf16 v[94:97], v[14:17], v[210:213], v[74:77]
	v_mfma_f32_16x16x32_bf16 v[74:77], v[156:159], v[206:209], v[222:225]
	v_mfma_f32_16x16x32_bf16 v[90:93], v[202:205], v[210:213], v[74:77]
	v_mfma_f32_16x16x32_bf16 v[74:77], v[10:13], v[214:217], v[102:105]
	v_mfma_f32_16x16x32_bf16 v[78:81], v[14:17], v[226:229], v[74:77]
	v_mfma_f32_16x16x32_bf16 v[74:77], v[156:159], v[214:217], v[98:101]
	v_mfma_f32_16x16x32_bf16 v[74:77], v[202:205], v[226:229], v[74:77]
	s_barrier
	ds_read_b128 v[132:135], v152
	ds_read_b128 v[222:225], v152 offset:1024
	ds_read_b128 v[238:241], v152 offset:2048
	ds_read_b128 v[152:155], v152 offset:3072
	s_waitcnt vmcnt(0)
	s_barrier
	s_waitcnt lgkmcnt(0)
	v_mfma_f32_16x16x32_bf16 v[98:101], v[132:135], v[26:29], v[230:233]
	v_mfma_f32_16x16x32_bf16 v[26:29], v[238:241], v[26:29], v[190:193]
	v_mfma_f32_16x16x32_bf16 v[114:117], v[152:155], v[30:33], v[26:29]
	v_mfma_f32_16x16x32_bf16 v[26:29], v[132:135], v[42:45], v[86:89]
	v_mfma_f32_16x16x32_bf16 v[102:105], v[222:225], v[46:49], v[26:29]
	v_mfma_f32_16x16x32_bf16 v[26:29], v[238:241], v[42:45], v[82:85]
	v_mfma_f32_16x16x32_bf16 v[118:121], v[222:225], v[30:33], v[98:101]
	v_mfma_f32_16x16x32_bf16 v[98:101], v[152:155], v[46:49], v[26:29]
	v_mfma_f32_16x16x32_bf16 v[26:29], v[132:135], v[206:209], v[194:197]
	v_mfma_f32_16x16x32_bf16 v[86:89], v[222:225], v[210:213], v[26:29]
	v_mfma_f32_16x16x32_bf16 v[26:29], v[238:241], v[206:209], v[198:201]
	v_mfma_f32_16x16x32_bf16 v[82:85], v[152:155], v[210:213], v[26:29]
	v_mfma_f32_16x16x32_bf16 v[26:29], v[132:135], v[214:217], v[70:73]
	v_mfma_f32_16x16x32_bf16 v[70:73], v[222:225], v[226:229], v[26:29]
	v_mfma_f32_16x16x32_bf16 v[26:29], v[238:241], v[214:217], v[66:69]
	v_mfma_f32_16x16x32_bf16 v[66:69], v[152:155], v[226:229], v[26:29]
	s_barrier
	ds_read_b128 v[190:193], v150 offset:49152
	ds_read_b128 v[194:197], v150 offset:50176
	ds_read_b128 v[198:201], v149 offset:49152
	ds_read_b128 v[206:209], v149 offset:50176
	ds_read_b128 v[210:213], v148 offset:49152
	ds_read_b128 v[148:151], v148 offset:50176
	ds_read_b128 v[214:217], v147 offset:49152
	ds_read_b128 v[226:229], v147 offset:50176
	s_barrier
	s_waitcnt lgkmcnt(0)
	v_mfma_f32_16x16x32_bf16 v[26:29], v[10:13], v[190:193], v[62:65]
	v_mfma_f32_16x16x32_bf16 v[62:65], v[14:17], v[194:197], v[26:29]
	v_mfma_f32_16x16x32_bf16 v[26:29], v[156:159], v[190:193], v[58:61]
	v_mfma_f32_16x16x32_bf16 v[58:61], v[202:205], v[194:197], v[26:29]
	v_mfma_f32_16x16x32_bf16 v[26:29], v[10:13], v[198:201], v[54:57]
	v_mfma_f32_16x16x32_bf16 v[46:49], v[14:17], v[206:209], v[26:29]
	v_mfma_f32_16x16x32_bf16 v[26:29], v[156:159], v[198:201], v[50:53]
	v_mfma_f32_16x16x32_bf16 v[42:45], v[202:205], v[206:209], v[26:29]
	v_mfma_f32_16x16x32_bf16 v[26:29], v[10:13], v[210:213], v[218:221]
	v_mfma_f32_16x16x32_bf16 v[10:13], v[10:13], v[214:217], v[38:41]
	v_mfma_f32_16x16x32_bf16 v[30:33], v[14:17], v[148:151], v[26:29]
	v_mfma_f32_16x16x32_bf16 v[26:29], v[156:159], v[210:213], v[234:237]
	v_mfma_f32_16x16x32_bf16 v[14:17], v[14:17], v[226:229], v[10:13]
	v_mfma_f32_16x16x32_bf16 v[10:13], v[156:159], v[214:217], v[34:37]
	v_mfma_f32_16x16x32_bf16 v[26:29], v[202:205], v[148:151], v[26:29]
	v_mfma_f32_16x16x32_bf16 v[10:13], v[202:205], v[226:229], v[10:13]
	v_mfma_f32_16x16x32_bf16 v[34:37], v[132:135], v[190:193], v[136:139]
	v_mfma_f32_16x16x32_bf16 v[54:57], v[222:225], v[194:197], v[34:37]
	v_mfma_f32_16x16x32_bf16 v[34:37], v[238:241], v[190:193], v[140:143]
	v_mfma_f32_16x16x32_bf16 v[18:21], v[238:241], v[198:201], v[18:21]
	v_mfma_f32_16x16x32_bf16 v[50:53], v[152:155], v[194:197], v[34:37]
	v_mfma_f32_16x16x32_bf16 v[22:25], v[132:135], v[198:201], v[22:25]
	v_mfma_f32_16x16x32_bf16 v[34:37], v[152:155], v[206:209], v[18:21]
	v_mfma_f32_16x16x32_bf16 v[18:21], v[132:135], v[210:213], v[170:173]
	v_mfma_f32_16x16x32_bf16 v[38:41], v[222:225], v[206:209], v[22:25]
	v_mfma_f32_16x16x32_bf16 v[22:25], v[222:225], v[148:151], v[18:21]
	v_mfma_f32_16x16x32_bf16 v[18:21], v[238:241], v[210:213], v[186:189]
	v_mfma_f32_16x16x32_bf16 v[6:9], v[132:135], v[214:217], v[6:9]
	v_mfma_f32_16x16x32_bf16 v[2:5], v[238:241], v[214:217], v[2:5]
	v_mfma_f32_16x16x32_bf16 v[18:21], v[152:155], v[148:151], v[18:21]
	v_mfma_f32_16x16x32_bf16 v[6:9], v[222:225], v[226:229], v[6:9]
	v_mfma_f32_16x16x32_bf16 v[2:5], v[152:155], v[226:229], v[2:5]
	v_cmp_gt_u32_e32 vcc, s96, v145
	s_barrier
	s_and_saveexec_b64 s[18:19], vcc
	s_cbranch_execz .LBB0_975
	s_barrier

; #define STAGE_A(P,br,kt) STAGE_G(P,c.A,c.lda,br,(long)(kt)*c.kstr)
; #define STAGE_B(P,br,kt) STAGE_G(P,c.Bt,c.K,br,(long)(kt)*BK)
; #define LDA(dst,b,h) for(int m=0;m<4;++m)for(int k=0;k<2;++k) \
;     dst[m][k]=*reinterpret_cast<const bf16x8*>((char*)SA(b,h)+lds_byte(wr*64+m*16+fr,k*32+fq*8))
; #define LDB(dst,b,h) for(int n=0;n<2;++n)for(int k=0;k<2;++k) \
;     dst[n][k]=*reinterpret_cast<const bf16x8*>((char*)SB(b,h)+lds_byte(wc*32+n*16+fr,k*32+fq*8))
; #define MMA(ai,bj,At,Bt_) do{__builtin_amdgcn_s_setprio(1); \
;     for(int m=0;m<4;++m)for(int n=0;n<2;++n)for(int k=0;k<2;++k) \
;       acc[ai][bj][m][n]=__builtin_amdgcn_mfma_f32_16x16x32_bf16(Bt_[n][k],At[m][k],acc[ai][bj][m][n],0,0,0); \
;     __builtin_amdgcn_s_setprio(0);}while(0)
; #define WAIT_L(n) asm volatile("s_waitcnt lgkmcnt(" #n ")":::"memory")
; #define BAR __builtin_amdgcn_s_barrier()
; #define SCHED __builtin_amdgcn_sched_barrier(0)
; template <int EPI>
; __device__ __forceinline__ void gemm_run(const GD& c, const bool has_next, const GD& nx, const Ctx& e, bf16* shm, float* rs, float* rs_nxt, float* racc_) {
;     ...
;   for(int t=0;t<nt-2;t+=2){
;     LDB(B0,0,0); SCHED; LDA(At,0,0); STAGE_A(SA(1,1),brow+HALF,t+1);
;     WAIT_L(8); BAR; WAIT_L(0); MMA(0,0,At,B0); BAR; SCHED;
;     LDB(B1,0,1); STAGE_B(SB(0,0),bcol,t+2);
;     BAR; WAIT_L(0); MMA(0,1,At,B1); BAR;
;     LDA(At,0,1); STAGE_A(SA(0,0),brow,t+2);
;     BAR; WAIT_L(0); MMA(1,0,At,B0); BAR; SCHED;
.LBB0_980:
	ds_read_b128 v[172:175], v159
	ds_read_b128 v[186:189], v159 offset:1024
	ds_read_b128 v[190:193], v159 offset:2048
	ds_read_b128 v[194:197], v159 offset:3072
	v_add_u32_e32 v169, 0xc000, v146
	v_lshl_add_u64 v[182:183], s[6:7], 0, v[132:133]
	v_readfirstlane_b32 s3, v169
	v_add_u32_e32 v170, 0xe000, v146
	v_lshl_add_u64 v[160:161], v[182:183], 0, s[18:19]
	s_mov_b32 m0, s3
	v_lshl_add_u64 v[246:247], s[6:7], 0, v[134:135]
	v_readfirstlane_b32 s3, v170
	ds_read_b128 v[198:201], v150
	ds_read_b128 v[202:205], v150 offset:1024
	ds_read_b128 v[206:209], v149
	ds_read_b128 v[210:213], v149 offset:1024
	ds_read_b128 v[214:217], v148
	ds_read_b128 v[218:221], v148 offset:1024
	ds_read_b128 v[222:225], v147
	ds_read_b128 v[226:229], v147 offset:1024
	global_load_lds_dwordx4 v[160:161], off
	v_lshl_add_u64 v[160:161], v[246:247], 0, s[18:19]
	s_mov_b32 m0, s3
	s_nop 0
	global_load_lds_dwordx4 v[160:161], off
	s_waitcnt lgkmcnt(8)
	s_barrier
	s_waitcnt lgkmcnt(0)
	v_mfma_f32_16x16x32_bf16 v[126:129], v[172:175], v[198:201], v[126:129]
	v_mfma_f32_16x16x32_bf16 v[122:125], v[190:193], v[198:201], v[122:125]
	v_mfma_f32_16x16x32_bf16 v[118:121], v[172:175], v[206:209], v[118:121]
	v_mfma_f32_16x16x32_bf16 v[114:117], v[190:193], v[206:209], v[114:117]
	v_mfma_f32_16x16x32_bf16 v[110:113], v[172:175], v[214:217], v[110:113]
	v_mfma_f32_16x16x32_bf16 v[106:109], v[190:193], v[214:217], v[106:109]
	v_mfma_f32_16x16x32_bf16 v[102:105], v[172:175], v[222:225], v[102:105]
	v_mfma_f32_16x16x32_bf16 v[98:101], v[190:193], v[222:225], v[98:101]
	v_mfma_f32_16x16x32_bf16 v[126:129], v[186:189], v[202:205], v[126:129]
	v_mfma_f32_16x16x32_bf16 v[122:125], v[194:197], v[202:205], v[122:125]
	v_mfma_f32_16x16x32_bf16 v[118:121], v[186:189], v[210:213], v[118:121]
	v_mfma_f32_16x16x32_bf16 v[114:117], v[194:197], v[210:213], v[114:117]
	v_mfma_f32_16x16x32_bf16 v[110:113], v[186:189], v[218:221], v[110:113]
	v_mfma_f32_16x16x32_bf16 v[106:109], v[194:197], v[218:221], v[106:109]
	v_mfma_f32_16x16x32_bf16 v[102:105], v[186:189], v[226:229], v[102:105]
	v_mfma_f32_16x16x32_bf16 v[98:101], v[194:197], v[226:229], v[98:101]
	s_barrier
	v_add_u32_e32 v160, s33, v152
	v_lshl_add_u64 v[248:249], s[6:7], 0, v[136:137]
	v_readfirstlane_b32 s3, v160
	v_add_u32_e32 v161, 0x2000, v160
	v_lshl_add_u64 v[162:163], v[248:249], 0, s[20:21]
	s_mov_b32 m0, s3
	v_lshl_add_u64 v[250:251], s[6:7], 0, v[138:139]
	v_readfirstlane_b32 s3, v161
	ds_read_b128 v[230:233], v157
	ds_read_b128 v[234:237], v157 offset:1024
	ds_read_b128 v[238:241], v157 offset:2048
	ds_read_b128 v[242:245], v157 offset:3072
	global_load_lds_dwordx4 v[162:163], off
	v_lshl_add_u64 v[162:163], v[250:251], 0, s[20:21]
	s_mov_b32 m0, s3
	s_nop 0
	global_load_lds_dwordx4 v[162:163], off
	s_barrier
	s_waitcnt lgkmcnt(0)
	v_mfma_f32_16x16x32_bf16 v[94:97], v[230:233], v[198:201], v[94:97]
	v_mfma_f32_16x16x32_bf16 v[90:93], v[238:241], v[198:201], v[90:93]
	v_mfma_f32_16x16x32_bf16 v[86:89], v[230:233], v[206:209], v[86:89]
	v_mfma_f32_16x16x32_bf16 v[82:85], v[238:241], v[206:209], v[82:85]
	v_mfma_f32_16x16x32_bf16 v[78:81], v[230:233], v[214:217], v[78:81]
	v_mfma_f32_16x16x32_bf16 v[74:77], v[238:241], v[214:217], v[74:77]
	v_mfma_f32_16x16x32_bf16 v[70:73], v[230:233], v[222:225], v[70:73]
	v_mfma_f32_16x16x32_bf16 v[66:69], v[238:241], v[222:225], v[66:69]
	v_mfma_f32_16x16x32_bf16 v[94:97], v[234:237], v[202:205], v[94:97]
	v_mfma_f32_16x16x32_bf16 v[90:93], v[242:245], v[202:205], v[90:93]
	v_mfma_f32_16x16x32_bf16 v[86:89], v[234:237], v[210:213], v[86:89]
	v_mfma_f32_16x16x32_bf16 v[82:85], v[242:245], v[210:213], v[82:85]
	v_mfma_f32_16x16x32_bf16 v[78:81], v[234:237], v[218:221], v[78:81]
	v_mfma_f32_16x16x32_bf16 v[74:77], v[242:245], v[218:221], v[74:77]
	v_mfma_f32_16x16x32_bf16 v[70:73], v[234:237], v[226:229], v[70:73]
	v_mfma_f32_16x16x32_bf16 v[66:69], v[242:245], v[226:229], v[66:69]
	s_barrier
	v_readfirstlane_b32 s3, v146
	v_lshl_add_u64 v[162:163], v[182:183], 0, s[22:23]
	s_mov_b32 m0, s3
	ds_read_b128 v[198:201], v150 offset:16384
	ds_read_b128 v[202:205], v150 offset:17408
	ds_read_b128 v[206:209], v149 offset:16384
	ds_read_b128 v[210:213], v149 offset:17408
	ds_read_b128 v[214:217], v148 offset:16384
	ds_read_b128 v[218:221], v148 offset:17408
	ds_read_b128 v[222:225], v147 offset:16384
	ds_read_b128 v[226:229], v147 offset:17408
	global_load_lds_dwordx4 v[162:163], off
	v_add_u32_e32 v162, 0x2000, v146
	v_lshl_add_u64 v[166:167], v[246:247], 0, s[22:23]
	v_readfirstlane_b32 s3, v162
	s_mov_b32 m0, s3
	s_nop 0
	global_load_lds_dwordx4 v[166:167], off
	s_barrier
	s_waitcnt lgkmcnt(0)
	v_mfma_f32_16x16x32_bf16 v[62:65], v[172:175], v[198:201], v[62:65]
	v_mfma_f32_16x16x32_bf16 v[58:61], v[190:193], v[198:201], v[58:61]
	v_mfma_f32_16x16x32_bf16 v[54:57], v[172:175], v[206:209], v[54:57]
	v_mfma_f32_16x16x32_bf16 v[50:53], v[190:193], v[206:209], v[50:53]
	v_mfma_f32_16x16x32_bf16 v[46:49], v[172:175], v[214:217], v[46:49]
	v_mfma_f32_16x16x32_bf16 v[42:45], v[190:193], v[214:217], v[42:45]
	v_mfma_f32_16x16x32_bf16 v[38:41], v[172:175], v[222:225], v[38:41]
	v_mfma_f32_16x16x32_bf16 v[34:37], v[190:193], v[222:225], v[34:37]
	v_mfma_f32_16x16x32_bf16 v[62:65], v[186:189], v[202:205], v[62:65]
	v_mfma_f32_16x16x32_bf16 v[58:61], v[194:197], v[202:205], v[58:61]
	v_mfma_f32_16x16x32_bf16 v[54:57], v[186:189], v[210:213], v[54:57]
	v_mfma_f32_16x16x32_bf16 v[50:53], v[194:197], v[210:213], v[50:53]
	v_mfma_f32_16x16x32_bf16 v[46:49], v[186:189], v[218:221], v[46:49]
	v_mfma_f32_16x16x32_bf16 v[42:45], v[194:197], v[218:221], v[42:45]
	v_mfma_f32_16x16x32_bf16 v[38:41], v[186:189], v[226:229], v[38:41]
	v_mfma_f32_16x16x32_bf16 v[34:37], v[194:197], v[226:229], v[34:37]
	s_barrier
; #define STAGE_A(P,br,kt) STAGE_G(P,c.A,c.lda,br,(long)(kt)*c.kstr)
; #define STAGE_B(P,br,kt) STAGE_G(P,c.Bt,c.K,br,(long)(kt)*BK)
; #define LDA(dst,b,h) for(int m=0;m<4;++m)for(int k=0;k<2;++k) \
;     dst[m][k]=*reinterpret_cast<const bf16x8*>((char*)SA(b,h)+lds_byte(wr*64+m*16+fr,k*32+fq*8))
; #define LDB(dst,b,h) for(int n=0;n<2;++n)for(int k=0;k<2;++k) \
;     dst[n][k]=*reinterpret_cast<const bf16x8*>((char*)SB(b,h)+lds_byte(wc*32+n*16+fr,k*32+fq*8))
; #define MMA(ai,bj,At,Bt_) do{__builtin_amdgcn_s_setprio(1); \
;     for(int m=0;m<4;++m)for(int n=0;n<2;++n)for(int k=0;k<2;++k) \
;       acc[ai][bj][m][n]=__builtin_amdgcn_mfma_f32_16x16x32_bf16(Bt_[n][k],At[m][k],acc[ai][bj][m][n],0,0,0); \
;     __builtin_amdgcn_s_setprio(0);}while(0)
; #define WAIT_V(n) asm volatile("s_waitcnt vmcnt(" #n ")":::"memory")
; #define WAIT_L(n) asm volatile("s_waitcnt lgkmcnt(" #n ")":::"memory")
; #define BAR __builtin_amdgcn_s_barrier()
; #define SCHED __builtin_amdgcn_sched_barrier(0)
; template <int EPI>
; __device__ __forceinline__ void gemm_run(const GD& c, const bool has_next, const GD& nx, const Ctx& e, bf16* shm, float* rs, float* rs_nxt, float* racc_) {
;     ...
;     STAGE_B(SB(0,1),bcol+HALF,t+2);
;     WAIT_V(6); BAR; MMA(1,1,At,B1); BAR;
;     LDB(B0,1,0); SCHED; LDA(At,1,0); STAGE_A(SA(0,1),brow+HALF,t+2);
;     WAIT_L(8); BAR; WAIT_L(0); MMA(0,0,At,B0); BAR; SCHED;
;     LDB(B1,1,1); STAGE_B(SB(1,0),bcol,t+3);
;     BAR; WAIT_L(0); MMA(0,1,At,B1); BAR;
;     LDA(At,1,1); STAGE_A(SA(1,0),brow,t+3);
	v_add_u32_e32 v163, s86, v152
	v_lshl_add_u64 v[166:167], v[248:249], 0, s[24:25]
	v_readfirstlane_b32 s3, v163
	s_mov_b32 m0, s3
	v_lshl_add_u64 v[172:173], v[250:251], 0, s[24:25]
	global_load_lds_dwordx4 v[166:167], off
	v_add_u32_e32 v166, 0x2000, v163
	s_nop 0
	v_readfirstlane_b32 s3, v166
	s_mov_b32 m0, s3
	s_nop 0
	global_load_lds_dwordx4 v[172:173], off
	s_waitcnt vmcnt(6)
	s_barrier
	v_mfma_f32_16x16x32_bf16 v[30:33], v[230:233], v[198:201], v[30:33]
	v_mfma_f32_16x16x32_bf16 v[26:29], v[238:241], v[198:201], v[26:29]
	v_mfma_f32_16x16x32_bf16 v[22:25], v[230:233], v[206:209], v[22:25]
	v_mfma_f32_16x16x32_bf16 v[18:21], v[238:241], v[206:209], v[18:21]
	v_mfma_f32_16x16x32_bf16 v[14:17], v[230:233], v[214:217], v[14:17]
	v_mfma_f32_16x16x32_bf16 v[10:13], v[238:241], v[214:217], v[10:13]
	v_mfma_f32_16x16x32_bf16 v[6:9], v[230:233], v[222:225], v[6:9]
	v_mfma_f32_16x16x32_bf16 v[2:5], v[238:241], v[222:225], v[2:5]
	v_mfma_f32_16x16x32_bf16 v[30:33], v[234:237], v[202:205], v[30:33]
	v_mfma_f32_16x16x32_bf16 v[26:29], v[242:245], v[202:205], v[26:29]
	v_mfma_f32_16x16x32_bf16 v[22:25], v[234:237], v[210:213], v[22:25]
	v_mfma_f32_16x16x32_bf16 v[18:21], v[242:245], v[210:213], v[18:21]
	v_mfma_f32_16x16x32_bf16 v[14:17], v[234:237], v[218:221], v[14:17]
	v_mfma_f32_16x16x32_bf16 v[10:13], v[242:245], v[218:221], v[10:13]
	v_mfma_f32_16x16x32_bf16 v[6:9], v[234:237], v[226:229], v[6:9]
	v_mfma_f32_16x16x32_bf16 v[2:5], v[242:245], v[226:229], v[2:5]
	s_barrier
	ds_read_b128 v[172:175], v153
	ds_read_b128 v[186:189], v153 offset:1024
	ds_read_b128 v[190:193], v153 offset:2048
	ds_read_b128 v[194:197], v153 offset:3072
	v_add_u32_e32 v167, 0x4000, v146
	v_add_u32_e32 v168, 0x6000, v146
	v_readfirstlane_b32 s3, v167
	v_lshl_add_u64 v[230:231], v[182:183], 0, s[28:29]
	s_mov_b32 m0, s3
	v_readfirstlane_b32 s3, v168
	ds_read_b128 v[198:201], v150 offset:32768
	ds_read_b128 v[202:205], v150 offset:33792
	ds_read_b128 v[206:209], v149 offset:32768
	ds_read_b128 v[210:213], v149 offset:33792
	ds_read_b128 v[214:217], v148 offset:32768
	ds_read_b128 v[218:221], v148 offset:33792
	ds_read_b128 v[222:225], v147 offset:32768
	ds_read_b128 v[226:229], v147 offset:33792
	global_load_lds_dwordx4 v[230:231], off
	v_lshl_add_u64 v[230:231], v[246:247], 0, s[28:29]
	s_mov_b32 m0, s3
	s_nop 0
	global_load_lds_dwordx4 v[230:231], off
	s_waitcnt lgkmcnt(8)
	s_barrier
	s_waitcnt lgkmcnt(0)
	v_mfma_f32_16x16x32_bf16 v[126:129], v[172:175], v[198:201], v[126:129]
	v_mfma_f32_16x16x32_bf16 v[122:125], v[190:193], v[198:201], v[122:125]
	v_mfma_f32_16x16x32_bf16 v[118:121], v[172:175], v[206:209], v[118:121]
	v_mfma_f32_16x16x32_bf16 v[114:117], v[190:193], v[206:209], v[114:117]
	v_mfma_f32_16x16x32_bf16 v[110:113], v[172:175], v[214:217], v[110:113]
	v_mfma_f32_16x16x32_bf16 v[106:109], v[190:193], v[214:217], v[106:109]
	v_mfma_f32_16x16x32_bf16 v[102:105], v[172:175], v[222:225], v[102:105]
	v_mfma_f32_16x16x32_bf16 v[98:101], v[190:193], v[222:225], v[98:101]
	v_mfma_f32_16x16x32_bf16 v[126:129], v[186:189], v[202:205], v[126:129]
	v_mfma_f32_16x16x32_bf16 v[122:125], v[194:197], v[202:205], v[122:125]
	v_mfma_f32_16x16x32_bf16 v[118:121], v[186:189], v[210:213], v[118:121]
	v_mfma_f32_16x16x32_bf16 v[114:117], v[194:197], v[210:213], v[114:117]
	v_mfma_f32_16x16x32_bf16 v[110:113], v[186:189], v[218:221], v[110:113]
	v_mfma_f32_16x16x32_bf16 v[106:109], v[194:197], v[218:221], v[106:109]
	v_mfma_f32_16x16x32_bf16 v[102:105], v[186:189], v[226:229], v[102:105]
	v_mfma_f32_16x16x32_bf16 v[98:101], v[194:197], v[226:229], v[98:101]
	s_barrier
	v_readfirstlane_b32 s3, v154
	v_add_u32_e32 v171, 0x2000, v154
	v_lshl_add_u64 v[252:253], v[248:249], 0, s[44:45]
	s_mov_b32 m0, s3
	v_readfirstlane_b32 s3, v171
	ds_read_b128 v[230:233], v151
	ds_read_b128 v[234:237], v151 offset:1024
	ds_read_b128 v[238:241], v151 offset:2048
	ds_read_b128 v[242:245], v151 offset:3072
	global_load_lds_dwordx4 v[252:253], off
	v_lshl_add_u64 v[252:253], v[250:251], 0, s[44:45]
	s_mov_b32 m0, s3
	s_nop 0
	global_load_lds_dwordx4 v[252:253], off
	s_barrier
	s_waitcnt lgkmcnt(0)
	v_mfma_f32_16x16x32_bf16 v[94:97], v[230:233], v[198:201], v[94:97]
	v_mfma_f32_16x16x32_bf16 v[90:93], v[238:241], v[198:201], v[90:93]
	v_mfma_f32_16x16x32_bf16 v[86:89], v[230:233], v[206:209], v[86:89]
	v_mfma_f32_16x16x32_bf16 v[82:85], v[238:241], v[206:209], v[82:85]
	v_mfma_f32_16x16x32_bf16 v[78:81], v[230:233], v[214:217], v[78:81]
	v_mfma_f32_16x16x32_bf16 v[74:77], v[238:241], v[214:217], v[74:77]
	v_mfma_f32_16x16x32_bf16 v[70:73], v[230:233], v[222:225], v[70:73]
	v_mfma_f32_16x16x32_bf16 v[66:69], v[238:241], v[222:225], v[66:69]
	v_mfma_f32_16x16x32_bf16 v[94:97], v[234:237], v[202:205], v[94:97]
	v_mfma_f32_16x16x32_bf16 v[90:93], v[242:245], v[202:205], v[90:93]
	v_mfma_f32_16x16x32_bf16 v[86:89], v[234:237], v[210:213], v[86:89]
	v_mfma_f32_16x16x32_bf16 v[82:85], v[242:245], v[210:213], v[82:85]
	v_mfma_f32_16x16x32_bf16 v[78:81], v[234:237], v[218:221], v[78:81]
	v_mfma_f32_16x16x32_bf16 v[74:77], v[242:245], v[218:221], v[74:77]
	v_mfma_f32_16x16x32_bf16 v[70:73], v[234:237], v[226:229], v[70:73]
	v_mfma_f32_16x16x32_bf16 v[66:69], v[242:245], v[226:229], v[66:69]
	s_barrier
	v_readfirstlane_b32 s3, v155
	v_lshl_add_u64 v[182:183], v[182:183], 0, s[46:47]
	s_mov_b32 m0, s3
	v_readfirstlane_b32 s3, v156
	ds_read_b128 v[198:201], v150 offset:49152
	ds_read_b128 v[202:205], v150 offset:50176
	ds_read_b128 v[206:209], v149 offset:49152
	ds_read_b128 v[210:213], v149 offset:50176
	ds_read_b128 v[214:217], v148 offset:49152
	ds_read_b128 v[218:221], v148 offset:50176
	ds_read_b128 v[222:225], v147 offset:49152
	ds_read_b128 v[226:229], v147 offset:50176
	global_load_lds_dwordx4 v[182:183], off
	v_lshl_add_u64 v[182:183], v[246:247], 0, s[46:47]
	s_mov_b32 m0, s3
	s_nop 0
	global_load_lds_dwordx4 v[182:183], off
	s_barrier
; #define STAGE_A(P,br,kt) STAGE_G(P,c.A,c.lda,br,(long)(kt)*c.kstr)
; #define STAGE_B(P,br,kt) STAGE_G(P,c.Bt,c.K,br,(long)(kt)*BK)
; #define LDA(dst,b,h) for(int m=0;m<4;++m)for(int k=0;k<2;++k) \
;     dst[m][k]=*reinterpret_cast<const bf16x8*>((char*)SA(b,h)+lds_byte(wr*64+m*16+fr,k*32+fq*8))
; #define LDB(dst,b,h) for(int n=0;n<2;++n)for(int k=0;k<2;++k) \
;     dst[n][k]=*reinterpret_cast<const bf16x8*>((char*)SB(b,h)+lds_byte(wc*32+n*16+fr,k*32+fq*8))
; #define MMA(ai,bj,At,Bt_) do{__builtin_amdgcn_s_setprio(1); \
;     for(int m=0;m<4;++m)for(int n=0;n<2;++n)for(int k=0;k<2;++k) \
;       acc[ai][bj][m][n]=__builtin_amdgcn_mfma_f32_16x16x32_bf16(Bt_[n][k],At[m][k],acc[ai][bj][m][n],0,0,0); \
;     __builtin_amdgcn_s_setprio(0);}while(0)
; #define WAIT_V(n) asm volatile("s_waitcnt vmcnt(" #n ")":::"memory")
; #define WAIT_L(n) asm volatile("s_waitcnt lgkmcnt(" #n ")":::"memory")
; #define BAR __builtin_amdgcn_s_barrier()
; #define SCHED __builtin_amdgcn_sched_barrier(0)
; template <int EPI>
; __device__ __forceinline__ void gemm_run(const GD& c, const bool has_next, const GD& nx, const Ctx& e, bf16* shm, float* rs, float* rs_nxt, float* racc_) {
;     ...
;     BAR; WAIT_L(0); MMA(1,0,At,B0); BAR; SCHED;
;     STAGE_B(SB(1,1),bcol+HALF,t+3);
;     WAIT_V(6); BAR; MMA(1,1,At,B1); BAR;
;   }
;   { LDB(B0,0,0); LDA(At,0,0); STAGE_A(SA(1,1),brow+HALF,nt-1);
;     BAR; WAIT_L(0); MMA(0,0,At,B0); BAR;
	s_waitcnt lgkmcnt(0)
	v_mfma_f32_16x16x32_bf16 v[62:65], v[172:175], v[198:201], v[62:65]
	v_mfma_f32_16x16x32_bf16 v[58:61], v[190:193], v[198:201], v[58:61]
	v_mfma_f32_16x16x32_bf16 v[54:57], v[172:175], v[206:209], v[54:57]
	v_mfma_f32_16x16x32_bf16 v[50:53], v[190:193], v[206:209], v[50:53]
	v_mfma_f32_16x16x32_bf16 v[46:49], v[172:175], v[214:217], v[46:49]
	v_mfma_f32_16x16x32_bf16 v[42:45], v[190:193], v[214:217], v[42:45]
	v_mfma_f32_16x16x32_bf16 v[38:41], v[172:175], v[222:225], v[38:41]
	v_mfma_f32_16x16x32_bf16 v[34:37], v[190:193], v[222:225], v[34:37]
	v_mfma_f32_16x16x32_bf16 v[62:65], v[186:189], v[202:205], v[62:65]
	v_mfma_f32_16x16x32_bf16 v[58:61], v[194:197], v[202:205], v[58:61]
	v_mfma_f32_16x16x32_bf16 v[54:57], v[186:189], v[210:213], v[54:57]
	v_mfma_f32_16x16x32_bf16 v[50:53], v[194:197], v[210:213], v[50:53]
	v_mfma_f32_16x16x32_bf16 v[46:49], v[186:189], v[218:221], v[46:49]
	v_mfma_f32_16x16x32_bf16 v[42:45], v[194:197], v[218:221], v[42:45]
	v_mfma_f32_16x16x32_bf16 v[38:41], v[186:189], v[226:229], v[38:41]
	v_mfma_f32_16x16x32_bf16 v[34:37], v[194:197], v[226:229], v[34:37]
	s_barrier
	v_readfirstlane_b32 s3, v158
	v_add_u32_e32 v171, 0x2000, v158
	v_lshl_add_u64 v[172:173], v[248:249], 0, s[48:49]
	s_mov_b32 m0, s3
	v_readfirstlane_b32 s3, v171
	global_load_lds_dwordx4 v[172:173], off
	v_lshl_add_u64 v[172:173], v[250:251], 0, s[48:49]
	s_mov_b32 m0, s3
	s_nop 0
	global_load_lds_dwordx4 v[172:173], off
	s_waitcnt vmcnt(6)
	s_barrier
	v_mfma_f32_16x16x32_bf16 v[30:33], v[230:233], v[198:201], v[30:33]
	v_mfma_f32_16x16x32_bf16 v[26:29], v[238:241], v[198:201], v[26:29]
	v_mfma_f32_16x16x32_bf16 v[22:25], v[230:233], v[206:209], v[22:25]
	v_mfma_f32_16x16x32_bf16 v[18:21], v[238:241], v[206:209], v[18:21]
	s_add_i32 s2, s2, 2
	v_mfma_f32_16x16x32_bf16 v[14:17], v[230:233], v[214:217], v[14:17]
	v_lshl_add_u64 v[132:133], v[132:133], 0, s[88:89]
	v_mfma_f32_16x16x32_bf16 v[10:13], v[238:241], v[214:217], v[10:13]
	v_lshl_add_u64 v[134:135], v[134:135], 0, s[88:89]
	v_mfma_f32_16x16x32_bf16 v[6:9], v[230:233], v[222:225], v[6:9]
	v_lshl_add_u64 v[136:137], v[136:137], 0, s[88:89]
	v_mfma_f32_16x16x32_bf16 v[2:5], v[238:241], v[222:225], v[2:5]
	s_cmp_lt_u32 s2, 4
	v_mfma_f32_16x16x32_bf16 v[30:33], v[234:237], v[202:205], v[30:33]
	v_lshl_add_u64 v[138:139], v[138:139], 0, s[88:89]
	v_mfma_f32_16x16x32_bf16 v[26:29], v[242:245], v[202:205], v[26:29]
	v_mfma_f32_16x16x32_bf16 v[22:25], v[234:237], v[210:213], v[22:25]
	v_mfma_f32_16x16x32_bf16 v[18:21], v[242:245], v[210:213], v[18:21]
	v_mfma_f32_16x16x32_bf16 v[14:17], v[234:237], v[218:221], v[14:17]
	v_mfma_f32_16x16x32_bf16 v[10:13], v[242:245], v[218:221], v[10:13]
	v_mfma_f32_16x16x32_bf16 v[6:9], v[234:237], v[226:229], v[6:9]
	v_mfma_f32_16x16x32_bf16 v[2:5], v[242:245], v[226:229], v[2:5]
	s_barrier
	s_cbranch_scc1 .LBB0_980
	v_lshl_add_u64 v[154:155], s[16:17], 0, v[0:1]
	s_mov_b64 s[18:19], 0x380
	v_readfirstlane_b32 s2, v169
	v_lshl_add_u64 v[154:155], v[154:155], 0, s[18:19]
	s_mov_b32 m0, s2
	ds_read_b128 v[132:135], v159
	ds_read_b128 v[136:139], v159 offset:1024
	ds_read_b128 v[172:175], v159 offset:2048
	ds_read_b128 v[186:189], v159 offset:3072
	ds_read_b128 v[190:193], v150
	ds_read_b128 v[194:197], v150 offset:1024
	ds_read_b128 v[198:201], v149
	ds_read_b128 v[202:205], v149 offset:1024
	ds_read_b128 v[206:209], v148
	ds_read_b128 v[210:213], v148 offset:1024
	ds_read_b128 v[214:217], v147
	ds_read_b128 v[218:221], v147 offset:1024
	global_load_lds_dwordx4 v[154:155], off
	v_lshl_add_u64 v[154:155], s[16:17], 0, v[130:131]
	v_readfirstlane_b32 s2, v170
	v_lshl_add_u64 v[154:155], v[154:155], 0, s[18:19]
	s_mov_b32 m0, s2
	s_nop 0
	global_load_lds_dwordx4 v[154:155], off
	s_barrier
	s_waitcnt lgkmcnt(0)
	v_mfma_f32_16x16x32_bf16 v[126:129], v[132:135], v[190:193], v[126:129]
	v_mfma_f32_16x16x32_bf16 v[122:125], v[172:175], v[190:193], v[122:125]
	v_mfma_f32_16x16x32_bf16 v[118:121], v[132:135], v[198:201], v[118:121]
	v_mfma_f32_16x16x32_bf16 v[114:117], v[172:175], v[198:201], v[114:117]
	v_mfma_f32_16x16x32_bf16 v[102:105], v[132:135], v[214:217], v[102:105]
	v_mfma_f32_16x16x32_bf16 v[98:101], v[172:175], v[214:217], v[98:101]
	v_mfma_f32_16x16x32_bf16 v[126:129], v[136:139], v[194:197], v[126:129]
	v_mfma_f32_16x16x32_bf16 v[122:125], v[186:189], v[194:197], v[122:125]
	v_mfma_f32_16x16x32_bf16 v[118:121], v[136:139], v[202:205], v[118:121]
	v_mfma_f32_16x16x32_bf16 v[114:117], v[186:189], v[202:205], v[114:117]
	v_mfma_f32_16x16x32_bf16 v[110:113], v[132:135], v[206:209], v[110:113]
	v_mfma_f32_16x16x32_bf16 v[106:109], v[172:175], v[206:209], v[106:109]
	v_mfma_f32_16x16x32_bf16 v[102:105], v[136:139], v[218:221], v[102:105]
	v_mfma_f32_16x16x32_bf16 v[98:101], v[186:189], v[218:221], v[98:101]
	v_mfma_f32_16x16x32_bf16 v[222:225], v[136:139], v[210:213], v[110:113]
	v_mfma_f32_16x16x32_bf16 v[226:229], v[186:189], v[210:213], v[106:109]
	s_barrier
	s_nop 1
	ds_read_b128 v[106:109], v157
	ds_read_b128 v[110:113], v157 offset:1024
	ds_read_b128 v[230:233], v157 offset:2048
	ds_read_b128 v[154:157], v157 offset:3072
	s_barrier
; #define LDA(dst,b,h) for(int m=0;m<4;++m)for(int k=0;k<2;++k) \
;     dst[m][k]=*reinterpret_cast<const bf16x8*>((char*)SA(b,h)+lds_byte(wr*64+m*16+fr,k*32+fq*8))
; #define LDB(dst,b,h) for(int n=0;n<2;++n)for(int k=0;k<2;++k) \
;     dst[n][k]=*reinterpret_cast<const bf16x8*>((char*)SB(b,h)+lds_byte(wc*32+n*16+fr,k*32+fq*8))
; #define MMA(ai,bj,At,Bt_) do{__builtin_amdgcn_s_setprio(1); \
;     for(int m=0;m<4;++m)for(int n=0;n<2;++n)for(int k=0;k<2;++k) \
;       acc[ai][bj][m][n]=__builtin_amdgcn_mfma_f32_16x16x32_bf16(Bt_[n][k],At[m][k],acc[ai][bj][m][n],0,0,0); \
;     __builtin_amdgcn_s_setprio(0);}while(0)
; #define WAIT_V(n) asm volatile("s_waitcnt vmcnt(" #n ")":::"memory")
; #define WAIT_L(n) asm volatile("s_waitcnt lgkmcnt(" #n ")":::"memory")
; #define BAR __builtin_amdgcn_s_barrier()
; template <int EPI>
; __device__ __forceinline__ void gemm_run(const GD& c, const bool has_next, const GD& nx, const Ctx& e, bf16* shm, float* rs, float* rs_nxt, float* racc_) {
;     ...
;     LDB(B1,0,1); BAR; WAIT_L(0); MMA(0,1,At,B1); BAR;
;     LDA(At,0,1); WAIT_V(4); BAR; WAIT_L(0); MMA(1,0,At,B0); MMA(1,1,At,B1); BAR; }
;   { LDB(B0,1,0); LDA(At,1,0); WAIT_V(2); BAR; WAIT_L(0); MMA(0,0,At,B0); BAR;
	s_waitcnt lgkmcnt(0)
	v_mfma_f32_16x16x32_bf16 v[86:89], v[106:109], v[198:201], v[86:89]
	v_mfma_f32_16x16x32_bf16 v[82:85], v[230:233], v[198:201], v[82:85]
	v_mfma_f32_16x16x32_bf16 v[70:73], v[106:109], v[214:217], v[70:73]
	v_mfma_f32_16x16x32_bf16 v[66:69], v[230:233], v[214:217], v[66:69]
	v_mfma_f32_16x16x32_bf16 v[94:97], v[106:109], v[190:193], v[94:97]
	v_mfma_f32_16x16x32_bf16 v[90:93], v[230:233], v[190:193], v[90:93]
	v_mfma_f32_16x16x32_bf16 v[86:89], v[110:113], v[202:205], v[86:89]
	v_mfma_f32_16x16x32_bf16 v[82:85], v[154:157], v[202:205], v[82:85]
	v_mfma_f32_16x16x32_bf16 v[78:81], v[106:109], v[206:209], v[78:81]
	v_mfma_f32_16x16x32_bf16 v[74:77], v[230:233], v[206:209], v[74:77]
	v_mfma_f32_16x16x32_bf16 v[70:73], v[110:113], v[218:221], v[70:73]
	v_mfma_f32_16x16x32_bf16 v[66:69], v[154:157], v[218:221], v[66:69]
	v_mfma_f32_16x16x32_bf16 v[234:237], v[110:113], v[194:197], v[94:97]
	v_mfma_f32_16x16x32_bf16 v[190:193], v[154:157], v[194:197], v[90:93]
	v_mfma_f32_16x16x32_bf16 v[194:197], v[110:113], v[210:213], v[78:81]
	v_mfma_f32_16x16x32_bf16 v[198:201], v[154:157], v[210:213], v[74:77]
	s_barrier
	s_nop 0
	ds_read_b128 v[74:77], v150 offset:16384
	ds_read_b128 v[78:81], v150 offset:17408
	ds_read_b128 v[90:93], v149 offset:16384
	ds_read_b128 v[94:97], v149 offset:17408
	ds_read_b128 v[202:205], v148 offset:16384
	ds_read_b128 v[206:209], v148 offset:17408
	ds_read_b128 v[210:213], v147 offset:16384
	ds_read_b128 v[214:217], v147 offset:17408
	s_waitcnt vmcnt(4)
	s_barrier
	s_waitcnt lgkmcnt(0)
	v_mfma_f32_16x16x32_bf16 v[62:65], v[132:135], v[74:77], v[62:65]
	v_mfma_f32_16x16x32_bf16 v[58:61], v[172:175], v[74:77], v[58:61]
	v_mfma_f32_16x16x32_bf16 v[54:57], v[132:135], v[90:93], v[54:57]
	v_mfma_f32_16x16x32_bf16 v[50:53], v[172:175], v[90:93], v[50:53]
	v_mfma_f32_16x16x32_bf16 v[38:41], v[132:135], v[210:213], v[38:41]
	v_mfma_f32_16x16x32_bf16 v[34:37], v[172:175], v[210:213], v[34:37]
	v_mfma_f32_16x16x32_bf16 v[62:65], v[136:139], v[78:81], v[62:65]
	v_mfma_f32_16x16x32_bf16 v[58:61], v[186:189], v[78:81], v[58:61]
	v_mfma_f32_16x16x32_bf16 v[54:57], v[136:139], v[94:97], v[54:57]
	v_mfma_f32_16x16x32_bf16 v[50:53], v[186:189], v[94:97], v[50:53]
	v_mfma_f32_16x16x32_bf16 v[46:49], v[132:135], v[202:205], v[46:49]
	v_mfma_f32_16x16x32_bf16 v[42:45], v[172:175], v[202:205], v[42:45]
	v_mfma_f32_16x16x32_bf16 v[38:41], v[136:139], v[214:217], v[38:41]
	v_mfma_f32_16x16x32_bf16 v[34:37], v[186:189], v[214:217], v[34:37]
	v_mfma_f32_16x16x32_bf16 v[218:221], v[136:139], v[206:209], v[46:49]
	v_mfma_f32_16x16x32_bf16 v[238:241], v[186:189], v[206:209], v[42:45]
	v_mfma_f32_16x16x32_bf16 v[22:25], v[106:109], v[90:93], v[22:25]
	v_mfma_f32_16x16x32_bf16 v[18:21], v[230:233], v[90:93], v[18:21]
	v_mfma_f32_16x16x32_bf16 v[6:9], v[106:109], v[210:213], v[6:9]
	v_mfma_f32_16x16x32_bf16 v[2:5], v[230:233], v[210:213], v[2:5]
	v_mfma_f32_16x16x32_bf16 v[30:33], v[106:109], v[74:77], v[30:33]
	v_mfma_f32_16x16x32_bf16 v[26:29], v[230:233], v[74:77], v[26:29]
	v_mfma_f32_16x16x32_bf16 v[22:25], v[110:113], v[94:97], v[22:25]
	v_mfma_f32_16x16x32_bf16 v[18:21], v[154:157], v[94:97], v[18:21]
	v_mfma_f32_16x16x32_bf16 v[14:17], v[106:109], v[202:205], v[14:17]
	v_mfma_f32_16x16x32_bf16 v[10:13], v[230:233], v[202:205], v[10:13]
	v_mfma_f32_16x16x32_bf16 v[6:9], v[110:113], v[214:217], v[6:9]
	v_mfma_f32_16x16x32_bf16 v[2:5], v[154:157], v[214:217], v[2:5]
	v_mfma_f32_16x16x32_bf16 v[132:135], v[110:113], v[78:81], v[30:33]
	v_mfma_f32_16x16x32_bf16 v[136:139], v[154:157], v[78:81], v[26:29]
	v_mfma_f32_16x16x32_bf16 v[170:173], v[110:113], v[206:209], v[14:17]
	v_mfma_f32_16x16x32_bf16 v[186:189], v[154:157], v[206:209], v[10:13]
	s_barrier
	s_nop 0
	ds_read_b128 v[10:13], v153
	ds_read_b128 v[14:17], v153 offset:1024
	ds_read_b128 v[154:157], v153 offset:2048
	ds_read_b128 v[202:205], v153 offset:3072
	ds_read_b128 v[26:29], v150 offset:32768
	ds_read_b128 v[30:33], v150 offset:33792
	ds_read_b128 v[42:45], v149 offset:32768
	ds_read_b128 v[46:49], v149 offset:33792
	ds_read_b128 v[206:209], v148 offset:32768
	ds_read_b128 v[210:213], v148 offset:33792
	ds_read_b128 v[214:217], v147 offset:32768
	ds_read_b128 v[230:233], v147 offset:33792
	s_waitcnt vmcnt(2)
	s_barrier
; #define LDA(dst,b,h) for(int m=0;m<4;++m)for(int k=0;k<2;++k) \
;     dst[m][k]=*reinterpret_cast<const bf16x8*>((char*)SA(b,h)+lds_byte(wr*64+m*16+fr,k*32+fq*8))
; #define LDB(dst,b,h) for(int n=0;n<2;++n)for(int k=0;k<2;++k) \
;     dst[n][k]=*reinterpret_cast<const bf16x8*>((char*)SB(b,h)+lds_byte(wc*32+n*16+fr,k*32+fq*8))
; #define MMA(ai,bj,At,Bt_) do{__builtin_amdgcn_s_setprio(1); \
;     for(int m=0;m<4;++m)for(int n=0;n<2;++n)for(int k=0;k<2;++k) \
;       acc[ai][bj][m][n]=__builtin_amdgcn_mfma_f32_16x16x32_bf16(Bt_[n][k],At[m][k],acc[ai][bj][m][n],0,0,0); \
;     __builtin_amdgcn_s_setprio(0);}while(0)
; #define WAIT_V(n) asm volatile("s_waitcnt vmcnt(" #n ")":::"memory")
; #define WAIT_L(n) asm volatile("s_waitcnt lgkmcnt(" #n ")":::"memory")
; #define BAR __builtin_amdgcn_s_barrier()
; template <int EPI>
; __device__ __forceinline__ void gemm_run(const GD& c, const bool has_next, const GD& nx, const Ctx& e, bf16* shm, float* rs, float* rs_nxt, float* racc_) {
;     ...
;   { LDB(B0,1,0); LDA(At,1,0); WAIT_V(2); BAR; WAIT_L(0); MMA(0,0,At,B0); BAR;
;     LDB(B1,1,1); WAIT_V(0); BAR; WAIT_L(0); MMA(0,1,At,B1); BAR;
;     LDA(At,1,1); BAR; WAIT_L(0); MMA(1,0,At,B0); MMA(1,1,At,B1); BAR; }
;   if(wr==0)BAR;
	s_waitcnt lgkmcnt(0)
	v_mfma_f32_16x16x32_bf16 v[74:77], v[10:13], v[26:29], v[126:129]
	v_mfma_f32_16x16x32_bf16 v[126:129], v[14:17], v[30:33], v[74:77]
	v_mfma_f32_16x16x32_bf16 v[74:77], v[154:157], v[26:29], v[122:125]
	v_mfma_f32_16x16x32_bf16 v[122:125], v[202:205], v[30:33], v[74:77]
	v_mfma_f32_16x16x32_bf16 v[74:77], v[10:13], v[42:45], v[118:121]
	v_mfma_f32_16x16x32_bf16 v[110:113], v[14:17], v[46:49], v[74:77]
	v_mfma_f32_16x16x32_bf16 v[74:77], v[154:157], v[42:45], v[114:117]
	v_mfma_f32_16x16x32_bf16 v[106:109], v[202:205], v[46:49], v[74:77]
	v_mfma_f32_16x16x32_bf16 v[74:77], v[10:13], v[206:209], v[222:225]
	v_mfma_f32_16x16x32_bf16 v[94:97], v[14:17], v[210:213], v[74:77]
	v_mfma_f32_16x16x32_bf16 v[74:77], v[154:157], v[206:209], v[226:229]
	v_mfma_f32_16x16x32_bf16 v[90:93], v[202:205], v[210:213], v[74:77]
	v_mfma_f32_16x16x32_bf16 v[74:77], v[10:13], v[214:217], v[102:105]
	v_mfma_f32_16x16x32_bf16 v[78:81], v[14:17], v[230:233], v[74:77]
	v_mfma_f32_16x16x32_bf16 v[74:77], v[154:157], v[214:217], v[98:101]
	v_mfma_f32_16x16x32_bf16 v[74:77], v[202:205], v[230:233], v[74:77]
	s_barrier
	ds_read_b128 v[222:225], v151
	ds_read_b128 v[226:229], v151 offset:1024
	ds_read_b128 v[242:245], v151 offset:2048
	ds_read_b128 v[246:249], v151 offset:3072
	s_waitcnt vmcnt(0)
	s_barrier
	s_waitcnt lgkmcnt(0)
	v_mfma_f32_16x16x32_bf16 v[98:101], v[222:225], v[26:29], v[234:237]
	v_mfma_f32_16x16x32_bf16 v[26:29], v[242:245], v[26:29], v[190:193]
	v_mfma_f32_16x16x32_bf16 v[114:117], v[246:249], v[30:33], v[26:29]
	v_mfma_f32_16x16x32_bf16 v[26:29], v[222:225], v[42:45], v[86:89]
	v_mfma_f32_16x16x32_bf16 v[102:105], v[226:229], v[46:49], v[26:29]
	v_mfma_f32_16x16x32_bf16 v[26:29], v[242:245], v[42:45], v[82:85]
	v_mfma_f32_16x16x32_bf16 v[118:121], v[226:229], v[30:33], v[98:101]
	v_mfma_f32_16x16x32_bf16 v[98:101], v[246:249], v[46:49], v[26:29]
	v_mfma_f32_16x16x32_bf16 v[26:29], v[222:225], v[206:209], v[194:197]
	v_mfma_f32_16x16x32_bf16 v[86:89], v[226:229], v[210:213], v[26:29]
	v_mfma_f32_16x16x32_bf16 v[26:29], v[242:245], v[206:209], v[198:201]
	v_mfma_f32_16x16x32_bf16 v[82:85], v[246:249], v[210:213], v[26:29]
	v_mfma_f32_16x16x32_bf16 v[26:29], v[222:225], v[214:217], v[70:73]
	v_mfma_f32_16x16x32_bf16 v[70:73], v[226:229], v[230:233], v[26:29]
	v_mfma_f32_16x16x32_bf16 v[26:29], v[242:245], v[214:217], v[66:69]
	v_mfma_f32_16x16x32_bf16 v[66:69], v[246:249], v[230:233], v[26:29]
	s_barrier
	ds_read_b128 v[190:193], v150 offset:49152
	ds_read_b128 v[150:153], v150 offset:50176
	ds_read_b128 v[194:197], v149 offset:49152
	ds_read_b128 v[198:201], v149 offset:50176
	ds_read_b128 v[206:209], v148 offset:49152
	ds_read_b128 v[210:213], v148 offset:50176
	ds_read_b128 v[214:217], v147 offset:49152
	ds_read_b128 v[230:233], v147 offset:50176
	s_barrier
	s_waitcnt lgkmcnt(0)
	v_mfma_f32_16x16x32_bf16 v[26:29], v[10:13], v[190:193], v[62:65]
	v_mfma_f32_16x16x32_bf16 v[62:65], v[14:17], v[150:153], v[26:29]
	v_mfma_f32_16x16x32_bf16 v[26:29], v[154:157], v[190:193], v[58:61]
	v_mfma_f32_16x16x32_bf16 v[58:61], v[202:205], v[150:153], v[26:29]
	v_mfma_f32_16x16x32_bf16 v[26:29], v[10:13], v[194:197], v[54:57]
	v_mfma_f32_16x16x32_bf16 v[46:49], v[14:17], v[198:201], v[26:29]
	v_mfma_f32_16x16x32_bf16 v[26:29], v[154:157], v[194:197], v[50:53]
	v_mfma_f32_16x16x32_bf16 v[42:45], v[202:205], v[198:201], v[26:29]
	v_mfma_f32_16x16x32_bf16 v[26:29], v[10:13], v[206:209], v[218:221]
	v_mfma_f32_16x16x32_bf16 v[10:13], v[10:13], v[214:217], v[38:41]
	v_mfma_f32_16x16x32_bf16 v[30:33], v[14:17], v[210:213], v[26:29]
	v_mfma_f32_16x16x32_bf16 v[26:29], v[154:157], v[206:209], v[238:241]
	v_mfma_f32_16x16x32_bf16 v[14:17], v[14:17], v[230:233], v[10:13]
	v_mfma_f32_16x16x32_bf16 v[10:13], v[154:157], v[214:217], v[34:37]
	v_mfma_f32_16x16x32_bf16 v[26:29], v[202:205], v[210:213], v[26:29]
	v_mfma_f32_16x16x32_bf16 v[10:13], v[202:205], v[230:233], v[10:13]
	v_mfma_f32_16x16x32_bf16 v[34:37], v[222:225], v[190:193], v[132:135]
	v_mfma_f32_16x16x32_bf16 v[54:57], v[226:229], v[150:153], v[34:37]
	v_mfma_f32_16x16x32_bf16 v[34:37], v[242:245], v[190:193], v[136:139]
	v_mfma_f32_16x16x32_bf16 v[18:21], v[242:245], v[194:197], v[18:21]
	v_mfma_f32_16x16x32_bf16 v[50:53], v[246:249], v[150:153], v[34:37]
	v_mfma_f32_16x16x32_bf16 v[22:25], v[222:225], v[194:197], v[22:25]
	v_mfma_f32_16x16x32_bf16 v[34:37], v[246:249], v[198:201], v[18:21]
	v_mfma_f32_16x16x32_bf16 v[18:21], v[222:225], v[206:209], v[170:173]
	v_mfma_f32_16x16x32_bf16 v[38:41], v[226:229], v[198:201], v[22:25]
	v_mfma_f32_16x16x32_bf16 v[22:25], v[226:229], v[210:213], v[18:21]
	v_mfma_f32_16x16x32_bf16 v[18:21], v[242:245], v[206:209], v[186:189]
	v_mfma_f32_16x16x32_bf16 v[6:9], v[222:225], v[214:217], v[6:9]
	v_mfma_f32_16x16x32_bf16 v[2:5], v[242:245], v[214:217], v[2:5]
	v_mfma_f32_16x16x32_bf16 v[18:21], v[246:249], v[210:213], v[18:21]
	v_mfma_f32_16x16x32_bf16 v[6:9], v[226:229], v[230:233], v[6:9]
	v_mfma_f32_16x16x32_bf16 v[2:5], v[246:249], v[230:233], v[2:5]
	v_cmp_gt_u32_e32 vcc, s96, v142
	s_barrier
	s_and_saveexec_b64 s[2:3], vcc
	s_cbranch_execz .LBB0_983
	s_barrier

; #define STAGE_A(P,br,kt) STAGE_G(P,c.A,c.lda,br,(long)(kt)*c.kstr)
; #define STAGE_B(P,br,kt) STAGE_G(P,c.Bt,c.K,br,(long)(kt)*BK)
; #define LDA(dst,b,h) for(int m=0;m<4;++m)for(int k=0;k<2;++k) \
;     dst[m][k]=*reinterpret_cast<const bf16x8*>((char*)SA(b,h)+lds_byte(wr*64+m*16+fr,k*32+fq*8))
; #define LDB(dst,b,h) for(int n=0;n<2;++n)for(int k=0;k<2;++k) \
;     dst[n][k]=*reinterpret_cast<const bf16x8*>((char*)SB(b,h)+lds_byte(wc*32+n*16+fr,k*32+fq*8))
; #define MMA(ai,bj,At,Bt_) do{__builtin_amdgcn_s_setprio(1); \
;     for(int m=0;m<4;++m)for(int n=0;n<2;++n)for(int k=0;k<2;++k) \
;       acc[ai][bj][m][n]=__builtin_amdgcn_mfma_f32_16x16x32_bf16(Bt_[n][k],At[m][k],acc[ai][bj][m][n],0,0,0); \
;     __builtin_amdgcn_s_setprio(0);}while(0)
; #define WAIT_L(n) asm volatile("s_waitcnt lgkmcnt(" #n ")":::"memory")
; #define BAR __builtin_amdgcn_s_barrier()
; #define SCHED __builtin_amdgcn_sched_barrier(0)
; template <int EPI>
; __device__ __forceinline__ void gemm_run(const GD& c, const bool has_next, const GD& nx, const Ctx& e, bf16* shm, float* rs, float* rs_nxt, float* racc_) {
;     ...
;   for(int t=0;t<nt-2;t+=2){
;     LDB(B0,0,0); SCHED; LDA(At,0,0); STAGE_A(SA(1,1),brow+HALF,t+1);
;     WAIT_L(8); BAR; WAIT_L(0); MMA(0,0,At,B0); BAR; SCHED;
;     LDB(B1,0,1); STAGE_B(SB(0,0),bcol,t+2);
;     BAR; WAIT_L(0); MMA(0,1,At,B1); BAR;
;     LDA(At,0,1); STAGE_A(SA(0,0),brow,t+2);
;     BAR; WAIT_L(0); MMA(1,0,At,B0); BAR; SCHED;
.LBB0_1035:
	ds_read_b128 v[168:171], v155
	ds_read_b128 v[172:175], v155 offset:1024
	ds_read_b128 v[186:189], v155 offset:2048
	ds_read_b128 v[190:193], v155 offset:3072
	v_add_u32_e32 v163, 0xc000, v142
	v_lshl_add_u64 v[182:183], s[6:7], 0, v[132:133]
	v_readfirstlane_b32 s3, v163
	v_add_u32_e32 v166, 0xe000, v142
	v_lshl_add_u64 v[156:157], v[182:183], 0, s[28:29]
	s_mov_b32 m0, s3
	v_lshl_add_u64 v[242:243], s[6:7], 0, v[134:135]
	v_readfirstlane_b32 s3, v166
	ds_read_b128 v[158:161], v146
	ds_read_b128 v[194:197], v146 offset:1024
	ds_read_b128 v[198:201], v145
	ds_read_b128 v[202:205], v145 offset:1024
	ds_read_b128 v[206:209], v144
	ds_read_b128 v[210:213], v144 offset:1024
	ds_read_b128 v[214:217], v143
	ds_read_b128 v[218:221], v143 offset:1024
	global_load_lds_dwordx4 v[156:157], off
	v_lshl_add_u64 v[156:157], v[242:243], 0, s[28:29]
	s_mov_b32 m0, s3
	s_nop 0
	global_load_lds_dwordx4 v[156:157], off
	s_waitcnt lgkmcnt(8)
	s_barrier
	s_waitcnt lgkmcnt(0)
	v_mfma_f32_16x16x32_bf16 v[126:129], v[168:171], v[158:161], v[126:129]
	v_mfma_f32_16x16x32_bf16 v[122:125], v[186:189], v[158:161], v[122:125]
	v_mfma_f32_16x16x32_bf16 v[118:121], v[168:171], v[198:201], v[118:121]
	v_mfma_f32_16x16x32_bf16 v[114:117], v[186:189], v[198:201], v[114:117]
	v_mfma_f32_16x16x32_bf16 v[110:113], v[168:171], v[206:209], v[110:113]
	v_mfma_f32_16x16x32_bf16 v[106:109], v[186:189], v[206:209], v[106:109]
	v_mfma_f32_16x16x32_bf16 v[102:105], v[168:171], v[214:217], v[102:105]
	v_mfma_f32_16x16x32_bf16 v[98:101], v[186:189], v[214:217], v[98:101]
	v_mfma_f32_16x16x32_bf16 v[126:129], v[172:175], v[194:197], v[126:129]
	v_mfma_f32_16x16x32_bf16 v[122:125], v[190:193], v[194:197], v[122:125]
	v_mfma_f32_16x16x32_bf16 v[118:121], v[172:175], v[202:205], v[118:121]
	v_mfma_f32_16x16x32_bf16 v[114:117], v[190:193], v[202:205], v[114:117]
	v_mfma_f32_16x16x32_bf16 v[110:113], v[172:175], v[210:213], v[110:113]
	v_mfma_f32_16x16x32_bf16 v[106:109], v[190:193], v[210:213], v[106:109]
	v_mfma_f32_16x16x32_bf16 v[102:105], v[172:175], v[218:221], v[102:105]
	v_mfma_f32_16x16x32_bf16 v[98:101], v[190:193], v[218:221], v[98:101]
	s_barrier
	v_add_u32_e32 v156, s33, v148
	v_lshl_add_u64 v[244:245], s[6:7], 0, v[136:137]
	v_readfirstlane_b32 s3, v156
	v_add_u32_e32 v157, 0x2000, v156
	v_lshl_add_u64 v[238:239], v[244:245], 0, s[30:31]
	s_mov_b32 m0, s3
	v_lshl_add_u64 v[246:247], s[6:7], 0, v[138:139]
	v_readfirstlane_b32 s3, v157
	ds_read_b128 v[222:225], v154
	ds_read_b128 v[226:229], v154 offset:1024
	ds_read_b128 v[230:233], v154 offset:2048
	ds_read_b128 v[234:237], v154 offset:3072
	global_load_lds_dwordx4 v[238:239], off
	v_lshl_add_u64 v[238:239], v[246:247], 0, s[30:31]
	s_mov_b32 m0, s3
	s_nop 0
	global_load_lds_dwordx4 v[238:239], off
	s_barrier
	s_waitcnt lgkmcnt(0)
	v_mfma_f32_16x16x32_bf16 v[94:97], v[222:225], v[158:161], v[94:97]
	v_mfma_f32_16x16x32_bf16 v[90:93], v[230:233], v[158:161], v[90:93]
	v_mfma_f32_16x16x32_bf16 v[86:89], v[222:225], v[198:201], v[86:89]
	v_mfma_f32_16x16x32_bf16 v[82:85], v[230:233], v[198:201], v[82:85]
	v_mfma_f32_16x16x32_bf16 v[78:81], v[222:225], v[206:209], v[78:81]
	v_mfma_f32_16x16x32_bf16 v[74:77], v[230:233], v[206:209], v[74:77]
	v_mfma_f32_16x16x32_bf16 v[70:73], v[222:225], v[214:217], v[70:73]
	v_mfma_f32_16x16x32_bf16 v[66:69], v[230:233], v[214:217], v[66:69]
	v_mfma_f32_16x16x32_bf16 v[94:97], v[226:229], v[194:197], v[94:97]
	v_mfma_f32_16x16x32_bf16 v[90:93], v[234:237], v[194:197], v[90:93]
	v_mfma_f32_16x16x32_bf16 v[86:89], v[226:229], v[202:205], v[86:89]
	v_mfma_f32_16x16x32_bf16 v[82:85], v[234:237], v[202:205], v[82:85]
	v_mfma_f32_16x16x32_bf16 v[78:81], v[226:229], v[210:213], v[78:81]
	v_mfma_f32_16x16x32_bf16 v[74:77], v[234:237], v[210:213], v[74:77]
	v_mfma_f32_16x16x32_bf16 v[70:73], v[226:229], v[218:221], v[70:73]
	v_mfma_f32_16x16x32_bf16 v[66:69], v[234:237], v[218:221], v[66:69]
	v_readfirstlane_b32 s3, v142
	v_lshl_add_u64 v[158:159], v[182:183], 0, s[34:35]
	s_mov_b32 m0, s3
	s_barrier
	ds_read_b128 v[194:197], v146 offset:16384
	ds_read_b128 v[198:201], v146 offset:17408
	ds_read_b128 v[202:205], v145 offset:16384
	ds_read_b128 v[206:209], v145 offset:17408
	ds_read_b128 v[210:213], v144 offset:16384
	ds_read_b128 v[214:217], v144 offset:17408
	ds_read_b128 v[218:221], v143 offset:16384
	ds_read_b128 v[238:241], v143 offset:17408
	global_load_lds_dwordx4 v[158:159], off
	v_add_u32_e32 v158, 0x2000, v142
	v_lshl_add_u64 v[160:161], v[242:243], 0, s[34:35]
	v_readfirstlane_b32 s3, v158
	s_mov_b32 m0, s3
	s_nop 0
	global_load_lds_dwordx4 v[160:161], off
	s_barrier
	s_waitcnt lgkmcnt(0)
	v_mfma_f32_16x16x32_bf16 v[62:65], v[168:171], v[194:197], v[62:65]
	v_mfma_f32_16x16x32_bf16 v[58:61], v[186:189], v[194:197], v[58:61]
	v_mfma_f32_16x16x32_bf16 v[54:57], v[168:171], v[202:205], v[54:57]
	v_mfma_f32_16x16x32_bf16 v[50:53], v[186:189], v[202:205], v[50:53]
	v_mfma_f32_16x16x32_bf16 v[46:49], v[168:171], v[210:213], v[46:49]
	v_mfma_f32_16x16x32_bf16 v[42:45], v[186:189], v[210:213], v[42:45]
	v_mfma_f32_16x16x32_bf16 v[38:41], v[168:171], v[218:221], v[38:41]
	v_mfma_f32_16x16x32_bf16 v[34:37], v[186:189], v[218:221], v[34:37]
	v_mfma_f32_16x16x32_bf16 v[62:65], v[172:175], v[198:201], v[62:65]
	v_mfma_f32_16x16x32_bf16 v[58:61], v[190:193], v[198:201], v[58:61]
	v_mfma_f32_16x16x32_bf16 v[54:57], v[172:175], v[206:209], v[54:57]
	v_mfma_f32_16x16x32_bf16 v[50:53], v[190:193], v[206:209], v[50:53]
	v_mfma_f32_16x16x32_bf16 v[46:49], v[172:175], v[214:217], v[46:49]
	v_mfma_f32_16x16x32_bf16 v[42:45], v[190:193], v[214:217], v[42:45]
	v_mfma_f32_16x16x32_bf16 v[38:41], v[172:175], v[238:241], v[38:41]
	v_mfma_f32_16x16x32_bf16 v[34:37], v[190:193], v[238:241], v[34:37]
	s_barrier
; #define STAGE_A(P,br,kt) STAGE_G(P,c.A,c.lda,br,(long)(kt)*c.kstr)
; #define STAGE_B(P,br,kt) STAGE_G(P,c.Bt,c.K,br,(long)(kt)*BK)
; #define LDA(dst,b,h) for(int m=0;m<4;++m)for(int k=0;k<2;++k) \
;     dst[m][k]=*reinterpret_cast<const bf16x8*>((char*)SA(b,h)+lds_byte(wr*64+m*16+fr,k*32+fq*8))
; #define LDB(dst,b,h) for(int n=0;n<2;++n)for(int k=0;k<2;++k) \
;     dst[n][k]=*reinterpret_cast<const bf16x8*>((char*)SB(b,h)+lds_byte(wc*32+n*16+fr,k*32+fq*8))
; #define MMA(ai,bj,At,Bt_) do{__builtin_amdgcn_s_setprio(1); \
;     for(int m=0;m<4;++m)for(int n=0;n<2;++n)for(int k=0;k<2;++k) \
;       acc[ai][bj][m][n]=__builtin_amdgcn_mfma_f32_16x16x32_bf16(Bt_[n][k],At[m][k],acc[ai][bj][m][n],0,0,0); \
;     __builtin_amdgcn_s_setprio(0);}while(0)
; #define WAIT_V(n) asm volatile("s_waitcnt vmcnt(" #n ")":::"memory")
; #define WAIT_L(n) asm volatile("s_waitcnt lgkmcnt(" #n ")":::"memory")
; #define BAR __builtin_amdgcn_s_barrier()
; #define SCHED __builtin_amdgcn_sched_barrier(0)
; template <int EPI>
; __device__ __forceinline__ void gemm_run(const GD& c, const bool has_next, const GD& nx, const Ctx& e, bf16* shm, float* rs, float* rs_nxt, float* racc_) {
;     ...
;     STAGE_B(SB(0,1),bcol+HALF,t+2);
;     WAIT_V(6); BAR; MMA(1,1,At,B1); BAR;
;     LDB(B0,1,0); SCHED; LDA(At,1,0); STAGE_A(SA(0,1),brow+HALF,t+2);
;     WAIT_L(8); BAR; WAIT_L(0); MMA(0,0,At,B0); BAR; SCHED;
;     LDB(B1,1,1); STAGE_B(SB(1,0),bcol,t+3);
;     BAR; WAIT_L(0); MMA(0,1,At,B1); BAR;
;     LDA(At,1,1); STAGE_A(SA(1,0),brow,t+3);
	v_add_u32_e32 v159, s86, v148
	v_lshl_add_u64 v[160:161], v[244:245], 0, s[36:37]
	v_readfirstlane_b32 s3, v159
	s_mov_b32 m0, s3
	v_lshl_add_u64 v[168:169], v[246:247], 0, s[36:37]
	global_load_lds_dwordx4 v[160:161], off
	v_add_u32_e32 v160, 0x2000, v159
	s_nop 0
	v_readfirstlane_b32 s3, v160
	s_mov_b32 m0, s3
	s_nop 0
	global_load_lds_dwordx4 v[168:169], off
	s_waitcnt vmcnt(6)
	s_barrier
	v_mfma_f32_16x16x32_bf16 v[30:33], v[222:225], v[194:197], v[30:33]
	v_mfma_f32_16x16x32_bf16 v[26:29], v[230:233], v[194:197], v[26:29]
	v_mfma_f32_16x16x32_bf16 v[22:25], v[222:225], v[202:205], v[22:25]
	v_mfma_f32_16x16x32_bf16 v[18:21], v[230:233], v[202:205], v[18:21]
	v_mfma_f32_16x16x32_bf16 v[14:17], v[222:225], v[210:213], v[14:17]
	v_mfma_f32_16x16x32_bf16 v[10:13], v[230:233], v[210:213], v[10:13]
	v_mfma_f32_16x16x32_bf16 v[6:9], v[222:225], v[218:221], v[6:9]
	v_mfma_f32_16x16x32_bf16 v[2:5], v[230:233], v[218:221], v[2:5]
	v_mfma_f32_16x16x32_bf16 v[30:33], v[226:229], v[198:201], v[30:33]
	v_mfma_f32_16x16x32_bf16 v[26:29], v[234:237], v[198:201], v[26:29]
	v_mfma_f32_16x16x32_bf16 v[22:25], v[226:229], v[206:209], v[22:25]
	v_mfma_f32_16x16x32_bf16 v[18:21], v[234:237], v[206:209], v[18:21]
	v_mfma_f32_16x16x32_bf16 v[14:17], v[226:229], v[214:217], v[14:17]
	v_mfma_f32_16x16x32_bf16 v[10:13], v[234:237], v[214:217], v[10:13]
	v_mfma_f32_16x16x32_bf16 v[6:9], v[226:229], v[238:241], v[6:9]
	v_mfma_f32_16x16x32_bf16 v[2:5], v[234:237], v[238:241], v[2:5]
	s_barrier
	ds_read_b128 v[168:171], v149
	ds_read_b128 v[172:175], v149 offset:1024
	ds_read_b128 v[186:189], v149 offset:2048
	ds_read_b128 v[190:193], v149 offset:3072
	v_add_u32_e32 v161, 0x4000, v142
	v_add_u32_e32 v162, 0x6000, v142
	v_readfirstlane_b32 s3, v161
	v_lshl_add_u64 v[226:227], v[182:183], 0, s[38:39]
	s_mov_b32 m0, s3
	v_readfirstlane_b32 s3, v162
	ds_read_b128 v[194:197], v146 offset:32768
	ds_read_b128 v[198:201], v146 offset:33792
	ds_read_b128 v[202:205], v145 offset:32768
	ds_read_b128 v[206:209], v145 offset:33792
	ds_read_b128 v[210:213], v144 offset:32768
	ds_read_b128 v[214:217], v144 offset:33792
	ds_read_b128 v[218:221], v143 offset:32768
	ds_read_b128 v[222:225], v143 offset:33792
	global_load_lds_dwordx4 v[226:227], off
	v_lshl_add_u64 v[226:227], v[242:243], 0, s[38:39]
	s_mov_b32 m0, s3
	s_nop 0
	global_load_lds_dwordx4 v[226:227], off
	s_waitcnt lgkmcnt(8)
	s_barrier
	s_waitcnt lgkmcnt(0)
	v_mfma_f32_16x16x32_bf16 v[126:129], v[168:171], v[194:197], v[126:129]
	v_mfma_f32_16x16x32_bf16 v[122:125], v[186:189], v[194:197], v[122:125]
	v_mfma_f32_16x16x32_bf16 v[118:121], v[168:171], v[202:205], v[118:121]
	v_mfma_f32_16x16x32_bf16 v[114:117], v[186:189], v[202:205], v[114:117]
	v_mfma_f32_16x16x32_bf16 v[110:113], v[168:171], v[210:213], v[110:113]
	v_mfma_f32_16x16x32_bf16 v[106:109], v[186:189], v[210:213], v[106:109]
	v_mfma_f32_16x16x32_bf16 v[102:105], v[168:171], v[218:221], v[102:105]
	v_mfma_f32_16x16x32_bf16 v[98:101], v[186:189], v[218:221], v[98:101]
	v_mfma_f32_16x16x32_bf16 v[126:129], v[172:175], v[198:201], v[126:129]
	v_mfma_f32_16x16x32_bf16 v[122:125], v[190:193], v[198:201], v[122:125]
	v_mfma_f32_16x16x32_bf16 v[118:121], v[172:175], v[206:209], v[118:121]
	v_mfma_f32_16x16x32_bf16 v[114:117], v[190:193], v[206:209], v[114:117]
	v_mfma_f32_16x16x32_bf16 v[110:113], v[172:175], v[214:217], v[110:113]
	v_mfma_f32_16x16x32_bf16 v[106:109], v[190:193], v[214:217], v[106:109]
	v_mfma_f32_16x16x32_bf16 v[102:105], v[172:175], v[222:225], v[102:105]
	v_mfma_f32_16x16x32_bf16 v[98:101], v[190:193], v[222:225], v[98:101]
	s_barrier
	v_readfirstlane_b32 s3, v150
	v_add_u32_e32 v167, 0x2000, v150
	v_lshl_add_u64 v[248:249], v[244:245], 0, s[40:41]
	s_mov_b32 m0, s3
	v_readfirstlane_b32 s3, v167
	ds_read_b128 v[226:229], v147
	ds_read_b128 v[230:233], v147 offset:1024
	ds_read_b128 v[234:237], v147 offset:2048
	ds_read_b128 v[238:241], v147 offset:3072
	global_load_lds_dwordx4 v[248:249], off
	v_lshl_add_u64 v[248:249], v[246:247], 0, s[40:41]
	s_mov_b32 m0, s3
	s_nop 0
	global_load_lds_dwordx4 v[248:249], off
	s_barrier
	s_waitcnt lgkmcnt(0)
	v_mfma_f32_16x16x32_bf16 v[94:97], v[226:229], v[194:197], v[94:97]
	v_mfma_f32_16x16x32_bf16 v[90:93], v[234:237], v[194:197], v[90:93]
	v_mfma_f32_16x16x32_bf16 v[86:89], v[226:229], v[202:205], v[86:89]
	v_mfma_f32_16x16x32_bf16 v[82:85], v[234:237], v[202:205], v[82:85]
	v_mfma_f32_16x16x32_bf16 v[78:81], v[226:229], v[210:213], v[78:81]
	v_mfma_f32_16x16x32_bf16 v[74:77], v[234:237], v[210:213], v[74:77]
	v_mfma_f32_16x16x32_bf16 v[70:73], v[226:229], v[218:221], v[70:73]
	v_mfma_f32_16x16x32_bf16 v[66:69], v[234:237], v[218:221], v[66:69]
	v_mfma_f32_16x16x32_bf16 v[94:97], v[230:233], v[198:201], v[94:97]
	v_mfma_f32_16x16x32_bf16 v[90:93], v[238:241], v[198:201], v[90:93]
	v_mfma_f32_16x16x32_bf16 v[86:89], v[230:233], v[206:209], v[86:89]
	v_mfma_f32_16x16x32_bf16 v[82:85], v[238:241], v[206:209], v[82:85]
	v_mfma_f32_16x16x32_bf16 v[78:81], v[230:233], v[214:217], v[78:81]
	v_mfma_f32_16x16x32_bf16 v[74:77], v[238:241], v[214:217], v[74:77]
	v_mfma_f32_16x16x32_bf16 v[70:73], v[230:233], v[222:225], v[70:73]
	v_mfma_f32_16x16x32_bf16 v[66:69], v[238:241], v[222:225], v[66:69]
	s_barrier
	v_readfirstlane_b32 s3, v151
	v_lshl_add_u64 v[182:183], v[182:183], 0, s[42:43]
	s_mov_b32 m0, s3
	v_readfirstlane_b32 s3, v152
	ds_read_b128 v[194:197], v146 offset:49152
	ds_read_b128 v[198:201], v146 offset:50176
	ds_read_b128 v[202:205], v145 offset:49152
	ds_read_b128 v[206:209], v145 offset:50176
	ds_read_b128 v[210:213], v144 offset:49152
	ds_read_b128 v[214:217], v144 offset:50176
	ds_read_b128 v[218:221], v143 offset:49152
	ds_read_b128 v[222:225], v143 offset:50176
	global_load_lds_dwordx4 v[182:183], off
	v_lshl_add_u64 v[182:183], v[242:243], 0, s[42:43]
	s_mov_b32 m0, s3
	s_nop 0
	global_load_lds_dwordx4 v[182:183], off
	s_barrier
; #define STAGE_A(P,br,kt) STAGE_G(P,c.A,c.lda,br,(long)(kt)*c.kstr)
; #define STAGE_B(P,br,kt) STAGE_G(P,c.Bt,c.K,br,(long)(kt)*BK)
; #define LDA(dst,b,h) for(int m=0;m<4;++m)for(int k=0;k<2;++k) \
;     dst[m][k]=*reinterpret_cast<const bf16x8*>((char*)SA(b,h)+lds_byte(wr*64+m*16+fr,k*32+fq*8))
; #define LDB(dst,b,h) for(int n=0;n<2;++n)for(int k=0;k<2;++k) \
;     dst[n][k]=*reinterpret_cast<const bf16x8*>((char*)SB(b,h)+lds_byte(wc*32+n*16+fr,k*32+fq*8))
; #define MMA(ai,bj,At,Bt_) do{__builtin_amdgcn_s_setprio(1); \
;     for(int m=0;m<4;++m)for(int n=0;n<2;++n)for(int k=0;k<2;++k) \
;       acc[ai][bj][m][n]=__builtin_amdgcn_mfma_f32_16x16x32_bf16(Bt_[n][k],At[m][k],acc[ai][bj][m][n],0,0,0); \
;     __builtin_amdgcn_s_setprio(0);}while(0)
; #define WAIT_V(n) asm volatile("s_waitcnt vmcnt(" #n ")":::"memory")
; #define WAIT_L(n) asm volatile("s_waitcnt lgkmcnt(" #n ")":::"memory")
; #define BAR __builtin_amdgcn_s_barrier()
; #define SCHED __builtin_amdgcn_sched_barrier(0)
; template <int EPI>
; __device__ __forceinline__ void gemm_run(const GD& c, const bool has_next, const GD& nx, const Ctx& e, bf16* shm, float* rs, float* rs_nxt, float* racc_) {
;     ...
;     BAR; WAIT_L(0); MMA(1,0,At,B0); BAR; SCHED;
;     STAGE_B(SB(1,1),bcol+HALF,t+3);
;     WAIT_V(6); BAR; MMA(1,1,At,B1); BAR;
;   }
;   { LDB(B0,0,0); LDA(At,0,0); STAGE_A(SA(1,1),brow+HALF,nt-1);
;     BAR; WAIT_L(0); MMA(0,0,At,B0); BAR;
	s_waitcnt lgkmcnt(0)
	v_mfma_f32_16x16x32_bf16 v[62:65], v[168:171], v[194:197], v[62:65]
	v_mfma_f32_16x16x32_bf16 v[58:61], v[186:189], v[194:197], v[58:61]
	v_mfma_f32_16x16x32_bf16 v[54:57], v[168:171], v[202:205], v[54:57]
	v_mfma_f32_16x16x32_bf16 v[50:53], v[186:189], v[202:205], v[50:53]
	v_mfma_f32_16x16x32_bf16 v[46:49], v[168:171], v[210:213], v[46:49]
	v_mfma_f32_16x16x32_bf16 v[42:45], v[186:189], v[210:213], v[42:45]
	v_mfma_f32_16x16x32_bf16 v[38:41], v[168:171], v[218:221], v[38:41]
	v_mfma_f32_16x16x32_bf16 v[34:37], v[186:189], v[218:221], v[34:37]
	v_mfma_f32_16x16x32_bf16 v[62:65], v[172:175], v[198:201], v[62:65]
	v_mfma_f32_16x16x32_bf16 v[58:61], v[190:193], v[198:201], v[58:61]
	v_mfma_f32_16x16x32_bf16 v[54:57], v[172:175], v[206:209], v[54:57]
	v_mfma_f32_16x16x32_bf16 v[50:53], v[190:193], v[206:209], v[50:53]
	v_mfma_f32_16x16x32_bf16 v[46:49], v[172:175], v[214:217], v[46:49]
	v_mfma_f32_16x16x32_bf16 v[42:45], v[190:193], v[214:217], v[42:45]
	v_mfma_f32_16x16x32_bf16 v[38:41], v[172:175], v[222:225], v[38:41]
	v_mfma_f32_16x16x32_bf16 v[34:37], v[190:193], v[222:225], v[34:37]
	s_barrier
	v_readfirstlane_b32 s3, v153
	v_add_u32_e32 v167, 0x2000, v153
	v_lshl_add_u64 v[168:169], v[244:245], 0, s[44:45]
	s_mov_b32 m0, s3
	v_readfirstlane_b32 s3, v167
	global_load_lds_dwordx4 v[168:169], off
	v_lshl_add_u64 v[168:169], v[246:247], 0, s[44:45]
	s_mov_b32 m0, s3
	s_nop 0
	global_load_lds_dwordx4 v[168:169], off
	s_waitcnt vmcnt(6)
	s_barrier
	v_mfma_f32_16x16x32_bf16 v[30:33], v[226:229], v[194:197], v[30:33]
	v_mfma_f32_16x16x32_bf16 v[26:29], v[234:237], v[194:197], v[26:29]
	v_mfma_f32_16x16x32_bf16 v[22:25], v[226:229], v[202:205], v[22:25]
	v_mfma_f32_16x16x32_bf16 v[18:21], v[234:237], v[202:205], v[18:21]
	s_add_i32 s2, s2, 2
	v_mfma_f32_16x16x32_bf16 v[14:17], v[226:229], v[210:213], v[14:17]
	v_lshl_add_u64 v[132:133], v[132:133], 0, s[88:89]
	v_mfma_f32_16x16x32_bf16 v[10:13], v[234:237], v[210:213], v[10:13]
	v_lshl_add_u64 v[134:135], v[134:135], 0, s[88:89]
	v_mfma_f32_16x16x32_bf16 v[6:9], v[226:229], v[218:221], v[6:9]
	v_lshl_add_u64 v[136:137], v[136:137], 0, s[88:89]
	v_mfma_f32_16x16x32_bf16 v[2:5], v[234:237], v[218:221], v[2:5]
	s_cmp_lt_u32 s2, 12
	v_mfma_f32_16x16x32_bf16 v[30:33], v[230:233], v[198:201], v[30:33]
	v_lshl_add_u64 v[138:139], v[138:139], 0, s[88:89]
	v_mfma_f32_16x16x32_bf16 v[26:29], v[238:241], v[198:201], v[26:29]
	v_mfma_f32_16x16x32_bf16 v[22:25], v[230:233], v[206:209], v[22:25]
	v_mfma_f32_16x16x32_bf16 v[18:21], v[238:241], v[206:209], v[18:21]
	v_mfma_f32_16x16x32_bf16 v[14:17], v[230:233], v[214:217], v[14:17]
	v_mfma_f32_16x16x32_bf16 v[10:13], v[238:241], v[214:217], v[10:13]
	v_mfma_f32_16x16x32_bf16 v[6:9], v[230:233], v[222:225], v[6:9]
	v_mfma_f32_16x16x32_bf16 v[2:5], v[238:241], v[222:225], v[2:5]
	s_barrier
	s_cbranch_scc1 .LBB0_1035
	s_or_b32 s2, s14, 0x80
	s_ashr_i32 s3, s2, 31
	s_lshl_b64 s[2:3], s[2:3], 11
	s_add_u32 s2, s24, s2
	s_addc_u32 s3, s25, s3
	v_readfirstlane_b32 s5, v163
	v_lshl_add_u64 v[182:183], s[2:3], 0, v[0:1]
	s_mov_b32 m0, s5
	ds_read_b128 v[132:135], v155
	ds_read_b128 v[136:139], v155 offset:1024
	ds_read_b128 v[150:153], v155 offset:2048
	ds_read_b128 v[168:171], v155 offset:3072
	ds_read_b128 v[172:175], v146
	ds_read_b128 v[186:189], v146 offset:1024
	ds_read_b128 v[190:193], v145
	ds_read_b128 v[194:197], v145 offset:1024
	ds_read_b128 v[198:201], v144
	ds_read_b128 v[202:205], v144 offset:1024
	ds_read_b128 v[206:209], v143
	ds_read_b128 v[210:213], v143 offset:1024
	global_load_lds_dwordx4 v[182:183], off
	v_lshl_add_u64 v[182:183], s[2:3], 0, v[130:131]
	v_readfirstlane_b32 s2, v166
	s_mov_b32 m0, s2
	s_nop 0
	global_load_lds_dwordx4 v[182:183], off
	s_barrier
	s_waitcnt lgkmcnt(0)
	v_mfma_f32_16x16x32_bf16 v[126:129], v[132:135], v[172:175], v[126:129]
	v_mfma_f32_16x16x32_bf16 v[122:125], v[150:153], v[172:175], v[122:125]
	v_mfma_f32_16x16x32_bf16 v[118:121], v[132:135], v[190:193], v[118:121]
	v_mfma_f32_16x16x32_bf16 v[114:117], v[150:153], v[190:193], v[114:117]
	v_mfma_f32_16x16x32_bf16 v[102:105], v[132:135], v[206:209], v[102:105]
	v_mfma_f32_16x16x32_bf16 v[98:101], v[150:153], v[206:209], v[98:101]
	v_mfma_f32_16x16x32_bf16 v[126:129], v[136:139], v[186:189], v[126:129]
	v_mfma_f32_16x16x32_bf16 v[122:125], v[168:171], v[186:189], v[122:125]
	v_mfma_f32_16x16x32_bf16 v[118:121], v[136:139], v[194:197], v[118:121]
	v_mfma_f32_16x16x32_bf16 v[114:117], v[168:171], v[194:197], v[114:117]
	v_mfma_f32_16x16x32_bf16 v[110:113], v[132:135], v[198:201], v[110:113]
	v_mfma_f32_16x16x32_bf16 v[106:109], v[150:153], v[198:201], v[106:109]
	v_mfma_f32_16x16x32_bf16 v[102:105], v[136:139], v[210:213], v[102:105]
	v_mfma_f32_16x16x32_bf16 v[98:101], v[168:171], v[210:213], v[98:101]
	v_mfma_f32_16x16x32_bf16 v[214:217], v[136:139], v[202:205], v[110:113]
	v_mfma_f32_16x16x32_bf16 v[218:221], v[168:171], v[202:205], v[106:109]
	s_barrier
	s_nop 1
	ds_read_b128 v[106:109], v154
	ds_read_b128 v[110:113], v154 offset:1024
	ds_read_b128 v[222:225], v154 offset:2048
	ds_read_b128 v[226:229], v154 offset:3072
	s_barrier
; #define LDA(dst,b,h) for(int m=0;m<4;++m)for(int k=0;k<2;++k) \
;     dst[m][k]=*reinterpret_cast<const bf16x8*>((char*)SA(b,h)+lds_byte(wr*64+m*16+fr,k*32+fq*8))
; #define LDB(dst,b,h) for(int n=0;n<2;++n)for(int k=0;k<2;++k) \
;     dst[n][k]=*reinterpret_cast<const bf16x8*>((char*)SB(b,h)+lds_byte(wc*32+n*16+fr,k*32+fq*8))
; #define MMA(ai,bj,At,Bt_) do{__builtin_amdgcn_s_setprio(1); \
;     for(int m=0;m<4;++m)for(int n=0;n<2;++n)for(int k=0;k<2;++k) \
;       acc[ai][bj][m][n]=__builtin_amdgcn_mfma_f32_16x16x32_bf16(Bt_[n][k],At[m][k],acc[ai][bj][m][n],0,0,0); \
;     __builtin_amdgcn_s_setprio(0);}while(0)
; #define WAIT_V(n) asm volatile("s_waitcnt vmcnt(" #n ")":::"memory")
; #define WAIT_L(n) asm volatile("s_waitcnt lgkmcnt(" #n ")":::"memory")
; #define BAR __builtin_amdgcn_s_barrier()
; template <int EPI>
; __device__ __forceinline__ void gemm_run(const GD& c, const bool has_next, const GD& nx, const Ctx& e, bf16* shm, float* rs, float* rs_nxt, float* racc_) {
;     ...
;     LDB(B1,0,1); BAR; WAIT_L(0); MMA(0,1,At,B1); BAR;
;     LDA(At,0,1); WAIT_V(4); BAR; WAIT_L(0); MMA(1,0,At,B0); MMA(1,1,At,B1); BAR; }
;   { LDB(B0,1,0); LDA(At,1,0); WAIT_V(2); BAR; WAIT_L(0); MMA(0,0,At,B0); BAR;
	s_waitcnt lgkmcnt(0)
	v_mfma_f32_16x16x32_bf16 v[86:89], v[106:109], v[190:193], v[86:89]
	v_mfma_f32_16x16x32_bf16 v[82:85], v[222:225], v[190:193], v[82:85]
	v_mfma_f32_16x16x32_bf16 v[70:73], v[106:109], v[206:209], v[70:73]
	v_mfma_f32_16x16x32_bf16 v[66:69], v[222:225], v[206:209], v[66:69]
	v_mfma_f32_16x16x32_bf16 v[94:97], v[106:109], v[172:175], v[94:97]
	v_mfma_f32_16x16x32_bf16 v[90:93], v[222:225], v[172:175], v[90:93]
	v_mfma_f32_16x16x32_bf16 v[86:89], v[110:113], v[194:197], v[86:89]
	v_mfma_f32_16x16x32_bf16 v[82:85], v[226:229], v[194:197], v[82:85]
	v_mfma_f32_16x16x32_bf16 v[78:81], v[106:109], v[198:201], v[78:81]
	v_mfma_f32_16x16x32_bf16 v[74:77], v[222:225], v[198:201], v[74:77]
	v_mfma_f32_16x16x32_bf16 v[70:73], v[110:113], v[210:213], v[70:73]
	v_mfma_f32_16x16x32_bf16 v[66:69], v[226:229], v[210:213], v[66:69]
	v_mfma_f32_16x16x32_bf16 v[230:233], v[110:113], v[186:189], v[94:97]
	v_mfma_f32_16x16x32_bf16 v[172:175], v[226:229], v[186:189], v[90:93]
	v_mfma_f32_16x16x32_bf16 v[186:189], v[110:113], v[202:205], v[78:81]
	v_mfma_f32_16x16x32_bf16 v[190:193], v[226:229], v[202:205], v[74:77]
	s_barrier
	s_nop 0
	ds_read_b128 v[74:77], v146 offset:16384
	ds_read_b128 v[78:81], v146 offset:17408
	ds_read_b128 v[90:93], v145 offset:16384
	ds_read_b128 v[94:97], v145 offset:17408
	ds_read_b128 v[194:197], v144 offset:16384
	ds_read_b128 v[198:201], v144 offset:17408
	ds_read_b128 v[202:205], v143 offset:16384
	ds_read_b128 v[206:209], v143 offset:17408
	s_waitcnt vmcnt(4)
	s_barrier
	s_waitcnt lgkmcnt(0)
	v_mfma_f32_16x16x32_bf16 v[62:65], v[132:135], v[74:77], v[62:65]
	v_mfma_f32_16x16x32_bf16 v[58:61], v[150:153], v[74:77], v[58:61]
	v_mfma_f32_16x16x32_bf16 v[54:57], v[132:135], v[90:93], v[54:57]
	v_mfma_f32_16x16x32_bf16 v[50:53], v[150:153], v[90:93], v[50:53]
	v_mfma_f32_16x16x32_bf16 v[38:41], v[132:135], v[202:205], v[38:41]
	v_mfma_f32_16x16x32_bf16 v[34:37], v[150:153], v[202:205], v[34:37]
	v_mfma_f32_16x16x32_bf16 v[62:65], v[136:139], v[78:81], v[62:65]
	v_mfma_f32_16x16x32_bf16 v[58:61], v[168:171], v[78:81], v[58:61]
	v_mfma_f32_16x16x32_bf16 v[54:57], v[136:139], v[94:97], v[54:57]
	v_mfma_f32_16x16x32_bf16 v[50:53], v[168:171], v[94:97], v[50:53]
	v_mfma_f32_16x16x32_bf16 v[46:49], v[132:135], v[194:197], v[46:49]
	v_mfma_f32_16x16x32_bf16 v[42:45], v[150:153], v[194:197], v[42:45]
	v_mfma_f32_16x16x32_bf16 v[38:41], v[136:139], v[206:209], v[38:41]
	v_mfma_f32_16x16x32_bf16 v[34:37], v[168:171], v[206:209], v[34:37]
	v_mfma_f32_16x16x32_bf16 v[210:213], v[136:139], v[198:201], v[46:49]
	v_mfma_f32_16x16x32_bf16 v[234:237], v[168:171], v[198:201], v[42:45]
	v_mfma_f32_16x16x32_bf16 v[22:25], v[106:109], v[90:93], v[22:25]
	v_mfma_f32_16x16x32_bf16 v[18:21], v[222:225], v[90:93], v[18:21]
	v_mfma_f32_16x16x32_bf16 v[6:9], v[106:109], v[202:205], v[6:9]
	v_mfma_f32_16x16x32_bf16 v[2:5], v[222:225], v[202:205], v[2:5]
	v_mfma_f32_16x16x32_bf16 v[30:33], v[106:109], v[74:77], v[30:33]
	v_mfma_f32_16x16x32_bf16 v[26:29], v[222:225], v[74:77], v[26:29]
	v_mfma_f32_16x16x32_bf16 v[22:25], v[110:113], v[94:97], v[22:25]
	v_mfma_f32_16x16x32_bf16 v[18:21], v[226:229], v[94:97], v[18:21]
	v_mfma_f32_16x16x32_bf16 v[14:17], v[106:109], v[194:197], v[14:17]
	v_mfma_f32_16x16x32_bf16 v[10:13], v[222:225], v[194:197], v[10:13]
	v_mfma_f32_16x16x32_bf16 v[6:9], v[110:113], v[206:209], v[6:9]
	v_mfma_f32_16x16x32_bf16 v[2:5], v[226:229], v[206:209], v[2:5]
	v_mfma_f32_16x16x32_bf16 v[132:135], v[110:113], v[78:81], v[30:33]
	v_mfma_f32_16x16x32_bf16 v[136:139], v[226:229], v[78:81], v[26:29]
	v_mfma_f32_16x16x32_bf16 v[150:153], v[110:113], v[198:201], v[14:17]
	v_mfma_f32_16x16x32_bf16 v[166:169], v[226:229], v[198:201], v[10:13]
	s_barrier
	s_nop 0
	ds_read_b128 v[10:13], v149
	ds_read_b128 v[14:17], v149 offset:1024
	ds_read_b128 v[194:197], v149 offset:2048
	ds_read_b128 v[198:201], v149 offset:3072
	ds_read_b128 v[26:29], v146 offset:32768
	ds_read_b128 v[30:33], v146 offset:33792
	ds_read_b128 v[42:45], v145 offset:32768
	ds_read_b128 v[46:49], v145 offset:33792
	ds_read_b128 v[202:205], v144 offset:32768
	ds_read_b128 v[206:209], v144 offset:33792
	ds_read_b128 v[222:225], v143 offset:32768
	ds_read_b128 v[226:229], v143 offset:33792
	s_waitcnt vmcnt(2)
	s_barrier
; #define LDA(dst,b,h) for(int m=0;m<4;++m)for(int k=0;k<2;++k) \
;     dst[m][k]=*reinterpret_cast<const bf16x8*>((char*)SA(b,h)+lds_byte(wr*64+m*16+fr,k*32+fq*8))
; #define LDB(dst,b,h) for(int n=0;n<2;++n)for(int k=0;k<2;++k) \
;     dst[n][k]=*reinterpret_cast<const bf16x8*>((char*)SB(b,h)+lds_byte(wc*32+n*16+fr,k*32+fq*8))
; #define MMA(ai,bj,At,Bt_) do{__builtin_amdgcn_s_setprio(1); \
;     for(int m=0;m<4;++m)for(int n=0;n<2;++n)for(int k=0;k<2;++k) \
;       acc[ai][bj][m][n]=__builtin_amdgcn_mfma_f32_16x16x32_bf16(Bt_[n][k],At[m][k],acc[ai][bj][m][n],0,0,0); \
;     __builtin_amdgcn_s_setprio(0);}while(0)
; #define WAIT_V(n) asm volatile("s_waitcnt vmcnt(" #n ")":::"memory")
; #define WAIT_L(n) asm volatile("s_waitcnt lgkmcnt(" #n ")":::"memory")
; #define BAR __builtin_amdgcn_s_barrier()
; template <int EPI>
; __device__ __forceinline__ void gemm_run(const GD& c, const bool has_next, const GD& nx, const Ctx& e, bf16* shm, float* rs, float* rs_nxt, float* racc_) {
;     ...
;   { LDB(B0,1,0); LDA(At,1,0); WAIT_V(2); BAR; WAIT_L(0); MMA(0,0,At,B0); BAR;
;     LDB(B1,1,1); WAIT_V(0); BAR; WAIT_L(0); MMA(0,1,At,B1); BAR;
;     LDA(At,1,1); BAR; WAIT_L(0); MMA(1,0,At,B0); MMA(1,1,At,B1); BAR; }
;   if(wr==0)BAR;
	s_waitcnt lgkmcnt(0)
	v_mfma_f32_16x16x32_bf16 v[74:77], v[10:13], v[26:29], v[126:129]
	v_mfma_f32_16x16x32_bf16 v[126:129], v[14:17], v[30:33], v[74:77]
	v_mfma_f32_16x16x32_bf16 v[74:77], v[194:197], v[26:29], v[122:125]
	v_mfma_f32_16x16x32_bf16 v[122:125], v[198:201], v[30:33], v[74:77]
	v_mfma_f32_16x16x32_bf16 v[74:77], v[10:13], v[42:45], v[118:121]
	v_mfma_f32_16x16x32_bf16 v[110:113], v[14:17], v[46:49], v[74:77]
	v_mfma_f32_16x16x32_bf16 v[74:77], v[194:197], v[42:45], v[114:117]
	v_mfma_f32_16x16x32_bf16 v[106:109], v[198:201], v[46:49], v[74:77]
	v_mfma_f32_16x16x32_bf16 v[74:77], v[10:13], v[202:205], v[214:217]
	v_mfma_f32_16x16x32_bf16 v[94:97], v[14:17], v[206:209], v[74:77]
	v_mfma_f32_16x16x32_bf16 v[74:77], v[194:197], v[202:205], v[218:221]
	v_mfma_f32_16x16x32_bf16 v[90:93], v[198:201], v[206:209], v[74:77]
	v_mfma_f32_16x16x32_bf16 v[74:77], v[10:13], v[222:225], v[102:105]
	v_mfma_f32_16x16x32_bf16 v[78:81], v[14:17], v[226:229], v[74:77]
	v_mfma_f32_16x16x32_bf16 v[74:77], v[194:197], v[222:225], v[98:101]
	v_mfma_f32_16x16x32_bf16 v[74:77], v[198:201], v[226:229], v[74:77]
	s_barrier
	ds_read_b128 v[214:217], v147
	ds_read_b128 v[218:221], v147 offset:1024
	ds_read_b128 v[238:241], v147 offset:2048
	ds_read_b128 v[242:245], v147 offset:3072
	s_waitcnt vmcnt(0)
	s_barrier
	s_waitcnt lgkmcnt(0)
	v_mfma_f32_16x16x32_bf16 v[98:101], v[214:217], v[26:29], v[230:233]
	v_mfma_f32_16x16x32_bf16 v[26:29], v[238:241], v[26:29], v[172:175]
	v_mfma_f32_16x16x32_bf16 v[114:117], v[242:245], v[30:33], v[26:29]
	v_mfma_f32_16x16x32_bf16 v[26:29], v[214:217], v[42:45], v[86:89]
	v_mfma_f32_16x16x32_bf16 v[102:105], v[218:221], v[46:49], v[26:29]
	v_mfma_f32_16x16x32_bf16 v[26:29], v[238:241], v[42:45], v[82:85]
	v_mfma_f32_16x16x32_bf16 v[118:121], v[218:221], v[30:33], v[98:101]
	v_mfma_f32_16x16x32_bf16 v[98:101], v[242:245], v[46:49], v[26:29]
	v_mfma_f32_16x16x32_bf16 v[26:29], v[214:217], v[202:205], v[186:189]
	v_mfma_f32_16x16x32_bf16 v[86:89], v[218:221], v[206:209], v[26:29]
	v_mfma_f32_16x16x32_bf16 v[26:29], v[238:241], v[202:205], v[190:193]
	v_mfma_f32_16x16x32_bf16 v[82:85], v[242:245], v[206:209], v[26:29]
	v_mfma_f32_16x16x32_bf16 v[26:29], v[214:217], v[222:225], v[70:73]
	v_mfma_f32_16x16x32_bf16 v[70:73], v[218:221], v[226:229], v[26:29]
	v_mfma_f32_16x16x32_bf16 v[26:29], v[238:241], v[222:225], v[66:69]
	v_mfma_f32_16x16x32_bf16 v[66:69], v[242:245], v[226:229], v[26:29]
	s_barrier
	ds_read_b128 v[170:173], v146 offset:49152
	ds_read_b128 v[146:149], v146 offset:50176
	ds_read_b128 v[186:189], v145 offset:49152
	ds_read_b128 v[190:193], v145 offset:50176
	ds_read_b128 v[202:205], v144 offset:49152
	ds_read_b128 v[206:209], v144 offset:50176
	ds_read_b128 v[222:225], v143 offset:49152
	ds_read_b128 v[226:229], v143 offset:50176
	s_barrier
	s_waitcnt lgkmcnt(0)
	v_mfma_f32_16x16x32_bf16 v[26:29], v[10:13], v[170:173], v[62:65]
	v_mfma_f32_16x16x32_bf16 v[62:65], v[14:17], v[146:149], v[26:29]
	v_mfma_f32_16x16x32_bf16 v[26:29], v[194:197], v[170:173], v[58:61]
	v_mfma_f32_16x16x32_bf16 v[58:61], v[198:201], v[146:149], v[26:29]
	v_mfma_f32_16x16x32_bf16 v[26:29], v[10:13], v[186:189], v[54:57]
	v_mfma_f32_16x16x32_bf16 v[46:49], v[14:17], v[190:193], v[26:29]
	v_mfma_f32_16x16x32_bf16 v[26:29], v[194:197], v[186:189], v[50:53]
	v_mfma_f32_16x16x32_bf16 v[42:45], v[198:201], v[190:193], v[26:29]
	v_mfma_f32_16x16x32_bf16 v[26:29], v[10:13], v[202:205], v[210:213]
	v_mfma_f32_16x16x32_bf16 v[10:13], v[10:13], v[222:225], v[38:41]
	v_mfma_f32_16x16x32_bf16 v[30:33], v[14:17], v[206:209], v[26:29]
	v_mfma_f32_16x16x32_bf16 v[26:29], v[194:197], v[202:205], v[234:237]
	v_mfma_f32_16x16x32_bf16 v[14:17], v[14:17], v[226:229], v[10:13]
	v_mfma_f32_16x16x32_bf16 v[10:13], v[194:197], v[222:225], v[34:37]
	v_mfma_f32_16x16x32_bf16 v[26:29], v[198:201], v[206:209], v[26:29]
	v_mfma_f32_16x16x32_bf16 v[10:13], v[198:201], v[226:229], v[10:13]
	v_mfma_f32_16x16x32_bf16 v[34:37], v[214:217], v[170:173], v[132:135]
	v_mfma_f32_16x16x32_bf16 v[54:57], v[218:221], v[146:149], v[34:37]
	v_mfma_f32_16x16x32_bf16 v[34:37], v[238:241], v[170:173], v[136:139]
	v_mfma_f32_16x16x32_bf16 v[18:21], v[238:241], v[186:189], v[18:21]
	v_mfma_f32_16x16x32_bf16 v[50:53], v[242:245], v[146:149], v[34:37]
	v_mfma_f32_16x16x32_bf16 v[22:25], v[214:217], v[186:189], v[22:25]
	v_mfma_f32_16x16x32_bf16 v[34:37], v[242:245], v[190:193], v[18:21]
	v_mfma_f32_16x16x32_bf16 v[18:21], v[214:217], v[202:205], v[150:153]
	v_mfma_f32_16x16x32_bf16 v[38:41], v[218:221], v[190:193], v[22:25]
	v_mfma_f32_16x16x32_bf16 v[22:25], v[218:221], v[206:209], v[18:21]
	v_mfma_f32_16x16x32_bf16 v[18:21], v[238:241], v[202:205], v[166:169]
	v_mfma_f32_16x16x32_bf16 v[6:9], v[214:217], v[222:225], v[6:9]
	v_mfma_f32_16x16x32_bf16 v[2:5], v[238:241], v[222:225], v[2:5]
	v_mfma_f32_16x16x32_bf16 v[18:21], v[242:245], v[206:209], v[18:21]
	v_mfma_f32_16x16x32_bf16 v[6:9], v[218:221], v[226:229], v[6:9]
	v_mfma_f32_16x16x32_bf16 v[2:5], v[242:245], v[226:229], v[2:5]
	v_cmp_gt_u32_e32 vcc, s96, v141
	s_barrier
	s_and_saveexec_b64 s[2:3], vcc
	s_cbranch_execz .LBB0_1038
	s_barrier

; #define STAGE_A(P,br,kt) STAGE_G(P,c.A,c.lda,br,(long)(kt)*c.kstr)
; #define STAGE_B(P,br,kt) STAGE_G(P,c.Bt,c.K,br,(long)(kt)*BK)
; #define LDA(dst,b,h) for(int m=0;m<4;++m)for(int k=0;k<2;++k) \
;     dst[m][k]=*reinterpret_cast<const bf16x8*>((char*)SA(b,h)+lds_byte(wr*64+m*16+fr,k*32+fq*8))
; #define LDB(dst,b,h) for(int n=0;n<2;++n)for(int k=0;k<2;++k) \
;     dst[n][k]=*reinterpret_cast<const bf16x8*>((char*)SB(b,h)+lds_byte(wc*32+n*16+fr,k*32+fq*8))
; #define MMA(ai,bj,At,Bt_) do{__builtin_amdgcn_s_setprio(1); \
;     for(int m=0;m<4;++m)for(int n=0;n<2;++n)for(int k=0;k<2;++k) \
;       acc[ai][bj][m][n]=__builtin_amdgcn_mfma_f32_16x16x32_bf16(Bt_[n][k],At[m][k],acc[ai][bj][m][n],0,0,0); \
;     __builtin_amdgcn_s_setprio(0);}while(0)
; #define WAIT_L(n) asm volatile("s_waitcnt lgkmcnt(" #n ")":::"memory")
; #define BAR __builtin_amdgcn_s_barrier()
; #define SCHED __builtin_amdgcn_sched_barrier(0)
; template <int EPI>
; __device__ __forceinline__ void gemm_run(const GD& c, const bool has_next, const GD& nx, const Ctx& e, bf16* shm, float* rs, float* rs_nxt, float* racc_) {
;     ...
;   for(int t=0;t<nt-2;t+=2){
;     LDB(B0,0,0); SCHED; LDA(At,0,0); STAGE_A(SA(1,1),brow+HALF,t+1);
;     WAIT_L(8); BAR; WAIT_L(0); MMA(0,0,At,B0); BAR; SCHED;
;     LDB(B1,0,1); STAGE_B(SB(0,0),bcol,t+2);
;     BAR; WAIT_L(0); MMA(0,1,At,B1); BAR;
;     LDA(At,0,1); STAGE_A(SA(0,0),brow,t+2);
;     BAR; WAIT_L(0); MMA(1,0,At,B0); BAR; SCHED;
.LBB0_1119:
	ds_read_b128 v[168:171], v155
	ds_read_b128 v[172:175], v155 offset:1024
	ds_read_b128 v[186:189], v155 offset:2048
	ds_read_b128 v[190:193], v155 offset:3072
	v_add_u32_e32 v163, 0xc000, v142
	v_lshl_add_u64 v[182:183], s[4:5], 0, v[130:131]
	v_readfirstlane_b32 s3, v163
	v_add_u32_e32 v166, 0xe000, v142
	v_lshl_add_u64 v[156:157], v[182:183], 0, s[94:95]
	s_mov_b32 m0, s3
	v_lshl_add_u64 v[242:243], s[4:5], 0, v[132:133]
	v_readfirstlane_b32 s3, v166
	ds_read_b128 v[158:161], v146
	ds_read_b128 v[194:197], v146 offset:1024
	ds_read_b128 v[198:201], v145
	ds_read_b128 v[202:205], v145 offset:1024
	ds_read_b128 v[206:209], v144
	ds_read_b128 v[210:213], v144 offset:1024
	ds_read_b128 v[214:217], v143
	ds_read_b128 v[218:221], v143 offset:1024
	global_load_lds_dwordx4 v[156:157], off
	v_lshl_add_u64 v[156:157], v[242:243], 0, s[94:95]
	s_mov_b32 m0, s3
	s_nop 0
	global_load_lds_dwordx4 v[156:157], off
	s_waitcnt lgkmcnt(8)
	s_barrier
	s_waitcnt lgkmcnt(0)
	v_mfma_f32_16x16x32_bf16 v[126:129], v[168:171], v[158:161], v[126:129]
	v_mfma_f32_16x16x32_bf16 v[122:125], v[186:189], v[158:161], v[122:125]
	v_mfma_f32_16x16x32_bf16 v[118:121], v[168:171], v[198:201], v[118:121]
	v_mfma_f32_16x16x32_bf16 v[114:117], v[186:189], v[198:201], v[114:117]
	v_mfma_f32_16x16x32_bf16 v[110:113], v[168:171], v[206:209], v[110:113]
	v_mfma_f32_16x16x32_bf16 v[106:109], v[186:189], v[206:209], v[106:109]
	v_mfma_f32_16x16x32_bf16 v[102:105], v[168:171], v[214:217], v[102:105]
	v_mfma_f32_16x16x32_bf16 v[98:101], v[186:189], v[214:217], v[98:101]
	v_mfma_f32_16x16x32_bf16 v[126:129], v[172:175], v[194:197], v[126:129]
	v_mfma_f32_16x16x32_bf16 v[122:125], v[190:193], v[194:197], v[122:125]
	v_mfma_f32_16x16x32_bf16 v[118:121], v[172:175], v[202:205], v[118:121]
	v_mfma_f32_16x16x32_bf16 v[114:117], v[190:193], v[202:205], v[114:117]
	v_mfma_f32_16x16x32_bf16 v[110:113], v[172:175], v[210:213], v[110:113]
	v_mfma_f32_16x16x32_bf16 v[106:109], v[190:193], v[210:213], v[106:109]
	v_mfma_f32_16x16x32_bf16 v[102:105], v[172:175], v[218:221], v[102:105]
	v_mfma_f32_16x16x32_bf16 v[98:101], v[190:193], v[218:221], v[98:101]
	s_barrier
	v_add_u32_e32 v156, s33, v148
	v_lshl_add_u64 v[244:245], s[4:5], 0, v[136:137]
	v_readfirstlane_b32 s3, v156
	v_add_u32_e32 v157, 0x2000, v156
	v_lshl_add_u64 v[238:239], v[244:245], 0, s[14:15]
	s_mov_b32 m0, s3
	v_lshl_add_u64 v[246:247], s[4:5], 0, v[138:139]
	v_readfirstlane_b32 s3, v157
	ds_read_b128 v[222:225], v154
	ds_read_b128 v[226:229], v154 offset:1024
	ds_read_b128 v[230:233], v154 offset:2048
	ds_read_b128 v[234:237], v154 offset:3072
	global_load_lds_dwordx4 v[238:239], off
	v_lshl_add_u64 v[238:239], v[246:247], 0, s[14:15]
	s_mov_b32 m0, s3
	s_nop 0
	global_load_lds_dwordx4 v[238:239], off
	s_barrier
	s_waitcnt lgkmcnt(0)
	v_mfma_f32_16x16x32_bf16 v[94:97], v[222:225], v[158:161], v[94:97]
	v_mfma_f32_16x16x32_bf16 v[90:93], v[230:233], v[158:161], v[90:93]
	v_mfma_f32_16x16x32_bf16 v[86:89], v[222:225], v[198:201], v[86:89]
	v_mfma_f32_16x16x32_bf16 v[82:85], v[230:233], v[198:201], v[82:85]
	v_mfma_f32_16x16x32_bf16 v[78:81], v[222:225], v[206:209], v[78:81]
	v_mfma_f32_16x16x32_bf16 v[74:77], v[230:233], v[206:209], v[74:77]
	v_mfma_f32_16x16x32_bf16 v[70:73], v[222:225], v[214:217], v[70:73]
	v_mfma_f32_16x16x32_bf16 v[66:69], v[230:233], v[214:217], v[66:69]
	v_mfma_f32_16x16x32_bf16 v[94:97], v[226:229], v[194:197], v[94:97]
	v_mfma_f32_16x16x32_bf16 v[90:93], v[234:237], v[194:197], v[90:93]
	v_mfma_f32_16x16x32_bf16 v[86:89], v[226:229], v[202:205], v[86:89]
	v_mfma_f32_16x16x32_bf16 v[82:85], v[234:237], v[202:205], v[82:85]
	v_mfma_f32_16x16x32_bf16 v[78:81], v[226:229], v[210:213], v[78:81]
	v_mfma_f32_16x16x32_bf16 v[74:77], v[234:237], v[210:213], v[74:77]
	v_mfma_f32_16x16x32_bf16 v[70:73], v[226:229], v[218:221], v[70:73]
	v_mfma_f32_16x16x32_bf16 v[66:69], v[234:237], v[218:221], v[66:69]
	v_readfirstlane_b32 s3, v142
	v_lshl_add_u64 v[158:159], v[182:183], 0, s[84:85]
	s_mov_b32 m0, s3
	s_barrier
	ds_read_b128 v[194:197], v146 offset:16384
	ds_read_b128 v[198:201], v146 offset:17408
	ds_read_b128 v[202:205], v145 offset:16384
	ds_read_b128 v[206:209], v145 offset:17408
	ds_read_b128 v[210:213], v144 offset:16384
	ds_read_b128 v[214:217], v144 offset:17408
	ds_read_b128 v[218:221], v143 offset:16384
	ds_read_b128 v[238:241], v143 offset:17408
	global_load_lds_dwordx4 v[158:159], off
	v_add_u32_e32 v158, 0x2000, v142
	v_lshl_add_u64 v[160:161], v[242:243], 0, s[84:85]
	v_readfirstlane_b32 s3, v158
	s_mov_b32 m0, s3
	s_nop 0
	global_load_lds_dwordx4 v[160:161], off
	s_barrier
	s_waitcnt lgkmcnt(0)
	v_mfma_f32_16x16x32_bf16 v[62:65], v[168:171], v[194:197], v[62:65]
	v_mfma_f32_16x16x32_bf16 v[58:61], v[186:189], v[194:197], v[58:61]
	v_mfma_f32_16x16x32_bf16 v[54:57], v[168:171], v[202:205], v[54:57]
	v_mfma_f32_16x16x32_bf16 v[50:53], v[186:189], v[202:205], v[50:53]
	v_mfma_f32_16x16x32_bf16 v[46:49], v[168:171], v[210:213], v[46:49]
	v_mfma_f32_16x16x32_bf16 v[42:45], v[186:189], v[210:213], v[42:45]
	v_mfma_f32_16x16x32_bf16 v[38:41], v[168:171], v[218:221], v[38:41]
	v_mfma_f32_16x16x32_bf16 v[34:37], v[186:189], v[218:221], v[34:37]
	v_mfma_f32_16x16x32_bf16 v[62:65], v[172:175], v[198:201], v[62:65]
	v_mfma_f32_16x16x32_bf16 v[58:61], v[190:193], v[198:201], v[58:61]
	v_mfma_f32_16x16x32_bf16 v[54:57], v[172:175], v[206:209], v[54:57]
	v_mfma_f32_16x16x32_bf16 v[50:53], v[190:193], v[206:209], v[50:53]
	v_mfma_f32_16x16x32_bf16 v[46:49], v[172:175], v[214:217], v[46:49]
	v_mfma_f32_16x16x32_bf16 v[42:45], v[190:193], v[214:217], v[42:45]
	v_mfma_f32_16x16x32_bf16 v[38:41], v[172:175], v[238:241], v[38:41]
	v_mfma_f32_16x16x32_bf16 v[34:37], v[190:193], v[238:241], v[34:37]
	s_barrier
; #define STAGE_A(P,br,kt) STAGE_G(P,c.A,c.lda,br,(long)(kt)*c.kstr)
; #define STAGE_B(P,br,kt) STAGE_G(P,c.Bt,c.K,br,(long)(kt)*BK)
; #define LDA(dst,b,h) for(int m=0;m<4;++m)for(int k=0;k<2;++k) \
;     dst[m][k]=*reinterpret_cast<const bf16x8*>((char*)SA(b,h)+lds_byte(wr*64+m*16+fr,k*32+fq*8))
; #define LDB(dst,b,h) for(int n=0;n<2;++n)for(int k=0;k<2;++k) \
;     dst[n][k]=*reinterpret_cast<const bf16x8*>((char*)SB(b,h)+lds_byte(wc*32+n*16+fr,k*32+fq*8))
; #define MMA(ai,bj,At,Bt_) do{__builtin_amdgcn_s_setprio(1); \
;     for(int m=0;m<4;++m)for(int n=0;n<2;++n)for(int k=0;k<2;++k) \
;       acc[ai][bj][m][n]=__builtin_amdgcn_mfma_f32_16x16x32_bf16(Bt_[n][k],At[m][k],acc[ai][bj][m][n],0,0,0); \
;     __builtin_amdgcn_s_setprio(0);}while(0)
; #define WAIT_V(n) asm volatile("s_waitcnt vmcnt(" #n ")":::"memory")
; #define WAIT_L(n) asm volatile("s_waitcnt lgkmcnt(" #n ")":::"memory")
; #define BAR __builtin_amdgcn_s_barrier()
; #define SCHED __builtin_amdgcn_sched_barrier(0)
; template <int EPI>
; __device__ __forceinline__ void gemm_run(const GD& c, const bool has_next, const GD& nx, const Ctx& e, bf16* shm, float* rs, float* rs_nxt, float* racc_) {
;     ...
;     STAGE_B(SB(0,1),bcol+HALF,t+2);
;     WAIT_V(6); BAR; MMA(1,1,At,B1); BAR;
;     LDB(B0,1,0); SCHED; LDA(At,1,0); STAGE_A(SA(0,1),brow+HALF,t+2);
;     WAIT_L(8); BAR; WAIT_L(0); MMA(0,0,At,B0); BAR; SCHED;
;     LDB(B1,1,1); STAGE_B(SB(1,0),bcol,t+3);
;     BAR; WAIT_L(0); MMA(0,1,At,B1); BAR;
;     LDA(At,1,1); STAGE_A(SA(1,0),brow,t+3);
	v_add_u32_e32 v159, s86, v148
	v_lshl_add_u64 v[160:161], v[244:245], 0, s[26:27]
	v_readfirstlane_b32 s3, v159
	s_mov_b32 m0, s3
	v_lshl_add_u64 v[168:169], v[246:247], 0, s[26:27]
	global_load_lds_dwordx4 v[160:161], off
	v_add_u32_e32 v160, 0x2000, v159
	s_nop 0
	v_readfirstlane_b32 s3, v160
	s_mov_b32 m0, s3
	s_nop 0
	global_load_lds_dwordx4 v[168:169], off
	s_waitcnt vmcnt(6)
	s_barrier
	v_mfma_f32_16x16x32_bf16 v[30:33], v[222:225], v[194:197], v[30:33]
	v_mfma_f32_16x16x32_bf16 v[26:29], v[230:233], v[194:197], v[26:29]
	v_mfma_f32_16x16x32_bf16 v[22:25], v[222:225], v[202:205], v[22:25]
	v_mfma_f32_16x16x32_bf16 v[18:21], v[230:233], v[202:205], v[18:21]
	v_mfma_f32_16x16x32_bf16 v[14:17], v[222:225], v[210:213], v[14:17]
	v_mfma_f32_16x16x32_bf16 v[10:13], v[230:233], v[210:213], v[10:13]
	v_mfma_f32_16x16x32_bf16 v[6:9], v[222:225], v[218:221], v[6:9]
	v_mfma_f32_16x16x32_bf16 v[2:5], v[230:233], v[218:221], v[2:5]
	v_mfma_f32_16x16x32_bf16 v[30:33], v[226:229], v[198:201], v[30:33]
	v_mfma_f32_16x16x32_bf16 v[26:29], v[234:237], v[198:201], v[26:29]
	v_mfma_f32_16x16x32_bf16 v[22:25], v[226:229], v[206:209], v[22:25]
	v_mfma_f32_16x16x32_bf16 v[18:21], v[234:237], v[206:209], v[18:21]
	v_mfma_f32_16x16x32_bf16 v[14:17], v[226:229], v[214:217], v[14:17]
	v_mfma_f32_16x16x32_bf16 v[10:13], v[234:237], v[214:217], v[10:13]
	v_mfma_f32_16x16x32_bf16 v[6:9], v[226:229], v[238:241], v[6:9]
	v_mfma_f32_16x16x32_bf16 v[2:5], v[234:237], v[238:241], v[2:5]
	s_barrier
	ds_read_b128 v[168:171], v149
	ds_read_b128 v[172:175], v149 offset:1024
	ds_read_b128 v[186:189], v149 offset:2048
	ds_read_b128 v[190:193], v149 offset:3072
	v_add_u32_e32 v161, 0x4000, v142
	v_add_u32_e32 v162, 0x6000, v142
	v_readfirstlane_b32 s3, v161
	v_lshl_add_u64 v[226:227], v[182:183], 0, s[92:93]
	s_mov_b32 m0, s3
	v_readfirstlane_b32 s3, v162
	ds_read_b128 v[194:197], v146 offset:32768
	ds_read_b128 v[198:201], v146 offset:33792
	ds_read_b128 v[202:205], v145 offset:32768
	ds_read_b128 v[206:209], v145 offset:33792
	ds_read_b128 v[210:213], v144 offset:32768
	ds_read_b128 v[214:217], v144 offset:33792
	ds_read_b128 v[218:221], v143 offset:32768
	ds_read_b128 v[222:225], v143 offset:33792
	global_load_lds_dwordx4 v[226:227], off
	v_lshl_add_u64 v[226:227], v[242:243], 0, s[92:93]
	s_mov_b32 m0, s3
	s_nop 0
	global_load_lds_dwordx4 v[226:227], off
	s_waitcnt lgkmcnt(8)
	s_barrier
	s_waitcnt lgkmcnt(0)
	v_mfma_f32_16x16x32_bf16 v[126:129], v[168:171], v[194:197], v[126:129]
	v_mfma_f32_16x16x32_bf16 v[122:125], v[186:189], v[194:197], v[122:125]
	v_mfma_f32_16x16x32_bf16 v[118:121], v[168:171], v[202:205], v[118:121]
	v_mfma_f32_16x16x32_bf16 v[114:117], v[186:189], v[202:205], v[114:117]
	v_mfma_f32_16x16x32_bf16 v[110:113], v[168:171], v[210:213], v[110:113]
	v_mfma_f32_16x16x32_bf16 v[106:109], v[186:189], v[210:213], v[106:109]
	v_mfma_f32_16x16x32_bf16 v[102:105], v[168:171], v[218:221], v[102:105]
	v_mfma_f32_16x16x32_bf16 v[98:101], v[186:189], v[218:221], v[98:101]
	v_mfma_f32_16x16x32_bf16 v[126:129], v[172:175], v[198:201], v[126:129]
	v_mfma_f32_16x16x32_bf16 v[122:125], v[190:193], v[198:201], v[122:125]
	v_mfma_f32_16x16x32_bf16 v[118:121], v[172:175], v[206:209], v[118:121]
	v_mfma_f32_16x16x32_bf16 v[114:117], v[190:193], v[206:209], v[114:117]
	v_mfma_f32_16x16x32_bf16 v[110:113], v[172:175], v[214:217], v[110:113]
	v_mfma_f32_16x16x32_bf16 v[106:109], v[190:193], v[214:217], v[106:109]
	v_mfma_f32_16x16x32_bf16 v[102:105], v[172:175], v[222:225], v[102:105]
	v_mfma_f32_16x16x32_bf16 v[98:101], v[190:193], v[222:225], v[98:101]
	s_barrier
	v_readfirstlane_b32 s3, v150
	v_add_u32_e32 v167, 0x2000, v150
	v_lshl_add_u64 v[248:249], v[244:245], 0, s[28:29]
	s_mov_b32 m0, s3
	v_readfirstlane_b32 s3, v167
	ds_read_b128 v[226:229], v147
	ds_read_b128 v[230:233], v147 offset:1024
	ds_read_b128 v[234:237], v147 offset:2048
	ds_read_b128 v[238:241], v147 offset:3072
	global_load_lds_dwordx4 v[248:249], off
	v_lshl_add_u64 v[248:249], v[246:247], 0, s[28:29]
	s_mov_b32 m0, s3
	s_nop 0
	global_load_lds_dwordx4 v[248:249], off
	s_barrier
	s_waitcnt lgkmcnt(0)
	v_mfma_f32_16x16x32_bf16 v[94:97], v[226:229], v[194:197], v[94:97]
	v_mfma_f32_16x16x32_bf16 v[90:93], v[234:237], v[194:197], v[90:93]
	v_mfma_f32_16x16x32_bf16 v[86:89], v[226:229], v[202:205], v[86:89]
	v_mfma_f32_16x16x32_bf16 v[82:85], v[234:237], v[202:205], v[82:85]
	v_mfma_f32_16x16x32_bf16 v[78:81], v[226:229], v[210:213], v[78:81]
	v_mfma_f32_16x16x32_bf16 v[74:77], v[234:237], v[210:213], v[74:77]
	v_mfma_f32_16x16x32_bf16 v[70:73], v[226:229], v[218:221], v[70:73]
	v_mfma_f32_16x16x32_bf16 v[66:69], v[234:237], v[218:221], v[66:69]
	v_mfma_f32_16x16x32_bf16 v[94:97], v[230:233], v[198:201], v[94:97]
	v_mfma_f32_16x16x32_bf16 v[90:93], v[238:241], v[198:201], v[90:93]
	v_mfma_f32_16x16x32_bf16 v[86:89], v[230:233], v[206:209], v[86:89]
	v_mfma_f32_16x16x32_bf16 v[82:85], v[238:241], v[206:209], v[82:85]
	v_mfma_f32_16x16x32_bf16 v[78:81], v[230:233], v[214:217], v[78:81]
	v_mfma_f32_16x16x32_bf16 v[74:77], v[238:241], v[214:217], v[74:77]
	v_mfma_f32_16x16x32_bf16 v[70:73], v[230:233], v[222:225], v[70:73]
	v_mfma_f32_16x16x32_bf16 v[66:69], v[238:241], v[222:225], v[66:69]
	s_barrier
	v_readfirstlane_b32 s3, v151
	v_lshl_add_u64 v[182:183], v[182:183], 0, s[80:81]
	s_mov_b32 m0, s3
	v_readfirstlane_b32 s3, v152
	ds_read_b128 v[194:197], v146 offset:49152
	ds_read_b128 v[198:201], v146 offset:50176
	ds_read_b128 v[202:205], v145 offset:49152
	ds_read_b128 v[206:209], v145 offset:50176
	ds_read_b128 v[210:213], v144 offset:49152
	ds_read_b128 v[214:217], v144 offset:50176
	ds_read_b128 v[218:221], v143 offset:49152
	ds_read_b128 v[222:225], v143 offset:50176
	global_load_lds_dwordx4 v[182:183], off
	v_lshl_add_u64 v[182:183], v[242:243], 0, s[80:81]
	s_mov_b32 m0, s3
	s_nop 0
	global_load_lds_dwordx4 v[182:183], off
	s_barrier
; #define STAGE_A(P,br,kt) STAGE_G(P,c.A,c.lda,br,(long)(kt)*c.kstr)
; #define STAGE_B(P,br,kt) STAGE_G(P,c.Bt,c.K,br,(long)(kt)*BK)
; #define LDA(dst,b,h) for(int m=0;m<4;++m)for(int k=0;k<2;++k) \
;     dst[m][k]=*reinterpret_cast<const bf16x8*>((char*)SA(b,h)+lds_byte(wr*64+m*16+fr,k*32+fq*8))
; #define LDB(dst,b,h) for(int n=0;n<2;++n)for(int k=0;k<2;++k) \
;     dst[n][k]=*reinterpret_cast<const bf16x8*>((char*)SB(b,h)+lds_byte(wc*32+n*16+fr,k*32+fq*8))
; #define MMA(ai,bj,At,Bt_) do{__builtin_amdgcn_s_setprio(1); \
;     for(int m=0;m<4;++m)for(int n=0;n<2;++n)for(int k=0;k<2;++k) \
;       acc[ai][bj][m][n]=__builtin_amdgcn_mfma_f32_16x16x32_bf16(Bt_[n][k],At[m][k],acc[ai][bj][m][n],0,0,0); \
;     __builtin_amdgcn_s_setprio(0);}while(0)
; #define WAIT_V(n) asm volatile("s_waitcnt vmcnt(" #n ")":::"memory")
; #define WAIT_L(n) asm volatile("s_waitcnt lgkmcnt(" #n ")":::"memory")
; #define BAR __builtin_amdgcn_s_barrier()
; #define SCHED __builtin_amdgcn_sched_barrier(0)
; template <int EPI>
; __device__ __forceinline__ void gemm_run(const GD& c, const bool has_next, const GD& nx, const Ctx& e, bf16* shm, float* rs, float* rs_nxt, float* racc_) {
;     ...
;     BAR; WAIT_L(0); MMA(1,0,At,B0); BAR; SCHED;
;     STAGE_B(SB(1,1),bcol+HALF,t+3);
;     WAIT_V(6); BAR; MMA(1,1,At,B1); BAR;
;   }
;   { LDB(B0,0,0); LDA(At,0,0); STAGE_A(SA(1,1),brow+HALF,nt-1);
;     BAR; WAIT_L(0); MMA(0,0,At,B0); BAR;
	s_waitcnt lgkmcnt(0)
	v_mfma_f32_16x16x32_bf16 v[62:65], v[168:171], v[194:197], v[62:65]
	v_mfma_f32_16x16x32_bf16 v[58:61], v[186:189], v[194:197], v[58:61]
	v_mfma_f32_16x16x32_bf16 v[54:57], v[168:171], v[202:205], v[54:57]
	v_mfma_f32_16x16x32_bf16 v[50:53], v[186:189], v[202:205], v[50:53]
	v_mfma_f32_16x16x32_bf16 v[46:49], v[168:171], v[210:213], v[46:49]
	v_mfma_f32_16x16x32_bf16 v[42:45], v[186:189], v[210:213], v[42:45]
	v_mfma_f32_16x16x32_bf16 v[38:41], v[168:171], v[218:221], v[38:41]
	v_mfma_f32_16x16x32_bf16 v[34:37], v[186:189], v[218:221], v[34:37]
	v_mfma_f32_16x16x32_bf16 v[62:65], v[172:175], v[198:201], v[62:65]
	v_mfma_f32_16x16x32_bf16 v[58:61], v[190:193], v[198:201], v[58:61]
	v_mfma_f32_16x16x32_bf16 v[54:57], v[172:175], v[206:209], v[54:57]
	v_mfma_f32_16x16x32_bf16 v[50:53], v[190:193], v[206:209], v[50:53]
	v_mfma_f32_16x16x32_bf16 v[46:49], v[172:175], v[214:217], v[46:49]
	v_mfma_f32_16x16x32_bf16 v[42:45], v[190:193], v[214:217], v[42:45]
	v_mfma_f32_16x16x32_bf16 v[38:41], v[172:175], v[222:225], v[38:41]
	v_mfma_f32_16x16x32_bf16 v[34:37], v[190:193], v[222:225], v[34:37]
	s_barrier
	v_readfirstlane_b32 s3, v153
	v_add_u32_e32 v167, 0x2000, v153
	v_lshl_add_u64 v[168:169], v[244:245], 0, s[30:31]
	s_mov_b32 m0, s3
	v_readfirstlane_b32 s3, v167
	global_load_lds_dwordx4 v[168:169], off
	v_lshl_add_u64 v[168:169], v[246:247], 0, s[30:31]
	s_mov_b32 m0, s3
	s_nop 0
	global_load_lds_dwordx4 v[168:169], off
	s_waitcnt vmcnt(6)
	s_barrier
	v_mfma_f32_16x16x32_bf16 v[30:33], v[226:229], v[194:197], v[30:33]
	v_mfma_f32_16x16x32_bf16 v[26:29], v[234:237], v[194:197], v[26:29]
	v_mfma_f32_16x16x32_bf16 v[22:25], v[226:229], v[202:205], v[22:25]
	v_mfma_f32_16x16x32_bf16 v[18:21], v[234:237], v[202:205], v[18:21]
	s_add_i32 s2, s2, 2
	v_mfma_f32_16x16x32_bf16 v[14:17], v[226:229], v[210:213], v[14:17]
	v_lshl_add_u64 v[130:131], v[130:131], 0, s[88:89]
	v_mfma_f32_16x16x32_bf16 v[10:13], v[234:237], v[210:213], v[10:13]
	v_lshl_add_u64 v[132:133], v[132:133], 0, s[88:89]
	v_mfma_f32_16x16x32_bf16 v[6:9], v[226:229], v[218:221], v[6:9]
	v_lshl_add_u64 v[136:137], v[136:137], 0, s[88:89]
	v_mfma_f32_16x16x32_bf16 v[2:5], v[234:237], v[218:221], v[2:5]
	s_cmp_lt_u32 s2, 12
	v_mfma_f32_16x16x32_bf16 v[30:33], v[230:233], v[198:201], v[30:33]
	v_lshl_add_u64 v[138:139], v[138:139], 0, s[88:89]
	v_mfma_f32_16x16x32_bf16 v[26:29], v[238:241], v[198:201], v[26:29]
	v_mfma_f32_16x16x32_bf16 v[22:25], v[230:233], v[206:209], v[22:25]
	v_mfma_f32_16x16x32_bf16 v[18:21], v[238:241], v[206:209], v[18:21]
	v_mfma_f32_16x16x32_bf16 v[14:17], v[230:233], v[214:217], v[14:17]
	v_mfma_f32_16x16x32_bf16 v[10:13], v[238:241], v[214:217], v[10:13]
	v_mfma_f32_16x16x32_bf16 v[6:9], v[230:233], v[222:225], v[6:9]
	v_mfma_f32_16x16x32_bf16 v[2:5], v[238:241], v[222:225], v[2:5]
	s_barrier
	s_cbranch_scc1 .LBB0_1119
	s_or_b32 s2, s10, 0x80
	s_ashr_i32 s3, s2, 31
	s_lshl_b64 s[2:3], s[2:3], 11
	s_add_u32 s2, s18, s2
	s_addc_u32 s3, s19, s3
	v_lshl_add_u64 v[182:183], s[2:3], 0, v[0:1]
	s_mov_b64 s[14:15], 0x780
	v_readfirstlane_b32 s11, v163
	v_lshl_add_u64 v[182:183], v[182:183], 0, s[14:15]
	s_mov_b32 m0, s11
	ds_read_b128 v[130:133], v155
	ds_read_b128 v[136:139], v155 offset:1024
	ds_read_b128 v[150:153], v155 offset:2048
	ds_read_b128 v[168:171], v155 offset:3072
	ds_read_b128 v[172:175], v146
	ds_read_b128 v[186:189], v146 offset:1024
	ds_read_b128 v[190:193], v145
	ds_read_b128 v[194:197], v145 offset:1024
	ds_read_b128 v[198:201], v144
	ds_read_b128 v[202:205], v144 offset:1024
	ds_read_b128 v[206:209], v143
	ds_read_b128 v[210:213], v143 offset:1024
	global_load_lds_dwordx4 v[182:183], off
	v_lshl_add_u64 v[182:183], s[2:3], 0, v[134:135]
	v_readfirstlane_b32 s2, v166
	v_lshl_add_u64 v[182:183], v[182:183], 0, s[14:15]
	s_mov_b32 m0, s2
	s_nop 0
	global_load_lds_dwordx4 v[182:183], off
	s_barrier
	s_waitcnt lgkmcnt(0)
	v_mfma_f32_16x16x32_bf16 v[126:129], v[130:133], v[172:175], v[126:129]
	v_mfma_f32_16x16x32_bf16 v[122:125], v[150:153], v[172:175], v[122:125]
	v_mfma_f32_16x16x32_bf16 v[118:121], v[130:133], v[190:193], v[118:121]
	v_mfma_f32_16x16x32_bf16 v[106:109], v[150:153], v[198:201], v[106:109]
	v_mfma_f32_16x16x32_bf16 v[102:105], v[130:133], v[206:209], v[102:105]
	v_mfma_f32_16x16x32_bf16 v[126:129], v[136:139], v[186:189], v[126:129]
	v_mfma_f32_16x16x32_bf16 v[122:125], v[168:171], v[186:189], v[122:125]
	v_mfma_f32_16x16x32_bf16 v[118:121], v[136:139], v[194:197], v[118:121]
	v_mfma_f32_16x16x32_bf16 v[114:117], v[150:153], v[190:193], v[114:117]
	v_mfma_f32_16x16x32_bf16 v[110:113], v[130:133], v[198:201], v[110:113]
	v_mfma_f32_16x16x32_bf16 v[106:109], v[168:171], v[202:205], v[106:109]
	v_mfma_f32_16x16x32_bf16 v[102:105], v[136:139], v[210:213], v[102:105]
	v_mfma_f32_16x16x32_bf16 v[98:101], v[150:153], v[206:209], v[98:101]
	v_mfma_f32_16x16x32_bf16 v[214:217], v[168:171], v[194:197], v[114:117]
	v_mfma_f32_16x16x32_bf16 v[218:221], v[136:139], v[202:205], v[110:113]
	v_mfma_f32_16x16x32_bf16 v[222:225], v[168:171], v[210:213], v[98:101]
	s_barrier
	s_nop 2
	ds_read_b128 v[98:101], v154
	ds_read_b128 v[110:113], v154 offset:1024
	ds_read_b128 v[114:117], v154 offset:2048
	ds_read_b128 v[226:229], v154 offset:3072
	s_barrier
; #define LDA(dst,b,h) for(int m=0;m<4;++m)for(int k=0;k<2;++k) \
;     dst[m][k]=*reinterpret_cast<const bf16x8*>((char*)SA(b,h)+lds_byte(wr*64+m*16+fr,k*32+fq*8))
; #define LDB(dst,b,h) for(int n=0;n<2;++n)for(int k=0;k<2;++k) \
;     dst[n][k]=*reinterpret_cast<const bf16x8*>((char*)SB(b,h)+lds_byte(wc*32+n*16+fr,k*32+fq*8))
; #define MMA(ai,bj,At,Bt_) do{__builtin_amdgcn_s_setprio(1); \
;     for(int m=0;m<4;++m)for(int n=0;n<2;++n)for(int k=0;k<2;++k) \
;       acc[ai][bj][m][n]=__builtin_amdgcn_mfma_f32_16x16x32_bf16(Bt_[n][k],At[m][k],acc[ai][bj][m][n],0,0,0); \
;     __builtin_amdgcn_s_setprio(0);}while(0)
; #define WAIT_V(n) asm volatile("s_waitcnt vmcnt(" #n ")":::"memory")
; #define WAIT_L(n) asm volatile("s_waitcnt lgkmcnt(" #n ")":::"memory")
; #define BAR __builtin_amdgcn_s_barrier()
; template <int EPI>
; __device__ __forceinline__ void gemm_run(const GD& c, const bool has_next, const GD& nx, const Ctx& e, bf16* shm, float* rs, float* rs_nxt, float* racc_) {
;     ...
;     LDB(B1,0,1); BAR; WAIT_L(0); MMA(0,1,At,B1); BAR;
;     LDA(At,0,1); WAIT_V(4); BAR; WAIT_L(0); MMA(1,0,At,B0); MMA(1,1,At,B1); BAR; }
;   { LDB(B0,1,0); LDA(At,1,0); WAIT_V(2); BAR; WAIT_L(0); MMA(0,0,At,B0); BAR;
	s_waitcnt lgkmcnt(0)
	v_mfma_f32_16x16x32_bf16 v[90:93], v[114:117], v[172:175], v[90:93]
	v_mfma_f32_16x16x32_bf16 v[86:89], v[98:101], v[190:193], v[86:89]
	v_mfma_f32_16x16x32_bf16 v[74:77], v[114:117], v[198:201], v[74:77]
	v_mfma_f32_16x16x32_bf16 v[70:73], v[98:101], v[206:209], v[70:73]
	v_mfma_f32_16x16x32_bf16 v[66:69], v[114:117], v[206:209], v[66:69]
	v_mfma_f32_16x16x32_bf16 v[94:97], v[98:101], v[172:175], v[94:97]
	v_mfma_f32_16x16x32_bf16 v[90:93], v[226:229], v[186:189], v[90:93]
	v_mfma_f32_16x16x32_bf16 v[86:89], v[110:113], v[194:197], v[86:89]
	v_mfma_f32_16x16x32_bf16 v[82:85], v[114:117], v[190:193], v[82:85]
	v_mfma_f32_16x16x32_bf16 v[78:81], v[98:101], v[198:201], v[78:81]
	v_mfma_f32_16x16x32_bf16 v[74:77], v[226:229], v[202:205], v[74:77]
	v_mfma_f32_16x16x32_bf16 v[70:73], v[110:113], v[210:213], v[70:73]
	v_mfma_f32_16x16x32_bf16 v[66:69], v[226:229], v[210:213], v[66:69]
	v_mfma_f32_16x16x32_bf16 v[230:233], v[110:113], v[186:189], v[94:97]
	v_mfma_f32_16x16x32_bf16 v[172:175], v[226:229], v[194:197], v[82:85]
	v_mfma_f32_16x16x32_bf16 v[186:189], v[110:113], v[202:205], v[78:81]
	s_barrier
	s_nop 0
	ds_read_b128 v[78:81], v146 offset:16384
	ds_read_b128 v[82:85], v146 offset:17408
	ds_read_b128 v[94:97], v145 offset:16384
	ds_read_b128 v[190:193], v145 offset:17408
	ds_read_b128 v[194:197], v144 offset:16384
	ds_read_b128 v[198:201], v144 offset:17408
	ds_read_b128 v[202:205], v143 offset:16384
	ds_read_b128 v[206:209], v143 offset:17408
	s_waitcnt vmcnt(4)
	s_barrier
	s_waitcnt lgkmcnt(0)
	v_mfma_f32_16x16x32_bf16 v[62:65], v[130:133], v[78:81], v[62:65]
	v_mfma_f32_16x16x32_bf16 v[58:61], v[150:153], v[78:81], v[58:61]
	v_mfma_f32_16x16x32_bf16 v[54:57], v[130:133], v[94:97], v[54:57]
	v_mfma_f32_16x16x32_bf16 v[42:45], v[150:153], v[194:197], v[42:45]
	v_mfma_f32_16x16x32_bf16 v[38:41], v[130:133], v[202:205], v[38:41]
	v_mfma_f32_16x16x32_bf16 v[62:65], v[136:139], v[82:85], v[62:65]
	v_mfma_f32_16x16x32_bf16 v[58:61], v[168:171], v[82:85], v[58:61]
	v_mfma_f32_16x16x32_bf16 v[54:57], v[136:139], v[190:193], v[54:57]
	v_mfma_f32_16x16x32_bf16 v[50:53], v[150:153], v[94:97], v[50:53]
	v_mfma_f32_16x16x32_bf16 v[46:49], v[130:133], v[194:197], v[46:49]
	v_mfma_f32_16x16x32_bf16 v[42:45], v[168:171], v[198:201], v[42:45]
	v_mfma_f32_16x16x32_bf16 v[38:41], v[136:139], v[206:209], v[38:41]
	v_mfma_f32_16x16x32_bf16 v[34:37], v[150:153], v[202:205], v[34:37]
	v_mfma_f32_16x16x32_bf16 v[210:213], v[168:171], v[190:193], v[50:53]
	v_mfma_f32_16x16x32_bf16 v[234:237], v[136:139], v[198:201], v[46:49]
	v_mfma_f32_16x16x32_bf16 v[136:139], v[168:171], v[206:209], v[34:37]
	v_mfma_f32_16x16x32_bf16 v[26:29], v[114:117], v[78:81], v[26:29]
	v_mfma_f32_16x16x32_bf16 v[22:25], v[98:101], v[94:97], v[22:25]
	v_mfma_f32_16x16x32_bf16 v[10:13], v[114:117], v[194:197], v[10:13]
	v_mfma_f32_16x16x32_bf16 v[6:9], v[98:101], v[202:205], v[6:9]
	v_mfma_f32_16x16x32_bf16 v[30:33], v[98:101], v[78:81], v[30:33]
	v_mfma_f32_16x16x32_bf16 v[26:29], v[226:229], v[82:85], v[26:29]
	v_mfma_f32_16x16x32_bf16 v[22:25], v[110:113], v[190:193], v[22:25]
	v_mfma_f32_16x16x32_bf16 v[18:21], v[114:117], v[94:97], v[18:21]
	v_mfma_f32_16x16x32_bf16 v[14:17], v[98:101], v[194:197], v[14:17]
	v_mfma_f32_16x16x32_bf16 v[10:13], v[226:229], v[198:201], v[10:13]
	v_mfma_f32_16x16x32_bf16 v[6:9], v[110:113], v[206:209], v[6:9]
	v_mfma_f32_16x16x32_bf16 v[2:5], v[114:117], v[202:205], v[2:5]
	v_mfma_f32_16x16x32_bf16 v[150:153], v[110:113], v[82:85], v[30:33]
	v_mfma_f32_16x16x32_bf16 v[166:169], v[226:229], v[190:193], v[18:21]
	v_mfma_f32_16x16x32_bf16 v[190:193], v[110:113], v[198:201], v[14:17]
	v_mfma_f32_16x16x32_bf16 v[2:5], v[226:229], v[206:209], v[2:5]
	s_barrier
	ds_read_b128 v[14:17], v149
	ds_read_b128 v[18:21], v149 offset:1024
	ds_read_b128 v[194:197], v149 offset:2048
	ds_read_b128 v[198:201], v149 offset:3072
	ds_read_b128 v[30:33], v146 offset:32768
	ds_read_b128 v[34:37], v146 offset:33792
	ds_read_b128 v[46:49], v145 offset:32768
	ds_read_b128 v[50:53], v145 offset:33792
	ds_read_b128 v[202:205], v144 offset:32768
	ds_read_b128 v[206:209], v144 offset:33792
	ds_read_b128 v[226:229], v143 offset:32768
	ds_read_b128 v[238:241], v143 offset:33792
	s_waitcnt vmcnt(2)
	s_barrier
; #define LDA(dst,b,h) for(int m=0;m<4;++m)for(int k=0;k<2;++k) \
;     dst[m][k]=*reinterpret_cast<const bf16x8*>((char*)SA(b,h)+lds_byte(wr*64+m*16+fr,k*32+fq*8))
; #define LDB(dst,b,h) for(int n=0;n<2;++n)for(int k=0;k<2;++k) \
;     dst[n][k]=*reinterpret_cast<const bf16x8*>((char*)SB(b,h)+lds_byte(wc*32+n*16+fr,k*32+fq*8))
; #define MMA(ai,bj,At,Bt_) do{__builtin_amdgcn_s_setprio(1); \
;     for(int m=0;m<4;++m)for(int n=0;n<2;++n)for(int k=0;k<2;++k) \
;       acc[ai][bj][m][n]=__builtin_amdgcn_mfma_f32_16x16x32_bf16(Bt_[n][k],At[m][k],acc[ai][bj][m][n],0,0,0); \
;     __builtin_amdgcn_s_setprio(0);}while(0)
; #define WAIT_V(n) asm volatile("s_waitcnt vmcnt(" #n ")":::"memory")
; #define WAIT_L(n) asm volatile("s_waitcnt lgkmcnt(" #n ")":::"memory")
; #define BAR __builtin_amdgcn_s_barrier()
; template <int EPI>
; __device__ __forceinline__ void gemm_run(const GD& c, const bool has_next, const GD& nx, const Ctx& e, bf16* shm, float* rs, float* rs_nxt, float* racc_) {
;     ...
;   { LDB(B0,1,0); LDA(At,1,0); WAIT_V(2); BAR; WAIT_L(0); MMA(0,0,At,B0); BAR;
;     LDB(B1,1,1); WAIT_V(0); BAR; WAIT_L(0); MMA(0,1,At,B1); BAR;
;     LDA(At,1,1); BAR; WAIT_L(0); MMA(1,0,At,B0); MMA(1,1,At,B1); BAR; }
;   if(wr==0)BAR;
	s_waitcnt lgkmcnt(0)
	v_mfma_f32_16x16x32_bf16 v[78:81], v[14:17], v[30:33], v[126:129]
	v_mfma_f32_16x16x32_bf16 v[130:133], v[18:21], v[34:37], v[78:81]
	v_mfma_f32_16x16x32_bf16 v[78:81], v[194:197], v[30:33], v[122:125]
	v_mfma_f32_16x16x32_bf16 v[126:129], v[198:201], v[34:37], v[78:81]
	v_mfma_f32_16x16x32_bf16 v[78:81], v[14:17], v[46:49], v[118:121]
	v_mfma_f32_16x16x32_bf16 v[114:117], v[18:21], v[50:53], v[78:81]
	v_mfma_f32_16x16x32_bf16 v[78:81], v[194:197], v[46:49], v[214:217]
	v_mfma_f32_16x16x32_bf16 v[110:113], v[198:201], v[50:53], v[78:81]
	v_mfma_f32_16x16x32_bf16 v[78:81], v[14:17], v[202:205], v[218:221]
	v_mfma_f32_16x16x32_bf16 v[98:101], v[18:21], v[206:209], v[78:81]
	v_mfma_f32_16x16x32_bf16 v[78:81], v[194:197], v[202:205], v[106:109]
	v_mfma_f32_16x16x32_bf16 v[94:97], v[198:201], v[206:209], v[78:81]
	v_mfma_f32_16x16x32_bf16 v[78:81], v[14:17], v[226:229], v[102:105]
	v_mfma_f32_16x16x32_bf16 v[82:85], v[18:21], v[238:241], v[78:81]
	v_mfma_f32_16x16x32_bf16 v[78:81], v[194:197], v[226:229], v[222:225]
	v_mfma_f32_16x16x32_bf16 v[78:81], v[198:201], v[238:241], v[78:81]
	s_barrier
	ds_read_b128 v[214:217], v147
	ds_read_b128 v[218:221], v147 offset:1024
	ds_read_b128 v[222:225], v147 offset:2048
	ds_read_b128 v[242:245], v147 offset:3072
	s_waitcnt vmcnt(0)
	s_barrier
	s_waitcnt lgkmcnt(0)
	v_mfma_f32_16x16x32_bf16 v[102:105], v[214:217], v[30:33], v[230:233]
	v_mfma_f32_16x16x32_bf16 v[30:33], v[222:225], v[30:33], v[90:93]
	v_mfma_f32_16x16x32_bf16 v[118:121], v[242:245], v[34:37], v[30:33]
	v_mfma_f32_16x16x32_bf16 v[30:33], v[214:217], v[46:49], v[86:89]
	v_mfma_f32_16x16x32_bf16 v[106:109], v[218:221], v[50:53], v[30:33]
	v_mfma_f32_16x16x32_bf16 v[30:33], v[222:225], v[46:49], v[172:175]
	v_mfma_f32_16x16x32_bf16 v[122:125], v[218:221], v[34:37], v[102:105]
	v_mfma_f32_16x16x32_bf16 v[102:105], v[242:245], v[50:53], v[30:33]
	v_mfma_f32_16x16x32_bf16 v[30:33], v[214:217], v[202:205], v[186:189]
	v_mfma_f32_16x16x32_bf16 v[90:93], v[218:221], v[206:209], v[30:33]
	v_mfma_f32_16x16x32_bf16 v[30:33], v[222:225], v[202:205], v[74:77]
	v_mfma_f32_16x16x32_bf16 v[86:89], v[242:245], v[206:209], v[30:33]
	v_mfma_f32_16x16x32_bf16 v[30:33], v[214:217], v[226:229], v[70:73]
	v_mfma_f32_16x16x32_bf16 v[74:77], v[218:221], v[238:241], v[30:33]
	v_mfma_f32_16x16x32_bf16 v[30:33], v[222:225], v[226:229], v[66:69]
	v_mfma_f32_16x16x32_bf16 v[70:73], v[242:245], v[238:241], v[30:33]
	s_barrier
	ds_read_b128 v[170:173], v146 offset:49152
	ds_read_b128 v[146:149], v146 offset:50176
	ds_read_b128 v[186:189], v145 offset:49152
	ds_read_b128 v[202:205], v145 offset:50176
	ds_read_b128 v[206:209], v144 offset:49152
	ds_read_b128 v[226:229], v144 offset:50176
	ds_read_b128 v[230:233], v143 offset:49152
	ds_read_b128 v[238:241], v143 offset:50176
	s_barrier
	s_waitcnt lgkmcnt(0)
	v_mfma_f32_16x16x32_bf16 v[30:33], v[14:17], v[170:173], v[62:65]
	v_mfma_f32_16x16x32_bf16 v[66:69], v[18:21], v[146:149], v[30:33]
	v_mfma_f32_16x16x32_bf16 v[30:33], v[194:197], v[170:173], v[58:61]
	v_mfma_f32_16x16x32_bf16 v[62:65], v[198:201], v[146:149], v[30:33]
	v_mfma_f32_16x16x32_bf16 v[30:33], v[14:17], v[186:189], v[54:57]
	v_mfma_f32_16x16x32_bf16 v[50:53], v[18:21], v[202:205], v[30:33]
	v_mfma_f32_16x16x32_bf16 v[30:33], v[194:197], v[186:189], v[210:213]
	v_mfma_f32_16x16x32_bf16 v[46:49], v[198:201], v[202:205], v[30:33]
	v_mfma_f32_16x16x32_bf16 v[30:33], v[14:17], v[206:209], v[234:237]
	v_mfma_f32_16x16x32_bf16 v[14:17], v[14:17], v[230:233], v[38:41]
	v_mfma_f32_16x16x32_bf16 v[34:37], v[18:21], v[226:229], v[30:33]
	v_mfma_f32_16x16x32_bf16 v[30:33], v[194:197], v[206:209], v[42:45]
	v_mfma_f32_16x16x32_bf16 v[18:21], v[18:21], v[238:241], v[14:17]
	v_mfma_f32_16x16x32_bf16 v[14:17], v[194:197], v[230:233], v[136:139]
	v_mfma_f32_16x16x32_bf16 v[30:33], v[198:201], v[226:229], v[30:33]
	v_mfma_f32_16x16x32_bf16 v[14:17], v[198:201], v[238:241], v[14:17]
	v_mfma_f32_16x16x32_bf16 v[22:25], v[214:217], v[186:189], v[22:25]
	v_mfma_f32_16x16x32_bf16 v[38:41], v[214:217], v[170:173], v[150:153]
	v_mfma_f32_16x16x32_bf16 v[42:45], v[218:221], v[202:205], v[22:25]
	v_mfma_f32_16x16x32_bf16 v[22:25], v[222:225], v[186:189], v[166:169]
	v_mfma_f32_16x16x32_bf16 v[58:61], v[218:221], v[146:149], v[38:41]
	v_mfma_f32_16x16x32_bf16 v[26:29], v[222:225], v[170:173], v[26:29]
	v_mfma_f32_16x16x32_bf16 v[38:41], v[242:245], v[202:205], v[22:25]
	v_mfma_f32_16x16x32_bf16 v[22:25], v[214:217], v[206:209], v[190:193]
	v_mfma_f32_16x16x32_bf16 v[10:13], v[222:225], v[206:209], v[10:13]
	v_mfma_f32_16x16x32_bf16 v[6:9], v[214:217], v[230:233], v[6:9]
	v_mfma_f32_16x16x32_bf16 v[2:5], v[222:225], v[230:233], v[2:5]
	v_mfma_f32_16x16x32_bf16 v[54:57], v[242:245], v[146:149], v[26:29]
	v_mfma_f32_16x16x32_bf16 v[26:29], v[218:221], v[226:229], v[22:25]
	v_mfma_f32_16x16x32_bf16 v[22:25], v[242:245], v[226:229], v[10:13]
	v_mfma_f32_16x16x32_bf16 v[10:13], v[218:221], v[238:241], v[6:9]
	v_mfma_f32_16x16x32_bf16 v[6:9], v[242:245], v[238:241], v[2:5]
	v_cmp_gt_u32_e32 vcc, s96, v140
	s_barrier
	s_and_saveexec_b64 s[2:3], vcc
	s_cbranch_execz .LBB0_1122
	s_barrier

; #define STAGE_A(P,br,kt) STAGE_G(P,c.A,c.lda,br,(long)(kt)*c.kstr)
; #define STAGE_B(P,br,kt) STAGE_G(P,c.Bt,c.K,br,(long)(kt)*BK)
; #define LDA(dst,b,h) for(int m=0;m<4;++m)for(int k=0;k<2;++k) \
;     dst[m][k]=*reinterpret_cast<const bf16x8*>((char*)SA(b,h)+lds_byte(wr*64+m*16+fr,k*32+fq*8))
; #define LDB(dst,b,h) for(int n=0;n<2;++n)for(int k=0;k<2;++k) \
;     dst[n][k]=*reinterpret_cast<const bf16x8*>((char*)SB(b,h)+lds_byte(wc*32+n*16+fr,k*32+fq*8))
; #define MMA(ai,bj,At,Bt_) do{__builtin_amdgcn_s_setprio(1); \
;     for(int m=0;m<4;++m)for(int n=0;n<2;++n)for(int k=0;k<2;++k) \
;       acc[ai][bj][m][n]=__builtin_amdgcn_mfma_f32_16x16x32_bf16(Bt_[n][k],At[m][k],acc[ai][bj][m][n],0,0,0); \
;     __builtin_amdgcn_s_setprio(0);}while(0)
; #define WAIT_L(n) asm volatile("s_waitcnt lgkmcnt(" #n ")":::"memory")
; #define BAR __builtin_amdgcn_s_barrier()
; #define SCHED __builtin_amdgcn_sched_barrier(0)
; template <int EPI>
; __device__ __forceinline__ void gemm_run(const GD& c, const bool has_next, const GD& nx, const Ctx& e, bf16* shm, float* rs, float* rs_nxt, float* racc_) {
;     ...
;   for(int t=0;t<nt-2;t+=2){
;     LDB(B0,0,0); SCHED; LDA(At,0,0); STAGE_A(SA(1,1),brow+HALF,t+1);
;     WAIT_L(8); BAR; WAIT_L(0); MMA(0,0,At,B0); BAR; SCHED;
;     LDB(B1,0,1); STAGE_B(SB(0,0),bcol,t+2);
;     BAR; WAIT_L(0); MMA(0,1,At,B1); BAR;
;     LDA(At,0,1); STAGE_A(SA(0,0),brow,t+2);
;     BAR; WAIT_L(0); MMA(1,0,At,B0); BAR; SCHED;
.LBB0_1178:
	ds_read_b128 v[168:171], v155
	ds_read_b128 v[172:175], v155 offset:1024
	ds_read_b128 v[186:189], v155 offset:2048
	ds_read_b128 v[190:193], v155 offset:3072
	v_add_u32_e32 v163, 0xc000, v142
	v_lshl_add_u64 v[182:183], s[6:7], 0, v[132:133]
	v_readfirstlane_b32 s3, v163
	v_add_u32_e32 v166, 0xe000, v142
	v_lshl_add_u64 v[156:157], v[182:183], 0, s[90:91]
	s_mov_b32 m0, s3
	v_lshl_add_u64 v[242:243], s[6:7], 0, v[134:135]
	v_readfirstlane_b32 s3, v166
	ds_read_b128 v[158:161], v146
	ds_read_b128 v[194:197], v146 offset:1024
	ds_read_b128 v[198:201], v145
	ds_read_b128 v[202:205], v145 offset:1024
	ds_read_b128 v[206:209], v144
	ds_read_b128 v[210:213], v144 offset:1024
	ds_read_b128 v[214:217], v143
	ds_read_b128 v[218:221], v143 offset:1024
	global_load_lds_dwordx4 v[156:157], off
	v_lshl_add_u64 v[156:157], v[242:243], 0, s[90:91]
	s_mov_b32 m0, s3
	s_nop 0
	global_load_lds_dwordx4 v[156:157], off
	s_waitcnt lgkmcnt(8)
	s_barrier
	s_waitcnt lgkmcnt(0)
	v_mfma_f32_16x16x32_bf16 v[126:129], v[168:171], v[158:161], v[126:129]
	v_mfma_f32_16x16x32_bf16 v[122:125], v[186:189], v[158:161], v[122:125]
	v_mfma_f32_16x16x32_bf16 v[118:121], v[168:171], v[198:201], v[118:121]
	v_mfma_f32_16x16x32_bf16 v[114:117], v[186:189], v[198:201], v[114:117]
	v_mfma_f32_16x16x32_bf16 v[110:113], v[168:171], v[206:209], v[110:113]
	v_mfma_f32_16x16x32_bf16 v[106:109], v[186:189], v[206:209], v[106:109]
	v_mfma_f32_16x16x32_bf16 v[102:105], v[168:171], v[214:217], v[102:105]
	v_mfma_f32_16x16x32_bf16 v[98:101], v[186:189], v[214:217], v[98:101]
	v_mfma_f32_16x16x32_bf16 v[126:129], v[172:175], v[194:197], v[126:129]
	v_mfma_f32_16x16x32_bf16 v[122:125], v[190:193], v[194:197], v[122:125]
	v_mfma_f32_16x16x32_bf16 v[118:121], v[172:175], v[202:205], v[118:121]
	v_mfma_f32_16x16x32_bf16 v[114:117], v[190:193], v[202:205], v[114:117]
	v_mfma_f32_16x16x32_bf16 v[110:113], v[172:175], v[210:213], v[110:113]
	v_mfma_f32_16x16x32_bf16 v[106:109], v[190:193], v[210:213], v[106:109]
	v_mfma_f32_16x16x32_bf16 v[102:105], v[172:175], v[218:221], v[102:105]
	v_mfma_f32_16x16x32_bf16 v[98:101], v[190:193], v[218:221], v[98:101]
	s_barrier
	v_add_u32_e32 v156, s33, v147
	v_lshl_add_u64 v[244:245], s[6:7], 0, v[136:137]
	v_readfirstlane_b32 s3, v156
	v_add_u32_e32 v157, 0x2000, v156
	v_lshl_add_u64 v[238:239], v[244:245], 0, s[28:29]
	s_mov_b32 m0, s3
	v_lshl_add_u64 v[246:247], s[6:7], 0, v[138:139]
	v_readfirstlane_b32 s3, v157
	ds_read_b128 v[222:225], v154
	ds_read_b128 v[226:229], v154 offset:1024
	ds_read_b128 v[230:233], v154 offset:2048
	ds_read_b128 v[234:237], v154 offset:3072
	global_load_lds_dwordx4 v[238:239], off
	v_lshl_add_u64 v[238:239], v[246:247], 0, s[28:29]
	s_mov_b32 m0, s3
	s_nop 0
	global_load_lds_dwordx4 v[238:239], off
	s_barrier
	s_waitcnt lgkmcnt(0)
	v_mfma_f32_16x16x32_bf16 v[94:97], v[222:225], v[158:161], v[94:97]
	v_mfma_f32_16x16x32_bf16 v[90:93], v[230:233], v[158:161], v[90:93]
	v_mfma_f32_16x16x32_bf16 v[86:89], v[222:225], v[198:201], v[86:89]
	v_mfma_f32_16x16x32_bf16 v[82:85], v[230:233], v[198:201], v[82:85]
	v_mfma_f32_16x16x32_bf16 v[78:81], v[222:225], v[206:209], v[78:81]
	v_mfma_f32_16x16x32_bf16 v[74:77], v[230:233], v[206:209], v[74:77]
	v_mfma_f32_16x16x32_bf16 v[70:73], v[222:225], v[214:217], v[70:73]
	v_mfma_f32_16x16x32_bf16 v[66:69], v[230:233], v[214:217], v[66:69]
	v_mfma_f32_16x16x32_bf16 v[94:97], v[226:229], v[194:197], v[94:97]
	v_mfma_f32_16x16x32_bf16 v[90:93], v[234:237], v[194:197], v[90:93]
	v_mfma_f32_16x16x32_bf16 v[86:89], v[226:229], v[202:205], v[86:89]
	v_mfma_f32_16x16x32_bf16 v[82:85], v[234:237], v[202:205], v[82:85]
	v_mfma_f32_16x16x32_bf16 v[78:81], v[226:229], v[210:213], v[78:81]
	v_mfma_f32_16x16x32_bf16 v[74:77], v[234:237], v[210:213], v[74:77]
	v_mfma_f32_16x16x32_bf16 v[70:73], v[226:229], v[218:221], v[70:73]
	v_mfma_f32_16x16x32_bf16 v[66:69], v[234:237], v[218:221], v[66:69]
	v_readfirstlane_b32 s3, v142
	v_lshl_add_u64 v[158:159], v[182:183], 0, s[0:1]
	s_mov_b32 m0, s3
	s_barrier
	ds_read_b128 v[194:197], v146 offset:16384
	ds_read_b128 v[198:201], v146 offset:17408
	ds_read_b128 v[202:205], v145 offset:16384
	ds_read_b128 v[206:209], v145 offset:17408
	ds_read_b128 v[210:213], v144 offset:16384
	ds_read_b128 v[214:217], v144 offset:17408
	ds_read_b128 v[218:221], v143 offset:16384
	ds_read_b128 v[238:241], v143 offset:17408
	global_load_lds_dwordx4 v[158:159], off
	v_add_u32_e32 v158, 0x2000, v142
	v_lshl_add_u64 v[160:161], v[242:243], 0, s[0:1]
	v_readfirstlane_b32 s3, v158
	s_mov_b32 m0, s3
	s_nop 0
	global_load_lds_dwordx4 v[160:161], off
	s_barrier
	s_waitcnt lgkmcnt(0)
	v_mfma_f32_16x16x32_bf16 v[62:65], v[168:171], v[194:197], v[62:65]
	v_mfma_f32_16x16x32_bf16 v[58:61], v[186:189], v[194:197], v[58:61]
	v_mfma_f32_16x16x32_bf16 v[54:57], v[168:171], v[202:205], v[54:57]
	v_mfma_f32_16x16x32_bf16 v[50:53], v[186:189], v[202:205], v[50:53]
	v_mfma_f32_16x16x32_bf16 v[46:49], v[168:171], v[210:213], v[46:49]
	v_mfma_f32_16x16x32_bf16 v[42:45], v[186:189], v[210:213], v[42:45]
	v_mfma_f32_16x16x32_bf16 v[38:41], v[168:171], v[218:221], v[38:41]
	v_mfma_f32_16x16x32_bf16 v[34:37], v[186:189], v[218:221], v[34:37]
	v_mfma_f32_16x16x32_bf16 v[62:65], v[172:175], v[198:201], v[62:65]
	v_mfma_f32_16x16x32_bf16 v[58:61], v[190:193], v[198:201], v[58:61]
	v_mfma_f32_16x16x32_bf16 v[54:57], v[172:175], v[206:209], v[54:57]
	v_mfma_f32_16x16x32_bf16 v[50:53], v[190:193], v[206:209], v[50:53]
	v_mfma_f32_16x16x32_bf16 v[46:49], v[172:175], v[214:217], v[46:49]
	v_mfma_f32_16x16x32_bf16 v[42:45], v[190:193], v[214:217], v[42:45]
	v_mfma_f32_16x16x32_bf16 v[38:41], v[172:175], v[238:241], v[38:41]
	v_mfma_f32_16x16x32_bf16 v[34:37], v[190:193], v[238:241], v[34:37]
	s_barrier
; #define STAGE_A(P,br,kt) STAGE_G(P,c.A,c.lda,br,(long)(kt)*c.kstr)
; #define STAGE_B(P,br,kt) STAGE_G(P,c.Bt,c.K,br,(long)(kt)*BK)
; #define LDA(dst,b,h) for(int m=0;m<4;++m)for(int k=0;k<2;++k) \
;     dst[m][k]=*reinterpret_cast<const bf16x8*>((char*)SA(b,h)+lds_byte(wr*64+m*16+fr,k*32+fq*8))
; #define LDB(dst,b,h) for(int n=0;n<2;++n)for(int k=0;k<2;++k) \
;     dst[n][k]=*reinterpret_cast<const bf16x8*>((char*)SB(b,h)+lds_byte(wc*32+n*16+fr,k*32+fq*8))
; #define MMA(ai,bj,At,Bt_) do{__builtin_amdgcn_s_setprio(1); \
;     for(int m=0;m<4;++m)for(int n=0;n<2;++n)for(int k=0;k<2;++k) \
;       acc[ai][bj][m][n]=__builtin_amdgcn_mfma_f32_16x16x32_bf16(Bt_[n][k],At[m][k],acc[ai][bj][m][n],0,0,0); \
;     __builtin_amdgcn_s_setprio(0);}while(0)
; #define WAIT_V(n) asm volatile("s_waitcnt vmcnt(" #n ")":::"memory")
; #define WAIT_L(n) asm volatile("s_waitcnt lgkmcnt(" #n ")":::"memory")
; #define BAR __builtin_amdgcn_s_barrier()
; #define SCHED __builtin_amdgcn_sched_barrier(0)
; template <int EPI>
; __device__ __forceinline__ void gemm_run(const GD& c, const bool has_next, const GD& nx, const Ctx& e, bf16* shm, float* rs, float* rs_nxt, float* racc_) {
;     ...
;     STAGE_B(SB(0,1),bcol+HALF,t+2);
;     WAIT_V(6); BAR; MMA(1,1,At,B1); BAR;
;     LDB(B0,1,0); SCHED; LDA(At,1,0); STAGE_A(SA(0,1),brow+HALF,t+2);
;     WAIT_L(8); BAR; WAIT_L(0); MMA(0,0,At,B0); BAR; SCHED;
;     LDB(B1,1,1); STAGE_B(SB(1,0),bcol,t+3);
;     BAR; WAIT_L(0); MMA(0,1,At,B1); BAR;
;     LDA(At,1,1); STAGE_A(SA(1,0),brow,t+3);
	v_add_u32_e32 v159, s86, v147
	v_lshl_add_u64 v[160:161], v[244:245], 0, s[30:31]
	v_readfirstlane_b32 s3, v159
	s_mov_b32 m0, s3
	v_lshl_add_u64 v[168:169], v[246:247], 0, s[30:31]
	global_load_lds_dwordx4 v[160:161], off
	v_add_u32_e32 v160, 0x2000, v159
	s_nop 0
	v_readfirstlane_b32 s3, v160
	s_mov_b32 m0, s3
	s_nop 0
	global_load_lds_dwordx4 v[168:169], off
	s_waitcnt vmcnt(6)
	s_barrier
	v_mfma_f32_16x16x32_bf16 v[30:33], v[222:225], v[194:197], v[30:33]
	v_mfma_f32_16x16x32_bf16 v[26:29], v[230:233], v[194:197], v[26:29]
	v_mfma_f32_16x16x32_bf16 v[22:25], v[222:225], v[202:205], v[22:25]
	v_mfma_f32_16x16x32_bf16 v[18:21], v[230:233], v[202:205], v[18:21]
	v_mfma_f32_16x16x32_bf16 v[14:17], v[222:225], v[210:213], v[14:17]
	v_mfma_f32_16x16x32_bf16 v[10:13], v[230:233], v[210:213], v[10:13]
	v_mfma_f32_16x16x32_bf16 v[6:9], v[222:225], v[218:221], v[6:9]
	v_mfma_f32_16x16x32_bf16 v[2:5], v[230:233], v[218:221], v[2:5]
	v_mfma_f32_16x16x32_bf16 v[30:33], v[226:229], v[198:201], v[30:33]
	v_mfma_f32_16x16x32_bf16 v[26:29], v[234:237], v[198:201], v[26:29]
	v_mfma_f32_16x16x32_bf16 v[22:25], v[226:229], v[206:209], v[22:25]
	v_mfma_f32_16x16x32_bf16 v[18:21], v[234:237], v[206:209], v[18:21]
	v_mfma_f32_16x16x32_bf16 v[14:17], v[226:229], v[214:217], v[14:17]
	v_mfma_f32_16x16x32_bf16 v[10:13], v[234:237], v[214:217], v[10:13]
	v_mfma_f32_16x16x32_bf16 v[6:9], v[226:229], v[238:241], v[6:9]
	v_mfma_f32_16x16x32_bf16 v[2:5], v[234:237], v[238:241], v[2:5]
	s_barrier
	ds_read_b128 v[168:171], v150
	ds_read_b128 v[172:175], v150 offset:1024
	ds_read_b128 v[186:189], v150 offset:2048
	ds_read_b128 v[190:193], v150 offset:3072
	v_add_u32_e32 v161, 0x4000, v142
	v_add_u32_e32 v162, 0x6000, v142
	v_readfirstlane_b32 s3, v161
	v_lshl_add_u64 v[226:227], v[182:183], 0, s[76:77]
	s_mov_b32 m0, s3
	v_readfirstlane_b32 s3, v162
	ds_read_b128 v[194:197], v146 offset:32768
	ds_read_b128 v[198:201], v146 offset:33792
	ds_read_b128 v[202:205], v145 offset:32768
	ds_read_b128 v[206:209], v145 offset:33792
	ds_read_b128 v[210:213], v144 offset:32768
	ds_read_b128 v[214:217], v144 offset:33792
	ds_read_b128 v[218:221], v143 offset:32768
	ds_read_b128 v[222:225], v143 offset:33792
	global_load_lds_dwordx4 v[226:227], off
	v_lshl_add_u64 v[226:227], v[242:243], 0, s[76:77]
	s_mov_b32 m0, s3
	s_nop 0
	global_load_lds_dwordx4 v[226:227], off
	s_waitcnt lgkmcnt(8)
	s_barrier
	s_waitcnt lgkmcnt(0)
	v_mfma_f32_16x16x32_bf16 v[126:129], v[168:171], v[194:197], v[126:129]
	v_mfma_f32_16x16x32_bf16 v[122:125], v[186:189], v[194:197], v[122:125]
	v_mfma_f32_16x16x32_bf16 v[118:121], v[168:171], v[202:205], v[118:121]
	v_mfma_f32_16x16x32_bf16 v[114:117], v[186:189], v[202:205], v[114:117]
	v_mfma_f32_16x16x32_bf16 v[110:113], v[168:171], v[210:213], v[110:113]
	v_mfma_f32_16x16x32_bf16 v[106:109], v[186:189], v[210:213], v[106:109]
	v_mfma_f32_16x16x32_bf16 v[102:105], v[168:171], v[218:221], v[102:105]
	v_mfma_f32_16x16x32_bf16 v[98:101], v[186:189], v[218:221], v[98:101]
	v_mfma_f32_16x16x32_bf16 v[126:129], v[172:175], v[198:201], v[126:129]
	v_mfma_f32_16x16x32_bf16 v[122:125], v[190:193], v[198:201], v[122:125]
	v_mfma_f32_16x16x32_bf16 v[118:121], v[172:175], v[206:209], v[118:121]
	v_mfma_f32_16x16x32_bf16 v[114:117], v[190:193], v[206:209], v[114:117]
	v_mfma_f32_16x16x32_bf16 v[110:113], v[172:175], v[214:217], v[110:113]
	v_mfma_f32_16x16x32_bf16 v[106:109], v[190:193], v[214:217], v[106:109]
	v_mfma_f32_16x16x32_bf16 v[102:105], v[172:175], v[222:225], v[102:105]
	v_mfma_f32_16x16x32_bf16 v[98:101], v[190:193], v[222:225], v[98:101]
	s_barrier
	v_readfirstlane_b32 s3, v149
	v_add_u32_e32 v167, 0x2000, v149
	v_lshl_add_u64 v[248:249], v[244:245], 0, s[34:35]
	s_mov_b32 m0, s3
	v_readfirstlane_b32 s3, v167
	ds_read_b128 v[226:229], v148
	ds_read_b128 v[230:233], v148 offset:1024
	ds_read_b128 v[234:237], v148 offset:2048
	ds_read_b128 v[238:241], v148 offset:3072
	global_load_lds_dwordx4 v[248:249], off
	v_lshl_add_u64 v[248:249], v[246:247], 0, s[34:35]
	s_mov_b32 m0, s3
	s_nop 0
	global_load_lds_dwordx4 v[248:249], off
	s_barrier
	s_waitcnt lgkmcnt(0)
	v_mfma_f32_16x16x32_bf16 v[94:97], v[226:229], v[194:197], v[94:97]
	v_mfma_f32_16x16x32_bf16 v[90:93], v[234:237], v[194:197], v[90:93]
	v_mfma_f32_16x16x32_bf16 v[86:89], v[226:229], v[202:205], v[86:89]
	v_mfma_f32_16x16x32_bf16 v[82:85], v[234:237], v[202:205], v[82:85]
	v_mfma_f32_16x16x32_bf16 v[78:81], v[226:229], v[210:213], v[78:81]
	v_mfma_f32_16x16x32_bf16 v[74:77], v[234:237], v[210:213], v[74:77]
	v_mfma_f32_16x16x32_bf16 v[70:73], v[226:229], v[218:221], v[70:73]
	v_mfma_f32_16x16x32_bf16 v[66:69], v[234:237], v[218:221], v[66:69]
	v_mfma_f32_16x16x32_bf16 v[94:97], v[230:233], v[198:201], v[94:97]
	v_mfma_f32_16x16x32_bf16 v[90:93], v[238:241], v[198:201], v[90:93]
	v_mfma_f32_16x16x32_bf16 v[86:89], v[230:233], v[206:209], v[86:89]
	v_mfma_f32_16x16x32_bf16 v[82:85], v[238:241], v[206:209], v[82:85]
	v_mfma_f32_16x16x32_bf16 v[78:81], v[230:233], v[214:217], v[78:81]
	v_mfma_f32_16x16x32_bf16 v[74:77], v[238:241], v[214:217], v[74:77]
	v_mfma_f32_16x16x32_bf16 v[70:73], v[230:233], v[222:225], v[70:73]
	v_mfma_f32_16x16x32_bf16 v[66:69], v[238:241], v[222:225], v[66:69]
	s_barrier
	v_readfirstlane_b32 s3, v151
	v_lshl_add_u64 v[182:183], v[182:183], 0, s[74:75]
	s_mov_b32 m0, s3
	v_readfirstlane_b32 s3, v152
	ds_read_b128 v[194:197], v146 offset:49152
	ds_read_b128 v[198:201], v146 offset:50176
	ds_read_b128 v[202:205], v145 offset:49152
	ds_read_b128 v[206:209], v145 offset:50176
	ds_read_b128 v[210:213], v144 offset:49152
	ds_read_b128 v[214:217], v144 offset:50176
	ds_read_b128 v[218:221], v143 offset:49152
	ds_read_b128 v[222:225], v143 offset:50176
	global_load_lds_dwordx4 v[182:183], off
	v_lshl_add_u64 v[182:183], v[242:243], 0, s[74:75]
	s_mov_b32 m0, s3
	s_nop 0
	global_load_lds_dwordx4 v[182:183], off
	s_barrier
; #define STAGE_A(P,br,kt) STAGE_G(P,c.A,c.lda,br,(long)(kt)*c.kstr)
; #define STAGE_B(P,br,kt) STAGE_G(P,c.Bt,c.K,br,(long)(kt)*BK)
; #define LDA(dst,b,h) for(int m=0;m<4;++m)for(int k=0;k<2;++k) \
;     dst[m][k]=*reinterpret_cast<const bf16x8*>((char*)SA(b,h)+lds_byte(wr*64+m*16+fr,k*32+fq*8))
; #define LDB(dst,b,h) for(int n=0;n<2;++n)for(int k=0;k<2;++k) \
;     dst[n][k]=*reinterpret_cast<const bf16x8*>((char*)SB(b,h)+lds_byte(wc*32+n*16+fr,k*32+fq*8))
; #define MMA(ai,bj,At,Bt_) do{__builtin_amdgcn_s_setprio(1); \
;     for(int m=0;m<4;++m)for(int n=0;n<2;++n)for(int k=0;k<2;++k) \
;       acc[ai][bj][m][n]=__builtin_amdgcn_mfma_f32_16x16x32_bf16(Bt_[n][k],At[m][k],acc[ai][bj][m][n],0,0,0); \
;     __builtin_amdgcn_s_setprio(0);}while(0)
; #define WAIT_V(n) asm volatile("s_waitcnt vmcnt(" #n ")":::"memory")
; #define WAIT_L(n) asm volatile("s_waitcnt lgkmcnt(" #n ")":::"memory")
; #define BAR __builtin_amdgcn_s_barrier()
; #define SCHED __builtin_amdgcn_sched_barrier(0)
; template <int EPI>
; __device__ __forceinline__ void gemm_run(const GD& c, const bool has_next, const GD& nx, const Ctx& e, bf16* shm, float* rs, float* rs_nxt, float* racc_) {
;     ...
;     BAR; WAIT_L(0); MMA(1,0,At,B0); BAR; SCHED;
;     STAGE_B(SB(1,1),bcol+HALF,t+3);
;     WAIT_V(6); BAR; MMA(1,1,At,B1); BAR;
;   }
;   { LDB(B0,0,0); LDA(At,0,0); STAGE_A(SA(1,1),brow+HALF,nt-1);
;     BAR; WAIT_L(0); MMA(0,0,At,B0); BAR;
	s_waitcnt lgkmcnt(0)
	v_mfma_f32_16x16x32_bf16 v[62:65], v[168:171], v[194:197], v[62:65]
	v_mfma_f32_16x16x32_bf16 v[58:61], v[186:189], v[194:197], v[58:61]
	v_mfma_f32_16x16x32_bf16 v[54:57], v[168:171], v[202:205], v[54:57]
	v_mfma_f32_16x16x32_bf16 v[50:53], v[186:189], v[202:205], v[50:53]
	v_mfma_f32_16x16x32_bf16 v[46:49], v[168:171], v[210:213], v[46:49]
	v_mfma_f32_16x16x32_bf16 v[42:45], v[186:189], v[210:213], v[42:45]
	v_mfma_f32_16x16x32_bf16 v[38:41], v[168:171], v[218:221], v[38:41]
	v_mfma_f32_16x16x32_bf16 v[34:37], v[186:189], v[218:221], v[34:37]
	v_mfma_f32_16x16x32_bf16 v[62:65], v[172:175], v[198:201], v[62:65]
	v_mfma_f32_16x16x32_bf16 v[58:61], v[190:193], v[198:201], v[58:61]
	v_mfma_f32_16x16x32_bf16 v[54:57], v[172:175], v[206:209], v[54:57]
	v_mfma_f32_16x16x32_bf16 v[50:53], v[190:193], v[206:209], v[50:53]
	v_mfma_f32_16x16x32_bf16 v[46:49], v[172:175], v[214:217], v[46:49]
	v_mfma_f32_16x16x32_bf16 v[42:45], v[190:193], v[214:217], v[42:45]
	v_mfma_f32_16x16x32_bf16 v[38:41], v[172:175], v[222:225], v[38:41]
	v_mfma_f32_16x16x32_bf16 v[34:37], v[190:193], v[222:225], v[34:37]
	s_barrier
	v_readfirstlane_b32 s3, v153
	v_add_u32_e32 v167, 0x2000, v153
	v_lshl_add_u64 v[168:169], v[244:245], 0, s[36:37]
	s_mov_b32 m0, s3
	v_readfirstlane_b32 s3, v167
	global_load_lds_dwordx4 v[168:169], off
	v_lshl_add_u64 v[168:169], v[246:247], 0, s[36:37]
	s_mov_b32 m0, s3
	s_nop 0
	global_load_lds_dwordx4 v[168:169], off
	s_waitcnt vmcnt(6)
	s_barrier
	v_mfma_f32_16x16x32_bf16 v[30:33], v[226:229], v[194:197], v[30:33]
	v_mfma_f32_16x16x32_bf16 v[26:29], v[234:237], v[194:197], v[26:29]
	v_mfma_f32_16x16x32_bf16 v[22:25], v[226:229], v[202:205], v[22:25]
	v_mfma_f32_16x16x32_bf16 v[18:21], v[234:237], v[202:205], v[18:21]
	s_add_i32 s2, s2, 2
	v_mfma_f32_16x16x32_bf16 v[14:17], v[226:229], v[210:213], v[14:17]
	v_lshl_add_u64 v[132:133], v[132:133], 0, s[88:89]
	v_mfma_f32_16x16x32_bf16 v[10:13], v[234:237], v[210:213], v[10:13]
	v_lshl_add_u64 v[134:135], v[134:135], 0, s[88:89]
	v_mfma_f32_16x16x32_bf16 v[6:9], v[226:229], v[218:221], v[6:9]
	v_lshl_add_u64 v[136:137], v[136:137], 0, s[88:89]
	v_mfma_f32_16x16x32_bf16 v[2:5], v[234:237], v[218:221], v[2:5]
	s_cmp_lt_u32 s2, 38
	v_mfma_f32_16x16x32_bf16 v[30:33], v[230:233], v[198:201], v[30:33]
	v_lshl_add_u64 v[138:139], v[138:139], 0, s[88:89]
	v_mfma_f32_16x16x32_bf16 v[26:29], v[238:241], v[198:201], v[26:29]
	v_mfma_f32_16x16x32_bf16 v[22:25], v[230:233], v[206:209], v[22:25]
	v_mfma_f32_16x16x32_bf16 v[18:21], v[238:241], v[206:209], v[18:21]
	v_mfma_f32_16x16x32_bf16 v[14:17], v[230:233], v[214:217], v[14:17]
	v_mfma_f32_16x16x32_bf16 v[10:13], v[238:241], v[214:217], v[10:13]
	v_mfma_f32_16x16x32_bf16 v[6:9], v[230:233], v[222:225], v[6:9]
	v_mfma_f32_16x16x32_bf16 v[2:5], v[238:241], v[222:225], v[2:5]
	s_barrier
	s_cbranch_scc1 .LBB0_1178
	s_or_b32 s2, s15, 0x80
	s_mul_hi_i32 s3, s2, 0x1500
	s_mulk_i32 s2, 0x1500
	s_add_u32 s2, s23, s2
	s_addc_u32 s3, s24, s3
	v_readfirstlane_b32 s28, v163
	v_lshl_add_u64 v[152:153], s[2:3], 0, v[0:1]
	s_mov_b32 m0, s28
	ds_read_b128 v[132:135], v155
	ds_read_b128 v[136:139], v155 offset:1024
	ds_read_b128 v[168:171], v155 offset:2048
	ds_read_b128 v[172:175], v155 offset:3072
	ds_read_b128 v[186:189], v146
	ds_read_b128 v[190:193], v146 offset:1024
	ds_read_b128 v[194:197], v145
	ds_read_b128 v[198:201], v145 offset:1024
	ds_read_b128 v[202:205], v144
	ds_read_b128 v[206:209], v144 offset:1024
	ds_read_b128 v[210:213], v143
	ds_read_b128 v[214:217], v143 offset:1024
	global_load_lds_dwordx4 v[152:153], off
	v_lshl_add_u64 v[152:153], s[2:3], 0, v[130:131]
	v_readfirstlane_b32 s2, v166
	s_mov_b32 m0, s2
	s_nop 0
	global_load_lds_dwordx4 v[152:153], off
	s_barrier
	s_waitcnt lgkmcnt(0)
	v_mfma_f32_16x16x32_bf16 v[126:129], v[132:135], v[186:189], v[126:129]
	v_mfma_f32_16x16x32_bf16 v[122:125], v[168:171], v[186:189], v[122:125]
	v_mfma_f32_16x16x32_bf16 v[118:121], v[132:135], v[194:197], v[118:121]
	v_mfma_f32_16x16x32_bf16 v[114:117], v[168:171], v[194:197], v[114:117]
	v_mfma_f32_16x16x32_bf16 v[102:105], v[132:135], v[210:213], v[102:105]
	v_mfma_f32_16x16x32_bf16 v[98:101], v[168:171], v[210:213], v[98:101]
	v_mfma_f32_16x16x32_bf16 v[126:129], v[136:139], v[190:193], v[126:129]
	v_mfma_f32_16x16x32_bf16 v[122:125], v[172:175], v[190:193], v[122:125]
	v_mfma_f32_16x16x32_bf16 v[118:121], v[136:139], v[198:201], v[118:121]
	v_mfma_f32_16x16x32_bf16 v[114:117], v[172:175], v[198:201], v[114:117]
	v_mfma_f32_16x16x32_bf16 v[110:113], v[132:135], v[202:205], v[110:113]
	v_mfma_f32_16x16x32_bf16 v[106:109], v[168:171], v[202:205], v[106:109]
	v_mfma_f32_16x16x32_bf16 v[102:105], v[136:139], v[214:217], v[102:105]
	v_mfma_f32_16x16x32_bf16 v[98:101], v[172:175], v[214:217], v[98:101]
	v_mfma_f32_16x16x32_bf16 v[218:221], v[136:139], v[206:209], v[110:113]
	v_mfma_f32_16x16x32_bf16 v[222:225], v[172:175], v[206:209], v[106:109]
	s_barrier
	s_nop 1
	ds_read_b128 v[106:109], v154
	ds_read_b128 v[110:113], v154 offset:1024
	ds_read_b128 v[226:229], v154 offset:2048
	ds_read_b128 v[152:155], v154 offset:3072
	s_barrier
; #define LDA(dst,b,h) for(int m=0;m<4;++m)for(int k=0;k<2;++k) \
;     dst[m][k]=*reinterpret_cast<const bf16x8*>((char*)SA(b,h)+lds_byte(wr*64+m*16+fr,k*32+fq*8))
; #define LDB(dst,b,h) for(int n=0;n<2;++n)for(int k=0;k<2;++k) \
;     dst[n][k]=*reinterpret_cast<const bf16x8*>((char*)SB(b,h)+lds_byte(wc*32+n*16+fr,k*32+fq*8))
; #define MMA(ai,bj,At,Bt_) do{__builtin_amdgcn_s_setprio(1); \
;     for(int m=0;m<4;++m)for(int n=0;n<2;++n)for(int k=0;k<2;++k) \
;       acc[ai][bj][m][n]=__builtin_amdgcn_mfma_f32_16x16x32_bf16(Bt_[n][k],At[m][k],acc[ai][bj][m][n],0,0,0); \
;     __builtin_amdgcn_s_setprio(0);}while(0)
; #define WAIT_V(n) asm volatile("s_waitcnt vmcnt(" #n ")":::"memory")
; #define WAIT_L(n) asm volatile("s_waitcnt lgkmcnt(" #n ")":::"memory")
; #define BAR __builtin_amdgcn_s_barrier()
; template <int EPI>
; __device__ __forceinline__ void gemm_run(const GD& c, const bool has_next, const GD& nx, const Ctx& e, bf16* shm, float* rs, float* rs_nxt, float* racc_) {
;     ...
;     LDB(B1,0,1); BAR; WAIT_L(0); MMA(0,1,At,B1); BAR;
;     LDA(At,0,1); WAIT_V(4); BAR; WAIT_L(0); MMA(1,0,At,B0); MMA(1,1,At,B1); BAR; }
;   { LDB(B0,1,0); LDA(At,1,0); WAIT_V(2); BAR; WAIT_L(0); MMA(0,0,At,B0); BAR;
	s_waitcnt lgkmcnt(0)
	v_mfma_f32_16x16x32_bf16 v[86:89], v[106:109], v[194:197], v[86:89]
	v_mfma_f32_16x16x32_bf16 v[82:85], v[226:229], v[194:197], v[82:85]
	v_mfma_f32_16x16x32_bf16 v[70:73], v[106:109], v[210:213], v[70:73]
	v_mfma_f32_16x16x32_bf16 v[66:69], v[226:229], v[210:213], v[66:69]
	v_mfma_f32_16x16x32_bf16 v[94:97], v[106:109], v[186:189], v[94:97]
	v_mfma_f32_16x16x32_bf16 v[90:93], v[226:229], v[186:189], v[90:93]
	v_mfma_f32_16x16x32_bf16 v[86:89], v[110:113], v[198:201], v[86:89]
	v_mfma_f32_16x16x32_bf16 v[82:85], v[152:155], v[198:201], v[82:85]
	v_mfma_f32_16x16x32_bf16 v[78:81], v[106:109], v[202:205], v[78:81]
	v_mfma_f32_16x16x32_bf16 v[74:77], v[226:229], v[202:205], v[74:77]
	v_mfma_f32_16x16x32_bf16 v[70:73], v[110:113], v[214:217], v[70:73]
	v_mfma_f32_16x16x32_bf16 v[66:69], v[152:155], v[214:217], v[66:69]
	v_mfma_f32_16x16x32_bf16 v[230:233], v[110:113], v[190:193], v[94:97]
	v_mfma_f32_16x16x32_bf16 v[186:189], v[152:155], v[190:193], v[90:93]
	v_mfma_f32_16x16x32_bf16 v[190:193], v[110:113], v[206:209], v[78:81]
	v_mfma_f32_16x16x32_bf16 v[194:197], v[152:155], v[206:209], v[74:77]
	s_barrier
	s_nop 0
	ds_read_b128 v[74:77], v146 offset:16384
	ds_read_b128 v[78:81], v146 offset:17408
	ds_read_b128 v[90:93], v145 offset:16384
	ds_read_b128 v[94:97], v145 offset:17408
	ds_read_b128 v[198:201], v144 offset:16384
	ds_read_b128 v[202:205], v144 offset:17408
	ds_read_b128 v[206:209], v143 offset:16384
	ds_read_b128 v[210:213], v143 offset:17408
	s_waitcnt vmcnt(4)
	s_barrier
	s_waitcnt lgkmcnt(0)
	v_mfma_f32_16x16x32_bf16 v[62:65], v[132:135], v[74:77], v[62:65]
	v_mfma_f32_16x16x32_bf16 v[58:61], v[168:171], v[74:77], v[58:61]
	v_mfma_f32_16x16x32_bf16 v[54:57], v[132:135], v[90:93], v[54:57]
	v_mfma_f32_16x16x32_bf16 v[50:53], v[168:171], v[90:93], v[50:53]
	v_mfma_f32_16x16x32_bf16 v[38:41], v[132:135], v[206:209], v[38:41]
	v_mfma_f32_16x16x32_bf16 v[34:37], v[168:171], v[206:209], v[34:37]
	v_mfma_f32_16x16x32_bf16 v[62:65], v[136:139], v[78:81], v[62:65]
	v_mfma_f32_16x16x32_bf16 v[58:61], v[172:175], v[78:81], v[58:61]
	v_mfma_f32_16x16x32_bf16 v[54:57], v[136:139], v[94:97], v[54:57]
	v_mfma_f32_16x16x32_bf16 v[50:53], v[172:175], v[94:97], v[50:53]
	v_mfma_f32_16x16x32_bf16 v[46:49], v[132:135], v[198:201], v[46:49]
	v_mfma_f32_16x16x32_bf16 v[42:45], v[168:171], v[198:201], v[42:45]
	v_mfma_f32_16x16x32_bf16 v[38:41], v[136:139], v[210:213], v[38:41]
	v_mfma_f32_16x16x32_bf16 v[34:37], v[172:175], v[210:213], v[34:37]
	v_mfma_f32_16x16x32_bf16 v[214:217], v[136:139], v[202:205], v[46:49]
	v_mfma_f32_16x16x32_bf16 v[234:237], v[172:175], v[202:205], v[42:45]
	v_mfma_f32_16x16x32_bf16 v[22:25], v[106:109], v[90:93], v[22:25]
	v_mfma_f32_16x16x32_bf16 v[18:21], v[226:229], v[90:93], v[18:21]
	v_mfma_f32_16x16x32_bf16 v[6:9], v[106:109], v[206:209], v[6:9]
	v_mfma_f32_16x16x32_bf16 v[2:5], v[226:229], v[206:209], v[2:5]
	v_mfma_f32_16x16x32_bf16 v[30:33], v[106:109], v[74:77], v[30:33]
	v_mfma_f32_16x16x32_bf16 v[26:29], v[226:229], v[74:77], v[26:29]
	v_mfma_f32_16x16x32_bf16 v[22:25], v[110:113], v[94:97], v[22:25]
	v_mfma_f32_16x16x32_bf16 v[18:21], v[152:155], v[94:97], v[18:21]
	v_mfma_f32_16x16x32_bf16 v[14:17], v[106:109], v[198:201], v[14:17]
	v_mfma_f32_16x16x32_bf16 v[10:13], v[226:229], v[198:201], v[10:13]
	v_mfma_f32_16x16x32_bf16 v[6:9], v[110:113], v[210:213], v[6:9]
	v_mfma_f32_16x16x32_bf16 v[2:5], v[152:155], v[210:213], v[2:5]
	v_mfma_f32_16x16x32_bf16 v[132:135], v[110:113], v[78:81], v[30:33]
	v_mfma_f32_16x16x32_bf16 v[136:139], v[152:155], v[78:81], v[26:29]
	v_mfma_f32_16x16x32_bf16 v[166:169], v[110:113], v[202:205], v[14:17]
	v_mfma_f32_16x16x32_bf16 v[170:173], v[152:155], v[202:205], v[10:13]
	s_barrier
	s_nop 0
	ds_read_b128 v[10:13], v150
	ds_read_b128 v[14:17], v150 offset:1024
	ds_read_b128 v[152:155], v150 offset:2048
	ds_read_b128 v[198:201], v150 offset:3072
	ds_read_b128 v[26:29], v146 offset:32768
	ds_read_b128 v[30:33], v146 offset:33792
	ds_read_b128 v[42:45], v145 offset:32768
	ds_read_b128 v[46:49], v145 offset:33792
	ds_read_b128 v[202:205], v144 offset:32768
	ds_read_b128 v[206:209], v144 offset:33792
	ds_read_b128 v[210:213], v143 offset:32768
	ds_read_b128 v[226:229], v143 offset:33792
	s_waitcnt vmcnt(2)
	s_barrier
; #define STAGE_A(P,br,kt) STAGE_G(P,c.A,c.lda,br,(long)(kt)*c.kstr)
; #define LDA(dst,b,h) for(int m=0;m<4;++m)for(int k=0;k<2;++k) \
;     dst[m][k]=*reinterpret_cast<const bf16x8*>((char*)SA(b,h)+lds_byte(wr*64+m*16+fr,k*32+fq*8))
; #define LDB(dst,b,h) for(int n=0;n<2;++n)for(int k=0;k<2;++k) \
;     dst[n][k]=*reinterpret_cast<const bf16x8*>((char*)SB(b,h)+lds_byte(wc*32+n*16+fr,k*32+fq*8))
; #define MMA(ai,bj,At,Bt_) do{__builtin_amdgcn_s_setprio(1); \
;     for(int m=0;m<4;++m)for(int n=0;n<2;++n)for(int k=0;k<2;++k) \
;       acc[ai][bj][m][n]=__builtin_amdgcn_mfma_f32_16x16x32_bf16(Bt_[n][k],At[m][k],acc[ai][bj][m][n],0,0,0); \
;     __builtin_amdgcn_s_setprio(0);}while(0)
; #define WAIT_V(n) asm volatile("s_waitcnt vmcnt(" #n ")":::"memory")
; #define WAIT_L(n) asm volatile("s_waitcnt lgkmcnt(" #n ")":::"memory")
; #define BAR __builtin_amdgcn_s_barrier()
; template <int EPI>
; __device__ __forceinline__ void gemm_run(const GD& c, const bool has_next, const GD& nx, const Ctx& e, bf16* shm, float* rs, float* rs_nxt, float* racc_) {
;     ...
;   { LDB(B0,0,0); LDA(At,0,0); STAGE_A(SA(1,1),brow+HALF,nt-1);
;     BAR; WAIT_L(0); MMA(0,0,At,B0); BAR;
;     LDB(B1,0,1); BAR; WAIT_L(0); MMA(0,1,At,B1); BAR;
;     LDA(At,0,1); WAIT_V(4); BAR; WAIT_L(0); MMA(1,0,At,B0); MMA(1,1,At,B1); BAR; }
;   { LDB(B0,1,0); LDA(At,1,0); WAIT_V(2); BAR; WAIT_L(0); MMA(0,0,At,B0); BAR;
;     LDB(B1,1,1); WAIT_V(0); BAR; WAIT_L(0); MMA(0,1,At,B1); BAR;
;     LDA(At,1,1); BAR; WAIT_L(0); MMA(1,0,At,B0); MMA(1,1,At,B1); BAR; }
;   if(wr==0)BAR;
	s_waitcnt lgkmcnt(0)
	v_mfma_f32_16x16x32_bf16 v[74:77], v[10:13], v[26:29], v[126:129]
	v_mfma_f32_16x16x32_bf16 v[126:129], v[14:17], v[30:33], v[74:77]
	v_mfma_f32_16x16x32_bf16 v[74:77], v[152:155], v[26:29], v[122:125]
	v_mfma_f32_16x16x32_bf16 v[122:125], v[198:201], v[30:33], v[74:77]
	v_mfma_f32_16x16x32_bf16 v[74:77], v[10:13], v[42:45], v[118:121]
	v_mfma_f32_16x16x32_bf16 v[110:113], v[14:17], v[46:49], v[74:77]
	v_mfma_f32_16x16x32_bf16 v[74:77], v[152:155], v[42:45], v[114:117]
	v_mfma_f32_16x16x32_bf16 v[106:109], v[198:201], v[46:49], v[74:77]
	v_mfma_f32_16x16x32_bf16 v[74:77], v[10:13], v[202:205], v[218:221]
	v_mfma_f32_16x16x32_bf16 v[94:97], v[14:17], v[206:209], v[74:77]
	v_mfma_f32_16x16x32_bf16 v[74:77], v[152:155], v[202:205], v[222:225]
	v_mfma_f32_16x16x32_bf16 v[90:93], v[198:201], v[206:209], v[74:77]
	v_mfma_f32_16x16x32_bf16 v[74:77], v[10:13], v[210:213], v[102:105]
	v_mfma_f32_16x16x32_bf16 v[78:81], v[14:17], v[226:229], v[74:77]
	v_mfma_f32_16x16x32_bf16 v[74:77], v[152:155], v[210:213], v[98:101]
	v_mfma_f32_16x16x32_bf16 v[74:77], v[198:201], v[226:229], v[74:77]
	s_barrier
	ds_read_b128 v[218:221], v148
	ds_read_b128 v[222:225], v148 offset:1024
	ds_read_b128 v[238:241], v148 offset:2048
	ds_read_b128 v[148:151], v148 offset:3072
	s_waitcnt vmcnt(0)
	s_barrier
	s_waitcnt lgkmcnt(0)
	v_mfma_f32_16x16x32_bf16 v[98:101], v[218:221], v[26:29], v[230:233]
	v_mfma_f32_16x16x32_bf16 v[26:29], v[238:241], v[26:29], v[186:189]
	v_mfma_f32_16x16x32_bf16 v[114:117], v[148:151], v[30:33], v[26:29]
	v_mfma_f32_16x16x32_bf16 v[26:29], v[218:221], v[42:45], v[86:89]
	v_mfma_f32_16x16x32_bf16 v[102:105], v[222:225], v[46:49], v[26:29]
	v_mfma_f32_16x16x32_bf16 v[26:29], v[238:241], v[42:45], v[82:85]
	v_mfma_f32_16x16x32_bf16 v[118:121], v[222:225], v[30:33], v[98:101]
	v_mfma_f32_16x16x32_bf16 v[98:101], v[148:151], v[46:49], v[26:29]
	v_mfma_f32_16x16x32_bf16 v[26:29], v[218:221], v[202:205], v[190:193]
	v_mfma_f32_16x16x32_bf16 v[86:89], v[222:225], v[206:209], v[26:29]
	v_mfma_f32_16x16x32_bf16 v[26:29], v[238:241], v[202:205], v[194:197]
	v_mfma_f32_16x16x32_bf16 v[82:85], v[148:151], v[206:209], v[26:29]
	v_mfma_f32_16x16x32_bf16 v[26:29], v[218:221], v[210:213], v[70:73]
	v_mfma_f32_16x16x32_bf16 v[70:73], v[222:225], v[226:229], v[26:29]
	v_mfma_f32_16x16x32_bf16 v[26:29], v[238:241], v[210:213], v[66:69]
	v_mfma_f32_16x16x32_bf16 v[66:69], v[148:151], v[226:229], v[26:29]
	s_barrier
	ds_read_b128 v[186:189], v146 offset:49152
	ds_read_b128 v[190:193], v146 offset:50176
	ds_read_b128 v[194:197], v145 offset:49152
	ds_read_b128 v[202:205], v145 offset:50176
	ds_read_b128 v[206:209], v144 offset:49152
	ds_read_b128 v[144:147], v144 offset:50176
	ds_read_b128 v[210:213], v143 offset:49152
	ds_read_b128 v[226:229], v143 offset:50176
	s_barrier
	s_waitcnt lgkmcnt(0)
	v_mfma_f32_16x16x32_bf16 v[26:29], v[10:13], v[186:189], v[62:65]
	v_mfma_f32_16x16x32_bf16 v[62:65], v[14:17], v[190:193], v[26:29]
	v_mfma_f32_16x16x32_bf16 v[26:29], v[152:155], v[186:189], v[58:61]
	v_mfma_f32_16x16x32_bf16 v[58:61], v[198:201], v[190:193], v[26:29]
	v_mfma_f32_16x16x32_bf16 v[26:29], v[10:13], v[194:197], v[54:57]
	v_mfma_f32_16x16x32_bf16 v[46:49], v[14:17], v[202:205], v[26:29]
	v_mfma_f32_16x16x32_bf16 v[26:29], v[152:155], v[194:197], v[50:53]
	v_mfma_f32_16x16x32_bf16 v[42:45], v[198:201], v[202:205], v[26:29]
	v_mfma_f32_16x16x32_bf16 v[26:29], v[10:13], v[206:209], v[214:217]
	v_mfma_f32_16x16x32_bf16 v[10:13], v[10:13], v[210:213], v[38:41]
	v_mfma_f32_16x16x32_bf16 v[30:33], v[14:17], v[144:147], v[26:29]
	v_mfma_f32_16x16x32_bf16 v[26:29], v[152:155], v[206:209], v[234:237]
	v_mfma_f32_16x16x32_bf16 v[14:17], v[14:17], v[226:229], v[10:13]
	v_mfma_f32_16x16x32_bf16 v[10:13], v[152:155], v[210:213], v[34:37]
	v_mfma_f32_16x16x32_bf16 v[26:29], v[198:201], v[144:147], v[26:29]
	v_mfma_f32_16x16x32_bf16 v[10:13], v[198:201], v[226:229], v[10:13]
	v_mfma_f32_16x16x32_bf16 v[34:37], v[218:221], v[186:189], v[132:135]
	v_mfma_f32_16x16x32_bf16 v[54:57], v[222:225], v[190:193], v[34:37]
	v_mfma_f32_16x16x32_bf16 v[34:37], v[238:241], v[186:189], v[136:139]
	v_mfma_f32_16x16x32_bf16 v[18:21], v[238:241], v[194:197], v[18:21]
	v_mfma_f32_16x16x32_bf16 v[50:53], v[148:151], v[190:193], v[34:37]
	v_mfma_f32_16x16x32_bf16 v[22:25], v[218:221], v[194:197], v[22:25]
	v_mfma_f32_16x16x32_bf16 v[34:37], v[148:151], v[202:205], v[18:21]
	v_mfma_f32_16x16x32_bf16 v[18:21], v[218:221], v[206:209], v[166:169]
	v_mfma_f32_16x16x32_bf16 v[38:41], v[222:225], v[202:205], v[22:25]
	v_mfma_f32_16x16x32_bf16 v[22:25], v[222:225], v[144:147], v[18:21]
	v_mfma_f32_16x16x32_bf16 v[18:21], v[238:241], v[206:209], v[170:173]
	v_mfma_f32_16x16x32_bf16 v[6:9], v[218:221], v[210:213], v[6:9]
	v_mfma_f32_16x16x32_bf16 v[2:5], v[238:241], v[210:213], v[2:5]
	v_mfma_f32_16x16x32_bf16 v[18:21], v[148:151], v[144:147], v[18:21]
	v_mfma_f32_16x16x32_bf16 v[6:9], v[222:225], v[226:229], v[6:9]
	v_mfma_f32_16x16x32_bf16 v[2:5], v[148:151], v[226:229], v[2:5]
	v_cmp_gt_u32_e32 vcc, s96, v141
	s_barrier
	s_and_saveexec_b64 s[2:3], vcc
	s_cbranch_execz .LBB0_1181
	s_barrier

; #define STAGE_A(P,br,kt) STAGE_G(P,c.A,c.lda,br,(long)(kt)*c.kstr)
; #define STAGE_B(P,br,kt) STAGE_G(P,c.Bt,c.K,br,(long)(kt)*BK)
; #define LDA(dst,b,h) for(int m=0;m<4;++m)for(int k=0;k<2;++k) \
;     dst[m][k]=*reinterpret_cast<const bf16x8*>((char*)SA(b,h)+lds_byte(wr*64+m*16+fr,k*32+fq*8))
; #define LDB(dst,b,h) for(int n=0;n<2;++n)for(int k=0;k<2;++k) \
;     dst[n][k]=*reinterpret_cast<const bf16x8*>((char*)SB(b,h)+lds_byte(wc*32+n*16+fr,k*32+fq*8))
; #define MMA(ai,bj,At,Bt_) do{__builtin_amdgcn_s_setprio(1); \
;     for(int m=0;m<4;++m)for(int n=0;n<2;++n)for(int k=0;k<2;++k) \
;       acc[ai][bj][m][n]=__builtin_amdgcn_mfma_f32_16x16x32_bf16(Bt_[n][k],At[m][k],acc[ai][bj][m][n],0,0,0); \
;     __builtin_amdgcn_s_setprio(0);}while(0)
; #define WAIT_L(n) asm volatile("s_waitcnt lgkmcnt(" #n ")":::"memory")
; #define BAR __builtin_amdgcn_s_barrier()
; #define SCHED __builtin_amdgcn_sched_barrier(0)
; template <int EPI>
; __device__ __forceinline__ void gemm_run(const GD& c, const bool has_next, const GD& nx, const Ctx& e, bf16* shm, float* rs, float* rs_nxt, float* racc_) {
;     ...
;   for(int t=0;t<nt-2;t+=2){
;     LDB(B0,0,0); SCHED; LDA(At,0,0); STAGE_A(SA(1,1),brow+HALF,t+1);
;     WAIT_L(8); BAR; WAIT_L(0); MMA(0,0,At,B0); BAR; SCHED;
;     LDB(B1,0,1); STAGE_B(SB(0,0),bcol,t+2);
;     BAR; WAIT_L(0); MMA(0,1,At,B1); BAR;
;     LDA(At,0,1); STAGE_A(SA(0,0),brow,t+2);
;     BAR; WAIT_L(0); MMA(1,0,At,B0); BAR; SCHED;
.LBB0_1426:
	ds_read_b128 v[168:171], v155
	ds_read_b128 v[172:175], v155 offset:1024
	ds_read_b128 v[186:189], v155 offset:2048
	ds_read_b128 v[190:193], v155 offset:3072
	v_add_u32_e32 v163, 0xc000, v142
	v_lshl_add_u64 v[182:183], s[2:3], 0, v[132:133]
	v_readfirstlane_b32 s15, v163
	v_add_u32_e32 v166, 0xe000, v142
	v_lshl_add_u64 v[156:157], v[182:183], 0, s[90:91]
	s_mov_b32 m0, s15
	v_lshl_add_u64 v[242:243], s[2:3], 0, v[134:135]
	v_readfirstlane_b32 s15, v166
	ds_read_b128 v[158:161], v146
	ds_read_b128 v[194:197], v146 offset:1024
	ds_read_b128 v[198:201], v145
	ds_read_b128 v[202:205], v145 offset:1024
	ds_read_b128 v[206:209], v144
	ds_read_b128 v[210:213], v144 offset:1024
	ds_read_b128 v[214:217], v143
	ds_read_b128 v[218:221], v143 offset:1024
	global_load_lds_dwordx4 v[156:157], off
	v_lshl_add_u64 v[156:157], v[242:243], 0, s[90:91]
	s_mov_b32 m0, s15
	s_nop 0
	global_load_lds_dwordx4 v[156:157], off
	s_waitcnt lgkmcnt(8)
	s_barrier
	s_waitcnt lgkmcnt(0)
	v_mfma_f32_16x16x32_bf16 v[126:129], v[168:171], v[158:161], v[126:129]
	v_mfma_f32_16x16x32_bf16 v[122:125], v[186:189], v[158:161], v[122:125]
	v_mfma_f32_16x16x32_bf16 v[118:121], v[168:171], v[198:201], v[118:121]
	v_mfma_f32_16x16x32_bf16 v[114:117], v[186:189], v[198:201], v[114:117]
	v_mfma_f32_16x16x32_bf16 v[110:113], v[168:171], v[206:209], v[110:113]
	v_mfma_f32_16x16x32_bf16 v[106:109], v[186:189], v[206:209], v[106:109]
	v_mfma_f32_16x16x32_bf16 v[102:105], v[168:171], v[214:217], v[102:105]
	v_mfma_f32_16x16x32_bf16 v[98:101], v[186:189], v[214:217], v[98:101]
	v_mfma_f32_16x16x32_bf16 v[126:129], v[172:175], v[194:197], v[126:129]
	v_mfma_f32_16x16x32_bf16 v[122:125], v[190:193], v[194:197], v[122:125]
	v_mfma_f32_16x16x32_bf16 v[118:121], v[172:175], v[202:205], v[118:121]
	v_mfma_f32_16x16x32_bf16 v[114:117], v[190:193], v[202:205], v[114:117]
	v_mfma_f32_16x16x32_bf16 v[110:113], v[172:175], v[210:213], v[110:113]
	v_mfma_f32_16x16x32_bf16 v[106:109], v[190:193], v[210:213], v[106:109]
	v_mfma_f32_16x16x32_bf16 v[102:105], v[172:175], v[218:221], v[102:105]
	v_mfma_f32_16x16x32_bf16 v[98:101], v[190:193], v[218:221], v[98:101]
	s_barrier
	v_add_u32_e32 v156, s33, v148
	v_lshl_add_u64 v[244:245], s[2:3], 0, v[136:137]
	v_readfirstlane_b32 s15, v156
	v_add_u32_e32 v157, 0x2000, v156
	v_lshl_add_u64 v[238:239], v[244:245], 0, s[28:29]
	s_mov_b32 m0, s15
	v_lshl_add_u64 v[246:247], s[2:3], 0, v[138:139]
	v_readfirstlane_b32 s15, v157
	ds_read_b128 v[222:225], v154
	ds_read_b128 v[226:229], v154 offset:1024
	ds_read_b128 v[230:233], v154 offset:2048
	ds_read_b128 v[234:237], v154 offset:3072
	global_load_lds_dwordx4 v[238:239], off
	v_lshl_add_u64 v[238:239], v[246:247], 0, s[28:29]
	s_mov_b32 m0, s15
	s_nop 0
	global_load_lds_dwordx4 v[238:239], off
	s_barrier
	s_waitcnt lgkmcnt(0)
	v_mfma_f32_16x16x32_bf16 v[94:97], v[222:225], v[158:161], v[94:97]
	v_mfma_f32_16x16x32_bf16 v[90:93], v[230:233], v[158:161], v[90:93]
	v_mfma_f32_16x16x32_bf16 v[86:89], v[222:225], v[198:201], v[86:89]
	v_mfma_f32_16x16x32_bf16 v[82:85], v[230:233], v[198:201], v[82:85]
	v_mfma_f32_16x16x32_bf16 v[78:81], v[222:225], v[206:209], v[78:81]
	v_mfma_f32_16x16x32_bf16 v[74:77], v[230:233], v[206:209], v[74:77]
	v_mfma_f32_16x16x32_bf16 v[70:73], v[222:225], v[214:217], v[70:73]
	v_mfma_f32_16x16x32_bf16 v[66:69], v[230:233], v[214:217], v[66:69]
	v_mfma_f32_16x16x32_bf16 v[94:97], v[226:229], v[194:197], v[94:97]
	v_mfma_f32_16x16x32_bf16 v[90:93], v[234:237], v[194:197], v[90:93]
	v_mfma_f32_16x16x32_bf16 v[86:89], v[226:229], v[202:205], v[86:89]
	v_mfma_f32_16x16x32_bf16 v[82:85], v[234:237], v[202:205], v[82:85]
	v_mfma_f32_16x16x32_bf16 v[78:81], v[226:229], v[210:213], v[78:81]
	v_mfma_f32_16x16x32_bf16 v[74:77], v[234:237], v[210:213], v[74:77]
	v_mfma_f32_16x16x32_bf16 v[70:73], v[226:229], v[218:221], v[70:73]
	v_mfma_f32_16x16x32_bf16 v[66:69], v[234:237], v[218:221], v[66:69]
	v_readfirstlane_b32 s15, v142
	v_lshl_add_u64 v[158:159], v[182:183], 0, s[0:1]
	s_mov_b32 m0, s15
	s_barrier
	ds_read_b128 v[194:197], v146 offset:16384
	ds_read_b128 v[198:201], v146 offset:17408
	ds_read_b128 v[202:205], v145 offset:16384
	ds_read_b128 v[206:209], v145 offset:17408
	ds_read_b128 v[210:213], v144 offset:16384
	ds_read_b128 v[214:217], v144 offset:17408
	ds_read_b128 v[218:221], v143 offset:16384
	ds_read_b128 v[238:241], v143 offset:17408
	global_load_lds_dwordx4 v[158:159], off
	v_add_u32_e32 v158, 0x2000, v142
	v_lshl_add_u64 v[160:161], v[242:243], 0, s[0:1]
	v_readfirstlane_b32 s15, v158
	s_mov_b32 m0, s15
	s_nop 0
	global_load_lds_dwordx4 v[160:161], off
	s_barrier
	s_waitcnt lgkmcnt(0)
	v_mfma_f32_16x16x32_bf16 v[62:65], v[168:171], v[194:197], v[62:65]
	v_mfma_f32_16x16x32_bf16 v[58:61], v[186:189], v[194:197], v[58:61]
	v_mfma_f32_16x16x32_bf16 v[54:57], v[168:171], v[202:205], v[54:57]
	v_mfma_f32_16x16x32_bf16 v[50:53], v[186:189], v[202:205], v[50:53]
	v_mfma_f32_16x16x32_bf16 v[46:49], v[168:171], v[210:213], v[46:49]
	v_mfma_f32_16x16x32_bf16 v[42:45], v[186:189], v[210:213], v[42:45]
	v_mfma_f32_16x16x32_bf16 v[38:41], v[168:171], v[218:221], v[38:41]
	v_mfma_f32_16x16x32_bf16 v[34:37], v[186:189], v[218:221], v[34:37]
	v_mfma_f32_16x16x32_bf16 v[62:65], v[172:175], v[198:201], v[62:65]
	v_mfma_f32_16x16x32_bf16 v[58:61], v[190:193], v[198:201], v[58:61]
	v_mfma_f32_16x16x32_bf16 v[54:57], v[172:175], v[206:209], v[54:57]
	v_mfma_f32_16x16x32_bf16 v[50:53], v[190:193], v[206:209], v[50:53]
	v_mfma_f32_16x16x32_bf16 v[46:49], v[172:175], v[214:217], v[46:49]
	v_mfma_f32_16x16x32_bf16 v[42:45], v[190:193], v[214:217], v[42:45]
	v_mfma_f32_16x16x32_bf16 v[38:41], v[172:175], v[238:241], v[38:41]
	v_mfma_f32_16x16x32_bf16 v[34:37], v[190:193], v[238:241], v[34:37]
	s_barrier
; #define STAGE_A(P,br,kt) STAGE_G(P,c.A,c.lda,br,(long)(kt)*c.kstr)
; #define STAGE_B(P,br,kt) STAGE_G(P,c.Bt,c.K,br,(long)(kt)*BK)
; #define LDA(dst,b,h) for(int m=0;m<4;++m)for(int k=0;k<2;++k) \
;     dst[m][k]=*reinterpret_cast<const bf16x8*>((char*)SA(b,h)+lds_byte(wr*64+m*16+fr,k*32+fq*8))
; #define LDB(dst,b,h) for(int n=0;n<2;++n)for(int k=0;k<2;++k) \
;     dst[n][k]=*reinterpret_cast<const bf16x8*>((char*)SB(b,h)+lds_byte(wc*32+n*16+fr,k*32+fq*8))
; #define MMA(ai,bj,At,Bt_) do{__builtin_amdgcn_s_setprio(1); \
;     for(int m=0;m<4;++m)for(int n=0;n<2;++n)for(int k=0;k<2;++k) \
;       acc[ai][bj][m][n]=__builtin_amdgcn_mfma_f32_16x16x32_bf16(Bt_[n][k],At[m][k],acc[ai][bj][m][n],0,0,0); \
;     __builtin_amdgcn_s_setprio(0);}while(0)
; #define WAIT_V(n) asm volatile("s_waitcnt vmcnt(" #n ")":::"memory")
; #define WAIT_L(n) asm volatile("s_waitcnt lgkmcnt(" #n ")":::"memory")
; #define BAR __builtin_amdgcn_s_barrier()
; #define SCHED __builtin_amdgcn_sched_barrier(0)
; template <int EPI>
; __device__ __forceinline__ void gemm_run(const GD& c, const bool has_next, const GD& nx, const Ctx& e, bf16* shm, float* rs, float* rs_nxt, float* racc_) {
;     ...
;     STAGE_B(SB(0,1),bcol+HALF,t+2);
;     WAIT_V(6); BAR; MMA(1,1,At,B1); BAR;
;     LDB(B0,1,0); SCHED; LDA(At,1,0); STAGE_A(SA(0,1),brow+HALF,t+2);
;     WAIT_L(8); BAR; WAIT_L(0); MMA(0,0,At,B0); BAR; SCHED;
;     LDB(B1,1,1); STAGE_B(SB(1,0),bcol,t+3);
;     BAR; WAIT_L(0); MMA(0,1,At,B1); BAR;
;     LDA(At,1,1); STAGE_A(SA(1,0),brow,t+3);
	v_add_u32_e32 v159, s86, v148
	v_lshl_add_u64 v[160:161], v[244:245], 0, s[30:31]
	v_readfirstlane_b32 s15, v159
	s_mov_b32 m0, s15
	v_lshl_add_u64 v[168:169], v[246:247], 0, s[30:31]
	global_load_lds_dwordx4 v[160:161], off
	v_add_u32_e32 v160, 0x2000, v159
	s_nop 0
	v_readfirstlane_b32 s15, v160
	s_mov_b32 m0, s15
	s_nop 0
	global_load_lds_dwordx4 v[168:169], off
	s_waitcnt vmcnt(6)
	s_barrier
	v_mfma_f32_16x16x32_bf16 v[30:33], v[222:225], v[194:197], v[30:33]
	v_mfma_f32_16x16x32_bf16 v[26:29], v[230:233], v[194:197], v[26:29]
	v_mfma_f32_16x16x32_bf16 v[22:25], v[222:225], v[202:205], v[22:25]
	v_mfma_f32_16x16x32_bf16 v[18:21], v[230:233], v[202:205], v[18:21]
	v_mfma_f32_16x16x32_bf16 v[14:17], v[222:225], v[210:213], v[14:17]
	v_mfma_f32_16x16x32_bf16 v[10:13], v[230:233], v[210:213], v[10:13]
	v_mfma_f32_16x16x32_bf16 v[6:9], v[222:225], v[218:221], v[6:9]
	v_mfma_f32_16x16x32_bf16 v[2:5], v[230:233], v[218:221], v[2:5]
	v_mfma_f32_16x16x32_bf16 v[30:33], v[226:229], v[198:201], v[30:33]
	v_mfma_f32_16x16x32_bf16 v[26:29], v[234:237], v[198:201], v[26:29]
	v_mfma_f32_16x16x32_bf16 v[22:25], v[226:229], v[206:209], v[22:25]
	v_mfma_f32_16x16x32_bf16 v[18:21], v[234:237], v[206:209], v[18:21]
	v_mfma_f32_16x16x32_bf16 v[14:17], v[226:229], v[214:217], v[14:17]
	v_mfma_f32_16x16x32_bf16 v[10:13], v[234:237], v[214:217], v[10:13]
	v_mfma_f32_16x16x32_bf16 v[6:9], v[226:229], v[238:241], v[6:9]
	v_mfma_f32_16x16x32_bf16 v[2:5], v[234:237], v[238:241], v[2:5]
	s_barrier
	ds_read_b128 v[168:171], v149
	ds_read_b128 v[172:175], v149 offset:1024
	ds_read_b128 v[186:189], v149 offset:2048
	ds_read_b128 v[190:193], v149 offset:3072
	v_add_u32_e32 v161, 0x4000, v142
	v_add_u32_e32 v162, 0x6000, v142
	v_readfirstlane_b32 s15, v161
	v_lshl_add_u64 v[226:227], v[182:183], 0, s[76:77]
	s_mov_b32 m0, s15
	v_readfirstlane_b32 s15, v162
	ds_read_b128 v[194:197], v146 offset:32768
	ds_read_b128 v[198:201], v146 offset:33792
	ds_read_b128 v[202:205], v145 offset:32768
	ds_read_b128 v[206:209], v145 offset:33792
	ds_read_b128 v[210:213], v144 offset:32768
	ds_read_b128 v[214:217], v144 offset:33792
	ds_read_b128 v[218:221], v143 offset:32768
	ds_read_b128 v[222:225], v143 offset:33792
	global_load_lds_dwordx4 v[226:227], off
	v_lshl_add_u64 v[226:227], v[242:243], 0, s[76:77]
	s_mov_b32 m0, s15
	s_nop 0
	global_load_lds_dwordx4 v[226:227], off
	s_waitcnt lgkmcnt(8)
	s_barrier
	s_waitcnt lgkmcnt(0)
	v_mfma_f32_16x16x32_bf16 v[126:129], v[168:171], v[194:197], v[126:129]
	v_mfma_f32_16x16x32_bf16 v[122:125], v[186:189], v[194:197], v[122:125]
	v_mfma_f32_16x16x32_bf16 v[118:121], v[168:171], v[202:205], v[118:121]
	v_mfma_f32_16x16x32_bf16 v[114:117], v[186:189], v[202:205], v[114:117]
	v_mfma_f32_16x16x32_bf16 v[110:113], v[168:171], v[210:213], v[110:113]
	v_mfma_f32_16x16x32_bf16 v[106:109], v[186:189], v[210:213], v[106:109]
	v_mfma_f32_16x16x32_bf16 v[102:105], v[168:171], v[218:221], v[102:105]
	v_mfma_f32_16x16x32_bf16 v[98:101], v[186:189], v[218:221], v[98:101]
	v_mfma_f32_16x16x32_bf16 v[126:129], v[172:175], v[198:201], v[126:129]
	v_mfma_f32_16x16x32_bf16 v[122:125], v[190:193], v[198:201], v[122:125]
	v_mfma_f32_16x16x32_bf16 v[118:121], v[172:175], v[206:209], v[118:121]
	v_mfma_f32_16x16x32_bf16 v[114:117], v[190:193], v[206:209], v[114:117]
	v_mfma_f32_16x16x32_bf16 v[110:113], v[172:175], v[214:217], v[110:113]
	v_mfma_f32_16x16x32_bf16 v[106:109], v[190:193], v[214:217], v[106:109]
	v_mfma_f32_16x16x32_bf16 v[102:105], v[172:175], v[222:225], v[102:105]
	v_mfma_f32_16x16x32_bf16 v[98:101], v[190:193], v[222:225], v[98:101]
	s_barrier
	v_readfirstlane_b32 s15, v150
	v_add_u32_e32 v167, 0x2000, v150
	v_lshl_add_u64 v[248:249], v[244:245], 0, s[34:35]
	s_mov_b32 m0, s15
	v_readfirstlane_b32 s15, v167
	ds_read_b128 v[226:229], v147
	ds_read_b128 v[230:233], v147 offset:1024
	ds_read_b128 v[234:237], v147 offset:2048
	ds_read_b128 v[238:241], v147 offset:3072
	global_load_lds_dwordx4 v[248:249], off
	v_lshl_add_u64 v[248:249], v[246:247], 0, s[34:35]
	s_mov_b32 m0, s15
	s_nop 0
	global_load_lds_dwordx4 v[248:249], off
	s_barrier
	s_waitcnt lgkmcnt(0)
	v_mfma_f32_16x16x32_bf16 v[94:97], v[226:229], v[194:197], v[94:97]
	v_mfma_f32_16x16x32_bf16 v[90:93], v[234:237], v[194:197], v[90:93]
	v_mfma_f32_16x16x32_bf16 v[86:89], v[226:229], v[202:205], v[86:89]
	v_mfma_f32_16x16x32_bf16 v[82:85], v[234:237], v[202:205], v[82:85]
	v_mfma_f32_16x16x32_bf16 v[78:81], v[226:229], v[210:213], v[78:81]
	v_mfma_f32_16x16x32_bf16 v[74:77], v[234:237], v[210:213], v[74:77]
	v_mfma_f32_16x16x32_bf16 v[70:73], v[226:229], v[218:221], v[70:73]
	v_mfma_f32_16x16x32_bf16 v[66:69], v[234:237], v[218:221], v[66:69]
	v_mfma_f32_16x16x32_bf16 v[94:97], v[230:233], v[198:201], v[94:97]
	v_mfma_f32_16x16x32_bf16 v[90:93], v[238:241], v[198:201], v[90:93]
	v_mfma_f32_16x16x32_bf16 v[86:89], v[230:233], v[206:209], v[86:89]
	v_mfma_f32_16x16x32_bf16 v[82:85], v[238:241], v[206:209], v[82:85]
	v_mfma_f32_16x16x32_bf16 v[78:81], v[230:233], v[214:217], v[78:81]
	v_mfma_f32_16x16x32_bf16 v[74:77], v[238:241], v[214:217], v[74:77]
	v_mfma_f32_16x16x32_bf16 v[70:73], v[230:233], v[222:225], v[70:73]
	v_mfma_f32_16x16x32_bf16 v[66:69], v[238:241], v[222:225], v[66:69]
	s_barrier
	v_readfirstlane_b32 s15, v151
	v_lshl_add_u64 v[182:183], v[182:183], 0, s[74:75]
	s_mov_b32 m0, s15
	v_readfirstlane_b32 s15, v152
	ds_read_b128 v[194:197], v146 offset:49152
	ds_read_b128 v[198:201], v146 offset:50176
	ds_read_b128 v[202:205], v145 offset:49152
	ds_read_b128 v[206:209], v145 offset:50176
	ds_read_b128 v[210:213], v144 offset:49152
	ds_read_b128 v[214:217], v144 offset:50176
	ds_read_b128 v[218:221], v143 offset:49152
	ds_read_b128 v[222:225], v143 offset:50176
	global_load_lds_dwordx4 v[182:183], off
	v_lshl_add_u64 v[182:183], v[242:243], 0, s[74:75]
	s_mov_b32 m0, s15
	s_nop 0
	global_load_lds_dwordx4 v[182:183], off
	s_barrier
; #define STAGE_A(P,br,kt) STAGE_G(P,c.A,c.lda,br,(long)(kt)*c.kstr)
; #define STAGE_B(P,br,kt) STAGE_G(P,c.Bt,c.K,br,(long)(kt)*BK)
; #define LDA(dst,b,h) for(int m=0;m<4;++m)for(int k=0;k<2;++k) \
;     dst[m][k]=*reinterpret_cast<const bf16x8*>((char*)SA(b,h)+lds_byte(wr*64+m*16+fr,k*32+fq*8))
; #define LDB(dst,b,h) for(int n=0;n<2;++n)for(int k=0;k<2;++k) \
;     dst[n][k]=*reinterpret_cast<const bf16x8*>((char*)SB(b,h)+lds_byte(wc*32+n*16+fr,k*32+fq*8))
; #define MMA(ai,bj,At,Bt_) do{__builtin_amdgcn_s_setprio(1); \
;     for(int m=0;m<4;++m)for(int n=0;n<2;++n)for(int k=0;k<2;++k) \
;       acc[ai][bj][m][n]=__builtin_amdgcn_mfma_f32_16x16x32_bf16(Bt_[n][k],At[m][k],acc[ai][bj][m][n],0,0,0); \
;     __builtin_amdgcn_s_setprio(0);}while(0)
; #define WAIT_V(n) asm volatile("s_waitcnt vmcnt(" #n ")":::"memory")
; #define WAIT_L(n) asm volatile("s_waitcnt lgkmcnt(" #n ")":::"memory")
; #define BAR __builtin_amdgcn_s_barrier()
; #define SCHED __builtin_amdgcn_sched_barrier(0)
; template <int EPI>
; __device__ __forceinline__ void gemm_run(const GD& c, const bool has_next, const GD& nx, const Ctx& e, bf16* shm, float* rs, float* rs_nxt, float* racc_) {
;     ...
;     BAR; WAIT_L(0); MMA(1,0,At,B0); BAR; SCHED;
;     STAGE_B(SB(1,1),bcol+HALF,t+3);
;     WAIT_V(6); BAR; MMA(1,1,At,B1); BAR;
;   }
;   { LDB(B0,0,0); LDA(At,0,0); STAGE_A(SA(1,1),brow+HALF,nt-1);
;     BAR; WAIT_L(0); MMA(0,0,At,B0); BAR;
	s_waitcnt lgkmcnt(0)
	v_mfma_f32_16x16x32_bf16 v[62:65], v[168:171], v[194:197], v[62:65]
	v_mfma_f32_16x16x32_bf16 v[58:61], v[186:189], v[194:197], v[58:61]
	v_mfma_f32_16x16x32_bf16 v[54:57], v[168:171], v[202:205], v[54:57]
	v_mfma_f32_16x16x32_bf16 v[50:53], v[186:189], v[202:205], v[50:53]
	v_mfma_f32_16x16x32_bf16 v[46:49], v[168:171], v[210:213], v[46:49]
	v_mfma_f32_16x16x32_bf16 v[42:45], v[186:189], v[210:213], v[42:45]
	v_mfma_f32_16x16x32_bf16 v[38:41], v[168:171], v[218:221], v[38:41]
	v_mfma_f32_16x16x32_bf16 v[34:37], v[186:189], v[218:221], v[34:37]
	v_mfma_f32_16x16x32_bf16 v[62:65], v[172:175], v[198:201], v[62:65]
	v_mfma_f32_16x16x32_bf16 v[58:61], v[190:193], v[198:201], v[58:61]
	v_mfma_f32_16x16x32_bf16 v[54:57], v[172:175], v[206:209], v[54:57]
	v_mfma_f32_16x16x32_bf16 v[50:53], v[190:193], v[206:209], v[50:53]
	v_mfma_f32_16x16x32_bf16 v[46:49], v[172:175], v[214:217], v[46:49]
	v_mfma_f32_16x16x32_bf16 v[42:45], v[190:193], v[214:217], v[42:45]
	v_mfma_f32_16x16x32_bf16 v[38:41], v[172:175], v[222:225], v[38:41]
	v_mfma_f32_16x16x32_bf16 v[34:37], v[190:193], v[222:225], v[34:37]
	s_barrier
	v_readfirstlane_b32 s15, v153
	v_add_u32_e32 v167, 0x2000, v153
	v_lshl_add_u64 v[168:169], v[244:245], 0, s[36:37]
	s_mov_b32 m0, s15
	v_readfirstlane_b32 s15, v167
	global_load_lds_dwordx4 v[168:169], off
	v_lshl_add_u64 v[168:169], v[246:247], 0, s[36:37]
	s_mov_b32 m0, s15
	s_nop 0
	global_load_lds_dwordx4 v[168:169], off
	s_waitcnt vmcnt(6)
	s_barrier
	v_mfma_f32_16x16x32_bf16 v[30:33], v[226:229], v[194:197], v[30:33]
	v_mfma_f32_16x16x32_bf16 v[26:29], v[234:237], v[194:197], v[26:29]
	v_mfma_f32_16x16x32_bf16 v[22:25], v[226:229], v[202:205], v[22:25]
	v_mfma_f32_16x16x32_bf16 v[18:21], v[234:237], v[202:205], v[18:21]
	s_add_i32 s14, s14, 2
	v_mfma_f32_16x16x32_bf16 v[14:17], v[226:229], v[210:213], v[14:17]
	s_add_u32 s2, s2, 0x100
	v_mfma_f32_16x16x32_bf16 v[10:13], v[234:237], v[210:213], v[10:13]
	s_addc_u32 s3, s3, 0
	v_mfma_f32_16x16x32_bf16 v[6:9], v[226:229], v[218:221], v[6:9]
	s_cmp_lt_u32 s14, 38
	v_mfma_f32_16x16x32_bf16 v[2:5], v[234:237], v[218:221], v[2:5]
	v_mfma_f32_16x16x32_bf16 v[30:33], v[230:233], v[198:201], v[30:33]
	v_mfma_f32_16x16x32_bf16 v[26:29], v[238:241], v[198:201], v[26:29]
	v_mfma_f32_16x16x32_bf16 v[22:25], v[230:233], v[206:209], v[22:25]
	v_mfma_f32_16x16x32_bf16 v[18:21], v[238:241], v[206:209], v[18:21]
	v_mfma_f32_16x16x32_bf16 v[14:17], v[230:233], v[214:217], v[14:17]
	v_mfma_f32_16x16x32_bf16 v[10:13], v[238:241], v[214:217], v[10:13]
	v_mfma_f32_16x16x32_bf16 v[6:9], v[230:233], v[222:225], v[6:9]
	v_mfma_f32_16x16x32_bf16 v[2:5], v[238:241], v[222:225], v[2:5]
	s_barrier
	s_cbranch_scc1 .LBB0_1426
	s_or_b32 s27, s25, 0x80
	s_mul_i32 s2, s27, 0x1500
	s_mul_hi_i32 s3, s27, 0x1500
	s_add_u32 s2, s21, s2
	s_addc_u32 s3, s22, s3
	v_readfirstlane_b32 s14, v163
	v_lshl_add_u64 v[182:183], s[2:3], 0, v[0:1]
	s_mov_b32 m0, s14
	ds_read_b128 v[132:135], v155
	ds_read_b128 v[136:139], v155 offset:1024
	ds_read_b128 v[150:153], v155 offset:2048
	ds_read_b128 v[168:171], v155 offset:3072
	ds_read_b128 v[172:175], v146
	ds_read_b128 v[186:189], v146 offset:1024
	ds_read_b128 v[190:193], v145
	ds_read_b128 v[194:197], v145 offset:1024
	ds_read_b128 v[198:201], v144
	ds_read_b128 v[202:205], v144 offset:1024
	ds_read_b128 v[206:209], v143
	ds_read_b128 v[210:213], v143 offset:1024
	global_load_lds_dwordx4 v[182:183], off
	v_lshl_add_u64 v[182:183], s[2:3], 0, v[130:131]
	v_readfirstlane_b32 s2, v166
	s_mov_b32 m0, s2
	s_nop 0
	global_load_lds_dwordx4 v[182:183], off
	s_barrier
	s_waitcnt lgkmcnt(0)
	v_mfma_f32_16x16x32_bf16 v[126:129], v[132:135], v[172:175], v[126:129]
	v_mfma_f32_16x16x32_bf16 v[122:125], v[150:153], v[172:175], v[122:125]
	v_mfma_f32_16x16x32_bf16 v[118:121], v[132:135], v[190:193], v[118:121]
	v_mfma_f32_16x16x32_bf16 v[114:117], v[150:153], v[190:193], v[114:117]
	v_mfma_f32_16x16x32_bf16 v[106:109], v[150:153], v[198:201], v[106:109]
	v_mfma_f32_16x16x32_bf16 v[98:101], v[150:153], v[206:209], v[98:101]
	v_mfma_f32_16x16x32_bf16 v[126:129], v[136:139], v[186:189], v[126:129]
	v_mfma_f32_16x16x32_bf16 v[122:125], v[168:171], v[186:189], v[122:125]
	v_mfma_f32_16x16x32_bf16 v[118:121], v[136:139], v[194:197], v[118:121]
	v_mfma_f32_16x16x32_bf16 v[114:117], v[168:171], v[194:197], v[114:117]
	v_mfma_f32_16x16x32_bf16 v[110:113], v[132:135], v[198:201], v[110:113]
	v_mfma_f32_16x16x32_bf16 v[106:109], v[168:171], v[202:205], v[106:109]
	v_mfma_f32_16x16x32_bf16 v[102:105], v[132:135], v[206:209], v[102:105]
	v_mfma_f32_16x16x32_bf16 v[98:101], v[168:171], v[210:213], v[98:101]
	v_mfma_f32_16x16x32_bf16 v[214:217], v[136:139], v[202:205], v[110:113]
	v_mfma_f32_16x16x32_bf16 v[218:221], v[136:139], v[210:213], v[102:105]
	s_barrier
	s_nop 2
	ds_read_b128 v[102:105], v154
	ds_read_b128 v[110:113], v154 offset:1024
	ds_read_b128 v[222:225], v154 offset:2048
	ds_read_b128 v[226:229], v154 offset:3072
	s_barrier
	s_waitcnt lgkmcnt(0)
	v_mfma_f32_16x16x32_bf16 v[90:93], v[222:225], v[172:175], v[90:93]
	v_mfma_f32_16x16x32_bf16 v[82:85], v[222:225], v[190:193], v[82:85]
	v_mfma_f32_16x16x32_bf16 v[74:77], v[222:225], v[198:201], v[74:77]
	v_mfma_f32_16x16x32_bf16 v[66:69], v[222:225], v[206:209], v[66:69]
	v_mfma_f32_16x16x32_bf16 v[94:97], v[102:105], v[172:175], v[94:97]
	v_mfma_f32_16x16x32_bf16 v[90:93], v[226:229], v[186:189], v[90:93]
	v_mfma_f32_16x16x32_bf16 v[86:89], v[102:105], v[190:193], v[86:89]
	v_mfma_f32_16x16x32_bf16 v[82:85], v[226:229], v[194:197], v[82:85]
	v_mfma_f32_16x16x32_bf16 v[78:81], v[102:105], v[198:201], v[78:81]
	v_mfma_f32_16x16x32_bf16 v[74:77], v[226:229], v[202:205], v[74:77]
	v_mfma_f32_16x16x32_bf16 v[70:73], v[102:105], v[206:209], v[70:73]
	v_mfma_f32_16x16x32_bf16 v[66:69], v[226:229], v[210:213], v[66:69]
	v_mfma_f32_16x16x32_bf16 v[230:233], v[110:113], v[186:189], v[94:97]
	v_mfma_f32_16x16x32_bf16 v[172:175], v[110:113], v[194:197], v[86:89]
	v_mfma_f32_16x16x32_bf16 v[186:189], v[110:113], v[202:205], v[78:81]
	v_mfma_f32_16x16x32_bf16 v[190:193], v[110:113], v[210:213], v[70:73]
	s_barrier
; #define LDA(dst,b,h) for(int m=0;m<4;++m)for(int k=0;k<2;++k) \
;     dst[m][k]=*reinterpret_cast<const bf16x8*>((char*)SA(b,h)+lds_byte(wr*64+m*16+fr,k*32+fq*8))
; #define LDB(dst,b,h) for(int n=0;n<2;++n)for(int k=0;k<2;++k) \
;     dst[n][k]=*reinterpret_cast<const bf16x8*>((char*)SB(b,h)+lds_byte(wc*32+n*16+fr,k*32+fq*8))
; #define MMA(ai,bj,At,Bt_) do{__builtin_amdgcn_s_setprio(1); \
;     for(int m=0;m<4;++m)for(int n=0;n<2;++n)for(int k=0;k<2;++k) \
;       acc[ai][bj][m][n]=__builtin_amdgcn_mfma_f32_16x16x32_bf16(Bt_[n][k],At[m][k],acc[ai][bj][m][n],0,0,0); \
;     __builtin_amdgcn_s_setprio(0);}while(0)
; #define WAIT_V(n) asm volatile("s_waitcnt vmcnt(" #n ")":::"memory")
; #define WAIT_L(n) asm volatile("s_waitcnt lgkmcnt(" #n ")":::"memory")
; #define BAR __builtin_amdgcn_s_barrier()
; template <int EPI>
; __device__ __forceinline__ void gemm_run(const GD& c, const bool has_next, const GD& nx, const Ctx& e, bf16* shm, float* rs, float* rs_nxt, float* racc_) {
;     ...
;     LDB(B1,0,1); BAR; WAIT_L(0); MMA(0,1,At,B1); BAR;
;     LDA(At,0,1); WAIT_V(4); BAR; WAIT_L(0); MMA(1,0,At,B0); MMA(1,1,At,B1); BAR; }
;   { LDB(B0,1,0); LDA(At,1,0); WAIT_V(2); BAR; WAIT_L(0); MMA(0,0,At,B0); BAR;
	s_nop 0
	ds_read_b128 v[70:73], v146 offset:16384
	ds_read_b128 v[78:81], v146 offset:17408
	ds_read_b128 v[86:89], v145 offset:16384
	ds_read_b128 v[94:97], v145 offset:17408
	ds_read_b128 v[194:197], v144 offset:16384
	ds_read_b128 v[198:201], v144 offset:17408
	ds_read_b128 v[202:205], v143 offset:16384
	ds_read_b128 v[206:209], v143 offset:17408
	s_waitcnt vmcnt(4)
	s_barrier
	s_waitcnt lgkmcnt(0)
	v_mfma_f32_16x16x32_bf16 v[62:65], v[132:135], v[70:73], v[62:65]
	v_mfma_f32_16x16x32_bf16 v[58:61], v[150:153], v[70:73], v[58:61]
	v_mfma_f32_16x16x32_bf16 v[54:57], v[132:135], v[86:89], v[54:57]
	v_mfma_f32_16x16x32_bf16 v[50:53], v[150:153], v[86:89], v[50:53]
	v_mfma_f32_16x16x32_bf16 v[38:41], v[132:135], v[202:205], v[38:41]
	v_mfma_f32_16x16x32_bf16 v[34:37], v[150:153], v[202:205], v[34:37]
	v_mfma_f32_16x16x32_bf16 v[62:65], v[136:139], v[78:81], v[62:65]
	v_mfma_f32_16x16x32_bf16 v[58:61], v[168:171], v[78:81], v[58:61]
	v_mfma_f32_16x16x32_bf16 v[54:57], v[136:139], v[94:97], v[54:57]
	v_mfma_f32_16x16x32_bf16 v[50:53], v[168:171], v[94:97], v[50:53]
	v_mfma_f32_16x16x32_bf16 v[46:49], v[132:135], v[194:197], v[46:49]
	v_mfma_f32_16x16x32_bf16 v[42:45], v[150:153], v[194:197], v[42:45]
	v_mfma_f32_16x16x32_bf16 v[38:41], v[136:139], v[206:209], v[38:41]
	v_mfma_f32_16x16x32_bf16 v[34:37], v[168:171], v[206:209], v[34:37]
	v_mfma_f32_16x16x32_bf16 v[210:213], v[136:139], v[198:201], v[46:49]
	v_mfma_f32_16x16x32_bf16 v[234:237], v[168:171], v[198:201], v[42:45]
	v_mfma_f32_16x16x32_bf16 v[22:25], v[102:105], v[86:89], v[22:25]
	v_mfma_f32_16x16x32_bf16 v[18:21], v[222:225], v[86:89], v[18:21]
	v_mfma_f32_16x16x32_bf16 v[6:9], v[102:105], v[202:205], v[6:9]
	v_mfma_f32_16x16x32_bf16 v[2:5], v[222:225], v[202:205], v[2:5]
	v_mfma_f32_16x16x32_bf16 v[30:33], v[102:105], v[70:73], v[30:33]
	v_mfma_f32_16x16x32_bf16 v[26:29], v[222:225], v[70:73], v[26:29]
	v_mfma_f32_16x16x32_bf16 v[22:25], v[110:113], v[94:97], v[22:25]
	v_mfma_f32_16x16x32_bf16 v[18:21], v[226:229], v[94:97], v[18:21]
	v_mfma_f32_16x16x32_bf16 v[14:17], v[102:105], v[194:197], v[14:17]
	v_mfma_f32_16x16x32_bf16 v[10:13], v[222:225], v[194:197], v[10:13]
	v_mfma_f32_16x16x32_bf16 v[6:9], v[110:113], v[206:209], v[6:9]
	v_mfma_f32_16x16x32_bf16 v[2:5], v[226:229], v[206:209], v[2:5]
	v_mfma_f32_16x16x32_bf16 v[132:135], v[110:113], v[78:81], v[30:33]
	v_mfma_f32_16x16x32_bf16 v[136:139], v[226:229], v[78:81], v[26:29]
	v_mfma_f32_16x16x32_bf16 v[150:153], v[110:113], v[198:201], v[14:17]
	v_mfma_f32_16x16x32_bf16 v[166:169], v[226:229], v[198:201], v[10:13]
	s_barrier
	s_nop 0
	ds_read_b128 v[10:13], v149
	ds_read_b128 v[14:17], v149 offset:1024
	ds_read_b128 v[194:197], v149 offset:2048
	ds_read_b128 v[198:201], v149 offset:3072
	ds_read_b128 v[26:29], v146 offset:32768
	ds_read_b128 v[30:33], v146 offset:33792
	ds_read_b128 v[42:45], v145 offset:32768
	ds_read_b128 v[46:49], v145 offset:33792
	ds_read_b128 v[202:205], v144 offset:32768
	ds_read_b128 v[206:209], v144 offset:33792
	ds_read_b128 v[222:225], v143 offset:32768
	ds_read_b128 v[226:229], v143 offset:33792
	s_waitcnt vmcnt(2)
	s_barrier
	s_waitcnt lgkmcnt(0)
	v_mfma_f32_16x16x32_bf16 v[70:73], v[10:13], v[26:29], v[126:129]
	v_mfma_f32_16x16x32_bf16 v[126:129], v[14:17], v[30:33], v[70:73]
	v_mfma_f32_16x16x32_bf16 v[70:73], v[194:197], v[26:29], v[122:125]
	v_mfma_f32_16x16x32_bf16 v[122:125], v[198:201], v[30:33], v[70:73]
	v_mfma_f32_16x16x32_bf16 v[70:73], v[10:13], v[42:45], v[118:121]
	v_mfma_f32_16x16x32_bf16 v[110:113], v[14:17], v[46:49], v[70:73]
	v_mfma_f32_16x16x32_bf16 v[70:73], v[194:197], v[42:45], v[114:117]
	v_mfma_f32_16x16x32_bf16 v[102:105], v[198:201], v[46:49], v[70:73]
	v_mfma_f32_16x16x32_bf16 v[70:73], v[10:13], v[202:205], v[214:217]
	v_mfma_f32_16x16x32_bf16 v[94:97], v[14:17], v[206:209], v[70:73]
	v_mfma_f32_16x16x32_bf16 v[70:73], v[194:197], v[202:205], v[106:109]
	v_mfma_f32_16x16x32_bf16 v[86:89], v[198:201], v[206:209], v[70:73]
	v_mfma_f32_16x16x32_bf16 v[70:73], v[10:13], v[222:225], v[218:221]
	v_mfma_f32_16x16x32_bf16 v[78:81], v[14:17], v[226:229], v[70:73]
	v_mfma_f32_16x16x32_bf16 v[70:73], v[194:197], v[222:225], v[98:101]
	v_mfma_f32_16x16x32_bf16 v[70:73], v[198:201], v[226:229], v[70:73]
	s_barrier
; #define LDA(dst,b,h) for(int m=0;m<4;++m)for(int k=0;k<2;++k) \
;     dst[m][k]=*reinterpret_cast<const bf16x8*>((char*)SA(b,h)+lds_byte(wr*64+m*16+fr,k*32+fq*8))
; #define LDB(dst,b,h) for(int n=0;n<2;++n)for(int k=0;k<2;++k) \
;     dst[n][k]=*reinterpret_cast<const bf16x8*>((char*)SB(b,h)+lds_byte(wc*32+n*16+fr,k*32+fq*8))
; #define MMA(ai,bj,At,Bt_) do{__builtin_amdgcn_s_setprio(1); \
;     for(int m=0;m<4;++m)for(int n=0;n<2;++n)for(int k=0;k<2;++k) \
;       acc[ai][bj][m][n]=__builtin_amdgcn_mfma_f32_16x16x32_bf16(Bt_[n][k],At[m][k],acc[ai][bj][m][n],0,0,0); \
;     __builtin_amdgcn_s_setprio(0);}while(0)
; #define WAIT_V(n) asm volatile("s_waitcnt vmcnt(" #n ")":::"memory")
; #define WAIT_L(n) asm volatile("s_waitcnt lgkmcnt(" #n ")":::"memory")
; #define BAR __builtin_amdgcn_s_barrier()
; template <int EPI>
; __device__ __forceinline__ void gemm_run(const GD& c, const bool has_next, const GD& nx, const Ctx& e, bf16* shm, float* rs, float* rs_nxt, float* racc_) {
;     ...
;     LDB(B1,1,1); WAIT_V(0); BAR; WAIT_L(0); MMA(0,1,At,B1); BAR;
;     LDA(At,1,1); BAR; WAIT_L(0); MMA(1,0,At,B0); MMA(1,1,At,B1); BAR; }
;   if(wr==0)BAR;
	ds_read_b128 v[214:217], v147
	ds_read_b128 v[218:221], v147 offset:1024
	ds_read_b128 v[238:241], v147 offset:2048
	ds_read_b128 v[242:245], v147 offset:3072
	s_waitcnt vmcnt(0)
	s_barrier
	s_waitcnt lgkmcnt(0)
	v_mfma_f32_16x16x32_bf16 v[98:101], v[214:217], v[26:29], v[230:233]
	v_mfma_f32_16x16x32_bf16 v[26:29], v[238:241], v[26:29], v[90:93]
	v_mfma_f32_16x16x32_bf16 v[114:117], v[242:245], v[30:33], v[26:29]
	v_mfma_f32_16x16x32_bf16 v[26:29], v[214:217], v[42:45], v[172:175]
	v_mfma_f32_16x16x32_bf16 v[106:109], v[218:221], v[46:49], v[26:29]
	v_mfma_f32_16x16x32_bf16 v[26:29], v[238:241], v[42:45], v[82:85]
	v_mfma_f32_16x16x32_bf16 v[118:121], v[218:221], v[30:33], v[98:101]
	v_mfma_f32_16x16x32_bf16 v[98:101], v[242:245], v[46:49], v[26:29]
	v_mfma_f32_16x16x32_bf16 v[26:29], v[214:217], v[202:205], v[186:189]
	v_mfma_f32_16x16x32_bf16 v[90:93], v[218:221], v[206:209], v[26:29]
	v_mfma_f32_16x16x32_bf16 v[26:29], v[238:241], v[202:205], v[74:77]
	v_mfma_f32_16x16x32_bf16 v[82:85], v[242:245], v[206:209], v[26:29]
	v_mfma_f32_16x16x32_bf16 v[26:29], v[214:217], v[222:225], v[190:193]
	v_mfma_f32_16x16x32_bf16 v[74:77], v[218:221], v[226:229], v[26:29]
	v_mfma_f32_16x16x32_bf16 v[26:29], v[238:241], v[222:225], v[66:69]
	v_mfma_f32_16x16x32_bf16 v[66:69], v[242:245], v[226:229], v[26:29]
	s_barrier
	ds_read_b128 v[170:173], v146 offset:49152
	ds_read_b128 v[146:149], v146 offset:50176
	ds_read_b128 v[186:189], v145 offset:49152
	ds_read_b128 v[190:193], v145 offset:50176
	ds_read_b128 v[202:205], v144 offset:49152
	ds_read_b128 v[206:209], v144 offset:50176
	ds_read_b128 v[222:225], v143 offset:49152
	ds_read_b128 v[226:229], v143 offset:50176
	s_barrier
	s_waitcnt lgkmcnt(0)
	v_mfma_f32_16x16x32_bf16 v[26:29], v[10:13], v[170:173], v[62:65]
	v_mfma_f32_16x16x32_bf16 v[62:65], v[14:17], v[146:149], v[26:29]
	v_mfma_f32_16x16x32_bf16 v[26:29], v[194:197], v[170:173], v[58:61]
	v_mfma_f32_16x16x32_bf16 v[58:61], v[198:201], v[146:149], v[26:29]
	v_mfma_f32_16x16x32_bf16 v[26:29], v[10:13], v[186:189], v[54:57]
	v_mfma_f32_16x16x32_bf16 v[46:49], v[14:17], v[190:193], v[26:29]
	v_mfma_f32_16x16x32_bf16 v[26:29], v[194:197], v[186:189], v[50:53]
	v_mfma_f32_16x16x32_bf16 v[42:45], v[198:201], v[190:193], v[26:29]
	v_mfma_f32_16x16x32_bf16 v[26:29], v[10:13], v[202:205], v[210:213]
	v_mfma_f32_16x16x32_bf16 v[10:13], v[10:13], v[222:225], v[38:41]
	v_mfma_f32_16x16x32_bf16 v[30:33], v[14:17], v[206:209], v[26:29]
	v_mfma_f32_16x16x32_bf16 v[26:29], v[194:197], v[202:205], v[234:237]
	v_mfma_f32_16x16x32_bf16 v[14:17], v[14:17], v[226:229], v[10:13]
	v_mfma_f32_16x16x32_bf16 v[10:13], v[194:197], v[222:225], v[34:37]
	v_mfma_f32_16x16x32_bf16 v[26:29], v[198:201], v[206:209], v[26:29]
	v_mfma_f32_16x16x32_bf16 v[10:13], v[198:201], v[226:229], v[10:13]
	v_mfma_f32_16x16x32_bf16 v[34:37], v[214:217], v[170:173], v[132:135]
	v_mfma_f32_16x16x32_bf16 v[54:57], v[218:221], v[146:149], v[34:37]
	v_mfma_f32_16x16x32_bf16 v[34:37], v[238:241], v[170:173], v[136:139]
	v_mfma_f32_16x16x32_bf16 v[18:21], v[238:241], v[186:189], v[18:21]
	v_mfma_f32_16x16x32_bf16 v[50:53], v[242:245], v[146:149], v[34:37]
	v_mfma_f32_16x16x32_bf16 v[22:25], v[214:217], v[186:189], v[22:25]
	v_mfma_f32_16x16x32_bf16 v[34:37], v[242:245], v[190:193], v[18:21]
	v_mfma_f32_16x16x32_bf16 v[18:21], v[214:217], v[202:205], v[150:153]
	v_mfma_f32_16x16x32_bf16 v[38:41], v[218:221], v[190:193], v[22:25]
	v_mfma_f32_16x16x32_bf16 v[22:25], v[218:221], v[206:209], v[18:21]
	v_mfma_f32_16x16x32_bf16 v[18:21], v[238:241], v[202:205], v[166:169]
	v_mfma_f32_16x16x32_bf16 v[6:9], v[214:217], v[222:225], v[6:9]
	v_mfma_f32_16x16x32_bf16 v[2:5], v[238:241], v[222:225], v[2:5]
	v_mfma_f32_16x16x32_bf16 v[18:21], v[242:245], v[206:209], v[18:21]
	v_mfma_f32_16x16x32_bf16 v[6:9], v[218:221], v[226:229], v[6:9]
	v_mfma_f32_16x16x32_bf16 v[2:5], v[242:245], v[226:229], v[2:5]
	v_cmp_gt_u32_e32 vcc, s96, v141
	s_barrier
	s_and_saveexec_b64 s[2:3], vcc
	s_cbranch_execz .LBB0_1429
	s_barrier

; #define STAGE_A(P,br,kt) STAGE_G(P,c.A,c.lda,br,(long)(kt)*c.kstr)
; #define STAGE_B(P,br,kt) STAGE_G(P,c.Bt,c.K,br,(long)(kt)*BK)
; #define LDA(dst,b,h) for(int m=0;m<4;++m)for(int k=0;k<2;++k) \
;     dst[m][k]=*reinterpret_cast<const bf16x8*>((char*)SA(b,h)+lds_byte(wr*64+m*16+fr,k*32+fq*8))
; #define LDB(dst,b,h) for(int n=0;n<2;++n)for(int k=0;k<2;++k) \
;     dst[n][k]=*reinterpret_cast<const bf16x8*>((char*)SB(b,h)+lds_byte(wc*32+n*16+fr,k*32+fq*8))
; #define MMA(ai,bj,At,Bt_) do{__builtin_amdgcn_s_setprio(1); \
;     for(int m=0;m<4;++m)for(int n=0;n<2;++n)for(int k=0;k<2;++k) \
;       acc[ai][bj][m][n]=__builtin_amdgcn_mfma_f32_16x16x32_bf16(Bt_[n][k],At[m][k],acc[ai][bj][m][n],0,0,0); \
;     __builtin_amdgcn_s_setprio(0);}while(0)
; #define WAIT_L(n) asm volatile("s_waitcnt lgkmcnt(" #n ")":::"memory")
; #define BAR __builtin_amdgcn_s_barrier()
; #define SCHED __builtin_amdgcn_sched_barrier(0)
; template <int EPI>
; __device__ __forceinline__ void gemm_run(const GD& c, const bool has_next, const GD& nx, const Ctx& e, bf16* shm, float* rs, float* rs_nxt, float* racc_) {
;     ...
;   for(int t=0;t<nt-2;t+=2){
;     LDB(B0,0,0); SCHED; LDA(At,0,0); STAGE_A(SA(1,1),brow+HALF,t+1);
;     WAIT_L(8); BAR; WAIT_L(0); MMA(0,0,At,B0); BAR; SCHED;
;     LDB(B1,0,1); STAGE_B(SB(0,0),bcol,t+2);
;     BAR; WAIT_L(0); MMA(0,1,At,B1); BAR;
;     LDA(At,0,1); STAGE_A(SA(0,0),brow,t+2);
;     BAR; WAIT_L(0); MMA(1,0,At,B0); BAR; SCHED;
.LBB0_1505:
	ds_read_b128 v[158:161], v155
	ds_read_b128 v[166:169], v155 offset:1024
	ds_read_b128 v[170:173], v155 offset:2048
	ds_read_b128 v[186:189], v155 offset:3072
	v_add_u32_e32 v156, 0xc000, v150
	v_lshl_add_u64 v[162:163], v[132:133], 0, s[8:9]
	v_readfirstlane_b32 s12, v156
	v_lshl_add_u64 v[174:175], v[162:163], 0, s[90:91]
	s_mov_b32 m0, s12
	v_add_u32_e32 v157, 0xe000, v150
	ds_read_b128 v[190:193], v145
	ds_read_b128 v[194:197], v145 offset:1024
	ds_read_b128 v[198:201], v144
	ds_read_b128 v[202:205], v144 offset:1024
	ds_read_b128 v[206:209], v143
	ds_read_b128 v[210:213], v143 offset:1024
	ds_read_b128 v[214:217], v142
	ds_read_b128 v[218:221], v142 offset:1024
	global_load_lds_dwordx4 v[174:175], off
	v_lshl_add_u64 v[174:175], v[134:135], 0, s[8:9]
	v_readfirstlane_b32 s12, v157
	v_lshl_add_u64 v[182:183], v[174:175], 0, s[90:91]
	s_mov_b32 m0, s12
	s_nop 0
	global_load_lds_dwordx4 v[182:183], off
	s_waitcnt lgkmcnt(8)
	s_barrier
	s_waitcnt lgkmcnt(0)
	v_mfma_f32_16x16x32_bf16 v[126:129], v[158:161], v[190:193], v[126:129]
	v_mfma_f32_16x16x32_bf16 v[122:125], v[170:173], v[190:193], v[122:125]
	v_mfma_f32_16x16x32_bf16 v[118:121], v[158:161], v[198:201], v[118:121]
	v_mfma_f32_16x16x32_bf16 v[114:117], v[170:173], v[198:201], v[114:117]
	v_mfma_f32_16x16x32_bf16 v[110:113], v[158:161], v[206:209], v[110:113]
	v_mfma_f32_16x16x32_bf16 v[106:109], v[170:173], v[206:209], v[106:109]
	v_mfma_f32_16x16x32_bf16 v[102:105], v[158:161], v[214:217], v[102:105]
	v_mfma_f32_16x16x32_bf16 v[98:101], v[170:173], v[214:217], v[98:101]
	v_mfma_f32_16x16x32_bf16 v[126:129], v[166:169], v[194:197], v[126:129]
	v_mfma_f32_16x16x32_bf16 v[122:125], v[186:189], v[194:197], v[122:125]
	v_mfma_f32_16x16x32_bf16 v[118:121], v[166:169], v[202:205], v[118:121]
	v_mfma_f32_16x16x32_bf16 v[114:117], v[186:189], v[202:205], v[114:117]
	v_mfma_f32_16x16x32_bf16 v[110:113], v[166:169], v[210:213], v[110:113]
	v_mfma_f32_16x16x32_bf16 v[106:109], v[186:189], v[210:213], v[106:109]
	v_mfma_f32_16x16x32_bf16 v[102:105], v[166:169], v[218:221], v[102:105]
	v_mfma_f32_16x16x32_bf16 v[98:101], v[186:189], v[218:221], v[98:101]
	s_barrier
	v_add_u32_e32 v176, s33, v146
	v_lshl_add_u64 v[182:183], v[136:137], 0, s[8:9]
	v_readfirstlane_b32 s12, v176
	v_lshl_add_u64 v[238:239], v[182:183], 0, s[24:25]
	s_mov_b32 m0, s12
	v_add_u32_e32 v176, 0x2000, v176
	ds_read_b128 v[222:225], v154
	ds_read_b128 v[226:229], v154 offset:1024
	ds_read_b128 v[230:233], v154 offset:2048
	ds_read_b128 v[234:237], v154 offset:3072
	global_load_lds_dwordx4 v[238:239], off
	v_lshl_add_u64 v[238:239], v[138:139], 0, s[8:9]
	v_readfirstlane_b32 s12, v176
	v_lshl_add_u64 v[240:241], v[238:239], 0, s[24:25]
	s_mov_b32 m0, s12
	s_add_i32 s11, s11, 2
	global_load_lds_dwordx4 v[240:241], off
	s_barrier
	s_waitcnt lgkmcnt(0)
	v_mfma_f32_16x16x32_bf16 v[94:97], v[222:225], v[190:193], v[94:97]
	v_mfma_f32_16x16x32_bf16 v[90:93], v[230:233], v[190:193], v[90:93]
	v_mfma_f32_16x16x32_bf16 v[86:89], v[222:225], v[198:201], v[86:89]
	v_mfma_f32_16x16x32_bf16 v[82:85], v[230:233], v[198:201], v[82:85]
	v_mfma_f32_16x16x32_bf16 v[78:81], v[222:225], v[206:209], v[78:81]
	v_mfma_f32_16x16x32_bf16 v[74:77], v[230:233], v[206:209], v[74:77]
	v_mfma_f32_16x16x32_bf16 v[70:73], v[222:225], v[214:217], v[70:73]
	v_mfma_f32_16x16x32_bf16 v[66:69], v[230:233], v[214:217], v[66:69]
	v_mfma_f32_16x16x32_bf16 v[94:97], v[226:229], v[194:197], v[94:97]
	v_mfma_f32_16x16x32_bf16 v[90:93], v[234:237], v[194:197], v[90:93]
	v_mfma_f32_16x16x32_bf16 v[86:89], v[226:229], v[202:205], v[86:89]
	v_mfma_f32_16x16x32_bf16 v[82:85], v[234:237], v[202:205], v[82:85]
	v_mfma_f32_16x16x32_bf16 v[78:81], v[226:229], v[210:213], v[78:81]
	v_mfma_f32_16x16x32_bf16 v[74:77], v[234:237], v[210:213], v[74:77]
	v_mfma_f32_16x16x32_bf16 v[70:73], v[226:229], v[218:221], v[70:73]
	v_mfma_f32_16x16x32_bf16 v[66:69], v[234:237], v[218:221], v[66:69]
	s_barrier
	v_readfirstlane_b32 s12, v150
	v_add_u32_e32 v176, 0x2000, v150
	v_lshl_add_u64 v[240:241], v[162:163], 0, s[0:1]
	s_mov_b32 m0, s12
	v_readfirstlane_b32 s12, v176
	ds_read_b128 v[190:193], v145 offset:16384
	ds_read_b128 v[194:197], v145 offset:17408
	ds_read_b128 v[198:201], v144 offset:16384
	ds_read_b128 v[202:205], v144 offset:17408
	ds_read_b128 v[206:209], v143 offset:16384
	ds_read_b128 v[210:213], v143 offset:17408
	ds_read_b128 v[214:217], v142 offset:16384
	ds_read_b128 v[218:221], v142 offset:17408
	global_load_lds_dwordx4 v[240:241], off
	v_lshl_add_u64 v[240:241], v[174:175], 0, s[0:1]
	s_mov_b32 m0, s12
	s_nop 0
	global_load_lds_dwordx4 v[240:241], off
	s_barrier
	s_waitcnt lgkmcnt(0)
	v_mfma_f32_16x16x32_bf16 v[62:65], v[158:161], v[190:193], v[62:65]
	v_mfma_f32_16x16x32_bf16 v[58:61], v[170:173], v[190:193], v[58:61]
	v_mfma_f32_16x16x32_bf16 v[54:57], v[158:161], v[198:201], v[54:57]
	v_mfma_f32_16x16x32_bf16 v[50:53], v[170:173], v[198:201], v[50:53]
	v_mfma_f32_16x16x32_bf16 v[46:49], v[158:161], v[206:209], v[46:49]
	v_mfma_f32_16x16x32_bf16 v[42:45], v[170:173], v[206:209], v[42:45]
	v_mfma_f32_16x16x32_bf16 v[38:41], v[158:161], v[214:217], v[38:41]
	v_mfma_f32_16x16x32_bf16 v[34:37], v[170:173], v[214:217], v[34:37]
	v_mfma_f32_16x16x32_bf16 v[62:65], v[166:169], v[194:197], v[62:65]
	v_mfma_f32_16x16x32_bf16 v[58:61], v[186:189], v[194:197], v[58:61]
	v_mfma_f32_16x16x32_bf16 v[54:57], v[166:169], v[202:205], v[54:57]
	v_mfma_f32_16x16x32_bf16 v[50:53], v[186:189], v[202:205], v[50:53]
	v_mfma_f32_16x16x32_bf16 v[46:49], v[166:169], v[210:213], v[46:49]
	v_mfma_f32_16x16x32_bf16 v[42:45], v[186:189], v[210:213], v[42:45]
	v_mfma_f32_16x16x32_bf16 v[38:41], v[166:169], v[218:221], v[38:41]
	v_mfma_f32_16x16x32_bf16 v[34:37], v[186:189], v[218:221], v[34:37]
	s_barrier
; #define STAGE_A(P,br,kt) STAGE_G(P,c.A,c.lda,br,(long)(kt)*c.kstr)
; #define STAGE_B(P,br,kt) STAGE_G(P,c.Bt,c.K,br,(long)(kt)*BK)
; #define LDA(dst,b,h) for(int m=0;m<4;++m)for(int k=0;k<2;++k) \
;     dst[m][k]=*reinterpret_cast<const bf16x8*>((char*)SA(b,h)+lds_byte(wr*64+m*16+fr,k*32+fq*8))
; #define LDB(dst,b,h) for(int n=0;n<2;++n)for(int k=0;k<2;++k) \
;     dst[n][k]=*reinterpret_cast<const bf16x8*>((char*)SB(b,h)+lds_byte(wc*32+n*16+fr,k*32+fq*8))
; #define MMA(ai,bj,At,Bt_) do{__builtin_amdgcn_s_setprio(1); \
;     for(int m=0;m<4;++m)for(int n=0;n<2;++n)for(int k=0;k<2;++k) \
;       acc[ai][bj][m][n]=__builtin_amdgcn_mfma_f32_16x16x32_bf16(Bt_[n][k],At[m][k],acc[ai][bj][m][n],0,0,0); \
;     __builtin_amdgcn_s_setprio(0);}while(0)
; #define WAIT_V(n) asm volatile("s_waitcnt vmcnt(" #n ")":::"memory")
; #define WAIT_L(n) asm volatile("s_waitcnt lgkmcnt(" #n ")":::"memory")
; #define BAR __builtin_amdgcn_s_barrier()
; #define SCHED __builtin_amdgcn_sched_barrier(0)
; template <int EPI>
; __device__ __forceinline__ void gemm_run(const GD& c, const bool has_next, const GD& nx, const Ctx& e, bf16* shm, float* rs, float* rs_nxt, float* racc_) {
;     ...
;     STAGE_B(SB(0,1),bcol+HALF,t+2);
;     WAIT_V(6); BAR; MMA(1,1,At,B1); BAR;
;     LDB(B0,1,0); SCHED; LDA(At,1,0); STAGE_A(SA(0,1),brow+HALF,t+2);
;     WAIT_L(8); BAR; WAIT_L(0); MMA(0,0,At,B0); BAR; SCHED;
;     LDB(B1,1,1); STAGE_B(SB(1,0),bcol,t+3);
;     BAR; WAIT_L(0); MMA(0,1,At,B1); BAR;
;     LDA(At,1,1); STAGE_A(SA(1,0),brow,t+3);
	v_add_u32_e32 v160, s86, v146
	v_lshl_add_u64 v[158:159], v[182:183], 0, s[26:27]
	v_readfirstlane_b32 s12, v160
	v_add_u32_e32 v160, 0x2000, v160
	s_mov_b32 m0, s12
	v_readfirstlane_b32 s12, v160
	global_load_lds_dwordx4 v[158:159], off
	v_lshl_add_u64 v[158:159], v[238:239], 0, s[26:27]
	s_mov_b32 m0, s12
	s_nop 0
	global_load_lds_dwordx4 v[158:159], off
	s_waitcnt vmcnt(6)
	s_barrier
	v_mfma_f32_16x16x32_bf16 v[30:33], v[222:225], v[190:193], v[30:33]
	v_mfma_f32_16x16x32_bf16 v[26:29], v[230:233], v[190:193], v[26:29]
	v_mfma_f32_16x16x32_bf16 v[22:25], v[222:225], v[198:201], v[22:25]
	v_mfma_f32_16x16x32_bf16 v[18:21], v[230:233], v[198:201], v[18:21]
	v_mfma_f32_16x16x32_bf16 v[14:17], v[222:225], v[206:209], v[14:17]
	v_mfma_f32_16x16x32_bf16 v[10:13], v[230:233], v[206:209], v[10:13]
	v_mfma_f32_16x16x32_bf16 v[6:9], v[222:225], v[214:217], v[6:9]
	v_mfma_f32_16x16x32_bf16 v[2:5], v[230:233], v[214:217], v[2:5]
	v_mfma_f32_16x16x32_bf16 v[30:33], v[226:229], v[194:197], v[30:33]
	v_mfma_f32_16x16x32_bf16 v[26:29], v[234:237], v[194:197], v[26:29]
	v_mfma_f32_16x16x32_bf16 v[22:25], v[226:229], v[202:205], v[22:25]
	v_mfma_f32_16x16x32_bf16 v[18:21], v[234:237], v[202:205], v[18:21]
	v_mfma_f32_16x16x32_bf16 v[14:17], v[226:229], v[210:213], v[14:17]
	v_mfma_f32_16x16x32_bf16 v[10:13], v[234:237], v[210:213], v[10:13]
	v_mfma_f32_16x16x32_bf16 v[6:9], v[226:229], v[218:221], v[6:9]
	v_mfma_f32_16x16x32_bf16 v[2:5], v[234:237], v[218:221], v[2:5]
	s_barrier
	ds_read_b128 v[158:161], v149
	ds_read_b128 v[166:169], v149 offset:1024
	ds_read_b128 v[170:173], v149 offset:2048
	ds_read_b128 v[186:189], v149 offset:3072
	v_add_u32_e32 v176, 0x4000, v150
	v_lshl_add_u64 v[222:223], v[162:163], 0, s[76:77]
	v_readfirstlane_b32 s12, v176
	v_add_u32_e32 v176, 0x6000, v150
	s_mov_b32 m0, s12
	v_readfirstlane_b32 s12, v176
	ds_read_b128 v[190:193], v145 offset:32768
	ds_read_b128 v[194:197], v145 offset:33792
	ds_read_b128 v[198:201], v144 offset:32768
	ds_read_b128 v[202:205], v144 offset:33792
	ds_read_b128 v[206:209], v143 offset:32768
	ds_read_b128 v[210:213], v143 offset:33792
	ds_read_b128 v[214:217], v142 offset:32768
	ds_read_b128 v[218:221], v142 offset:33792
	global_load_lds_dwordx4 v[222:223], off
	v_lshl_add_u64 v[222:223], v[174:175], 0, s[76:77]
	s_mov_b32 m0, s12
	s_nop 0
	global_load_lds_dwordx4 v[222:223], off
	s_waitcnt lgkmcnt(8)
	s_barrier
	s_waitcnt lgkmcnt(0)
	v_mfma_f32_16x16x32_bf16 v[126:129], v[158:161], v[190:193], v[126:129]
	v_mfma_f32_16x16x32_bf16 v[122:125], v[170:173], v[190:193], v[122:125]
	v_mfma_f32_16x16x32_bf16 v[118:121], v[158:161], v[198:201], v[118:121]
	v_mfma_f32_16x16x32_bf16 v[114:117], v[170:173], v[198:201], v[114:117]
	v_mfma_f32_16x16x32_bf16 v[110:113], v[158:161], v[206:209], v[110:113]
	v_mfma_f32_16x16x32_bf16 v[106:109], v[170:173], v[206:209], v[106:109]
	v_mfma_f32_16x16x32_bf16 v[102:105], v[158:161], v[214:217], v[102:105]
	v_mfma_f32_16x16x32_bf16 v[98:101], v[170:173], v[214:217], v[98:101]
	v_mfma_f32_16x16x32_bf16 v[126:129], v[166:169], v[194:197], v[126:129]
	v_mfma_f32_16x16x32_bf16 v[122:125], v[186:189], v[194:197], v[122:125]
	v_mfma_f32_16x16x32_bf16 v[118:121], v[166:169], v[202:205], v[118:121]
	v_mfma_f32_16x16x32_bf16 v[114:117], v[186:189], v[202:205], v[114:117]
	v_mfma_f32_16x16x32_bf16 v[110:113], v[166:169], v[210:213], v[110:113]
	v_mfma_f32_16x16x32_bf16 v[106:109], v[186:189], v[210:213], v[106:109]
	v_mfma_f32_16x16x32_bf16 v[102:105], v[166:169], v[218:221], v[102:105]
	v_mfma_f32_16x16x32_bf16 v[98:101], v[186:189], v[218:221], v[98:101]
	s_barrier
	v_readfirstlane_b32 s12, v148
	v_add_u32_e32 v176, 0x2000, v148
	v_lshl_add_u64 v[240:241], v[182:183], 0, s[28:29]
	s_mov_b32 m0, s12
	v_readfirstlane_b32 s12, v176
	ds_read_b128 v[222:225], v147
	ds_read_b128 v[226:229], v147 offset:1024
	ds_read_b128 v[230:233], v147 offset:2048
	ds_read_b128 v[234:237], v147 offset:3072
	global_load_lds_dwordx4 v[240:241], off
	v_lshl_add_u64 v[240:241], v[238:239], 0, s[28:29]
	s_mov_b32 m0, s12
	s_nop 0
	global_load_lds_dwordx4 v[240:241], off
	s_barrier
	s_waitcnt lgkmcnt(0)
	v_mfma_f32_16x16x32_bf16 v[94:97], v[222:225], v[190:193], v[94:97]
	v_mfma_f32_16x16x32_bf16 v[90:93], v[230:233], v[190:193], v[90:93]
	v_mfma_f32_16x16x32_bf16 v[86:89], v[222:225], v[198:201], v[86:89]
	v_mfma_f32_16x16x32_bf16 v[82:85], v[230:233], v[198:201], v[82:85]
	v_mfma_f32_16x16x32_bf16 v[78:81], v[222:225], v[206:209], v[78:81]
	v_mfma_f32_16x16x32_bf16 v[74:77], v[230:233], v[206:209], v[74:77]
	v_mfma_f32_16x16x32_bf16 v[70:73], v[222:225], v[214:217], v[70:73]
	v_mfma_f32_16x16x32_bf16 v[66:69], v[230:233], v[214:217], v[66:69]
	v_mfma_f32_16x16x32_bf16 v[94:97], v[226:229], v[194:197], v[94:97]
	v_mfma_f32_16x16x32_bf16 v[90:93], v[234:237], v[194:197], v[90:93]
	v_mfma_f32_16x16x32_bf16 v[86:89], v[226:229], v[202:205], v[86:89]
	v_mfma_f32_16x16x32_bf16 v[82:85], v[234:237], v[202:205], v[82:85]
	v_mfma_f32_16x16x32_bf16 v[78:81], v[226:229], v[210:213], v[78:81]
	v_mfma_f32_16x16x32_bf16 v[74:77], v[234:237], v[210:213], v[74:77]
	v_mfma_f32_16x16x32_bf16 v[70:73], v[226:229], v[218:221], v[70:73]
	v_mfma_f32_16x16x32_bf16 v[66:69], v[234:237], v[218:221], v[66:69]
	s_barrier
	v_readfirstlane_b32 s12, v151
	v_lshl_add_u64 v[162:163], v[162:163], 0, s[74:75]
	s_mov_b32 m0, s12
	v_readfirstlane_b32 s12, v152
	ds_read_b128 v[190:193], v145 offset:49152
	ds_read_b128 v[194:197], v145 offset:50176
	ds_read_b128 v[198:201], v144 offset:49152
	ds_read_b128 v[202:205], v144 offset:50176
	ds_read_b128 v[206:209], v143 offset:49152
	ds_read_b128 v[210:213], v143 offset:50176
	ds_read_b128 v[214:217], v142 offset:49152
	ds_read_b128 v[218:221], v142 offset:50176
	global_load_lds_dwordx4 v[162:163], off
	v_lshl_add_u64 v[162:163], v[174:175], 0, s[74:75]
	s_mov_b32 m0, s12
	s_nop 0
	global_load_lds_dwordx4 v[162:163], off
	s_barrier
; #define STAGE_A(P,br,kt) STAGE_G(P,c.A,c.lda,br,(long)(kt)*c.kstr)
; #define STAGE_B(P,br,kt) STAGE_G(P,c.Bt,c.K,br,(long)(kt)*BK)
; #define LDA(dst,b,h) for(int m=0;m<4;++m)for(int k=0;k<2;++k) \
;     dst[m][k]=*reinterpret_cast<const bf16x8*>((char*)SA(b,h)+lds_byte(wr*64+m*16+fr,k*32+fq*8))
; #define LDB(dst,b,h) for(int n=0;n<2;++n)for(int k=0;k<2;++k) \
;     dst[n][k]=*reinterpret_cast<const bf16x8*>((char*)SB(b,h)+lds_byte(wc*32+n*16+fr,k*32+fq*8))
; #define MMA(ai,bj,At,Bt_) do{__builtin_amdgcn_s_setprio(1); \
;     for(int m=0;m<4;++m)for(int n=0;n<2;++n)for(int k=0;k<2;++k) \
;       acc[ai][bj][m][n]=__builtin_amdgcn_mfma_f32_16x16x32_bf16(Bt_[n][k],At[m][k],acc[ai][bj][m][n],0,0,0); \
;     __builtin_amdgcn_s_setprio(0);}while(0)
; #define WAIT_V(n) asm volatile("s_waitcnt vmcnt(" #n ")":::"memory")
; #define WAIT_L(n) asm volatile("s_waitcnt lgkmcnt(" #n ")":::"memory")
; #define BAR __builtin_amdgcn_s_barrier()
; #define SCHED __builtin_amdgcn_sched_barrier(0)
; template <int EPI>
; __device__ __forceinline__ void gemm_run(const GD& c, const bool has_next, const GD& nx, const Ctx& e, bf16* shm, float* rs, float* rs_nxt, float* racc_) {
;     ...
;     BAR; WAIT_L(0); MMA(1,0,At,B0); BAR; SCHED;
;     STAGE_B(SB(1,1),bcol+HALF,t+3);
;     WAIT_V(6); BAR; MMA(1,1,At,B1); BAR;
;   }
;   { LDB(B0,0,0); LDA(At,0,0); STAGE_A(SA(1,1),brow+HALF,nt-1);
;     BAR; WAIT_L(0); MMA(0,0,At,B0); BAR;
	s_waitcnt lgkmcnt(0)
	v_mfma_f32_16x16x32_bf16 v[62:65], v[158:161], v[190:193], v[62:65]
	v_mfma_f32_16x16x32_bf16 v[58:61], v[170:173], v[190:193], v[58:61]
	v_mfma_f32_16x16x32_bf16 v[54:57], v[158:161], v[198:201], v[54:57]
	v_mfma_f32_16x16x32_bf16 v[50:53], v[170:173], v[198:201], v[50:53]
	v_mfma_f32_16x16x32_bf16 v[46:49], v[158:161], v[206:209], v[46:49]
	v_mfma_f32_16x16x32_bf16 v[42:45], v[170:173], v[206:209], v[42:45]
	v_mfma_f32_16x16x32_bf16 v[38:41], v[158:161], v[214:217], v[38:41]
	v_mfma_f32_16x16x32_bf16 v[34:37], v[170:173], v[214:217], v[34:37]
	v_mfma_f32_16x16x32_bf16 v[62:65], v[166:169], v[194:197], v[62:65]
	v_mfma_f32_16x16x32_bf16 v[58:61], v[186:189], v[194:197], v[58:61]
	v_mfma_f32_16x16x32_bf16 v[54:57], v[166:169], v[202:205], v[54:57]
	v_mfma_f32_16x16x32_bf16 v[50:53], v[186:189], v[202:205], v[50:53]
	v_mfma_f32_16x16x32_bf16 v[46:49], v[166:169], v[210:213], v[46:49]
	v_mfma_f32_16x16x32_bf16 v[42:45], v[186:189], v[210:213], v[42:45]
	v_mfma_f32_16x16x32_bf16 v[38:41], v[166:169], v[218:221], v[38:41]
	v_mfma_f32_16x16x32_bf16 v[34:37], v[186:189], v[218:221], v[34:37]
	s_barrier
	v_readfirstlane_b32 s12, v153
	v_add_u32_e32 v160, 0x2000, v153
	v_lshl_add_u64 v[158:159], v[182:183], 0, s[30:31]
	s_mov_b32 m0, s12
	v_readfirstlane_b32 s12, v160
	global_load_lds_dwordx4 v[158:159], off
	v_lshl_add_u64 v[158:159], v[238:239], 0, s[30:31]
	s_mov_b32 m0, s12
	s_nop 0
	global_load_lds_dwordx4 v[158:159], off
	s_waitcnt vmcnt(6)
	s_barrier
	v_mfma_f32_16x16x32_bf16 v[30:33], v[222:225], v[190:193], v[30:33]
	v_mfma_f32_16x16x32_bf16 v[26:29], v[230:233], v[190:193], v[26:29]
	v_mfma_f32_16x16x32_bf16 v[22:25], v[222:225], v[198:201], v[22:25]
	v_mfma_f32_16x16x32_bf16 v[18:21], v[230:233], v[198:201], v[18:21]
	v_lshl_add_u64 v[132:133], v[132:133], 0, s[88:89]
	v_mfma_f32_16x16x32_bf16 v[14:17], v[222:225], v[206:209], v[14:17]
	v_lshl_add_u64 v[134:135], v[134:135], 0, s[88:89]
	v_mfma_f32_16x16x32_bf16 v[10:13], v[230:233], v[206:209], v[10:13]
	v_lshl_add_u64 v[136:137], v[136:137], 0, s[88:89]
	v_mfma_f32_16x16x32_bf16 v[6:9], v[222:225], v[214:217], v[6:9]
	s_cmp_lt_u32 s11, s10
	v_mfma_f32_16x16x32_bf16 v[2:5], v[230:233], v[214:217], v[2:5]
	v_lshl_add_u64 v[138:139], v[138:139], 0, s[88:89]
	v_mfma_f32_16x16x32_bf16 v[30:33], v[226:229], v[194:197], v[30:33]
	v_mfma_f32_16x16x32_bf16 v[26:29], v[234:237], v[194:197], v[26:29]
	v_mfma_f32_16x16x32_bf16 v[22:25], v[226:229], v[202:205], v[22:25]
	v_mfma_f32_16x16x32_bf16 v[18:21], v[234:237], v[202:205], v[18:21]
	v_mfma_f32_16x16x32_bf16 v[14:17], v[226:229], v[210:213], v[14:17]
	v_mfma_f32_16x16x32_bf16 v[10:13], v[234:237], v[210:213], v[10:13]
	v_mfma_f32_16x16x32_bf16 v[6:9], v[226:229], v[218:221], v[6:9]
	v_mfma_f32_16x16x32_bf16 v[2:5], v[234:237], v[218:221], v[2:5]
	s_barrier
	s_cbranch_scc1 .LBB0_1505
	s_lshl_b32 s7, s7, 7
	s_add_u32 s2, s2, s7
	s_addc_u32 s3, s3, 0
	s_movk_i32 s8, 0xff80
	v_lshl_add_u64 v[162:163], s[2:3], 0, v[0:1]
	s_mov_b32 s9, -1
	v_readfirstlane_b32 s7, v156
	v_lshl_add_u64 v[162:163], v[162:163], 0, s[8:9]
	s_mov_b32 m0, s7
	v_lshl_add_u64 v[130:131], s[2:3], 0, v[130:131]
	v_readfirstlane_b32 s2, v157
	ds_read_b128 v[132:135], v155
	ds_read_b128 v[136:139], v155 offset:1024
	ds_read_b128 v[150:153], v155 offset:2048
	ds_read_b128 v[158:161], v155 offset:3072
	ds_read_b128 v[166:169], v145
	ds_read_b128 v[170:173], v145 offset:1024
	ds_read_b128 v[186:189], v144
	ds_read_b128 v[190:193], v144 offset:1024
	ds_read_b128 v[194:197], v143
	ds_read_b128 v[198:201], v143 offset:1024
	ds_read_b128 v[202:205], v142
	ds_read_b128 v[206:209], v142 offset:1024
	global_load_lds_dwordx4 v[162:163], off
	v_lshl_add_u64 v[130:131], v[130:131], 0, s[8:9]
	s_mov_b32 m0, s2
	s_nop 0
	global_load_lds_dwordx4 v[130:131], off
	s_barrier
	s_waitcnt lgkmcnt(0)
	v_mfma_f32_16x16x32_bf16 v[126:129], v[132:135], v[166:169], v[126:129]
	v_mfma_f32_16x16x32_bf16 v[122:125], v[150:153], v[166:169], v[122:125]
	v_mfma_f32_16x16x32_bf16 v[118:121], v[132:135], v[186:189], v[118:121]
	v_mfma_f32_16x16x32_bf16 v[114:117], v[150:153], v[186:189], v[114:117]
	v_mfma_f32_16x16x32_bf16 v[110:113], v[132:135], v[194:197], v[110:113]
	v_mfma_f32_16x16x32_bf16 v[106:109], v[150:153], v[194:197], v[106:109]
	v_mfma_f32_16x16x32_bf16 v[102:105], v[132:135], v[202:205], v[102:105]
	v_mfma_f32_16x16x32_bf16 v[98:101], v[150:153], v[202:205], v[98:101]
	v_mfma_f32_16x16x32_bf16 v[126:129], v[136:139], v[170:173], v[126:129]
	v_mfma_f32_16x16x32_bf16 v[122:125], v[158:161], v[170:173], v[122:125]
	v_mfma_f32_16x16x32_bf16 v[118:121], v[136:139], v[190:193], v[118:121]
	v_mfma_f32_16x16x32_bf16 v[114:117], v[158:161], v[190:193], v[114:117]
	v_mfma_f32_16x16x32_bf16 v[110:113], v[136:139], v[198:201], v[110:113]
	v_mfma_f32_16x16x32_bf16 v[106:109], v[158:161], v[198:201], v[106:109]
	v_mfma_f32_16x16x32_bf16 v[102:105], v[136:139], v[206:209], v[102:105]
	v_mfma_f32_16x16x32_bf16 v[98:101], v[158:161], v[206:209], v[98:101]
	s_barrier
	ds_read_b128 v[210:213], v154
	ds_read_b128 v[214:217], v154 offset:1024
	ds_read_b128 v[218:221], v154 offset:2048
	ds_read_b128 v[154:157], v154 offset:3072
	s_barrier
; #define LDA(dst,b,h) for(int m=0;m<4;++m)for(int k=0;k<2;++k) \
;     dst[m][k]=*reinterpret_cast<const bf16x8*>((char*)SA(b,h)+lds_byte(wr*64+m*16+fr,k*32+fq*8))
; #define LDB(dst,b,h) for(int n=0;n<2;++n)for(int k=0;k<2;++k) \
;     dst[n][k]=*reinterpret_cast<const bf16x8*>((char*)SB(b,h)+lds_byte(wc*32+n*16+fr,k*32+fq*8))
; #define MMA(ai,bj,At,Bt_) do{__builtin_amdgcn_s_setprio(1); \
;     for(int m=0;m<4;++m)for(int n=0;n<2;++n)for(int k=0;k<2;++k) \
;       acc[ai][bj][m][n]=__builtin_amdgcn_mfma_f32_16x16x32_bf16(Bt_[n][k],At[m][k],acc[ai][bj][m][n],0,0,0); \
;     __builtin_amdgcn_s_setprio(0);}while(0)
; #define WAIT_V(n) asm volatile("s_waitcnt vmcnt(" #n ")":::"memory")
; #define WAIT_L(n) asm volatile("s_waitcnt lgkmcnt(" #n ")":::"memory")
; #define BAR __builtin_amdgcn_s_barrier()
; template <int EPI>
; __device__ __forceinline__ void gemm_run(const GD& c, const bool has_next, const GD& nx, const Ctx& e, bf16* shm, float* rs, float* rs_nxt, float* racc_) {
;     ...
;     LDB(B1,0,1); BAR; WAIT_L(0); MMA(0,1,At,B1); BAR;
;     LDA(At,0,1); WAIT_V(4); BAR; WAIT_L(0); MMA(1,0,At,B0); MMA(1,1,At,B1); BAR; }
;   { LDB(B0,1,0); LDA(At,1,0); WAIT_V(2); BAR; WAIT_L(0); MMA(0,0,At,B0); BAR;
	s_waitcnt lgkmcnt(0)
	v_mfma_f32_16x16x32_bf16 v[94:97], v[210:213], v[166:169], v[94:97]
	v_mfma_f32_16x16x32_bf16 v[90:93], v[218:221], v[166:169], v[90:93]
	v_mfma_f32_16x16x32_bf16 v[86:89], v[210:213], v[186:189], v[86:89]
	v_mfma_f32_16x16x32_bf16 v[82:85], v[218:221], v[186:189], v[82:85]
	v_mfma_f32_16x16x32_bf16 v[74:77], v[218:221], v[194:197], v[74:77]
	v_mfma_f32_16x16x32_bf16 v[70:73], v[210:213], v[202:205], v[70:73]
	v_mfma_f32_16x16x32_bf16 v[94:97], v[214:217], v[170:173], v[94:97]
	v_mfma_f32_16x16x32_bf16 v[90:93], v[154:157], v[170:173], v[90:93]
	v_mfma_f32_16x16x32_bf16 v[86:89], v[214:217], v[190:193], v[86:89]
	v_mfma_f32_16x16x32_bf16 v[82:85], v[154:157], v[190:193], v[82:85]
	v_mfma_f32_16x16x32_bf16 v[78:81], v[210:213], v[194:197], v[78:81]
	v_mfma_f32_16x16x32_bf16 v[74:77], v[154:157], v[198:201], v[74:77]
	v_mfma_f32_16x16x32_bf16 v[70:73], v[214:217], v[206:209], v[70:73]
	v_mfma_f32_16x16x32_bf16 v[66:69], v[218:221], v[202:205], v[66:69]
	v_mfma_f32_16x16x32_bf16 v[166:169], v[214:217], v[198:201], v[78:81]
	v_mfma_f32_16x16x32_bf16 v[170:173], v[154:157], v[206:209], v[66:69]
	s_barrier
	s_nop 3
	ds_read_b128 v[66:69], v145 offset:16384
	ds_read_b128 v[78:81], v145 offset:17408
	ds_read_b128 v[186:189], v144 offset:16384
	ds_read_b128 v[190:193], v144 offset:17408
	ds_read_b128 v[194:197], v143 offset:16384
	ds_read_b128 v[198:201], v143 offset:17408
	ds_read_b128 v[202:205], v142 offset:16384
	ds_read_b128 v[206:209], v142 offset:17408
	s_waitcnt vmcnt(4)
	s_barrier
	s_waitcnt lgkmcnt(0)
	v_mfma_f32_16x16x32_bf16 v[62:65], v[132:135], v[66:69], v[62:65]
	v_mfma_f32_16x16x32_bf16 v[54:57], v[132:135], v[186:189], v[54:57]
	v_mfma_f32_16x16x32_bf16 v[46:49], v[132:135], v[194:197], v[46:49]
	v_mfma_f32_16x16x32_bf16 v[38:41], v[132:135], v[202:205], v[38:41]
	v_mfma_f32_16x16x32_bf16 v[62:65], v[136:139], v[78:81], v[62:65]
	v_mfma_f32_16x16x32_bf16 v[58:61], v[150:153], v[66:69], v[58:61]
	v_mfma_f32_16x16x32_bf16 v[54:57], v[136:139], v[190:193], v[54:57]
	v_mfma_f32_16x16x32_bf16 v[50:53], v[150:153], v[186:189], v[50:53]
	v_mfma_f32_16x16x32_bf16 v[46:49], v[136:139], v[198:201], v[46:49]
	v_mfma_f32_16x16x32_bf16 v[42:45], v[150:153], v[194:197], v[42:45]
	v_mfma_f32_16x16x32_bf16 v[38:41], v[136:139], v[206:209], v[38:41]
	v_mfma_f32_16x16x32_bf16 v[34:37], v[150:153], v[202:205], v[34:37]
	v_mfma_f32_16x16x32_bf16 v[222:225], v[158:161], v[78:81], v[58:61]
	v_mfma_f32_16x16x32_bf16 v[226:229], v[158:161], v[190:193], v[50:53]
	v_mfma_f32_16x16x32_bf16 v[230:233], v[158:161], v[198:201], v[42:45]
	v_mfma_f32_16x16x32_bf16 v[130:133], v[158:161], v[206:209], v[34:37]
	v_mfma_f32_16x16x32_bf16 v[30:33], v[210:213], v[66:69], v[30:33]
	v_mfma_f32_16x16x32_bf16 v[26:29], v[218:221], v[66:69], v[26:29]
	v_mfma_f32_16x16x32_bf16 v[22:25], v[210:213], v[186:189], v[22:25]
	v_mfma_f32_16x16x32_bf16 v[18:21], v[218:221], v[186:189], v[18:21]
	v_mfma_f32_16x16x32_bf16 v[14:17], v[210:213], v[194:197], v[14:17]
	v_mfma_f32_16x16x32_bf16 v[10:13], v[218:221], v[194:197], v[10:13]
	v_mfma_f32_16x16x32_bf16 v[6:9], v[210:213], v[202:205], v[6:9]
	v_mfma_f32_16x16x32_bf16 v[2:5], v[218:221], v[202:205], v[2:5]
	v_mfma_f32_16x16x32_bf16 v[134:137], v[214:217], v[78:81], v[30:33]
	v_mfma_f32_16x16x32_bf16 v[150:153], v[154:157], v[78:81], v[26:29]
	v_mfma_f32_16x16x32_bf16 v[158:161], v[214:217], v[190:193], v[22:25]
	v_mfma_f32_16x16x32_bf16 v[186:189], v[154:157], v[190:193], v[18:21]
	v_mfma_f32_16x16x32_bf16 v[190:193], v[214:217], v[198:201], v[14:17]
	v_mfma_f32_16x16x32_bf16 v[194:197], v[154:157], v[198:201], v[10:13]
	v_mfma_f32_16x16x32_bf16 v[198:201], v[214:217], v[206:209], v[6:9]
	v_mfma_f32_16x16x32_bf16 v[154:157], v[154:157], v[206:209], v[2:5]
	s_barrier
	ds_read_b128 v[34:37], v149
	ds_read_b128 v[202:205], v149 offset:1024
	ds_read_b128 v[206:209], v149 offset:2048
	ds_read_b128 v[210:213], v149 offset:3072
	ds_read_b128 v[42:45], v145 offset:32768
	ds_read_b128 v[50:53], v145 offset:33792
	ds_read_b128 v[58:61], v144 offset:32768
	ds_read_b128 v[66:69], v144 offset:33792
	ds_read_b128 v[214:217], v143 offset:32768
	ds_read_b128 v[218:221], v143 offset:33792
	ds_read_b128 v[234:237], v142 offset:32768
	ds_read_b128 v[238:241], v142 offset:33792
	s_waitcnt vmcnt(2)
	s_barrier
; #define LDA(dst,b,h) for(int m=0;m<4;++m)for(int k=0;k<2;++k) \
;     dst[m][k]=*reinterpret_cast<const bf16x8*>((char*)SA(b,h)+lds_byte(wr*64+m*16+fr,k*32+fq*8))
; #define LDB(dst,b,h) for(int n=0;n<2;++n)for(int k=0;k<2;++k) \
;     dst[n][k]=*reinterpret_cast<const bf16x8*>((char*)SB(b,h)+lds_byte(wc*32+n*16+fr,k*32+fq*8))
; #define MMA(ai,bj,At,Bt_) do{__builtin_amdgcn_s_setprio(1); \
;     for(int m=0;m<4;++m)for(int n=0;n<2;++n)for(int k=0;k<2;++k) \
;       acc[ai][bj][m][n]=__builtin_amdgcn_mfma_f32_16x16x32_bf16(Bt_[n][k],At[m][k],acc[ai][bj][m][n],0,0,0); \
;     __builtin_amdgcn_s_setprio(0);}while(0)
; #define WAIT_V(n) asm volatile("s_waitcnt vmcnt(" #n ")":::"memory")
; #define WAIT_L(n) asm volatile("s_waitcnt lgkmcnt(" #n ")":::"memory")
; #define BAR __builtin_amdgcn_s_barrier()
; template <int EPI>
; __device__ __forceinline__ void gemm_run(const GD& c, const bool has_next, const GD& nx, const Ctx& e, bf16* shm, float* rs, float* rs_nxt, float* racc_) {
;     ...
;   { LDB(B0,1,0); LDA(At,1,0); WAIT_V(2); BAR; WAIT_L(0); MMA(0,0,At,B0); BAR;
;     LDB(B1,1,1); WAIT_V(0); BAR; WAIT_L(0); MMA(0,1,At,B1); BAR;
;     LDA(At,1,1); BAR; WAIT_L(0); MMA(1,0,At,B0); MMA(1,1,At,B1); BAR; }
;   if(wr==0)BAR;
	s_waitcnt lgkmcnt(0)
	v_mfma_f32_16x16x32_bf16 v[2:5], v[34:37], v[42:45], v[126:129]
	v_mfma_f32_16x16x32_bf16 v[26:29], v[202:205], v[50:53], v[2:5]
	v_mfma_f32_16x16x32_bf16 v[2:5], v[206:209], v[42:45], v[122:125]
	v_mfma_f32_16x16x32_bf16 v[30:33], v[210:213], v[50:53], v[2:5]
	v_mfma_f32_16x16x32_bf16 v[2:5], v[34:37], v[58:61], v[118:121]
	v_mfma_f32_16x16x32_bf16 v[18:21], v[202:205], v[66:69], v[2:5]
	v_mfma_f32_16x16x32_bf16 v[2:5], v[206:209], v[58:61], v[114:117]
	v_mfma_f32_16x16x32_bf16 v[22:25], v[210:213], v[66:69], v[2:5]
	v_mfma_f32_16x16x32_bf16 v[2:5], v[34:37], v[214:217], v[110:113]
	v_mfma_f32_16x16x32_bf16 v[10:13], v[202:205], v[218:221], v[2:5]
	v_mfma_f32_16x16x32_bf16 v[2:5], v[206:209], v[214:217], v[106:109]
	v_mfma_f32_16x16x32_bf16 v[14:17], v[210:213], v[218:221], v[2:5]
	v_mfma_f32_16x16x32_bf16 v[2:5], v[34:37], v[234:237], v[102:105]
	v_mfma_f32_16x16x32_bf16 v[6:9], v[206:209], v[234:237], v[98:101]
	v_mfma_f32_16x16x32_bf16 v[2:5], v[202:205], v[238:241], v[2:5]
	v_mfma_f32_16x16x32_bf16 v[6:9], v[210:213], v[238:241], v[6:9]
	s_barrier
	ds_read_b128 v[242:245], v147
	ds_read_b128 v[246:249], v147 offset:1024
	ds_read_b128 v[250:253], v147 offset:2048
	ds_read_b128 v[146:149], v147 offset:3072
	s_waitcnt vmcnt(0)
	s_barrier
	s_waitcnt lgkmcnt(0)
	v_mfma_f32_16x16x32_bf16 v[78:81], v[242:245], v[42:45], v[94:97]
	v_mfma_f32_16x16x32_bf16 v[42:45], v[250:253], v[42:45], v[90:93]
	v_mfma_f32_16x16x32_bf16 v[102:105], v[146:149], v[50:53], v[42:45]
	v_mfma_f32_16x16x32_bf16 v[42:45], v[242:245], v[58:61], v[86:89]
	v_mfma_f32_16x16x32_bf16 v[98:101], v[246:249], v[50:53], v[78:81]
	v_mfma_f32_16x16x32_bf16 v[78:81], v[246:249], v[66:69], v[42:45]
	v_mfma_f32_16x16x32_bf16 v[42:45], v[250:253], v[58:61], v[82:85]
	v_mfma_f32_16x16x32_bf16 v[86:89], v[146:149], v[66:69], v[42:45]
	v_mfma_f32_16x16x32_bf16 v[42:45], v[242:245], v[214:217], v[166:169]
	v_mfma_f32_16x16x32_bf16 v[58:61], v[246:249], v[218:221], v[42:45]
	v_mfma_f32_16x16x32_bf16 v[42:45], v[250:253], v[214:217], v[74:77]
	v_mfma_f32_16x16x32_bf16 v[66:69], v[146:149], v[218:221], v[42:45]
	v_mfma_f32_16x16x32_bf16 v[42:45], v[242:245], v[234:237], v[70:73]
	v_mfma_f32_16x16x32_bf16 v[50:53], v[250:253], v[234:237], v[170:173]
	v_mfma_f32_16x16x32_bf16 v[42:45], v[246:249], v[238:241], v[42:45]
	v_mfma_f32_16x16x32_bf16 v[50:53], v[146:149], v[238:241], v[50:53]
	s_barrier
	ds_read_b128 v[74:77], v145 offset:49152
	ds_read_b128 v[94:97], v145 offset:50176
	ds_read_b128 v[106:109], v144 offset:49152
	ds_read_b128 v[110:113], v144 offset:50176
	ds_read_b128 v[166:169], v143 offset:49152
	ds_read_b128 v[170:173], v143 offset:50176
	ds_read_b128 v[214:217], v142 offset:49152
	ds_read_b128 v[142:145], v142 offset:50176
	s_barrier
	s_waitcnt lgkmcnt(0)
	v_mfma_f32_16x16x32_bf16 v[62:65], v[34:37], v[74:77], v[62:65]
	v_mfma_f32_16x16x32_bf16 v[82:85], v[202:205], v[94:97], v[62:65]
	v_mfma_f32_16x16x32_bf16 v[62:65], v[206:209], v[74:77], v[222:225]
	v_mfma_f32_16x16x32_bf16 v[54:57], v[34:37], v[106:109], v[54:57]
	v_mfma_f32_16x16x32_bf16 v[90:93], v[210:213], v[94:97], v[62:65]
	v_mfma_f32_16x16x32_bf16 v[62:65], v[202:205], v[110:113], v[54:57]
	v_mfma_f32_16x16x32_bf16 v[54:57], v[206:209], v[106:109], v[226:229]
	v_mfma_f32_16x16x32_bf16 v[70:73], v[210:213], v[110:113], v[54:57]
	v_mfma_f32_16x16x32_bf16 v[46:49], v[34:37], v[166:169], v[46:49]
	v_mfma_f32_16x16x32_bf16 v[54:57], v[206:209], v[166:169], v[230:233]
	v_mfma_f32_16x16x32_bf16 v[34:37], v[34:37], v[214:217], v[38:41]
	v_mfma_f32_16x16x32_bf16 v[38:41], v[206:209], v[214:217], v[130:133]
	v_mfma_f32_16x16x32_bf16 v[46:49], v[202:205], v[170:173], v[46:49]
	v_mfma_f32_16x16x32_bf16 v[54:57], v[210:213], v[170:173], v[54:57]
	v_mfma_f32_16x16x32_bf16 v[34:37], v[202:205], v[142:145], v[34:37]
	v_mfma_f32_16x16x32_bf16 v[38:41], v[210:213], v[142:145], v[38:41]
	v_mfma_f32_16x16x32_bf16 v[114:117], v[242:245], v[74:77], v[134:137]
	v_mfma_f32_16x16x32_bf16 v[74:77], v[250:253], v[74:77], v[150:153]
	v_mfma_f32_16x16x32_bf16 v[126:129], v[146:149], v[94:97], v[74:77]
	v_mfma_f32_16x16x32_bf16 v[74:77], v[242:245], v[106:109], v[158:161]
	v_mfma_f32_16x16x32_bf16 v[122:125], v[246:249], v[94:97], v[114:117]
	v_mfma_f32_16x16x32_bf16 v[114:117], v[246:249], v[110:113], v[74:77]
	v_mfma_f32_16x16x32_bf16 v[74:77], v[250:253], v[106:109], v[186:189]
	v_mfma_f32_16x16x32_bf16 v[118:121], v[146:149], v[110:113], v[74:77]
	v_mfma_f32_16x16x32_bf16 v[74:77], v[242:245], v[166:169], v[190:193]
	v_mfma_f32_16x16x32_bf16 v[106:109], v[246:249], v[170:173], v[74:77]
	v_mfma_f32_16x16x32_bf16 v[74:77], v[250:253], v[166:169], v[194:197]
	v_mfma_f32_16x16x32_bf16 v[110:113], v[146:149], v[170:173], v[74:77]
	v_mfma_f32_16x16x32_bf16 v[74:77], v[242:245], v[214:217], v[198:201]
	v_mfma_f32_16x16x32_bf16 v[94:97], v[246:249], v[142:145], v[74:77]
	v_mfma_f32_16x16x32_bf16 v[74:77], v[250:253], v[214:217], v[154:157]
	v_mfma_f32_16x16x32_bf16 v[74:77], v[146:149], v[142:145], v[74:77]
	v_cmp_gt_u32_e32 vcc, s96, v141
	s_barrier
	s_and_saveexec_b64 s[2:3], vcc
	s_cbranch_execz .LBB0_1501
	s_barrier
	s_branch .LBB0_1501
